# GEMM K-loops: removed no-op s_setprio 0/1 pairs in the middle of each 32-MFMA run and the duplicate lgkmcnt(0) before the first MFMA (72 sites each)
# baseline (speedup 1.0000x reference)
; #define PG8_STAGE(bufoff, gbase, voff) do { _Pragma("unroll") for (int _i = 0; _i < 2; ++_i) \
;         __builtin_amdgcn_global_load_lds((const unsigned*)((const char*)(gbase) + (voff)[_i]), (PG8_LAS unsigned*)(lds + (bufoff) + ldsw + _i * 8192), 16, 0, 0); } while (0)
; #define PG8_LDA(dst, b, h) do { _Pragma("unroll") for (int m = 0; m < 4; ++m) _Pragma("unroll") for (int k = 0; k < 2; ++k) dst[m][k] = *(const PG8_LAS bf16x8*)(lds + PG8_SA(b, h) + aoff + m * 2048 + k * 1024); } while (0)
; #define PG8_LDB(dst, b, h) do { _Pragma("unroll") for (int n = 0; n < 2; ++n) _Pragma("unroll") for (int k = 0; k < 2; ++k) dst[n][k] = *(const PG8_LAS bf16x8*)(lds + PG8_SB(b, h) + boff + n * 2048 + k * 1024); } while (0)
; #define PG8_MMA(ai, bj, At, Bt) do { __builtin_amdgcn_s_setprio(1); _Pragma("unroll") for (int m = 0; m < 4; ++m) _Pragma("unroll") for (int n = 0; n < 2; ++n) _Pragma("unroll") for (int k = 0; k < 2; ++k) \
;         acc[ai][bj][m][n] = __builtin_amdgcn_mfma_f32_16x16x32_bf16(Bt[n][k], At[m][k], acc[ai][bj][m][n], 0, 0, 0); __builtin_amdgcn_s_setprio(0); } while (0)
; #define PG8_WAIT_V(n) asm volatile("s_waitcnt vmcnt(" #n ")" ::: "memory")
; #define PG8_WAIT_L(n) asm volatile("s_waitcnt lgkmcnt(" #n ")" ::: "memory")
; #define PG8_BAR __builtin_amdgcn_s_barrier()
; #define PG8_SCHED __builtin_amdgcn_sched_barrier(0)
; template <class Epi, class Sched, bool ALIGN_EPI = true, bool SP2 = true>
; __device__ __forceinline__ void gemm_phase(PG8_LAS unsigned char* lds, const Gemm g, const Sched& S, const Epi& E) {
;     ...
;             PG8_LDB(B0, 0, 0); PG8_LDB(B1, 0, 1); PG8_SCHED; PG8_LDA(At, 0, 0); PG8_STAGE(PG8_SA(1, 1), a1 + hstepA, voffA);
;             PG8_WAIT_V(8); PG8_WAIT_L(0); PG8_BAR; PG8_MMA(0, 0, At, B0); PG8_MMA(0, 1, At, B1); PG8_BAR; PG8_SCHED;
;             PG8_LDA(At, 0, 1); PG8_STAGE(PG8_SB(0, 0), b2, voffB); PG8_STAGE(PG8_SB(0, 1), b2 + hstepB, voffB); PG8_STAGE(PG8_SA(0, 0), a2, voffA);
;             PG8_WAIT_V(8); PG8_WAIT_L(0); PG8_BAR; PG8_MMA(1, 0, At, B0); PG8_MMA(1, 1, At, B1); PG8_BAR; PG8_SCHED;
.LBB0_132:
	ds_read_b128 v[150:153], v147
	ds_read_b128 v[154:157], v147 offset:1024
	ds_read_b128 v[158:161], v147 offset:2048
	ds_read_b128 v[162:165], v147 offset:3072
	ds_read_b128 v[166:169], v148
	ds_read_b128 v[170:173], v148 offset:1024
	ds_read_b128 v[174:177], v148 offset:2048
	ds_read_b128 v[178:181], v148 offset:3072
	s_add_u32 s24, s22, 0xfffc0080
	s_addc_u32 s25, s23, -1
	s_cmp_eq_u32 s58, 12
	s_cselect_b32 s27, s17, s25
	s_cselect_b32 s26, s50, s24
	s_cselect_b32 s25, s15, s57
	s_cselect_b32 s24, s51, s56
	v_lshl_add_u64 v[214:215], s[22:23], 0, v[138:139]
	s_add_i32 m0, s13, 0xc000
	ds_read_b128 v[182:185], v149
	ds_read_b128 v[186:189], v149 offset:1024
	ds_read_b128 v[190:193], v149 offset:2048
	ds_read_b128 v[194:197], v149 offset:3072
	ds_read_b128 v[198:201], v149 offset:4096
	ds_read_b128 v[202:205], v149 offset:5120
	ds_read_b128 v[206:209], v149 offset:6144
	ds_read_b128 v[210:213], v149 offset:7168
	global_load_lds_dwordx4 v[214:215], off
	v_lshl_add_u64 v[214:215], s[22:23], 0, v[136:137]
	s_add_i32 m0, s13, 0xe000
	s_nop 0
	global_load_lds_dwordx4 v[214:215], off
	s_waitcnt vmcnt(8)
	s_waitcnt lgkmcnt(0)
	s_barrier
	s_setprio 1
	v_mfma_f32_16x16x32_bf16 v[124:127], v[150:153], v[182:185], v[124:127]
	v_mfma_f32_16x16x32_bf16 v[120:123], v[158:161], v[182:185], v[120:123]
	v_mfma_f32_16x16x32_bf16 v[116:119], v[150:153], v[190:193], v[116:119]
	v_mfma_f32_16x16x32_bf16 v[112:115], v[158:161], v[190:193], v[112:115]
	v_mfma_f32_16x16x32_bf16 v[100:103], v[150:153], v[198:201], v[100:103]
	v_mfma_f32_16x16x32_bf16 v[96:99], v[158:161], v[198:201], v[96:99]
	v_mfma_f32_16x16x32_bf16 v[84:87], v[150:153], v[206:209], v[84:87]
	v_mfma_f32_16x16x32_bf16 v[80:83], v[158:161], v[206:209], v[80:83]
	v_mfma_f32_16x16x32_bf16 v[124:127], v[154:157], v[186:189], v[124:127]
	v_mfma_f32_16x16x32_bf16 v[120:123], v[162:165], v[186:189], v[120:123]
	v_mfma_f32_16x16x32_bf16 v[116:119], v[154:157], v[194:197], v[116:119]
	v_mfma_f32_16x16x32_bf16 v[112:115], v[162:165], v[194:197], v[112:115]
	v_mfma_f32_16x16x32_bf16 v[100:103], v[154:157], v[202:205], v[100:103]
	v_mfma_f32_16x16x32_bf16 v[96:99], v[162:165], v[202:205], v[96:99]
	v_mfma_f32_16x16x32_bf16 v[84:87], v[154:157], v[210:213], v[84:87]
	v_mfma_f32_16x16x32_bf16 v[80:83], v[162:165], v[210:213], v[80:83]
	v_mfma_f32_16x16x32_bf16 v[108:111], v[166:169], v[182:185], v[108:111]
	v_mfma_f32_16x16x32_bf16 v[104:107], v[174:177], v[182:185], v[104:107]
	v_mfma_f32_16x16x32_bf16 v[92:95], v[166:169], v[190:193], v[92:95]
	v_mfma_f32_16x16x32_bf16 v[88:91], v[174:177], v[190:193], v[88:91]
	v_mfma_f32_16x16x32_bf16 v[76:79], v[166:169], v[198:201], v[76:79]
	v_mfma_f32_16x16x32_bf16 v[72:75], v[174:177], v[198:201], v[72:75]
	v_mfma_f32_16x16x32_bf16 v[68:71], v[166:169], v[206:209], v[68:71]
	v_mfma_f32_16x16x32_bf16 v[64:67], v[174:177], v[206:209], v[64:67]
	v_mfma_f32_16x16x32_bf16 v[108:111], v[170:173], v[186:189], v[108:111]
	v_mfma_f32_16x16x32_bf16 v[104:107], v[178:181], v[186:189], v[104:107]
	v_mfma_f32_16x16x32_bf16 v[92:95], v[170:173], v[194:197], v[92:95]
	v_mfma_f32_16x16x32_bf16 v[88:91], v[178:181], v[194:197], v[88:91]
	v_mfma_f32_16x16x32_bf16 v[76:79], v[170:173], v[202:205], v[76:79]
	v_mfma_f32_16x16x32_bf16 v[72:75], v[178:181], v[202:205], v[72:75]
	v_mfma_f32_16x16x32_bf16 v[68:71], v[170:173], v[210:213], v[68:71]
	v_mfma_f32_16x16x32_bf16 v[64:67], v[178:181], v[210:213], v[64:67]
	s_setprio 0
	s_barrier
	s_add_i32 s52, s46, s31
	v_lshl_add_u64 v[214:215], s[24:25], 0, v[132:133]
	s_mov_b32 m0, s52
	ds_read_b128 v[182:185], v149 offset:16384
	ds_read_b128 v[186:189], v149 offset:17408
	ds_read_b128 v[190:193], v149 offset:18432
	ds_read_b128 v[194:197], v149 offset:19456
	ds_read_b128 v[198:201], v149 offset:20480
	ds_read_b128 v[202:205], v149 offset:21504
	ds_read_b128 v[206:209], v149 offset:22528
	ds_read_b128 v[210:213], v149 offset:23552
	global_load_lds_dwordx4 v[214:215], off
	s_add_i32 m0, s52, 0x2000
	s_add_u32 s60, s24, 0x40000
	v_lshl_add_u64 v[216:217], s[24:25], 0, v[128:129]
	s_addc_u32 s61, s25, 0
	s_add_i32 s52, s47, s31
	global_load_lds_dwordx4 v[216:217], off
	v_lshl_add_u64 v[218:219], s[60:61], 0, v[132:133]
	s_mov_b32 m0, s52
	v_lshl_add_u64 v[220:221], s[26:27], 0, v[130:131]
	global_load_lds_dwordx4 v[218:219], off
	v_lshl_add_u64 v[218:219], s[60:61], 0, v[128:129]
	s_add_i32 m0, s52, 0x2000
	s_nop 0
	global_load_lds_dwordx4 v[218:219], off
	v_lshl_add_u64 v[218:219], s[26:27], 0, v[134:135]
	s_mov_b32 m0, s13
	s_nop 0
	global_load_lds_dwordx4 v[218:219], off
	s_mov_b32 m0, s36
	s_nop 0
	global_load_lds_dwordx4 v[220:221], off
	s_waitcnt vmcnt(8)
	s_waitcnt lgkmcnt(0)
	s_barrier
; #define PG8_STAGE(bufoff, gbase, voff) do { _Pragma("unroll") for (int _i = 0; _i < 2; ++_i) \
;         __builtin_amdgcn_global_load_lds((const unsigned*)((const char*)(gbase) + (voff)[_i]), (PG8_LAS unsigned*)(lds + (bufoff) + ldsw + _i * 8192), 16, 0, 0); } while (0)
; #define PG8_LDA(dst, b, h) do { _Pragma("unroll") for (int m = 0; m < 4; ++m) _Pragma("unroll") for (int k = 0; k < 2; ++k) dst[m][k] = *(const PG8_LAS bf16x8*)(lds + PG8_SA(b, h) + aoff + m * 2048 + k * 1024); } while (0)
; #define PG8_LDB(dst, b, h) do { _Pragma("unroll") for (int n = 0; n < 2; ++n) _Pragma("unroll") for (int k = 0; k < 2; ++k) dst[n][k] = *(const PG8_LAS bf16x8*)(lds + PG8_SB(b, h) + boff + n * 2048 + k * 1024); } while (0)
; #define PG8_MMA(ai, bj, At, Bt) do { __builtin_amdgcn_s_setprio(1); _Pragma("unroll") for (int m = 0; m < 4; ++m) _Pragma("unroll") for (int n = 0; n < 2; ++n) _Pragma("unroll") for (int k = 0; k < 2; ++k) \
;         acc[ai][bj][m][n] = __builtin_amdgcn_mfma_f32_16x16x32_bf16(Bt[n][k], At[m][k], acc[ai][bj][m][n], 0, 0, 0); __builtin_amdgcn_s_setprio(0); } while (0)
; #define PG8_WAIT_V(n) asm volatile("s_waitcnt vmcnt(" #n ")" ::: "memory")
; #define PG8_WAIT_L(n) asm volatile("s_waitcnt lgkmcnt(" #n ")" ::: "memory")
; #define PG8_BAR __builtin_amdgcn_s_barrier()
; #define PG8_SCHED __builtin_amdgcn_sched_barrier(0)
; template <class Epi, class Sched, bool ALIGN_EPI = true, bool SP2 = true>
; __device__ __forceinline__ void gemm_phase(PG8_LAS unsigned char* lds, const Gemm g, const Sched& S, const Epi& E) {
;     ...
;             PG8_WAIT_V(8); PG8_WAIT_L(0); PG8_BAR; PG8_MMA(1, 0, At, B0); PG8_MMA(1, 1, At, B1); PG8_BAR; PG8_SCHED;
;             PG8_LDB(B0, 1, 0); PG8_LDB(B1, 1, 1); PG8_SCHED; PG8_LDA(At, 1, 0); PG8_STAGE(PG8_SA(0, 1), a2 + hstepA, voffA);
;             PG8_WAIT_V(8); PG8_WAIT_L(0); PG8_BAR; PG8_MMA(0, 0, At, B0); PG8_MMA(0, 1, At, B1); PG8_BAR; PG8_SCHED;
;             PG8_LDA(At, 1, 1); PG8_STAGE(PG8_SB(1, 0), b3, voffB); PG8_STAGE(PG8_SB(1, 1), b3 + hstepB, voffB); PG8_STAGE(PG8_SA(1, 0), a3, voffA);
	s_setprio 1
	v_mfma_f32_16x16x32_bf16 v[60:63], v[150:153], v[182:185], v[60:63]
	v_mfma_f32_16x16x32_bf16 v[56:59], v[158:161], v[182:185], v[56:59]
	v_mfma_f32_16x16x32_bf16 v[52:55], v[150:153], v[190:193], v[52:55]
	v_mfma_f32_16x16x32_bf16 v[48:51], v[158:161], v[190:193], v[48:51]
	v_mfma_f32_16x16x32_bf16 v[36:39], v[150:153], v[198:201], v[36:39]
	v_mfma_f32_16x16x32_bf16 v[32:35], v[158:161], v[198:201], v[32:35]
	v_mfma_f32_16x16x32_bf16 v[20:23], v[150:153], v[206:209], v[20:23]
	v_mfma_f32_16x16x32_bf16 v[16:19], v[158:161], v[206:209], v[16:19]
	v_mfma_f32_16x16x32_bf16 v[60:63], v[154:157], v[186:189], v[60:63]
	v_mfma_f32_16x16x32_bf16 v[56:59], v[162:165], v[186:189], v[56:59]
	v_mfma_f32_16x16x32_bf16 v[52:55], v[154:157], v[194:197], v[52:55]
	v_mfma_f32_16x16x32_bf16 v[48:51], v[162:165], v[194:197], v[48:51]
	v_mfma_f32_16x16x32_bf16 v[36:39], v[154:157], v[202:205], v[36:39]
	v_mfma_f32_16x16x32_bf16 v[32:35], v[162:165], v[202:205], v[32:35]
	v_mfma_f32_16x16x32_bf16 v[20:23], v[154:157], v[210:213], v[20:23]
	v_mfma_f32_16x16x32_bf16 v[16:19], v[162:165], v[210:213], v[16:19]
	v_mfma_f32_16x16x32_bf16 v[44:47], v[166:169], v[182:185], v[44:47]
	v_mfma_f32_16x16x32_bf16 v[40:43], v[174:177], v[182:185], v[40:43]
	v_mfma_f32_16x16x32_bf16 v[28:31], v[166:169], v[190:193], v[28:31]
	v_mfma_f32_16x16x32_bf16 v[24:27], v[174:177], v[190:193], v[24:27]
	v_mfma_f32_16x16x32_bf16 v[12:15], v[166:169], v[198:201], v[12:15]
	v_mfma_f32_16x16x32_bf16 v[8:11], v[174:177], v[198:201], v[8:11]
	v_mfma_f32_16x16x32_bf16 v[4:7], v[166:169], v[206:209], v[4:7]
	v_mfma_f32_16x16x32_bf16 v[0:3], v[174:177], v[206:209], v[0:3]
	v_mfma_f32_16x16x32_bf16 v[44:47], v[170:173], v[186:189], v[44:47]
	v_mfma_f32_16x16x32_bf16 v[40:43], v[178:181], v[186:189], v[40:43]
	v_mfma_f32_16x16x32_bf16 v[28:31], v[170:173], v[194:197], v[28:31]
	v_mfma_f32_16x16x32_bf16 v[24:27], v[178:181], v[194:197], v[24:27]
	v_mfma_f32_16x16x32_bf16 v[12:15], v[170:173], v[202:205], v[12:15]
	v_mfma_f32_16x16x32_bf16 v[8:11], v[178:181], v[202:205], v[8:11]
	v_mfma_f32_16x16x32_bf16 v[4:7], v[170:173], v[210:213], v[4:7]
	v_mfma_f32_16x16x32_bf16 v[0:3], v[178:181], v[210:213], v[0:3]
	s_setprio 0
	s_barrier
	s_add_i32 s52, 0, 0x18000
	s_add_i32 s53, 0, 0x1c000
	v_add_u32_e32 v162, s52, v145
	v_add_u32_e32 v178, s53, v145
	ds_read_b128 v[150:153], v162
	ds_read_b128 v[154:157], v162 offset:1024
	ds_read_b128 v[158:161], v162 offset:2048
	ds_read_b128 v[162:165], v162 offset:3072
	ds_read_b128 v[166:169], v178
	ds_read_b128 v[170:173], v178 offset:1024
	ds_read_b128 v[174:177], v178 offset:2048
	ds_read_b128 v[178:181], v178 offset:3072
	s_add_u32 s26, s26, 0x40000
	s_addc_u32 s27, s27, 0
	s_mov_b32 m0, s37
	v_lshl_add_u64 v[222:223], s[26:27], 0, v[134:135]
	ds_read_b128 v[182:185], v149 offset:32768
	ds_read_b128 v[186:189], v149 offset:33792
	ds_read_b128 v[190:193], v149 offset:34816
	ds_read_b128 v[194:197], v149 offset:35840
	ds_read_b128 v[198:201], v149 offset:36864
	ds_read_b128 v[202:205], v149 offset:37888
	ds_read_b128 v[206:209], v149 offset:38912
	ds_read_b128 v[210:213], v149 offset:39936
	global_load_lds_dwordx4 v[222:223], off
	v_lshl_add_u64 v[222:223], s[26:27], 0, v[130:131]
	s_mov_b32 m0, s38
	s_nop 0
	global_load_lds_dwordx4 v[222:223], off
	s_waitcnt vmcnt(8)
	s_waitcnt lgkmcnt(0)
	s_barrier
	s_setprio 1
	v_mfma_f32_16x16x32_bf16 v[124:127], v[150:153], v[182:185], v[124:127]
	v_mfma_f32_16x16x32_bf16 v[120:123], v[158:161], v[182:185], v[120:123]
	v_mfma_f32_16x16x32_bf16 v[116:119], v[150:153], v[190:193], v[116:119]
	v_mfma_f32_16x16x32_bf16 v[112:115], v[158:161], v[190:193], v[112:115]
	v_mfma_f32_16x16x32_bf16 v[100:103], v[150:153], v[198:201], v[100:103]
	v_mfma_f32_16x16x32_bf16 v[96:99], v[158:161], v[198:201], v[96:99]
	v_mfma_f32_16x16x32_bf16 v[84:87], v[150:153], v[206:209], v[84:87]
	v_mfma_f32_16x16x32_bf16 v[80:83], v[158:161], v[206:209], v[80:83]
	v_mfma_f32_16x16x32_bf16 v[124:127], v[154:157], v[186:189], v[124:127]
	v_mfma_f32_16x16x32_bf16 v[120:123], v[162:165], v[186:189], v[120:123]
	v_mfma_f32_16x16x32_bf16 v[116:119], v[154:157], v[194:197], v[116:119]
	v_mfma_f32_16x16x32_bf16 v[112:115], v[162:165], v[194:197], v[112:115]
	v_mfma_f32_16x16x32_bf16 v[100:103], v[154:157], v[202:205], v[100:103]
	v_mfma_f32_16x16x32_bf16 v[96:99], v[162:165], v[202:205], v[96:99]
	v_mfma_f32_16x16x32_bf16 v[84:87], v[154:157], v[210:213], v[84:87]
	v_mfma_f32_16x16x32_bf16 v[80:83], v[162:165], v[210:213], v[80:83]
	v_mfma_f32_16x16x32_bf16 v[108:111], v[166:169], v[182:185], v[108:111]
	v_mfma_f32_16x16x32_bf16 v[104:107], v[174:177], v[182:185], v[104:107]
	v_mfma_f32_16x16x32_bf16 v[92:95], v[166:169], v[190:193], v[92:95]
	v_mfma_f32_16x16x32_bf16 v[88:91], v[174:177], v[190:193], v[88:91]
	v_mfma_f32_16x16x32_bf16 v[76:79], v[166:169], v[198:201], v[76:79]
	v_mfma_f32_16x16x32_bf16 v[72:75], v[174:177], v[198:201], v[72:75]
	v_mfma_f32_16x16x32_bf16 v[68:71], v[166:169], v[206:209], v[68:71]
	v_mfma_f32_16x16x32_bf16 v[64:67], v[174:177], v[206:209], v[64:67]
	v_mfma_f32_16x16x32_bf16 v[108:111], v[170:173], v[186:189], v[108:111]
	v_mfma_f32_16x16x32_bf16 v[104:107], v[178:181], v[186:189], v[104:107]
	v_mfma_f32_16x16x32_bf16 v[92:95], v[170:173], v[194:197], v[92:95]
	v_mfma_f32_16x16x32_bf16 v[88:91], v[178:181], v[194:197], v[88:91]
	v_mfma_f32_16x16x32_bf16 v[76:79], v[170:173], v[202:205], v[76:79]
	v_mfma_f32_16x16x32_bf16 v[72:75], v[178:181], v[202:205], v[72:75]
	v_mfma_f32_16x16x32_bf16 v[68:71], v[170:173], v[210:213], v[68:71]
	v_mfma_f32_16x16x32_bf16 v[64:67], v[178:181], v[210:213], v[64:67]
	s_setprio 0
	s_barrier
; #define PG8_STAGE(bufoff, gbase, voff) do { _Pragma("unroll") for (int _i = 0; _i < 2; ++_i) \
;         __builtin_amdgcn_global_load_lds((const unsigned*)((const char*)(gbase) + (voff)[_i]), (PG8_LAS unsigned*)(lds + (bufoff) + ldsw + _i * 8192), 16, 0, 0); } while (0)
; #define PG8_LDA(dst, b, h) do { _Pragma("unroll") for (int m = 0; m < 4; ++m) _Pragma("unroll") for (int k = 0; k < 2; ++k) dst[m][k] = *(const PG8_LAS bf16x8*)(lds + PG8_SA(b, h) + aoff + m * 2048 + k * 1024); } while (0)
; #define PG8_MMA(ai, bj, At, Bt) do { __builtin_amdgcn_s_setprio(1); _Pragma("unroll") for (int m = 0; m < 4; ++m) _Pragma("unroll") for (int n = 0; n < 2; ++n) _Pragma("unroll") for (int k = 0; k < 2; ++k) \
;         acc[ai][bj][m][n] = __builtin_amdgcn_mfma_f32_16x16x32_bf16(Bt[n][k], At[m][k], acc[ai][bj][m][n], 0, 0, 0); __builtin_amdgcn_s_setprio(0); } while (0)
; #define PG8_WAIT_V(n) asm volatile("s_waitcnt vmcnt(" #n ")" ::: "memory")
; #define PG8_WAIT_L(n) asm volatile("s_waitcnt lgkmcnt(" #n ")" ::: "memory")
; #define PG8_BAR __builtin_amdgcn_s_barrier()
; #define PG8_SCHED __builtin_amdgcn_sched_barrier(0)
; template <class Epi, class Sched, bool ALIGN_EPI = true, bool SP2 = true>
; __device__ __forceinline__ void gemm_phase(PG8_LAS unsigned char* lds, const Gemm g, const Sched& S, const Epi& E) {
;     ...
;             PG8_WAIT_V(8); PG8_WAIT_L(0); PG8_BAR; PG8_MMA(0, 0, At, B0); PG8_MMA(0, 1, At, B1); PG8_BAR; PG8_SCHED;
;             PG8_LDA(At, 1, 1); PG8_STAGE(PG8_SB(1, 0), b3, voffB); PG8_STAGE(PG8_SB(1, 1), b3 + hstepB, voffB); PG8_STAGE(PG8_SA(1, 0), a3, voffA);
;             PG8_WAIT_V(8); PG8_WAIT_L(0); PG8_BAR; PG8_MMA(1, 0, At, B0); PG8_MMA(1, 1, At, B1); PG8_BAR; PG8_SCHED;
;         }
	s_add_i32 s26, s52, s31
	v_lshl_add_u64 v[214:215], v[214:215], 0, s[8:9]
	s_mov_b32 m0, s26
	ds_read_b128 v[182:185], v149 offset:49152
	ds_read_b128 v[186:189], v149 offset:50176
	ds_read_b128 v[190:193], v149 offset:51200
	ds_read_b128 v[194:197], v149 offset:52224
	ds_read_b128 v[198:201], v149 offset:53248
	ds_read_b128 v[202:205], v149 offset:54272
	ds_read_b128 v[206:209], v149 offset:55296
	ds_read_b128 v[210:213], v149 offset:56320
	global_load_lds_dwordx4 v[214:215], off
	s_add_i32 m0, s26, 0x2000
	s_add_u32 s24, s24, 0x40080
	v_lshl_add_u64 v[214:215], v[216:217], 0, s[8:9]
	s_addc_u32 s25, s25, 0
	s_add_i32 s26, s53, s31
	global_load_lds_dwordx4 v[214:215], off
	v_lshl_add_u64 v[214:215], s[24:25], 0, v[132:133]
	s_mov_b32 m0, s26
	s_nop 0
	global_load_lds_dwordx4 v[214:215], off
	v_lshl_add_u64 v[214:215], s[24:25], 0, v[128:129]
	s_add_i32 m0, s26, 0x2000
	s_nop 0
	global_load_lds_dwordx4 v[214:215], off
	v_lshl_add_u64 v[214:215], v[218:219], 0, s[8:9]
	s_mov_b32 m0, s39
	s_nop 0
	global_load_lds_dwordx4 v[214:215], off
	v_lshl_add_u64 v[214:215], v[220:221], 0, s[8:9]
	s_mov_b32 m0, s40
	s_nop 0
	global_load_lds_dwordx4 v[214:215], off
	s_waitcnt vmcnt(8)
	s_waitcnt lgkmcnt(0)
	s_barrier
	s_setprio 1
	v_mfma_f32_16x16x32_bf16 v[60:63], v[150:153], v[182:185], v[60:63]
	v_mfma_f32_16x16x32_bf16 v[56:59], v[158:161], v[182:185], v[56:59]
	v_mfma_f32_16x16x32_bf16 v[52:55], v[150:153], v[190:193], v[52:55]
	v_mfma_f32_16x16x32_bf16 v[48:51], v[158:161], v[190:193], v[48:51]
	v_mfma_f32_16x16x32_bf16 v[36:39], v[150:153], v[198:201], v[36:39]
	v_mfma_f32_16x16x32_bf16 v[32:35], v[158:161], v[198:201], v[32:35]
	v_mfma_f32_16x16x32_bf16 v[20:23], v[150:153], v[206:209], v[20:23]
	v_mfma_f32_16x16x32_bf16 v[16:19], v[158:161], v[206:209], v[16:19]
	v_mfma_f32_16x16x32_bf16 v[60:63], v[154:157], v[186:189], v[60:63]
	v_mfma_f32_16x16x32_bf16 v[56:59], v[162:165], v[186:189], v[56:59]
	v_mfma_f32_16x16x32_bf16 v[52:55], v[154:157], v[194:197], v[52:55]
	v_mfma_f32_16x16x32_bf16 v[48:51], v[162:165], v[194:197], v[48:51]
	v_mfma_f32_16x16x32_bf16 v[36:39], v[154:157], v[202:205], v[36:39]
	v_mfma_f32_16x16x32_bf16 v[32:35], v[162:165], v[202:205], v[32:35]
	v_mfma_f32_16x16x32_bf16 v[20:23], v[154:157], v[210:213], v[20:23]
	v_mfma_f32_16x16x32_bf16 v[16:19], v[162:165], v[210:213], v[16:19]
	v_mfma_f32_16x16x32_bf16 v[44:47], v[166:169], v[182:185], v[44:47]
	v_mfma_f32_16x16x32_bf16 v[40:43], v[174:177], v[182:185], v[40:43]
	v_mfma_f32_16x16x32_bf16 v[28:31], v[166:169], v[190:193], v[28:31]
	v_mfma_f32_16x16x32_bf16 v[24:27], v[174:177], v[190:193], v[24:27]
	v_mfma_f32_16x16x32_bf16 v[12:15], v[166:169], v[198:201], v[12:15]
	v_mfma_f32_16x16x32_bf16 v[8:11], v[174:177], v[198:201], v[8:11]
	v_mfma_f32_16x16x32_bf16 v[4:7], v[166:169], v[206:209], v[4:7]
	v_mfma_f32_16x16x32_bf16 v[0:3], v[174:177], v[206:209], v[0:3]
	v_mfma_f32_16x16x32_bf16 v[44:47], v[170:173], v[186:189], v[44:47]
	v_mfma_f32_16x16x32_bf16 v[40:43], v[178:181], v[186:189], v[40:43]
	v_mfma_f32_16x16x32_bf16 v[28:31], v[170:173], v[194:197], v[28:31]
	v_mfma_f32_16x16x32_bf16 v[24:27], v[178:181], v[194:197], v[24:27]
	v_mfma_f32_16x16x32_bf16 v[12:15], v[170:173], v[202:205], v[12:15]
	v_mfma_f32_16x16x32_bf16 v[8:11], v[178:181], v[202:205], v[8:11]
	v_mfma_f32_16x16x32_bf16 v[4:7], v[170:173], v[210:213], v[4:7]
	v_mfma_f32_16x16x32_bf16 v[0:3], v[178:181], v[210:213], v[0:3]
	s_setprio 0
	s_barrier
	s_add_i32 s58, s58, 2
	s_add_u32 s56, s56, 0x100
	s_addc_u32 s57, s57, 0
	s_add_u32 s22, s22, 0x100
	s_addc_u32 s23, s23, 0
	s_cmp_gt_u32 s58, 13
	s_cbranch_scc0 .LBB0_132
	s_and_b64 vcc, exec, s[10:11]
	s_cbranch_vccz .LBB0_135
	s_barrier

; #define PG8_STAGE(bufoff, gbase, voff) do { _Pragma("unroll") for (int _i = 0; _i < 2; ++_i) \
;         __builtin_amdgcn_global_load_lds((const unsigned*)((const char*)(gbase) + (voff)[_i]), (PG8_LAS unsigned*)(lds + (bufoff) + ldsw + _i * 8192), 16, 0, 0); } while (0)
; #define PG8_LDA(dst, b, h) do { _Pragma("unroll") for (int m = 0; m < 4; ++m) _Pragma("unroll") for (int k = 0; k < 2; ++k) dst[m][k] = *(const PG8_LAS bf16x8*)(lds + PG8_SA(b, h) + aoff + m * 2048 + k * 1024); } while (0)
; #define PG8_LDB(dst, b, h) do { _Pragma("unroll") for (int n = 0; n < 2; ++n) _Pragma("unroll") for (int k = 0; k < 2; ++k) dst[n][k] = *(const PG8_LAS bf16x8*)(lds + PG8_SB(b, h) + boff + n * 2048 + k * 1024); } while (0)
; #define PG8_MMA(ai, bj, At, Bt) do { __builtin_amdgcn_s_setprio(1); _Pragma("unroll") for (int m = 0; m < 4; ++m) _Pragma("unroll") for (int n = 0; n < 2; ++n) _Pragma("unroll") for (int k = 0; k < 2; ++k) \
;         acc[ai][bj][m][n] = __builtin_amdgcn_mfma_f32_16x16x32_bf16(Bt[n][k], At[m][k], acc[ai][bj][m][n], 0, 0, 0); __builtin_amdgcn_s_setprio(0); } while (0)
; #define PG8_WAIT_V(n) asm volatile("s_waitcnt vmcnt(" #n ")" ::: "memory")
; #define PG8_WAIT_L(n) asm volatile("s_waitcnt lgkmcnt(" #n ")" ::: "memory")
; #define PG8_BAR __builtin_amdgcn_s_barrier()
; #define PG8_SCHED __builtin_amdgcn_sched_barrier(0)
; template <class Epi, class Sched, bool ALIGN_EPI = true, bool SP2 = true>
; __device__ __forceinline__ void gemm_phase(PG8_LAS unsigned char* lds, const Gemm g, const Sched& S, const Epi& E) {
;     ...
;             PG8_LDB(B0, 0, 0); PG8_LDB(B1, 0, 1); PG8_SCHED; PG8_LDA(At, 0, 0); PG8_STAGE(PG8_SA(1, 1), a1 + hstepA, voffA);
;             PG8_WAIT_V(8); PG8_WAIT_L(0); PG8_BAR; PG8_MMA(0, 0, At, B0); PG8_MMA(0, 1, At, B1); PG8_BAR; PG8_SCHED;
;             PG8_LDA(At, 0, 1); PG8_STAGE(PG8_SB(0, 0), b2, voffB); PG8_STAGE(PG8_SB(0, 1), b2 + hstepB, voffB); PG8_STAGE(PG8_SA(0, 0), a2, voffA);
.LBB0_200:
	ds_read_b128 v[146:149], v143
	ds_read_b128 v[150:153], v143 offset:1024
	ds_read_b128 v[154:157], v143 offset:2048
	ds_read_b128 v[158:161], v143 offset:3072
	ds_read_b128 v[162:165], v144
	ds_read_b128 v[166:169], v144 offset:1024
	ds_read_b128 v[170:173], v144 offset:2048
	ds_read_b128 v[174:177], v144 offset:3072
	s_add_u32 s24, s22, 0xfffc0080
	s_addc_u32 s25, s23, -1
	s_cmp_eq_u32 s57, 12
	s_cselect_b32 s27, s17, s25
	s_cselect_b32 s26, s49, s24
	s_cselect_b32 s25, s15, s56
	s_cselect_b32 s24, s50, s51
	v_lshl_add_u64 v[210:211], s[22:23], 0, v[138:139]
	s_add_i32 m0, s35, 0xc000
	ds_read_b128 v[178:181], v145
	ds_read_b128 v[182:185], v145 offset:1024
	ds_read_b128 v[186:189], v145 offset:2048
	ds_read_b128 v[190:193], v145 offset:3072
	ds_read_b128 v[194:197], v145 offset:4096
	ds_read_b128 v[198:201], v145 offset:5120
	ds_read_b128 v[202:205], v145 offset:6144
	ds_read_b128 v[206:209], v145 offset:7168
	global_load_lds_dwordx4 v[210:211], off
	v_lshl_add_u64 v[210:211], s[22:23], 0, v[136:137]
	s_add_i32 m0, s35, 0xe000
	s_nop 0
	global_load_lds_dwordx4 v[210:211], off
	s_waitcnt vmcnt(8)
	s_waitcnt lgkmcnt(0)
	s_barrier
	s_setprio 1
	v_mfma_f32_16x16x32_bf16 v[124:127], v[146:149], v[178:181], v[124:127]
	v_mfma_f32_16x16x32_bf16 v[120:123], v[154:157], v[178:181], v[120:123]
	v_mfma_f32_16x16x32_bf16 v[116:119], v[146:149], v[186:189], v[116:119]
	v_mfma_f32_16x16x32_bf16 v[112:115], v[154:157], v[186:189], v[112:115]
	v_mfma_f32_16x16x32_bf16 v[100:103], v[146:149], v[194:197], v[100:103]
	v_mfma_f32_16x16x32_bf16 v[96:99], v[154:157], v[194:197], v[96:99]
	v_mfma_f32_16x16x32_bf16 v[84:87], v[146:149], v[202:205], v[84:87]
	v_mfma_f32_16x16x32_bf16 v[80:83], v[154:157], v[202:205], v[80:83]
	v_mfma_f32_16x16x32_bf16 v[124:127], v[150:153], v[182:185], v[124:127]
	v_mfma_f32_16x16x32_bf16 v[120:123], v[158:161], v[182:185], v[120:123]
	v_mfma_f32_16x16x32_bf16 v[116:119], v[150:153], v[190:193], v[116:119]
	v_mfma_f32_16x16x32_bf16 v[112:115], v[158:161], v[190:193], v[112:115]
	v_mfma_f32_16x16x32_bf16 v[100:103], v[150:153], v[198:201], v[100:103]
	v_mfma_f32_16x16x32_bf16 v[96:99], v[158:161], v[198:201], v[96:99]
	v_mfma_f32_16x16x32_bf16 v[84:87], v[150:153], v[206:209], v[84:87]
	v_mfma_f32_16x16x32_bf16 v[80:83], v[158:161], v[206:209], v[80:83]
	v_mfma_f32_16x16x32_bf16 v[108:111], v[162:165], v[178:181], v[108:111]
	v_mfma_f32_16x16x32_bf16 v[104:107], v[170:173], v[178:181], v[104:107]
	v_mfma_f32_16x16x32_bf16 v[92:95], v[162:165], v[186:189], v[92:95]
	v_mfma_f32_16x16x32_bf16 v[88:91], v[170:173], v[186:189], v[88:91]
	v_mfma_f32_16x16x32_bf16 v[76:79], v[162:165], v[194:197], v[76:79]
	v_mfma_f32_16x16x32_bf16 v[72:75], v[170:173], v[194:197], v[72:75]
	v_mfma_f32_16x16x32_bf16 v[68:71], v[162:165], v[202:205], v[68:71]
	v_mfma_f32_16x16x32_bf16 v[64:67], v[170:173], v[202:205], v[64:67]
	v_mfma_f32_16x16x32_bf16 v[108:111], v[166:169], v[182:185], v[108:111]
	v_mfma_f32_16x16x32_bf16 v[104:107], v[174:177], v[182:185], v[104:107]
	v_mfma_f32_16x16x32_bf16 v[92:95], v[166:169], v[190:193], v[92:95]
	v_mfma_f32_16x16x32_bf16 v[88:91], v[174:177], v[190:193], v[88:91]
	v_mfma_f32_16x16x32_bf16 v[76:79], v[166:169], v[198:201], v[76:79]
	v_mfma_f32_16x16x32_bf16 v[72:75], v[174:177], v[198:201], v[72:75]
	v_mfma_f32_16x16x32_bf16 v[68:71], v[166:169], v[206:209], v[68:71]
	v_mfma_f32_16x16x32_bf16 v[64:67], v[174:177], v[206:209], v[64:67]
	s_setprio 0
	s_barrier
	s_add_i32 s52, s46, s34
	v_lshl_add_u64 v[210:211], s[24:25], 0, v[130:131]
	s_mov_b32 m0, s52
	ds_read_b128 v[178:181], v145 offset:16384
	ds_read_b128 v[182:185], v145 offset:17408
	ds_read_b128 v[186:189], v145 offset:18432
	ds_read_b128 v[190:193], v145 offset:19456
	ds_read_b128 v[194:197], v145 offset:20480
	ds_read_b128 v[198:201], v145 offset:21504
	ds_read_b128 v[202:205], v145 offset:22528
	ds_read_b128 v[206:209], v145 offset:23552
	global_load_lds_dwordx4 v[210:211], off
	s_add_i32 m0, s52, 0x2000
	s_add_u32 s58, s24, 0x40000
	v_lshl_add_u64 v[212:213], s[24:25], 0, v[134:135]
	s_addc_u32 s59, s25, 0
	s_add_i32 s52, s47, s34
	global_load_lds_dwordx4 v[212:213], off
	v_lshl_add_u64 v[214:215], s[58:59], 0, v[130:131]
	s_mov_b32 m0, s52
	v_lshl_add_u64 v[216:217], s[26:27], 0, v[132:133]
	global_load_lds_dwordx4 v[214:215], off
	v_lshl_add_u64 v[214:215], s[58:59], 0, v[134:135]
	s_add_i32 m0, s52, 0x2000
	s_nop 0
	global_load_lds_dwordx4 v[214:215], off
	v_lshl_add_u64 v[214:215], s[26:27], 0, v[128:129]
	s_mov_b32 m0, s35
	s_nop 0
	global_load_lds_dwordx4 v[214:215], off
	s_mov_b32 m0, s36
	s_nop 0
	global_load_lds_dwordx4 v[216:217], off
	s_waitcnt vmcnt(8)
	s_waitcnt lgkmcnt(0)
	s_barrier
; #define PG8_STAGE(bufoff, gbase, voff) do { _Pragma("unroll") for (int _i = 0; _i < 2; ++_i) \
;         __builtin_amdgcn_global_load_lds((const unsigned*)((const char*)(gbase) + (voff)[_i]), (PG8_LAS unsigned*)(lds + (bufoff) + ldsw + _i * 8192), 16, 0, 0); } while (0)
; #define PG8_LDA(dst, b, h) do { _Pragma("unroll") for (int m = 0; m < 4; ++m) _Pragma("unroll") for (int k = 0; k < 2; ++k) dst[m][k] = *(const PG8_LAS bf16x8*)(lds + PG8_SA(b, h) + aoff + m * 2048 + k * 1024); } while (0)
; #define PG8_LDB(dst, b, h) do { _Pragma("unroll") for (int n = 0; n < 2; ++n) _Pragma("unroll") for (int k = 0; k < 2; ++k) dst[n][k] = *(const PG8_LAS bf16x8*)(lds + PG8_SB(b, h) + boff + n * 2048 + k * 1024); } while (0)
; #define PG8_MMA(ai, bj, At, Bt) do { __builtin_amdgcn_s_setprio(1); _Pragma("unroll") for (int m = 0; m < 4; ++m) _Pragma("unroll") for (int n = 0; n < 2; ++n) _Pragma("unroll") for (int k = 0; k < 2; ++k) \
;         acc[ai][bj][m][n] = __builtin_amdgcn_mfma_f32_16x16x32_bf16(Bt[n][k], At[m][k], acc[ai][bj][m][n], 0, 0, 0); __builtin_amdgcn_s_setprio(0); } while (0)
; #define PG8_WAIT_V(n) asm volatile("s_waitcnt vmcnt(" #n ")" ::: "memory")
; #define PG8_WAIT_L(n) asm volatile("s_waitcnt lgkmcnt(" #n ")" ::: "memory")
; #define PG8_BAR __builtin_amdgcn_s_barrier()
; #define PG8_SCHED __builtin_amdgcn_sched_barrier(0)
; template <class Epi, class Sched, bool ALIGN_EPI = true, bool SP2 = true>
; __device__ __forceinline__ void gemm_phase(PG8_LAS unsigned char* lds, const Gemm g, const Sched& S, const Epi& E) {
;     ...
;             PG8_WAIT_V(8); PG8_WAIT_L(0); PG8_BAR; PG8_MMA(1, 0, At, B0); PG8_MMA(1, 1, At, B1); PG8_BAR; PG8_SCHED;
;             PG8_LDB(B0, 1, 0); PG8_LDB(B1, 1, 1); PG8_SCHED; PG8_LDA(At, 1, 0); PG8_STAGE(PG8_SA(0, 1), a2 + hstepA, voffA);
;             PG8_WAIT_V(8); PG8_WAIT_L(0); PG8_BAR; PG8_MMA(0, 0, At, B0); PG8_MMA(0, 1, At, B1); PG8_BAR; PG8_SCHED;
	s_setprio 1
	v_mfma_f32_16x16x32_bf16 v[60:63], v[146:149], v[178:181], v[60:63]
	v_mfma_f32_16x16x32_bf16 v[56:59], v[154:157], v[178:181], v[56:59]
	v_mfma_f32_16x16x32_bf16 v[52:55], v[146:149], v[186:189], v[52:55]
	v_mfma_f32_16x16x32_bf16 v[48:51], v[154:157], v[186:189], v[48:51]
	v_mfma_f32_16x16x32_bf16 v[36:39], v[146:149], v[194:197], v[36:39]
	v_mfma_f32_16x16x32_bf16 v[32:35], v[154:157], v[194:197], v[32:35]
	v_mfma_f32_16x16x32_bf16 v[20:23], v[146:149], v[202:205], v[20:23]
	v_mfma_f32_16x16x32_bf16 v[16:19], v[154:157], v[202:205], v[16:19]
	v_mfma_f32_16x16x32_bf16 v[60:63], v[150:153], v[182:185], v[60:63]
	v_mfma_f32_16x16x32_bf16 v[56:59], v[158:161], v[182:185], v[56:59]
	v_mfma_f32_16x16x32_bf16 v[52:55], v[150:153], v[190:193], v[52:55]
	v_mfma_f32_16x16x32_bf16 v[48:51], v[158:161], v[190:193], v[48:51]
	v_mfma_f32_16x16x32_bf16 v[36:39], v[150:153], v[198:201], v[36:39]
	v_mfma_f32_16x16x32_bf16 v[32:35], v[158:161], v[198:201], v[32:35]
	v_mfma_f32_16x16x32_bf16 v[20:23], v[150:153], v[206:209], v[20:23]
	v_mfma_f32_16x16x32_bf16 v[16:19], v[158:161], v[206:209], v[16:19]
	v_mfma_f32_16x16x32_bf16 v[44:47], v[162:165], v[178:181], v[44:47]
	v_mfma_f32_16x16x32_bf16 v[40:43], v[170:173], v[178:181], v[40:43]
	v_mfma_f32_16x16x32_bf16 v[28:31], v[162:165], v[186:189], v[28:31]
	v_mfma_f32_16x16x32_bf16 v[24:27], v[170:173], v[186:189], v[24:27]
	v_mfma_f32_16x16x32_bf16 v[12:15], v[162:165], v[194:197], v[12:15]
	v_mfma_f32_16x16x32_bf16 v[8:11], v[170:173], v[194:197], v[8:11]
	v_mfma_f32_16x16x32_bf16 v[4:7], v[162:165], v[202:205], v[4:7]
	v_mfma_f32_16x16x32_bf16 v[0:3], v[170:173], v[202:205], v[0:3]
	v_mfma_f32_16x16x32_bf16 v[44:47], v[166:169], v[182:185], v[44:47]
	v_mfma_f32_16x16x32_bf16 v[40:43], v[174:177], v[182:185], v[40:43]
	v_mfma_f32_16x16x32_bf16 v[28:31], v[166:169], v[190:193], v[28:31]
	v_mfma_f32_16x16x32_bf16 v[24:27], v[174:177], v[190:193], v[24:27]
	v_mfma_f32_16x16x32_bf16 v[12:15], v[166:169], v[198:201], v[12:15]
	v_mfma_f32_16x16x32_bf16 v[8:11], v[174:177], v[198:201], v[8:11]
	v_mfma_f32_16x16x32_bf16 v[4:7], v[166:169], v[206:209], v[4:7]
	v_mfma_f32_16x16x32_bf16 v[0:3], v[174:177], v[206:209], v[0:3]
	s_setprio 0
	s_barrier
	s_add_i32 s52, 0, 0x18000
	s_add_i32 s53, 0, 0x1c000
	v_add_u32_e32 v158, s52, v141
	v_add_u32_e32 v174, s53, v141
	ds_read_b128 v[146:149], v158
	ds_read_b128 v[150:153], v158 offset:1024
	ds_read_b128 v[154:157], v158 offset:2048
	ds_read_b128 v[158:161], v158 offset:3072
	ds_read_b128 v[162:165], v174
	ds_read_b128 v[166:169], v174 offset:1024
	ds_read_b128 v[170:173], v174 offset:2048
	ds_read_b128 v[174:177], v174 offset:3072
	s_add_u32 s26, s26, 0x40000
	s_addc_u32 s27, s27, 0
	s_mov_b32 m0, s37
	v_lshl_add_u64 v[218:219], s[26:27], 0, v[128:129]
	ds_read_b128 v[178:181], v145 offset:32768
	ds_read_b128 v[182:185], v145 offset:33792
	ds_read_b128 v[186:189], v145 offset:34816
	ds_read_b128 v[190:193], v145 offset:35840
	ds_read_b128 v[194:197], v145 offset:36864
	ds_read_b128 v[198:201], v145 offset:37888
	ds_read_b128 v[202:205], v145 offset:38912
	ds_read_b128 v[206:209], v145 offset:39936
	global_load_lds_dwordx4 v[218:219], off
	v_lshl_add_u64 v[218:219], s[26:27], 0, v[132:133]
	s_mov_b32 m0, s38
	s_nop 0
	global_load_lds_dwordx4 v[218:219], off
	s_waitcnt vmcnt(8)
	s_waitcnt lgkmcnt(0)
	s_barrier
	s_setprio 1
	v_mfma_f32_16x16x32_bf16 v[124:127], v[146:149], v[178:181], v[124:127]
	v_mfma_f32_16x16x32_bf16 v[120:123], v[154:157], v[178:181], v[120:123]
	v_mfma_f32_16x16x32_bf16 v[116:119], v[146:149], v[186:189], v[116:119]
	v_mfma_f32_16x16x32_bf16 v[112:115], v[154:157], v[186:189], v[112:115]
	v_mfma_f32_16x16x32_bf16 v[100:103], v[146:149], v[194:197], v[100:103]
	v_mfma_f32_16x16x32_bf16 v[96:99], v[154:157], v[194:197], v[96:99]
	v_mfma_f32_16x16x32_bf16 v[84:87], v[146:149], v[202:205], v[84:87]
	v_mfma_f32_16x16x32_bf16 v[80:83], v[154:157], v[202:205], v[80:83]
	v_mfma_f32_16x16x32_bf16 v[124:127], v[150:153], v[182:185], v[124:127]
	v_mfma_f32_16x16x32_bf16 v[120:123], v[158:161], v[182:185], v[120:123]
	v_mfma_f32_16x16x32_bf16 v[116:119], v[150:153], v[190:193], v[116:119]
	v_mfma_f32_16x16x32_bf16 v[112:115], v[158:161], v[190:193], v[112:115]
	v_mfma_f32_16x16x32_bf16 v[100:103], v[150:153], v[198:201], v[100:103]
	v_mfma_f32_16x16x32_bf16 v[96:99], v[158:161], v[198:201], v[96:99]
	v_mfma_f32_16x16x32_bf16 v[84:87], v[150:153], v[206:209], v[84:87]
	v_mfma_f32_16x16x32_bf16 v[80:83], v[158:161], v[206:209], v[80:83]
	v_mfma_f32_16x16x32_bf16 v[108:111], v[162:165], v[178:181], v[108:111]
	v_mfma_f32_16x16x32_bf16 v[104:107], v[170:173], v[178:181], v[104:107]
	v_mfma_f32_16x16x32_bf16 v[92:95], v[162:165], v[186:189], v[92:95]
	v_mfma_f32_16x16x32_bf16 v[88:91], v[170:173], v[186:189], v[88:91]
	v_mfma_f32_16x16x32_bf16 v[76:79], v[162:165], v[194:197], v[76:79]
	v_mfma_f32_16x16x32_bf16 v[72:75], v[170:173], v[194:197], v[72:75]
	v_mfma_f32_16x16x32_bf16 v[68:71], v[162:165], v[202:205], v[68:71]
	v_mfma_f32_16x16x32_bf16 v[64:67], v[170:173], v[202:205], v[64:67]
	v_mfma_f32_16x16x32_bf16 v[108:111], v[166:169], v[182:185], v[108:111]
	v_mfma_f32_16x16x32_bf16 v[104:107], v[174:177], v[182:185], v[104:107]
	v_mfma_f32_16x16x32_bf16 v[92:95], v[166:169], v[190:193], v[92:95]
	v_mfma_f32_16x16x32_bf16 v[88:91], v[174:177], v[190:193], v[88:91]
	v_mfma_f32_16x16x32_bf16 v[76:79], v[166:169], v[198:201], v[76:79]
	v_mfma_f32_16x16x32_bf16 v[72:75], v[174:177], v[198:201], v[72:75]
	v_mfma_f32_16x16x32_bf16 v[68:71], v[166:169], v[206:209], v[68:71]
	v_mfma_f32_16x16x32_bf16 v[64:67], v[174:177], v[206:209], v[64:67]
	s_setprio 0
	s_barrier
; #define PG8_STAGE(bufoff, gbase, voff) do { _Pragma("unroll") for (int _i = 0; _i < 2; ++_i) \
;         __builtin_amdgcn_global_load_lds((const unsigned*)((const char*)(gbase) + (voff)[_i]), (PG8_LAS unsigned*)(lds + (bufoff) + ldsw + _i * 8192), 16, 0, 0); } while (0)
; #define PG8_LDA(dst, b, h) do { _Pragma("unroll") for (int m = 0; m < 4; ++m) _Pragma("unroll") for (int k = 0; k < 2; ++k) dst[m][k] = *(const PG8_LAS bf16x8*)(lds + PG8_SA(b, h) + aoff + m * 2048 + k * 1024); } while (0)
; #define PG8_MMA(ai, bj, At, Bt) do { __builtin_amdgcn_s_setprio(1); _Pragma("unroll") for (int m = 0; m < 4; ++m) _Pragma("unroll") for (int n = 0; n < 2; ++n) _Pragma("unroll") for (int k = 0; k < 2; ++k) \
;         acc[ai][bj][m][n] = __builtin_amdgcn_mfma_f32_16x16x32_bf16(Bt[n][k], At[m][k], acc[ai][bj][m][n], 0, 0, 0); __builtin_amdgcn_s_setprio(0); } while (0)
; #define PG8_WAIT_V(n) asm volatile("s_waitcnt vmcnt(" #n ")" ::: "memory")
; #define PG8_WAIT_L(n) asm volatile("s_waitcnt lgkmcnt(" #n ")" ::: "memory")
; #define PG8_BAR __builtin_amdgcn_s_barrier()
; #define PG8_SCHED __builtin_amdgcn_sched_barrier(0)
; template <class Epi, class Sched, bool ALIGN_EPI = true, bool SP2 = true>
; __device__ __forceinline__ void gemm_phase(PG8_LAS unsigned char* lds, const Gemm g, const Sched& S, const Epi& E) {
;     ...
;             PG8_LDA(At, 1, 1); PG8_STAGE(PG8_SB(1, 0), b3, voffB); PG8_STAGE(PG8_SB(1, 1), b3 + hstepB, voffB); PG8_STAGE(PG8_SA(1, 0), a3, voffA);
;             PG8_WAIT_V(8); PG8_WAIT_L(0); PG8_BAR; PG8_MMA(1, 0, At, B0); PG8_MMA(1, 1, At, B1); PG8_BAR; PG8_SCHED;
;         }
;         if constexpr (ALIGN_EPI) { if (wr == 0) PG8_BAR; }
	s_add_i32 s26, s52, s34
	v_lshl_add_u64 v[210:211], v[210:211], 0, s[6:7]
	s_mov_b32 m0, s26
	ds_read_b128 v[178:181], v145 offset:49152
	ds_read_b128 v[182:185], v145 offset:50176
	ds_read_b128 v[186:189], v145 offset:51200
	ds_read_b128 v[190:193], v145 offset:52224
	ds_read_b128 v[194:197], v145 offset:53248
	ds_read_b128 v[198:201], v145 offset:54272
	ds_read_b128 v[202:205], v145 offset:55296
	ds_read_b128 v[206:209], v145 offset:56320
	global_load_lds_dwordx4 v[210:211], off
	s_add_i32 m0, s26, 0x2000
	s_add_u32 s24, s24, 0x40080
	v_lshl_add_u64 v[210:211], v[212:213], 0, s[6:7]
	s_addc_u32 s25, s25, 0
	s_add_i32 s26, s53, s34
	global_load_lds_dwordx4 v[210:211], off
	v_lshl_add_u64 v[210:211], s[24:25], 0, v[130:131]
	s_mov_b32 m0, s26
	s_nop 0
	global_load_lds_dwordx4 v[210:211], off
	v_lshl_add_u64 v[210:211], s[24:25], 0, v[134:135]
	s_add_i32 m0, s26, 0x2000
	s_nop 0
	global_load_lds_dwordx4 v[210:211], off
	v_lshl_add_u64 v[210:211], v[214:215], 0, s[6:7]
	s_mov_b32 m0, s40
	s_nop 0
	global_load_lds_dwordx4 v[210:211], off
	v_lshl_add_u64 v[210:211], v[216:217], 0, s[6:7]
	s_mov_b32 m0, s41
	s_nop 0
	global_load_lds_dwordx4 v[210:211], off
	s_waitcnt vmcnt(8)
	s_waitcnt lgkmcnt(0)
	s_barrier
	s_setprio 1
	v_mfma_f32_16x16x32_bf16 v[60:63], v[146:149], v[178:181], v[60:63]
	v_mfma_f32_16x16x32_bf16 v[56:59], v[154:157], v[178:181], v[56:59]
	v_mfma_f32_16x16x32_bf16 v[52:55], v[146:149], v[186:189], v[52:55]
	v_mfma_f32_16x16x32_bf16 v[48:51], v[154:157], v[186:189], v[48:51]
	v_mfma_f32_16x16x32_bf16 v[36:39], v[146:149], v[194:197], v[36:39]
	v_mfma_f32_16x16x32_bf16 v[32:35], v[154:157], v[194:197], v[32:35]
	v_mfma_f32_16x16x32_bf16 v[20:23], v[146:149], v[202:205], v[20:23]
	v_mfma_f32_16x16x32_bf16 v[16:19], v[154:157], v[202:205], v[16:19]
	v_mfma_f32_16x16x32_bf16 v[60:63], v[150:153], v[182:185], v[60:63]
	v_mfma_f32_16x16x32_bf16 v[56:59], v[158:161], v[182:185], v[56:59]
	v_mfma_f32_16x16x32_bf16 v[52:55], v[150:153], v[190:193], v[52:55]
	v_mfma_f32_16x16x32_bf16 v[48:51], v[158:161], v[190:193], v[48:51]
	v_mfma_f32_16x16x32_bf16 v[36:39], v[150:153], v[198:201], v[36:39]
	v_mfma_f32_16x16x32_bf16 v[32:35], v[158:161], v[198:201], v[32:35]
	v_mfma_f32_16x16x32_bf16 v[20:23], v[150:153], v[206:209], v[20:23]
	v_mfma_f32_16x16x32_bf16 v[16:19], v[158:161], v[206:209], v[16:19]
	v_mfma_f32_16x16x32_bf16 v[44:47], v[162:165], v[178:181], v[44:47]
	v_mfma_f32_16x16x32_bf16 v[40:43], v[170:173], v[178:181], v[40:43]
	v_mfma_f32_16x16x32_bf16 v[28:31], v[162:165], v[186:189], v[28:31]
	v_mfma_f32_16x16x32_bf16 v[24:27], v[170:173], v[186:189], v[24:27]
	v_mfma_f32_16x16x32_bf16 v[12:15], v[162:165], v[194:197], v[12:15]
	v_mfma_f32_16x16x32_bf16 v[8:11], v[170:173], v[194:197], v[8:11]
	v_mfma_f32_16x16x32_bf16 v[4:7], v[162:165], v[202:205], v[4:7]
	v_mfma_f32_16x16x32_bf16 v[0:3], v[170:173], v[202:205], v[0:3]
	v_mfma_f32_16x16x32_bf16 v[44:47], v[166:169], v[182:185], v[44:47]
	v_mfma_f32_16x16x32_bf16 v[40:43], v[174:177], v[182:185], v[40:43]
	v_mfma_f32_16x16x32_bf16 v[28:31], v[166:169], v[190:193], v[28:31]
	v_mfma_f32_16x16x32_bf16 v[24:27], v[174:177], v[190:193], v[24:27]
	v_mfma_f32_16x16x32_bf16 v[12:15], v[166:169], v[198:201], v[12:15]
	v_mfma_f32_16x16x32_bf16 v[8:11], v[174:177], v[198:201], v[8:11]
	v_mfma_f32_16x16x32_bf16 v[4:7], v[166:169], v[206:209], v[4:7]
	v_mfma_f32_16x16x32_bf16 v[0:3], v[174:177], v[206:209], v[0:3]
	s_setprio 0
	s_barrier
	s_add_i32 s57, s57, 2
	s_add_u32 s51, s51, 0x100
	s_addc_u32 s56, s56, 0
	s_add_u32 s22, s22, 0x100
	s_addc_u32 s23, s23, 0
	s_cmp_gt_u32 s57, 13
	s_cbranch_scc0 .LBB0_200
	s_and_b64 vcc, exec, s[8:9]
	s_cbranch_vccz .LBB0_203
	s_barrier

; #define PG8_STAGE(bufoff, gbase, voff) do { _Pragma("unroll") for (int _i = 0; _i < 2; ++_i) \
;         __builtin_amdgcn_global_load_lds((const unsigned*)((const char*)(gbase) + (voff)[_i]), (PG8_LAS unsigned*)(lds + (bufoff) + ldsw + _i * 8192), 16, 0, 0); } while (0)
; #define PG8_LDA(dst, b, h) do { _Pragma("unroll") for (int m = 0; m < 4; ++m) _Pragma("unroll") for (int k = 0; k < 2; ++k) dst[m][k] = *(const PG8_LAS bf16x8*)(lds + PG8_SA(b, h) + aoff + m * 2048 + k * 1024); } while (0)
; #define PG8_LDB(dst, b, h) do { _Pragma("unroll") for (int n = 0; n < 2; ++n) _Pragma("unroll") for (int k = 0; k < 2; ++k) dst[n][k] = *(const PG8_LAS bf16x8*)(lds + PG8_SB(b, h) + boff + n * 2048 + k * 1024); } while (0)
; #define PG8_MMA(ai, bj, At, Bt) do { __builtin_amdgcn_s_setprio(1); _Pragma("unroll") for (int m = 0; m < 4; ++m) _Pragma("unroll") for (int n = 0; n < 2; ++n) _Pragma("unroll") for (int k = 0; k < 2; ++k) \
;         acc[ai][bj][m][n] = __builtin_amdgcn_mfma_f32_16x16x32_bf16(Bt[n][k], At[m][k], acc[ai][bj][m][n], 0, 0, 0); __builtin_amdgcn_s_setprio(0); } while (0)
; #define PG8_WAIT_V(n) asm volatile("s_waitcnt vmcnt(" #n ")" ::: "memory")
; #define PG8_WAIT_L(n) asm volatile("s_waitcnt lgkmcnt(" #n ")" ::: "memory")
; #define PG8_BAR __builtin_amdgcn_s_barrier()
; #define PG8_SCHED __builtin_amdgcn_sched_barrier(0)
; template <class Epi, class Sched, bool ALIGN_EPI = true, bool SP2 = true>
; __device__ __forceinline__ void gemm_phase(PG8_LAS unsigned char* lds, const Gemm g, const Sched& S, const Epi& E) {
;     ...
;             const bool last = (t == nt - 2);
;             const char* a1 = cA + (size_t)(t + 1) * kstep;
;             const char* a2 = last ? nA : cA + (size_t)(t + 2) * kstep; const char* b2 = last ? nB : cB + (size_t)(t + 2) * kstep;
;             const char* a3 = a2 + kstep; const char* b3 = b2 + kstep;
;             PG8_LDB(B0, 0, 0); PG8_LDB(B1, 0, 1); PG8_SCHED; PG8_LDA(At, 0, 0); PG8_STAGE(PG8_SA(1, 1), a1 + hstepA, voffA);
;             PG8_WAIT_V(8); PG8_WAIT_L(0); PG8_BAR; PG8_MMA(0, 0, At, B0); PG8_MMA(0, 1, At, B1); PG8_BAR; PG8_SCHED;
;             PG8_LDA(At, 0, 1); PG8_STAGE(PG8_SB(0, 0), b2, voffB); PG8_STAGE(PG8_SB(0, 1), b2 + hstepB, voffB); PG8_STAGE(PG8_SA(0, 0), a2, voffA);
.LBB0_226:
	ds_read_b128 v[142:145], v155
	ds_read_b128 v[146:149], v155 offset:1024
	ds_read_b128 v[158:161], v155 offset:2048
	ds_read_b128 v[162:165], v155 offset:3072
	ds_read_b128 v[166:169], v156
	ds_read_b128 v[170:173], v156 offset:1024
	ds_read_b128 v[174:177], v156 offset:2048
	ds_read_b128 v[178:181], v156 offset:3072
	s_add_u32 s30, s28, 0xfffc0080
	s_addc_u32 s31, s29, -1
	s_cmp_eq_u32 s61, 12
	s_cselect_b32 s35, s3, s31
	s_cselect_b32 s34, s5, s30
	s_cselect_b32 s31, s21, s60
	s_cselect_b32 s30, s23, s59
	v_lshl_add_u64 v[150:151], s[28:29], 0, v[140:141]
	s_add_i32 m0, s40, 0xc000
	ds_read_b128 v[182:185], v157
	ds_read_b128 v[186:189], v157 offset:1024
	ds_read_b128 v[190:193], v157 offset:2048
	ds_read_b128 v[194:197], v157 offset:3072
	ds_read_b128 v[198:201], v157 offset:4096
	ds_read_b128 v[202:205], v157 offset:5120
	ds_read_b128 v[206:209], v157 offset:6144
	ds_read_b128 v[210:213], v157 offset:7168
	global_load_lds_dwordx4 v[150:151], off
	v_lshl_add_u64 v[150:151], s[28:29], 0, v[138:139]
	s_add_i32 m0, s40, 0xe000
	s_nop 0
	global_load_lds_dwordx4 v[150:151], off
	s_waitcnt vmcnt(8)
	s_waitcnt lgkmcnt(0)
	s_barrier
	s_setprio 1
	v_mfma_f32_16x16x32_bf16 v[124:127], v[142:145], v[182:185], v[124:127]
	v_mfma_f32_16x16x32_bf16 v[120:123], v[158:161], v[182:185], v[120:123]
	v_mfma_f32_16x16x32_bf16 v[108:111], v[142:145], v[190:193], v[108:111]
	v_mfma_f32_16x16x32_bf16 v[104:107], v[158:161], v[190:193], v[104:107]
	v_mfma_f32_16x16x32_bf16 v[92:95], v[142:145], v[198:201], v[92:95]
	v_mfma_f32_16x16x32_bf16 v[88:91], v[158:161], v[198:201], v[88:91]
	v_mfma_f32_16x16x32_bf16 v[76:79], v[142:145], v[206:209], v[76:79]
	v_mfma_f32_16x16x32_bf16 v[72:75], v[158:161], v[206:209], v[72:75]
	v_mfma_f32_16x16x32_bf16 v[124:127], v[146:149], v[186:189], v[124:127]
	v_mfma_f32_16x16x32_bf16 v[120:123], v[162:165], v[186:189], v[120:123]
	v_mfma_f32_16x16x32_bf16 v[108:111], v[146:149], v[194:197], v[108:111]
	v_mfma_f32_16x16x32_bf16 v[104:107], v[162:165], v[194:197], v[104:107]
	v_mfma_f32_16x16x32_bf16 v[92:95], v[146:149], v[202:205], v[92:95]
	v_mfma_f32_16x16x32_bf16 v[88:91], v[162:165], v[202:205], v[88:91]
	v_mfma_f32_16x16x32_bf16 v[76:79], v[146:149], v[210:213], v[76:79]
	v_mfma_f32_16x16x32_bf16 v[72:75], v[162:165], v[210:213], v[72:75]
	v_mfma_f32_16x16x32_bf16 v[116:119], v[166:169], v[182:185], v[116:119]
	v_mfma_f32_16x16x32_bf16 v[112:115], v[174:177], v[182:185], v[112:115]
	v_mfma_f32_16x16x32_bf16 v[100:103], v[166:169], v[190:193], v[100:103]
	v_mfma_f32_16x16x32_bf16 v[96:99], v[174:177], v[190:193], v[96:99]
	v_mfma_f32_16x16x32_bf16 v[84:87], v[166:169], v[198:201], v[84:87]
	v_mfma_f32_16x16x32_bf16 v[80:83], v[174:177], v[198:201], v[80:83]
	v_mfma_f32_16x16x32_bf16 v[68:71], v[166:169], v[206:209], v[68:71]
	v_mfma_f32_16x16x32_bf16 v[64:67], v[174:177], v[206:209], v[64:67]
	v_mfma_f32_16x16x32_bf16 v[116:119], v[170:173], v[186:189], v[116:119]
	v_mfma_f32_16x16x32_bf16 v[112:115], v[178:181], v[186:189], v[112:115]
	v_mfma_f32_16x16x32_bf16 v[100:103], v[170:173], v[194:197], v[100:103]
	v_mfma_f32_16x16x32_bf16 v[96:99], v[178:181], v[194:197], v[96:99]
	v_mfma_f32_16x16x32_bf16 v[84:87], v[170:173], v[202:205], v[84:87]
	v_mfma_f32_16x16x32_bf16 v[80:83], v[178:181], v[202:205], v[80:83]
	v_mfma_f32_16x16x32_bf16 v[68:71], v[170:173], v[210:213], v[68:71]
	v_mfma_f32_16x16x32_bf16 v[64:67], v[178:181], v[210:213], v[64:67]
	s_setprio 0
	s_barrier
	s_add_i32 s52, s56, s39
	v_lshl_add_u64 v[150:151], s[30:31], 0, v[130:131]
	s_mov_b32 m0, s52
	ds_read_b128 v[182:185], v157 offset:16384
	ds_read_b128 v[186:189], v157 offset:17408
	ds_read_b128 v[190:193], v157 offset:18432
	ds_read_b128 v[194:197], v157 offset:19456
	ds_read_b128 v[198:201], v157 offset:20480
	ds_read_b128 v[202:205], v157 offset:21504
	ds_read_b128 v[206:209], v157 offset:22528
	ds_read_b128 v[210:213], v157 offset:23552
	global_load_lds_dwordx4 v[150:151], off
	s_add_i32 m0, s52, 0x2000
	s_add_u32 s62, s30, 0x40000
	v_lshl_add_u64 v[214:215], s[30:31], 0, v[134:135]
	s_addc_u32 s63, s31, 0
	s_add_i32 s52, s57, s39
	global_load_lds_dwordx4 v[214:215], off
	v_lshl_add_u64 v[216:217], s[62:63], 0, v[130:131]
	s_mov_b32 m0, s52
	v_lshl_add_u64 v[218:219], s[34:35], 0, v[132:133]
	global_load_lds_dwordx4 v[216:217], off
	v_lshl_add_u64 v[216:217], s[62:63], 0, v[134:135]
	s_add_i32 m0, s52, 0x2000
	s_nop 0
	global_load_lds_dwordx4 v[216:217], off
	v_lshl_add_u64 v[216:217], s[34:35], 0, v[128:129]
	s_mov_b32 m0, s40
	s_nop 0
	global_load_lds_dwordx4 v[216:217], off
	s_mov_b32 m0, s41
	s_nop 0
	global_load_lds_dwordx4 v[218:219], off
	s_waitcnt vmcnt(8)
	s_waitcnt lgkmcnt(0)
	s_barrier
; #define PG8_STAGE(bufoff, gbase, voff) do { _Pragma("unroll") for (int _i = 0; _i < 2; ++_i) \
;         __builtin_amdgcn_global_load_lds((const unsigned*)((const char*)(gbase) + (voff)[_i]), (PG8_LAS unsigned*)(lds + (bufoff) + ldsw + _i * 8192), 16, 0, 0); } while (0)
; #define PG8_LDA(dst, b, h) do { _Pragma("unroll") for (int m = 0; m < 4; ++m) _Pragma("unroll") for (int k = 0; k < 2; ++k) dst[m][k] = *(const PG8_LAS bf16x8*)(lds + PG8_SA(b, h) + aoff + m * 2048 + k * 1024); } while (0)
; #define PG8_LDB(dst, b, h) do { _Pragma("unroll") for (int n = 0; n < 2; ++n) _Pragma("unroll") for (int k = 0; k < 2; ++k) dst[n][k] = *(const PG8_LAS bf16x8*)(lds + PG8_SB(b, h) + boff + n * 2048 + k * 1024); } while (0)
; #define PG8_MMA(ai, bj, At, Bt) do { __builtin_amdgcn_s_setprio(1); _Pragma("unroll") for (int m = 0; m < 4; ++m) _Pragma("unroll") for (int n = 0; n < 2; ++n) _Pragma("unroll") for (int k = 0; k < 2; ++k) \
;         acc[ai][bj][m][n] = __builtin_amdgcn_mfma_f32_16x16x32_bf16(Bt[n][k], At[m][k], acc[ai][bj][m][n], 0, 0, 0); __builtin_amdgcn_s_setprio(0); } while (0)
; #define PG8_WAIT_V(n) asm volatile("s_waitcnt vmcnt(" #n ")" ::: "memory")
; #define PG8_WAIT_L(n) asm volatile("s_waitcnt lgkmcnt(" #n ")" ::: "memory")
; #define PG8_BAR __builtin_amdgcn_s_barrier()
; #define PG8_SCHED __builtin_amdgcn_sched_barrier(0)
; template <class Epi, class Sched, bool ALIGN_EPI = true, bool SP2 = true>
; __device__ __forceinline__ void gemm_phase(PG8_LAS unsigned char* lds, const Gemm g, const Sched& S, const Epi& E) {
;     ...
;             PG8_WAIT_V(8); PG8_WAIT_L(0); PG8_BAR; PG8_MMA(1, 0, At, B0); PG8_MMA(1, 1, At, B1); PG8_BAR; PG8_SCHED;
;             PG8_LDB(B0, 1, 0); PG8_LDB(B1, 1, 1); PG8_SCHED; PG8_LDA(At, 1, 0); PG8_STAGE(PG8_SA(0, 1), a2 + hstepA, voffA);
;             PG8_WAIT_V(8); PG8_WAIT_L(0); PG8_BAR; PG8_MMA(0, 0, At, B0); PG8_MMA(0, 1, At, B1); PG8_BAR; PG8_SCHED;
	s_setprio 1
	v_mfma_f32_16x16x32_bf16 v[60:63], v[142:145], v[182:185], v[60:63]
	v_mfma_f32_16x16x32_bf16 v[56:59], v[158:161], v[182:185], v[56:59]
	v_mfma_f32_16x16x32_bf16 v[44:47], v[142:145], v[190:193], v[44:47]
	v_mfma_f32_16x16x32_bf16 v[40:43], v[158:161], v[190:193], v[40:43]
	v_mfma_f32_16x16x32_bf16 v[28:31], v[142:145], v[198:201], v[28:31]
	v_mfma_f32_16x16x32_bf16 v[24:27], v[158:161], v[198:201], v[24:27]
	v_mfma_f32_16x16x32_bf16 v[12:15], v[142:145], v[206:209], v[12:15]
	v_mfma_f32_16x16x32_bf16 v[8:11], v[158:161], v[206:209], v[8:11]
	v_mfma_f32_16x16x32_bf16 v[60:63], v[146:149], v[186:189], v[60:63]
	v_mfma_f32_16x16x32_bf16 v[56:59], v[162:165], v[186:189], v[56:59]
	v_mfma_f32_16x16x32_bf16 v[44:47], v[146:149], v[194:197], v[44:47]
	v_mfma_f32_16x16x32_bf16 v[40:43], v[162:165], v[194:197], v[40:43]
	v_mfma_f32_16x16x32_bf16 v[28:31], v[146:149], v[202:205], v[28:31]
	v_mfma_f32_16x16x32_bf16 v[24:27], v[162:165], v[202:205], v[24:27]
	v_mfma_f32_16x16x32_bf16 v[12:15], v[146:149], v[210:213], v[12:15]
	v_mfma_f32_16x16x32_bf16 v[8:11], v[162:165], v[210:213], v[8:11]
	v_mfma_f32_16x16x32_bf16 v[52:55], v[166:169], v[182:185], v[52:55]
	v_mfma_f32_16x16x32_bf16 v[48:51], v[174:177], v[182:185], v[48:51]
	v_mfma_f32_16x16x32_bf16 v[36:39], v[166:169], v[190:193], v[36:39]
	v_mfma_f32_16x16x32_bf16 v[32:35], v[174:177], v[190:193], v[32:35]
	v_mfma_f32_16x16x32_bf16 v[20:23], v[166:169], v[198:201], v[20:23]
	v_mfma_f32_16x16x32_bf16 v[16:19], v[174:177], v[198:201], v[16:19]
	v_mfma_f32_16x16x32_bf16 v[4:7], v[166:169], v[206:209], v[4:7]
	v_mfma_f32_16x16x32_bf16 v[0:3], v[174:177], v[206:209], v[0:3]
	v_mfma_f32_16x16x32_bf16 v[52:55], v[170:173], v[186:189], v[52:55]
	v_mfma_f32_16x16x32_bf16 v[48:51], v[178:181], v[186:189], v[48:51]
	v_mfma_f32_16x16x32_bf16 v[36:39], v[170:173], v[194:197], v[36:39]
	v_mfma_f32_16x16x32_bf16 v[32:35], v[178:181], v[194:197], v[32:35]
	v_mfma_f32_16x16x32_bf16 v[20:23], v[170:173], v[202:205], v[20:23]
	v_mfma_f32_16x16x32_bf16 v[16:19], v[178:181], v[202:205], v[16:19]
	v_mfma_f32_16x16x32_bf16 v[4:7], v[170:173], v[210:213], v[4:7]
	v_mfma_f32_16x16x32_bf16 v[0:3], v[178:181], v[210:213], v[0:3]
	s_setprio 0
	s_barrier
	s_add_i32 s52, 0, 0x18000
	v_add_u32_e32 v136, s52, v153
	s_add_i32 s53, 0, 0x1c000
	ds_read_b128 v[142:145], v136
	ds_read_b128 v[146:149], v136 offset:1024
	ds_read_b128 v[158:161], v136 offset:2048
	ds_read_b128 v[162:165], v136 offset:3072
	v_add_u32_e32 v136, s53, v153
	ds_read_b128 v[166:169], v136
	ds_read_b128 v[170:173], v136 offset:1024
	ds_read_b128 v[174:177], v136 offset:2048
	ds_read_b128 v[178:181], v136 offset:3072
	s_add_u32 s34, s34, 0x40000
	s_addc_u32 s35, s35, 0
	s_mov_b32 m0, s43
	v_lshl_add_u64 v[220:221], s[34:35], 0, v[128:129]
	ds_read_b128 v[182:185], v157 offset:32768
	ds_read_b128 v[186:189], v157 offset:33792
	ds_read_b128 v[190:193], v157 offset:34816
	ds_read_b128 v[194:197], v157 offset:35840
	ds_read_b128 v[198:201], v157 offset:36864
	ds_read_b128 v[202:205], v157 offset:37888
	ds_read_b128 v[206:209], v157 offset:38912
	ds_read_b128 v[210:213], v157 offset:39936
	global_load_lds_dwordx4 v[220:221], off
	v_lshl_add_u64 v[220:221], s[34:35], 0, v[132:133]
	s_mov_b32 m0, s45
	s_nop 0
	global_load_lds_dwordx4 v[220:221], off
	s_waitcnt vmcnt(8)
	s_waitcnt lgkmcnt(0)
	s_barrier
	s_setprio 1
	v_mfma_f32_16x16x32_bf16 v[124:127], v[142:145], v[182:185], v[124:127]
	v_mfma_f32_16x16x32_bf16 v[120:123], v[158:161], v[182:185], v[120:123]
	v_mfma_f32_16x16x32_bf16 v[108:111], v[142:145], v[190:193], v[108:111]
	v_mfma_f32_16x16x32_bf16 v[104:107], v[158:161], v[190:193], v[104:107]
	v_mfma_f32_16x16x32_bf16 v[92:95], v[142:145], v[198:201], v[92:95]
	v_mfma_f32_16x16x32_bf16 v[88:91], v[158:161], v[198:201], v[88:91]
	v_mfma_f32_16x16x32_bf16 v[76:79], v[142:145], v[206:209], v[76:79]
	v_mfma_f32_16x16x32_bf16 v[72:75], v[158:161], v[206:209], v[72:75]
	v_mfma_f32_16x16x32_bf16 v[124:127], v[146:149], v[186:189], v[124:127]
	v_mfma_f32_16x16x32_bf16 v[120:123], v[162:165], v[186:189], v[120:123]
	v_mfma_f32_16x16x32_bf16 v[108:111], v[146:149], v[194:197], v[108:111]
	v_mfma_f32_16x16x32_bf16 v[104:107], v[162:165], v[194:197], v[104:107]
	v_mfma_f32_16x16x32_bf16 v[92:95], v[146:149], v[202:205], v[92:95]
	v_mfma_f32_16x16x32_bf16 v[88:91], v[162:165], v[202:205], v[88:91]
	v_mfma_f32_16x16x32_bf16 v[76:79], v[146:149], v[210:213], v[76:79]
	v_mfma_f32_16x16x32_bf16 v[72:75], v[162:165], v[210:213], v[72:75]
	v_mfma_f32_16x16x32_bf16 v[116:119], v[166:169], v[182:185], v[116:119]
	v_mfma_f32_16x16x32_bf16 v[112:115], v[174:177], v[182:185], v[112:115]
	v_mfma_f32_16x16x32_bf16 v[100:103], v[166:169], v[190:193], v[100:103]
	v_mfma_f32_16x16x32_bf16 v[96:99], v[174:177], v[190:193], v[96:99]
	v_mfma_f32_16x16x32_bf16 v[84:87], v[166:169], v[198:201], v[84:87]
	v_mfma_f32_16x16x32_bf16 v[80:83], v[174:177], v[198:201], v[80:83]
	v_mfma_f32_16x16x32_bf16 v[68:71], v[166:169], v[206:209], v[68:71]
	v_mfma_f32_16x16x32_bf16 v[64:67], v[174:177], v[206:209], v[64:67]
	v_mfma_f32_16x16x32_bf16 v[116:119], v[170:173], v[186:189], v[116:119]
	v_mfma_f32_16x16x32_bf16 v[112:115], v[178:181], v[186:189], v[112:115]
	v_mfma_f32_16x16x32_bf16 v[100:103], v[170:173], v[194:197], v[100:103]
	v_mfma_f32_16x16x32_bf16 v[96:99], v[178:181], v[194:197], v[96:99]
	v_mfma_f32_16x16x32_bf16 v[84:87], v[170:173], v[202:205], v[84:87]
	v_mfma_f32_16x16x32_bf16 v[80:83], v[178:181], v[202:205], v[80:83]
	v_mfma_f32_16x16x32_bf16 v[68:71], v[170:173], v[210:213], v[68:71]
	v_mfma_f32_16x16x32_bf16 v[64:67], v[178:181], v[210:213], v[64:67]
	s_setprio 0
	s_barrier
; #define PG8_STAGE(bufoff, gbase, voff) do { _Pragma("unroll") for (int _i = 0; _i < 2; ++_i) \
;         __builtin_amdgcn_global_load_lds((const unsigned*)((const char*)(gbase) + (voff)[_i]), (PG8_LAS unsigned*)(lds + (bufoff) + ldsw + _i * 8192), 16, 0, 0); } while (0)
; #define PG8_LDA(dst, b, h) do { _Pragma("unroll") for (int m = 0; m < 4; ++m) _Pragma("unroll") for (int k = 0; k < 2; ++k) dst[m][k] = *(const PG8_LAS bf16x8*)(lds + PG8_SA(b, h) + aoff + m * 2048 + k * 1024); } while (0)
; #define PG8_MMA(ai, bj, At, Bt) do { __builtin_amdgcn_s_setprio(1); _Pragma("unroll") for (int m = 0; m < 4; ++m) _Pragma("unroll") for (int n = 0; n < 2; ++n) _Pragma("unroll") for (int k = 0; k < 2; ++k) \
;         acc[ai][bj][m][n] = __builtin_amdgcn_mfma_f32_16x16x32_bf16(Bt[n][k], At[m][k], acc[ai][bj][m][n], 0, 0, 0); __builtin_amdgcn_s_setprio(0); } while (0)
; #define PG8_WAIT_V(n) asm volatile("s_waitcnt vmcnt(" #n ")" ::: "memory")
; #define PG8_WAIT_L(n) asm volatile("s_waitcnt lgkmcnt(" #n ")" ::: "memory")
; #define PG8_BAR __builtin_amdgcn_s_barrier()
; #define PG8_SCHED __builtin_amdgcn_sched_barrier(0)
; template <class Epi, class Sched, bool ALIGN_EPI = true, bool SP2 = true>
; __device__ __forceinline__ void gemm_phase(PG8_LAS unsigned char* lds, const Gemm g, const Sched& S, const Epi& E) {
;     ...
;             PG8_LDA(At, 1, 1); PG8_STAGE(PG8_SB(1, 0), b3, voffB); PG8_STAGE(PG8_SB(1, 1), b3 + hstepB, voffB); PG8_STAGE(PG8_SA(1, 0), a3, voffA);
;             PG8_WAIT_V(8); PG8_WAIT_L(0); PG8_BAR; PG8_MMA(1, 0, At, B0); PG8_MMA(1, 1, At, B1); PG8_BAR; PG8_SCHED;
;         }
;         if constexpr (ALIGN_EPI) { if (wr == 0) PG8_BAR; }
	s_add_i32 s34, s52, s39
	v_lshl_add_u64 v[150:151], v[150:151], 0, s[12:13]
	s_mov_b32 m0, s34
	ds_read_b128 v[182:185], v157 offset:49152
	ds_read_b128 v[186:189], v157 offset:50176
	ds_read_b128 v[190:193], v157 offset:51200
	ds_read_b128 v[194:197], v157 offset:52224
	ds_read_b128 v[198:201], v157 offset:53248
	ds_read_b128 v[202:205], v157 offset:54272
	ds_read_b128 v[206:209], v157 offset:55296
	ds_read_b128 v[210:213], v157 offset:56320
	global_load_lds_dwordx4 v[150:151], off
	s_add_i32 m0, s34, 0x2000
	s_add_u32 s30, s30, 0x40080
	v_lshl_add_u64 v[150:151], v[214:215], 0, s[12:13]
	s_addc_u32 s31, s31, 0
	s_add_i32 s34, s53, s39
	global_load_lds_dwordx4 v[150:151], off
	v_lshl_add_u64 v[150:151], s[30:31], 0, v[130:131]
	s_mov_b32 m0, s34
	s_nop 0
	global_load_lds_dwordx4 v[150:151], off
	v_lshl_add_u64 v[150:151], s[30:31], 0, v[134:135]
	s_add_i32 m0, s34, 0x2000
	s_nop 0
	global_load_lds_dwordx4 v[150:151], off
	v_lshl_add_u64 v[150:151], v[216:217], 0, s[12:13]
	s_mov_b32 m0, s47
	s_nop 0
	global_load_lds_dwordx4 v[150:151], off
	v_lshl_add_u64 v[150:151], v[218:219], 0, s[12:13]
	s_mov_b32 m0, s48
	s_nop 0
	global_load_lds_dwordx4 v[150:151], off
	s_waitcnt vmcnt(8)
	s_waitcnt lgkmcnt(0)
	s_barrier
	s_setprio 1
	v_mfma_f32_16x16x32_bf16 v[60:63], v[142:145], v[182:185], v[60:63]
	v_mfma_f32_16x16x32_bf16 v[56:59], v[158:161], v[182:185], v[56:59]
	v_mfma_f32_16x16x32_bf16 v[44:47], v[142:145], v[190:193], v[44:47]
	v_mfma_f32_16x16x32_bf16 v[40:43], v[158:161], v[190:193], v[40:43]
	v_mfma_f32_16x16x32_bf16 v[28:31], v[142:145], v[198:201], v[28:31]
	v_mfma_f32_16x16x32_bf16 v[24:27], v[158:161], v[198:201], v[24:27]
	v_mfma_f32_16x16x32_bf16 v[12:15], v[142:145], v[206:209], v[12:15]
	v_mfma_f32_16x16x32_bf16 v[8:11], v[158:161], v[206:209], v[8:11]
	v_mfma_f32_16x16x32_bf16 v[60:63], v[146:149], v[186:189], v[60:63]
	v_mfma_f32_16x16x32_bf16 v[56:59], v[162:165], v[186:189], v[56:59]
	v_mfma_f32_16x16x32_bf16 v[44:47], v[146:149], v[194:197], v[44:47]
	v_mfma_f32_16x16x32_bf16 v[40:43], v[162:165], v[194:197], v[40:43]
	v_mfma_f32_16x16x32_bf16 v[28:31], v[146:149], v[202:205], v[28:31]
	v_mfma_f32_16x16x32_bf16 v[24:27], v[162:165], v[202:205], v[24:27]
	v_mfma_f32_16x16x32_bf16 v[12:15], v[146:149], v[210:213], v[12:15]
	v_mfma_f32_16x16x32_bf16 v[8:11], v[162:165], v[210:213], v[8:11]
	v_mfma_f32_16x16x32_bf16 v[52:55], v[166:169], v[182:185], v[52:55]
	v_mfma_f32_16x16x32_bf16 v[48:51], v[174:177], v[182:185], v[48:51]
	v_mfma_f32_16x16x32_bf16 v[36:39], v[166:169], v[190:193], v[36:39]
	v_mfma_f32_16x16x32_bf16 v[32:35], v[174:177], v[190:193], v[32:35]
	v_mfma_f32_16x16x32_bf16 v[20:23], v[166:169], v[198:201], v[20:23]
	v_mfma_f32_16x16x32_bf16 v[16:19], v[174:177], v[198:201], v[16:19]
	v_mfma_f32_16x16x32_bf16 v[4:7], v[166:169], v[206:209], v[4:7]
	v_mfma_f32_16x16x32_bf16 v[0:3], v[174:177], v[206:209], v[0:3]
	v_mfma_f32_16x16x32_bf16 v[52:55], v[170:173], v[186:189], v[52:55]
	v_mfma_f32_16x16x32_bf16 v[48:51], v[178:181], v[186:189], v[48:51]
	v_mfma_f32_16x16x32_bf16 v[36:39], v[170:173], v[194:197], v[36:39]
	v_mfma_f32_16x16x32_bf16 v[32:35], v[178:181], v[194:197], v[32:35]
	v_mfma_f32_16x16x32_bf16 v[20:23], v[170:173], v[202:205], v[20:23]
	v_mfma_f32_16x16x32_bf16 v[16:19], v[178:181], v[202:205], v[16:19]
	v_mfma_f32_16x16x32_bf16 v[4:7], v[170:173], v[210:213], v[4:7]
	v_mfma_f32_16x16x32_bf16 v[0:3], v[178:181], v[210:213], v[0:3]
	s_setprio 0
	s_barrier
	s_add_i32 s61, s61, 2
	s_add_u32 s59, s59, 0x100
	s_addc_u32 s60, s60, 0
	s_add_u32 s28, s28, 0x100
	s_addc_u32 s29, s29, 0
	s_cmp_gt_u32 s61, 13
	s_cbranch_scc0 .LBB0_226
	s_and_b64 vcc, exec, s[14:15]
	s_cbranch_vccz .LBB0_229
	s_barrier

; #define PG8_STAGE(bufoff, gbase, voff) do { _Pragma("unroll") for (int _i = 0; _i < 2; ++_i) \
;         __builtin_amdgcn_global_load_lds((const unsigned*)((const char*)(gbase) + (voff)[_i]), (PG8_LAS unsigned*)(lds + (bufoff) + ldsw + _i * 8192), 16, 0, 0); } while (0)
; #define PG8_LDA(dst, b, h) do { _Pragma("unroll") for (int m = 0; m < 4; ++m) _Pragma("unroll") for (int k = 0; k < 2; ++k) dst[m][k] = *(const PG8_LAS bf16x8*)(lds + PG8_SA(b, h) + aoff + m * 2048 + k * 1024); } while (0)
; #define PG8_LDB(dst, b, h) do { _Pragma("unroll") for (int n = 0; n < 2; ++n) _Pragma("unroll") for (int k = 0; k < 2; ++k) dst[n][k] = *(const PG8_LAS bf16x8*)(lds + PG8_SB(b, h) + boff + n * 2048 + k * 1024); } while (0)
; #define PG8_MMA(ai, bj, At, Bt) do { __builtin_amdgcn_s_setprio(1); _Pragma("unroll") for (int m = 0; m < 4; ++m) _Pragma("unroll") for (int n = 0; n < 2; ++n) _Pragma("unroll") for (int k = 0; k < 2; ++k) \
;         acc[ai][bj][m][n] = __builtin_amdgcn_mfma_f32_16x16x32_bf16(Bt[n][k], At[m][k], acc[ai][bj][m][n], 0, 0, 0); __builtin_amdgcn_s_setprio(0); } while (0)
; #define PG8_WAIT_V(n) asm volatile("s_waitcnt vmcnt(" #n ")" ::: "memory")
; #define PG8_WAIT_L(n) asm volatile("s_waitcnt lgkmcnt(" #n ")" ::: "memory")
; #define PG8_BAR __builtin_amdgcn_s_barrier()
; #define PG8_SCHED __builtin_amdgcn_sched_barrier(0)
; template <class Epi, class Sched, bool ALIGN_EPI = true, bool SP2 = true>
; __device__ __forceinline__ void gemm_phase(PG8_LAS unsigned char* lds, const Gemm g, const Sched& S, const Epi& E) {
;     ...
;             const bool last = (t == nt - 2);
;             const char* a1 = cA + (size_t)(t + 1) * kstep;
;             const char* a2 = last ? nA : cA + (size_t)(t + 2) * kstep; const char* b2 = last ? nB : cB + (size_t)(t + 2) * kstep;
;             const char* a3 = a2 + kstep; const char* b3 = b2 + kstep;
;             PG8_LDB(B0, 0, 0); PG8_LDB(B1, 0, 1); PG8_SCHED; PG8_LDA(At, 0, 0); PG8_STAGE(PG8_SA(1, 1), a1 + hstepA, voffA);
;             PG8_WAIT_V(8); PG8_WAIT_L(0); PG8_BAR; PG8_MMA(0, 0, At, B0); PG8_MMA(0, 1, At, B1); PG8_BAR; PG8_SCHED;
;             PG8_LDA(At, 0, 1); PG8_STAGE(PG8_SB(0, 0), b2, voffB); PG8_STAGE(PG8_SB(0, 1), b2 + hstepB, voffB); PG8_STAGE(PG8_SA(0, 0), a2, voffA);
.LBB0_306:
	ds_read_b128 v[146:149], v143
	ds_read_b128 v[150:153], v143 offset:1024
	ds_read_b128 v[154:157], v143 offset:2048
	ds_read_b128 v[158:161], v143 offset:3072
	ds_read_b128 v[162:165], v144
	ds_read_b128 v[166:169], v144 offset:1024
	ds_read_b128 v[170:173], v144 offset:2048
	ds_read_b128 v[174:177], v144 offset:3072
	s_add_u32 s36, s34, 0xfffc0080
	s_addc_u32 s37, s35, -1
	s_cmp_eq_u32 s73, 12
	s_cselect_b32 s39, s25, s37
	s_cselect_b32 s38, s66, s36
	s_cselect_b32 s37, s23, s72
	s_cselect_b32 s36, s70, s71
	v_lshl_add_u64 v[210:211], s[34:35], 0, v[138:139]
	s_add_i32 m0, s48, 0xc000
	ds_read_b128 v[178:181], v145
	ds_read_b128 v[182:185], v145 offset:1024
	ds_read_b128 v[186:189], v145 offset:2048
	ds_read_b128 v[190:193], v145 offset:3072
	ds_read_b128 v[194:197], v145 offset:4096
	ds_read_b128 v[198:201], v145 offset:5120
	ds_read_b128 v[202:205], v145 offset:6144
	ds_read_b128 v[206:209], v145 offset:7168
	global_load_lds_dwordx4 v[210:211], off
	v_lshl_add_u64 v[210:211], s[34:35], 0, v[136:137]
	s_add_i32 m0, s48, 0xe000
	s_nop 0
	global_load_lds_dwordx4 v[210:211], off
	s_waitcnt vmcnt(8)
	s_waitcnt lgkmcnt(0)
	s_barrier
	s_setprio 1
	v_mfma_f32_16x16x32_bf16 v[124:127], v[146:149], v[178:181], v[124:127]
	v_mfma_f32_16x16x32_bf16 v[120:123], v[154:157], v[178:181], v[120:123]
	v_mfma_f32_16x16x32_bf16 v[116:119], v[146:149], v[186:189], v[116:119]
	v_mfma_f32_16x16x32_bf16 v[112:115], v[154:157], v[186:189], v[112:115]
	v_mfma_f32_16x16x32_bf16 v[100:103], v[146:149], v[194:197], v[100:103]
	v_mfma_f32_16x16x32_bf16 v[96:99], v[154:157], v[194:197], v[96:99]
	v_mfma_f32_16x16x32_bf16 v[84:87], v[146:149], v[202:205], v[84:87]
	v_mfma_f32_16x16x32_bf16 v[80:83], v[154:157], v[202:205], v[80:83]
	v_mfma_f32_16x16x32_bf16 v[124:127], v[150:153], v[182:185], v[124:127]
	v_mfma_f32_16x16x32_bf16 v[120:123], v[158:161], v[182:185], v[120:123]
	v_mfma_f32_16x16x32_bf16 v[116:119], v[150:153], v[190:193], v[116:119]
	v_mfma_f32_16x16x32_bf16 v[112:115], v[158:161], v[190:193], v[112:115]
	v_mfma_f32_16x16x32_bf16 v[100:103], v[150:153], v[198:201], v[100:103]
	v_mfma_f32_16x16x32_bf16 v[96:99], v[158:161], v[198:201], v[96:99]
	v_mfma_f32_16x16x32_bf16 v[84:87], v[150:153], v[206:209], v[84:87]
	v_mfma_f32_16x16x32_bf16 v[80:83], v[158:161], v[206:209], v[80:83]
	v_mfma_f32_16x16x32_bf16 v[108:111], v[162:165], v[178:181], v[108:111]
	v_mfma_f32_16x16x32_bf16 v[104:107], v[170:173], v[178:181], v[104:107]
	v_mfma_f32_16x16x32_bf16 v[92:95], v[162:165], v[186:189], v[92:95]
	v_mfma_f32_16x16x32_bf16 v[88:91], v[170:173], v[186:189], v[88:91]
	v_mfma_f32_16x16x32_bf16 v[76:79], v[162:165], v[194:197], v[76:79]
	v_mfma_f32_16x16x32_bf16 v[72:75], v[170:173], v[194:197], v[72:75]
	v_mfma_f32_16x16x32_bf16 v[68:71], v[162:165], v[202:205], v[68:71]
	v_mfma_f32_16x16x32_bf16 v[64:67], v[170:173], v[202:205], v[64:67]
	v_mfma_f32_16x16x32_bf16 v[108:111], v[166:169], v[182:185], v[108:111]
	v_mfma_f32_16x16x32_bf16 v[104:107], v[174:177], v[182:185], v[104:107]
	v_mfma_f32_16x16x32_bf16 v[92:95], v[166:169], v[190:193], v[92:95]
	v_mfma_f32_16x16x32_bf16 v[88:91], v[174:177], v[190:193], v[88:91]
	v_mfma_f32_16x16x32_bf16 v[76:79], v[166:169], v[198:201], v[76:79]
	v_mfma_f32_16x16x32_bf16 v[72:75], v[174:177], v[198:201], v[72:75]
	v_mfma_f32_16x16x32_bf16 v[68:71], v[166:169], v[206:209], v[68:71]
	v_mfma_f32_16x16x32_bf16 v[64:67], v[174:177], v[206:209], v[64:67]
	s_setprio 0
	s_barrier
	s_add_i32 s52, s60, s46
	v_lshl_add_u64 v[210:211], s[36:37], 0, v[132:133]
	s_mov_b32 m0, s52
	ds_read_b128 v[178:181], v145 offset:16384
	ds_read_b128 v[182:185], v145 offset:17408
	ds_read_b128 v[186:189], v145 offset:18432
	ds_read_b128 v[190:193], v145 offset:19456
	ds_read_b128 v[194:197], v145 offset:20480
	ds_read_b128 v[198:201], v145 offset:21504
	ds_read_b128 v[202:205], v145 offset:22528
	ds_read_b128 v[206:209], v145 offset:23552
	global_load_lds_dwordx4 v[210:211], off
	s_add_i32 m0, s52, 0x2000
	s_add_u32 s74, s36, 0x40000
	v_lshl_add_u64 v[212:213], s[36:37], 0, v[128:129]
	s_addc_u32 s75, s37, 0
	s_add_i32 s52, s61, s46
	global_load_lds_dwordx4 v[212:213], off
	v_lshl_add_u64 v[214:215], s[74:75], 0, v[132:133]
	s_mov_b32 m0, s52
	v_lshl_add_u64 v[216:217], s[38:39], 0, v[130:131]
	global_load_lds_dwordx4 v[214:215], off
	v_lshl_add_u64 v[214:215], s[74:75], 0, v[128:129]
	s_add_i32 m0, s52, 0x2000
	s_nop 0
	global_load_lds_dwordx4 v[214:215], off
	v_lshl_add_u64 v[214:215], s[38:39], 0, v[134:135]
	s_mov_b32 m0, s48
	s_nop 0
	global_load_lds_dwordx4 v[214:215], off
	s_mov_b32 m0, s49
	s_nop 0
	global_load_lds_dwordx4 v[216:217], off
	s_waitcnt vmcnt(8)
	s_waitcnt lgkmcnt(0)
	s_barrier
; #define PG8_STAGE(bufoff, gbase, voff) do { _Pragma("unroll") for (int _i = 0; _i < 2; ++_i) \
;         __builtin_amdgcn_global_load_lds((const unsigned*)((const char*)(gbase) + (voff)[_i]), (PG8_LAS unsigned*)(lds + (bufoff) + ldsw + _i * 8192), 16, 0, 0); } while (0)
; #define PG8_LDA(dst, b, h) do { _Pragma("unroll") for (int m = 0; m < 4; ++m) _Pragma("unroll") for (int k = 0; k < 2; ++k) dst[m][k] = *(const PG8_LAS bf16x8*)(lds + PG8_SA(b, h) + aoff + m * 2048 + k * 1024); } while (0)
; #define PG8_LDB(dst, b, h) do { _Pragma("unroll") for (int n = 0; n < 2; ++n) _Pragma("unroll") for (int k = 0; k < 2; ++k) dst[n][k] = *(const PG8_LAS bf16x8*)(lds + PG8_SB(b, h) + boff + n * 2048 + k * 1024); } while (0)
; #define PG8_MMA(ai, bj, At, Bt) do { __builtin_amdgcn_s_setprio(1); _Pragma("unroll") for (int m = 0; m < 4; ++m) _Pragma("unroll") for (int n = 0; n < 2; ++n) _Pragma("unroll") for (int k = 0; k < 2; ++k) \
;         acc[ai][bj][m][n] = __builtin_amdgcn_mfma_f32_16x16x32_bf16(Bt[n][k], At[m][k], acc[ai][bj][m][n], 0, 0, 0); __builtin_amdgcn_s_setprio(0); } while (0)
; #define PG8_WAIT_V(n) asm volatile("s_waitcnt vmcnt(" #n ")" ::: "memory")
; #define PG8_WAIT_L(n) asm volatile("s_waitcnt lgkmcnt(" #n ")" ::: "memory")
; #define PG8_BAR __builtin_amdgcn_s_barrier()
; #define PG8_SCHED __builtin_amdgcn_sched_barrier(0)
; template <class Epi, class Sched, bool ALIGN_EPI = true, bool SP2 = true>
; __device__ __forceinline__ void gemm_phase(PG8_LAS unsigned char* lds, const Gemm g, const Sched& S, const Epi& E) {
;     ...
;             PG8_WAIT_V(8); PG8_WAIT_L(0); PG8_BAR; PG8_MMA(1, 0, At, B0); PG8_MMA(1, 1, At, B1); PG8_BAR; PG8_SCHED;
;             PG8_LDB(B0, 1, 0); PG8_LDB(B1, 1, 1); PG8_SCHED; PG8_LDA(At, 1, 0); PG8_STAGE(PG8_SA(0, 1), a2 + hstepA, voffA);
;             PG8_WAIT_V(8); PG8_WAIT_L(0); PG8_BAR; PG8_MMA(0, 0, At, B0); PG8_MMA(0, 1, At, B1); PG8_BAR; PG8_SCHED;
	s_setprio 1
	v_mfma_f32_16x16x32_bf16 v[60:63], v[146:149], v[178:181], v[60:63]
	v_mfma_f32_16x16x32_bf16 v[56:59], v[154:157], v[178:181], v[56:59]
	v_mfma_f32_16x16x32_bf16 v[52:55], v[146:149], v[186:189], v[52:55]
	v_mfma_f32_16x16x32_bf16 v[48:51], v[154:157], v[186:189], v[48:51]
	v_mfma_f32_16x16x32_bf16 v[36:39], v[146:149], v[194:197], v[36:39]
	v_mfma_f32_16x16x32_bf16 v[32:35], v[154:157], v[194:197], v[32:35]
	v_mfma_f32_16x16x32_bf16 v[20:23], v[146:149], v[202:205], v[20:23]
	v_mfma_f32_16x16x32_bf16 v[16:19], v[154:157], v[202:205], v[16:19]
	v_mfma_f32_16x16x32_bf16 v[60:63], v[150:153], v[182:185], v[60:63]
	v_mfma_f32_16x16x32_bf16 v[56:59], v[158:161], v[182:185], v[56:59]
	v_mfma_f32_16x16x32_bf16 v[52:55], v[150:153], v[190:193], v[52:55]
	v_mfma_f32_16x16x32_bf16 v[48:51], v[158:161], v[190:193], v[48:51]
	v_mfma_f32_16x16x32_bf16 v[36:39], v[150:153], v[198:201], v[36:39]
	v_mfma_f32_16x16x32_bf16 v[32:35], v[158:161], v[198:201], v[32:35]
	v_mfma_f32_16x16x32_bf16 v[20:23], v[150:153], v[206:209], v[20:23]
	v_mfma_f32_16x16x32_bf16 v[16:19], v[158:161], v[206:209], v[16:19]
	v_mfma_f32_16x16x32_bf16 v[44:47], v[162:165], v[178:181], v[44:47]
	v_mfma_f32_16x16x32_bf16 v[40:43], v[170:173], v[178:181], v[40:43]
	v_mfma_f32_16x16x32_bf16 v[28:31], v[162:165], v[186:189], v[28:31]
	v_mfma_f32_16x16x32_bf16 v[24:27], v[170:173], v[186:189], v[24:27]
	v_mfma_f32_16x16x32_bf16 v[12:15], v[162:165], v[194:197], v[12:15]
	v_mfma_f32_16x16x32_bf16 v[8:11], v[170:173], v[194:197], v[8:11]
	v_mfma_f32_16x16x32_bf16 v[4:7], v[162:165], v[202:205], v[4:7]
	v_mfma_f32_16x16x32_bf16 v[0:3], v[170:173], v[202:205], v[0:3]
	v_mfma_f32_16x16x32_bf16 v[44:47], v[166:169], v[182:185], v[44:47]
	v_mfma_f32_16x16x32_bf16 v[40:43], v[174:177], v[182:185], v[40:43]
	v_mfma_f32_16x16x32_bf16 v[28:31], v[166:169], v[190:193], v[28:31]
	v_mfma_f32_16x16x32_bf16 v[24:27], v[174:177], v[190:193], v[24:27]
	v_mfma_f32_16x16x32_bf16 v[12:15], v[166:169], v[198:201], v[12:15]
	v_mfma_f32_16x16x32_bf16 v[8:11], v[174:177], v[198:201], v[8:11]
	v_mfma_f32_16x16x32_bf16 v[4:7], v[166:169], v[206:209], v[4:7]
	v_mfma_f32_16x16x32_bf16 v[0:3], v[174:177], v[206:209], v[0:3]
	s_setprio 0
	s_barrier
	s_add_i32 s52, 0, 0x18000
	s_add_i32 s53, 0, 0x1c000
	v_add_u32_e32 v158, s52, v141
	v_add_u32_e32 v174, s53, v141
	ds_read_b128 v[146:149], v158
	ds_read_b128 v[150:153], v158 offset:1024
	ds_read_b128 v[154:157], v158 offset:2048
	ds_read_b128 v[158:161], v158 offset:3072
	ds_read_b128 v[162:165], v174
	ds_read_b128 v[166:169], v174 offset:1024
	ds_read_b128 v[170:173], v174 offset:2048
	ds_read_b128 v[174:177], v174 offset:3072
	s_add_u32 s38, s38, 0x40000
	s_addc_u32 s39, s39, 0
	s_mov_b32 m0, s50
	v_lshl_add_u64 v[218:219], s[38:39], 0, v[134:135]
	ds_read_b128 v[178:181], v145 offset:32768
	ds_read_b128 v[182:185], v145 offset:33792
	ds_read_b128 v[186:189], v145 offset:34816
	ds_read_b128 v[190:193], v145 offset:35840
	ds_read_b128 v[194:197], v145 offset:36864
	ds_read_b128 v[198:201], v145 offset:37888
	ds_read_b128 v[202:205], v145 offset:38912
	ds_read_b128 v[206:209], v145 offset:39936
	global_load_lds_dwordx4 v[218:219], off
	v_lshl_add_u64 v[218:219], s[38:39], 0, v[130:131]
	s_mov_b32 m0, s51
	s_nop 0
	global_load_lds_dwordx4 v[218:219], off
	s_waitcnt vmcnt(8)
	s_waitcnt lgkmcnt(0)
	s_barrier
	s_setprio 1
	v_mfma_f32_16x16x32_bf16 v[124:127], v[146:149], v[178:181], v[124:127]
	v_mfma_f32_16x16x32_bf16 v[120:123], v[154:157], v[178:181], v[120:123]
	v_mfma_f32_16x16x32_bf16 v[116:119], v[146:149], v[186:189], v[116:119]
	v_mfma_f32_16x16x32_bf16 v[112:115], v[154:157], v[186:189], v[112:115]
	v_mfma_f32_16x16x32_bf16 v[100:103], v[146:149], v[194:197], v[100:103]
	v_mfma_f32_16x16x32_bf16 v[96:99], v[154:157], v[194:197], v[96:99]
	v_mfma_f32_16x16x32_bf16 v[84:87], v[146:149], v[202:205], v[84:87]
	v_mfma_f32_16x16x32_bf16 v[80:83], v[154:157], v[202:205], v[80:83]
	v_mfma_f32_16x16x32_bf16 v[124:127], v[150:153], v[182:185], v[124:127]
	v_mfma_f32_16x16x32_bf16 v[120:123], v[158:161], v[182:185], v[120:123]
	v_mfma_f32_16x16x32_bf16 v[116:119], v[150:153], v[190:193], v[116:119]
	v_mfma_f32_16x16x32_bf16 v[112:115], v[158:161], v[190:193], v[112:115]
	v_mfma_f32_16x16x32_bf16 v[100:103], v[150:153], v[198:201], v[100:103]
	v_mfma_f32_16x16x32_bf16 v[96:99], v[158:161], v[198:201], v[96:99]
	v_mfma_f32_16x16x32_bf16 v[84:87], v[150:153], v[206:209], v[84:87]
	v_mfma_f32_16x16x32_bf16 v[80:83], v[158:161], v[206:209], v[80:83]
	v_mfma_f32_16x16x32_bf16 v[108:111], v[162:165], v[178:181], v[108:111]
	v_mfma_f32_16x16x32_bf16 v[104:107], v[170:173], v[178:181], v[104:107]
	v_mfma_f32_16x16x32_bf16 v[92:95], v[162:165], v[186:189], v[92:95]
	v_mfma_f32_16x16x32_bf16 v[88:91], v[170:173], v[186:189], v[88:91]
	v_mfma_f32_16x16x32_bf16 v[76:79], v[162:165], v[194:197], v[76:79]
	v_mfma_f32_16x16x32_bf16 v[72:75], v[170:173], v[194:197], v[72:75]
	v_mfma_f32_16x16x32_bf16 v[68:71], v[162:165], v[202:205], v[68:71]
	v_mfma_f32_16x16x32_bf16 v[64:67], v[170:173], v[202:205], v[64:67]
	v_mfma_f32_16x16x32_bf16 v[108:111], v[166:169], v[182:185], v[108:111]
	v_mfma_f32_16x16x32_bf16 v[104:107], v[174:177], v[182:185], v[104:107]
	v_mfma_f32_16x16x32_bf16 v[92:95], v[166:169], v[190:193], v[92:95]
	v_mfma_f32_16x16x32_bf16 v[88:91], v[174:177], v[190:193], v[88:91]
	v_mfma_f32_16x16x32_bf16 v[76:79], v[166:169], v[198:201], v[76:79]
	v_mfma_f32_16x16x32_bf16 v[72:75], v[174:177], v[198:201], v[72:75]
	v_mfma_f32_16x16x32_bf16 v[68:71], v[166:169], v[206:209], v[68:71]
	v_mfma_f32_16x16x32_bf16 v[64:67], v[174:177], v[206:209], v[64:67]
	s_setprio 0
	s_barrier
; #define PG8_STAGE(bufoff, gbase, voff) do { _Pragma("unroll") for (int _i = 0; _i < 2; ++_i) \
;         __builtin_amdgcn_global_load_lds((const unsigned*)((const char*)(gbase) + (voff)[_i]), (PG8_LAS unsigned*)(lds + (bufoff) + ldsw + _i * 8192), 16, 0, 0); } while (0)
; #define PG8_LDA(dst, b, h) do { _Pragma("unroll") for (int m = 0; m < 4; ++m) _Pragma("unroll") for (int k = 0; k < 2; ++k) dst[m][k] = *(const PG8_LAS bf16x8*)(lds + PG8_SA(b, h) + aoff + m * 2048 + k * 1024); } while (0)
; #define PG8_MMA(ai, bj, At, Bt) do { __builtin_amdgcn_s_setprio(1); _Pragma("unroll") for (int m = 0; m < 4; ++m) _Pragma("unroll") for (int n = 0; n < 2; ++n) _Pragma("unroll") for (int k = 0; k < 2; ++k) \
;         acc[ai][bj][m][n] = __builtin_amdgcn_mfma_f32_16x16x32_bf16(Bt[n][k], At[m][k], acc[ai][bj][m][n], 0, 0, 0); __builtin_amdgcn_s_setprio(0); } while (0)
; #define PG8_WAIT_V(n) asm volatile("s_waitcnt vmcnt(" #n ")" ::: "memory")
; #define PG8_WAIT_L(n) asm volatile("s_waitcnt lgkmcnt(" #n ")" ::: "memory")
; #define PG8_BAR __builtin_amdgcn_s_barrier()
; #define PG8_SCHED __builtin_amdgcn_sched_barrier(0)
; template <class Epi, class Sched, bool ALIGN_EPI = true, bool SP2 = true>
; __device__ __forceinline__ void gemm_phase(PG8_LAS unsigned char* lds, const Gemm g, const Sched& S, const Epi& E) {
;     ...
;             PG8_LDA(At, 1, 1); PG8_STAGE(PG8_SB(1, 0), b3, voffB); PG8_STAGE(PG8_SB(1, 1), b3 + hstepB, voffB); PG8_STAGE(PG8_SA(1, 0), a3, voffA);
;             PG8_WAIT_V(8); PG8_WAIT_L(0); PG8_BAR; PG8_MMA(1, 0, At, B0); PG8_MMA(1, 1, At, B1); PG8_BAR; PG8_SCHED;
;         }
;         if constexpr (ALIGN_EPI) { if (wr == 0) PG8_BAR; }
	s_add_i32 s38, s52, s46
	v_lshl_add_u64 v[210:211], v[210:211], 0, s[8:9]
	s_mov_b32 m0, s38
	ds_read_b128 v[178:181], v145 offset:49152
	ds_read_b128 v[182:185], v145 offset:50176
	ds_read_b128 v[186:189], v145 offset:51200
	ds_read_b128 v[190:193], v145 offset:52224
	ds_read_b128 v[194:197], v145 offset:53248
	ds_read_b128 v[198:201], v145 offset:54272
	ds_read_b128 v[202:205], v145 offset:55296
	ds_read_b128 v[206:209], v145 offset:56320
	global_load_lds_dwordx4 v[210:211], off
	s_add_i32 m0, s38, 0x2000
	s_add_u32 s36, s36, 0x40080
	v_lshl_add_u64 v[210:211], v[212:213], 0, s[8:9]
	s_addc_u32 s37, s37, 0
	s_add_i32 s38, s53, s46
	global_load_lds_dwordx4 v[210:211], off
	v_lshl_add_u64 v[210:211], s[36:37], 0, v[132:133]
	s_mov_b32 m0, s38
	s_nop 0
	global_load_lds_dwordx4 v[210:211], off
	v_lshl_add_u64 v[210:211], s[36:37], 0, v[128:129]
	s_add_i32 m0, s38, 0x2000
	s_nop 0
	global_load_lds_dwordx4 v[210:211], off
	v_lshl_add_u64 v[210:211], v[214:215], 0, s[8:9]
	s_mov_b32 m0, s56
	s_nop 0
	global_load_lds_dwordx4 v[210:211], off
	v_lshl_add_u64 v[210:211], v[216:217], 0, s[8:9]
	s_mov_b32 m0, s57
	s_nop 0
	global_load_lds_dwordx4 v[210:211], off
	s_waitcnt vmcnt(8)
	s_waitcnt lgkmcnt(0)
	s_barrier
	s_setprio 1
	v_mfma_f32_16x16x32_bf16 v[60:63], v[146:149], v[178:181], v[60:63]
	v_mfma_f32_16x16x32_bf16 v[56:59], v[154:157], v[178:181], v[56:59]
	v_mfma_f32_16x16x32_bf16 v[52:55], v[146:149], v[186:189], v[52:55]
	v_mfma_f32_16x16x32_bf16 v[48:51], v[154:157], v[186:189], v[48:51]
	v_mfma_f32_16x16x32_bf16 v[36:39], v[146:149], v[194:197], v[36:39]
	v_mfma_f32_16x16x32_bf16 v[32:35], v[154:157], v[194:197], v[32:35]
	v_mfma_f32_16x16x32_bf16 v[20:23], v[146:149], v[202:205], v[20:23]
	v_mfma_f32_16x16x32_bf16 v[16:19], v[154:157], v[202:205], v[16:19]
	v_mfma_f32_16x16x32_bf16 v[60:63], v[150:153], v[182:185], v[60:63]
	v_mfma_f32_16x16x32_bf16 v[56:59], v[158:161], v[182:185], v[56:59]
	v_mfma_f32_16x16x32_bf16 v[52:55], v[150:153], v[190:193], v[52:55]
	v_mfma_f32_16x16x32_bf16 v[48:51], v[158:161], v[190:193], v[48:51]
	v_mfma_f32_16x16x32_bf16 v[36:39], v[150:153], v[198:201], v[36:39]
	v_mfma_f32_16x16x32_bf16 v[32:35], v[158:161], v[198:201], v[32:35]
	v_mfma_f32_16x16x32_bf16 v[20:23], v[150:153], v[206:209], v[20:23]
	v_mfma_f32_16x16x32_bf16 v[16:19], v[158:161], v[206:209], v[16:19]
	v_mfma_f32_16x16x32_bf16 v[44:47], v[162:165], v[178:181], v[44:47]
	v_mfma_f32_16x16x32_bf16 v[40:43], v[170:173], v[178:181], v[40:43]
	v_mfma_f32_16x16x32_bf16 v[28:31], v[162:165], v[186:189], v[28:31]
	v_mfma_f32_16x16x32_bf16 v[24:27], v[170:173], v[186:189], v[24:27]
	v_mfma_f32_16x16x32_bf16 v[12:15], v[162:165], v[194:197], v[12:15]
	v_mfma_f32_16x16x32_bf16 v[8:11], v[170:173], v[194:197], v[8:11]
	v_mfma_f32_16x16x32_bf16 v[4:7], v[162:165], v[202:205], v[4:7]
	v_mfma_f32_16x16x32_bf16 v[0:3], v[170:173], v[202:205], v[0:3]
	v_mfma_f32_16x16x32_bf16 v[44:47], v[166:169], v[182:185], v[44:47]
	v_mfma_f32_16x16x32_bf16 v[40:43], v[174:177], v[182:185], v[40:43]
	v_mfma_f32_16x16x32_bf16 v[28:31], v[166:169], v[190:193], v[28:31]
	v_mfma_f32_16x16x32_bf16 v[24:27], v[174:177], v[190:193], v[24:27]
	v_mfma_f32_16x16x32_bf16 v[12:15], v[166:169], v[198:201], v[12:15]
	v_mfma_f32_16x16x32_bf16 v[8:11], v[174:177], v[198:201], v[8:11]
	v_mfma_f32_16x16x32_bf16 v[4:7], v[166:169], v[206:209], v[4:7]
	v_mfma_f32_16x16x32_bf16 v[0:3], v[174:177], v[206:209], v[0:3]
	s_setprio 0
	s_barrier
	s_add_i32 s73, s73, 2
	s_add_u32 s71, s71, 0x100
	s_addc_u32 s72, s72, 0
	s_add_u32 s34, s34, 0x100
	s_addc_u32 s35, s35, 0
	s_cmp_gt_u32 s73, 13
	s_cbranch_scc0 .LBB0_306
	s_and_b64 vcc, exec, s[10:11]
	s_cbranch_vccz .LBB0_309
	s_barrier

; #define PG8_STAGE(bufoff, gbase, voff) do { _Pragma("unroll") for (int _i = 0; _i < 2; ++_i) \
;         __builtin_amdgcn_global_load_lds((const unsigned*)((const char*)(gbase) + (voff)[_i]), (PG8_LAS unsigned*)(lds + (bufoff) + ldsw + _i * 8192), 16, 0, 0); } while (0)
; #define PG8_LDA(dst, b, h) do { _Pragma("unroll") for (int m = 0; m < 4; ++m) _Pragma("unroll") for (int k = 0; k < 2; ++k) dst[m][k] = *(const PG8_LAS bf16x8*)(lds + PG8_SA(b, h) + aoff + m * 2048 + k * 1024); } while (0)
; #define PG8_LDB(dst, b, h) do { _Pragma("unroll") for (int n = 0; n < 2; ++n) _Pragma("unroll") for (int k = 0; k < 2; ++k) dst[n][k] = *(const PG8_LAS bf16x8*)(lds + PG8_SB(b, h) + boff + n * 2048 + k * 1024); } while (0)
; #define PG8_MMA(ai, bj, At, Bt) do { __builtin_amdgcn_s_setprio(1); _Pragma("unroll") for (int m = 0; m < 4; ++m) _Pragma("unroll") for (int n = 0; n < 2; ++n) _Pragma("unroll") for (int k = 0; k < 2; ++k) \
;         acc[ai][bj][m][n] = __builtin_amdgcn_mfma_f32_16x16x32_bf16(Bt[n][k], At[m][k], acc[ai][bj][m][n], 0, 0, 0); __builtin_amdgcn_s_setprio(0); } while (0)
; #define PG8_WAIT_V(n) asm volatile("s_waitcnt vmcnt(" #n ")" ::: "memory")
; #define PG8_WAIT_L(n) asm volatile("s_waitcnt lgkmcnt(" #n ")" ::: "memory")
; #define PG8_BAR __builtin_amdgcn_s_barrier()
; #define PG8_SCHED __builtin_amdgcn_sched_barrier(0)
; template <class Epi, class Sched, bool ALIGN_EPI = true, bool SP2 = true>
; __device__ __forceinline__ void gemm_phase(PG8_LAS unsigned char* lds, const Gemm g, const Sched& S, const Epi& E) {
;     ...
;             const bool last = (t == nt - 2);
;             const char* a1 = cA + (size_t)(t + 1) * kstep;
;             const char* a2 = last ? nA : cA + (size_t)(t + 2) * kstep; const char* b2 = last ? nB : cB + (size_t)(t + 2) * kstep;
;             const char* a3 = a2 + kstep; const char* b3 = b2 + kstep;
;             PG8_LDB(B0, 0, 0); PG8_LDB(B1, 0, 1); PG8_SCHED; PG8_LDA(At, 0, 0); PG8_STAGE(PG8_SA(1, 1), a1 + hstepA, voffA);
;             PG8_WAIT_V(8); PG8_WAIT_L(0); PG8_BAR; PG8_MMA(0, 0, At, B0); PG8_MMA(0, 1, At, B1); PG8_BAR; PG8_SCHED;
;             PG8_LDA(At, 0, 1); PG8_STAGE(PG8_SB(0, 0), b2, voffB); PG8_STAGE(PG8_SB(0, 1), b2 + hstepB, voffB); PG8_STAGE(PG8_SA(0, 0), a2, voffA);
.LBB0_387:
	s_add_u32 s31, s20, s30
	s_addc_u32 s38, s21, 0
	s_add_u32 s36, s31, 0x100
	s_addc_u32 s37, s38, 0
	s_and_b64 s[34:35], s[28:29], exec
	s_cselect_b32 s35, s17, s37
	s_cselect_b32 s34, s63, s36
	s_add_u32 s30, s18, s30
	s_addc_u32 s36, s19, 0
	s_add_u32 s30, s30, 0x100
	s_addc_u32 s36, s36, 0
	s_and_b64 s[28:29], s[28:29], exec
	s_cselect_b32 s37, s15, s36
	s_cselect_b32 s36, s64, s30
	s_add_u32 s40, s31, 0x10080
	ds_read_b128 v[146:149], v143
	ds_read_b128 v[150:153], v143 offset:1024
	ds_read_b128 v[154:157], v143 offset:2048
	ds_read_b128 v[158:161], v143 offset:3072
	ds_read_b128 v[162:165], v144
	ds_read_b128 v[166:169], v144 offset:1024
	ds_read_b128 v[170:173], v144 offset:2048
	ds_read_b128 v[174:177], v144 offset:3072
	s_addc_u32 s41, s38, 0
	s_add_i32 s76, s59, s46
	s_add_i32 m0, s13, 0xc000
	s_add_i32 s52, s13, 0xe000
	s_add_i32 s73, s76, 0x2000
	s_add_u32 s38, s36, 0x10000
	s_addc_u32 s39, s37, 0
	s_add_i32 s75, s60, s46
	s_add_i32 s74, s75, 0x2000
	s_add_i32 s72, 0, 0x18000
	s_add_i32 s71, 0, 0x1c000
	s_add_u32 s30, s34, 0x10000
	s_addc_u32 s31, s35, 0
	s_add_i32 s66, s72, s46
	s_add_i32 s65, s66, 0x2000
	s_add_u32 s28, s36, 0x10080
	s_addc_u32 s29, s37, 0
	s_add_i32 s78, s71, s46
	s_add_i32 s77, s78, 0x2000
	v_lshl_add_u64 v[210:211], s[40:41], 0, v[134:135]
	ds_read_b128 v[178:181], v145
	ds_read_b128 v[182:185], v145 offset:1024
	ds_read_b128 v[186:189], v145 offset:2048
	ds_read_b128 v[190:193], v145 offset:3072
	ds_read_b128 v[194:197], v145 offset:4096
	ds_read_b128 v[198:201], v145 offset:5120
	ds_read_b128 v[202:205], v145 offset:6144
	ds_read_b128 v[206:209], v145 offset:7168
	global_load_lds_dwordx4 v[210:211], off
	v_lshl_add_u64 v[210:211], s[40:41], 0, v[130:131]
	s_mov_b32 m0, s52
	s_nop 0
	global_load_lds_dwordx4 v[210:211], off
	s_waitcnt vmcnt(8)
	s_waitcnt lgkmcnt(0)
	s_barrier
	s_setprio 1
	v_mfma_f32_16x16x32_bf16 v[124:127], v[146:149], v[178:181], v[124:127]
	v_mfma_f32_16x16x32_bf16 v[120:123], v[154:157], v[178:181], v[120:123]
	v_mfma_f32_16x16x32_bf16 v[116:119], v[146:149], v[186:189], v[116:119]
	v_mfma_f32_16x16x32_bf16 v[112:115], v[154:157], v[186:189], v[112:115]
	v_mfma_f32_16x16x32_bf16 v[100:103], v[146:149], v[194:197], v[100:103]
	v_mfma_f32_16x16x32_bf16 v[96:99], v[154:157], v[194:197], v[96:99]
	v_mfma_f32_16x16x32_bf16 v[84:87], v[146:149], v[202:205], v[84:87]
	v_mfma_f32_16x16x32_bf16 v[80:83], v[154:157], v[202:205], v[80:83]
	v_mfma_f32_16x16x32_bf16 v[124:127], v[150:153], v[182:185], v[124:127]
	v_mfma_f32_16x16x32_bf16 v[120:123], v[158:161], v[182:185], v[120:123]
	v_mfma_f32_16x16x32_bf16 v[116:119], v[150:153], v[190:193], v[116:119]
	v_mfma_f32_16x16x32_bf16 v[112:115], v[158:161], v[190:193], v[112:115]
	v_mfma_f32_16x16x32_bf16 v[100:103], v[150:153], v[198:201], v[100:103]
	v_mfma_f32_16x16x32_bf16 v[96:99], v[158:161], v[198:201], v[96:99]
	v_mfma_f32_16x16x32_bf16 v[84:87], v[150:153], v[206:209], v[84:87]
	v_mfma_f32_16x16x32_bf16 v[80:83], v[158:161], v[206:209], v[80:83]
	v_mfma_f32_16x16x32_bf16 v[108:111], v[162:165], v[178:181], v[108:111]
	v_mfma_f32_16x16x32_bf16 v[104:107], v[170:173], v[178:181], v[104:107]
	v_mfma_f32_16x16x32_bf16 v[92:95], v[162:165], v[186:189], v[92:95]
	v_mfma_f32_16x16x32_bf16 v[88:91], v[170:173], v[186:189], v[88:91]
	v_mfma_f32_16x16x32_bf16 v[76:79], v[162:165], v[194:197], v[76:79]
	v_mfma_f32_16x16x32_bf16 v[72:75], v[170:173], v[194:197], v[72:75]
	v_mfma_f32_16x16x32_bf16 v[68:71], v[162:165], v[202:205], v[68:71]
	v_mfma_f32_16x16x32_bf16 v[64:67], v[170:173], v[202:205], v[64:67]
	v_mfma_f32_16x16x32_bf16 v[108:111], v[166:169], v[182:185], v[108:111]
	v_mfma_f32_16x16x32_bf16 v[104:107], v[174:177], v[182:185], v[104:107]
	v_mfma_f32_16x16x32_bf16 v[92:95], v[166:169], v[190:193], v[92:95]
	v_mfma_f32_16x16x32_bf16 v[88:91], v[174:177], v[190:193], v[88:91]
	v_mfma_f32_16x16x32_bf16 v[76:79], v[166:169], v[198:201], v[76:79]
	v_mfma_f32_16x16x32_bf16 v[72:75], v[174:177], v[198:201], v[72:75]
	v_mfma_f32_16x16x32_bf16 v[68:71], v[166:169], v[206:209], v[68:71]
	v_mfma_f32_16x16x32_bf16 v[64:67], v[174:177], v[206:209], v[64:67]
	s_setprio 0
	s_barrier
	s_mov_b32 m0, s76
	v_lshl_add_u64 v[210:211], s[36:37], 0, v[132:133]
	ds_read_b128 v[178:181], v145 offset:16384
	ds_read_b128 v[182:185], v145 offset:17408
	ds_read_b128 v[186:189], v145 offset:18432
	ds_read_b128 v[190:193], v145 offset:19456
	ds_read_b128 v[194:197], v145 offset:20480
	ds_read_b128 v[198:201], v145 offset:21504
	ds_read_b128 v[202:205], v145 offset:22528
	ds_read_b128 v[206:209], v145 offset:23552
	global_load_lds_dwordx4 v[210:211], off
	v_lshl_add_u64 v[212:213], s[36:37], 0, v[128:129]
	s_mov_b32 m0, s73
	v_lshl_add_u64 v[214:215], s[38:39], 0, v[132:133]
	global_load_lds_dwordx4 v[212:213], off
	s_mov_b32 m0, s75
	v_lshl_add_u64 v[216:217], s[34:35], 0, v[130:131]
	global_load_lds_dwordx4 v[214:215], off
	v_lshl_add_u64 v[214:215], s[38:39], 0, v[128:129]
	s_mov_b32 m0, s74
	s_nop 0
	global_load_lds_dwordx4 v[214:215], off
	v_lshl_add_u64 v[214:215], s[34:35], 0, v[134:135]
	s_mov_b32 m0, s13
	s_nop 0
	global_load_lds_dwordx4 v[214:215], off
	s_mov_b32 m0, s48
	s_nop 0
	global_load_lds_dwordx4 v[216:217], off
	s_waitcnt vmcnt(8)
	s_waitcnt lgkmcnt(0)
	s_barrier
; #define PG8_STAGE(bufoff, gbase, voff) do { _Pragma("unroll") for (int _i = 0; _i < 2; ++_i) \
;         __builtin_amdgcn_global_load_lds((const unsigned*)((const char*)(gbase) + (voff)[_i]), (PG8_LAS unsigned*)(lds + (bufoff) + ldsw + _i * 8192), 16, 0, 0); } while (0)
; #define PG8_LDA(dst, b, h) do { _Pragma("unroll") for (int m = 0; m < 4; ++m) _Pragma("unroll") for (int k = 0; k < 2; ++k) dst[m][k] = *(const PG8_LAS bf16x8*)(lds + PG8_SA(b, h) + aoff + m * 2048 + k * 1024); } while (0)
; #define PG8_LDB(dst, b, h) do { _Pragma("unroll") for (int n = 0; n < 2; ++n) _Pragma("unroll") for (int k = 0; k < 2; ++k) dst[n][k] = *(const PG8_LAS bf16x8*)(lds + PG8_SB(b, h) + boff + n * 2048 + k * 1024); } while (0)
; #define PG8_MMA(ai, bj, At, Bt) do { __builtin_amdgcn_s_setprio(1); _Pragma("unroll") for (int m = 0; m < 4; ++m) _Pragma("unroll") for (int n = 0; n < 2; ++n) _Pragma("unroll") for (int k = 0; k < 2; ++k) \
;         acc[ai][bj][m][n] = __builtin_amdgcn_mfma_f32_16x16x32_bf16(Bt[n][k], At[m][k], acc[ai][bj][m][n], 0, 0, 0); __builtin_amdgcn_s_setprio(0); } while (0)
; #define PG8_WAIT_V(n) asm volatile("s_waitcnt vmcnt(" #n ")" ::: "memory")
; #define PG8_WAIT_L(n) asm volatile("s_waitcnt lgkmcnt(" #n ")" ::: "memory")
; #define PG8_BAR __builtin_amdgcn_s_barrier()
; #define PG8_SCHED __builtin_amdgcn_sched_barrier(0)
; template <class Epi, class Sched, bool ALIGN_EPI = true, bool SP2 = true>
; __device__ __forceinline__ void gemm_phase(PG8_LAS unsigned char* lds, const Gemm g, const Sched& S, const Epi& E) {
;     ...
;             PG8_WAIT_V(8); PG8_WAIT_L(0); PG8_BAR; PG8_MMA(1, 0, At, B0); PG8_MMA(1, 1, At, B1); PG8_BAR; PG8_SCHED;
;             PG8_LDB(B0, 1, 0); PG8_LDB(B1, 1, 1); PG8_SCHED; PG8_LDA(At, 1, 0); PG8_STAGE(PG8_SA(0, 1), a2 + hstepA, voffA);
;             PG8_WAIT_V(8); PG8_WAIT_L(0); PG8_BAR; PG8_MMA(0, 0, At, B0); PG8_MMA(0, 1, At, B1); PG8_BAR; PG8_SCHED;
	s_setprio 1
	v_mfma_f32_16x16x32_bf16 v[60:63], v[146:149], v[178:181], v[60:63]
	v_mfma_f32_16x16x32_bf16 v[56:59], v[154:157], v[178:181], v[56:59]
	v_mfma_f32_16x16x32_bf16 v[52:55], v[146:149], v[186:189], v[52:55]
	v_mfma_f32_16x16x32_bf16 v[48:51], v[154:157], v[186:189], v[48:51]
	v_mfma_f32_16x16x32_bf16 v[36:39], v[146:149], v[194:197], v[36:39]
	v_mfma_f32_16x16x32_bf16 v[32:35], v[154:157], v[194:197], v[32:35]
	v_mfma_f32_16x16x32_bf16 v[20:23], v[146:149], v[202:205], v[20:23]
	v_mfma_f32_16x16x32_bf16 v[16:19], v[154:157], v[202:205], v[16:19]
	v_mfma_f32_16x16x32_bf16 v[60:63], v[150:153], v[182:185], v[60:63]
	v_mfma_f32_16x16x32_bf16 v[56:59], v[158:161], v[182:185], v[56:59]
	v_mfma_f32_16x16x32_bf16 v[52:55], v[150:153], v[190:193], v[52:55]
	v_mfma_f32_16x16x32_bf16 v[48:51], v[158:161], v[190:193], v[48:51]
	v_mfma_f32_16x16x32_bf16 v[36:39], v[150:153], v[198:201], v[36:39]
	v_mfma_f32_16x16x32_bf16 v[32:35], v[158:161], v[198:201], v[32:35]
	v_mfma_f32_16x16x32_bf16 v[20:23], v[150:153], v[206:209], v[20:23]
	v_mfma_f32_16x16x32_bf16 v[16:19], v[158:161], v[206:209], v[16:19]
	v_mfma_f32_16x16x32_bf16 v[44:47], v[162:165], v[178:181], v[44:47]
	v_mfma_f32_16x16x32_bf16 v[40:43], v[170:173], v[178:181], v[40:43]
	v_mfma_f32_16x16x32_bf16 v[28:31], v[162:165], v[186:189], v[28:31]
	v_mfma_f32_16x16x32_bf16 v[24:27], v[170:173], v[186:189], v[24:27]
	v_mfma_f32_16x16x32_bf16 v[12:15], v[162:165], v[194:197], v[12:15]
	v_mfma_f32_16x16x32_bf16 v[8:11], v[170:173], v[194:197], v[8:11]
	v_mfma_f32_16x16x32_bf16 v[4:7], v[162:165], v[202:205], v[4:7]
	v_mfma_f32_16x16x32_bf16 v[0:3], v[170:173], v[202:205], v[0:3]
	v_mfma_f32_16x16x32_bf16 v[44:47], v[166:169], v[182:185], v[44:47]
	v_mfma_f32_16x16x32_bf16 v[40:43], v[174:177], v[182:185], v[40:43]
	v_mfma_f32_16x16x32_bf16 v[28:31], v[166:169], v[190:193], v[28:31]
	v_mfma_f32_16x16x32_bf16 v[24:27], v[174:177], v[190:193], v[24:27]
	v_mfma_f32_16x16x32_bf16 v[12:15], v[166:169], v[198:201], v[12:15]
	v_mfma_f32_16x16x32_bf16 v[8:11], v[174:177], v[198:201], v[8:11]
	v_mfma_f32_16x16x32_bf16 v[4:7], v[166:169], v[206:209], v[4:7]
	v_mfma_f32_16x16x32_bf16 v[0:3], v[174:177], v[206:209], v[0:3]
	s_setprio 0
	s_barrier
	v_add_u32_e32 v158, s72, v141
	v_add_u32_e32 v174, s71, v141
	ds_read_b128 v[146:149], v158
	ds_read_b128 v[150:153], v158 offset:1024
	ds_read_b128 v[154:157], v158 offset:2048
	ds_read_b128 v[158:161], v158 offset:3072
	ds_read_b128 v[162:165], v174
	ds_read_b128 v[166:169], v174 offset:1024
	ds_read_b128 v[170:173], v174 offset:2048
	ds_read_b128 v[174:177], v174 offset:3072
	s_mov_b32 m0, s49
	v_lshl_add_u64 v[218:219], s[30:31], 0, v[134:135]
	ds_read_b128 v[178:181], v145 offset:32768
	ds_read_b128 v[182:185], v145 offset:33792
	ds_read_b128 v[186:189], v145 offset:34816
	ds_read_b128 v[190:193], v145 offset:35840
	ds_read_b128 v[194:197], v145 offset:36864
	ds_read_b128 v[198:201], v145 offset:37888
	ds_read_b128 v[202:205], v145 offset:38912
	ds_read_b128 v[206:209], v145 offset:39936
	global_load_lds_dwordx4 v[218:219], off
	v_lshl_add_u64 v[218:219], s[30:31], 0, v[130:131]
	s_mov_b32 m0, s50
	s_nop 0
	global_load_lds_dwordx4 v[218:219], off
	s_waitcnt vmcnt(8)
	s_waitcnt lgkmcnt(0)
	s_barrier
	s_setprio 1
	v_mfma_f32_16x16x32_bf16 v[124:127], v[146:149], v[178:181], v[124:127]
	v_mfma_f32_16x16x32_bf16 v[120:123], v[154:157], v[178:181], v[120:123]
	v_mfma_f32_16x16x32_bf16 v[116:119], v[146:149], v[186:189], v[116:119]
	v_mfma_f32_16x16x32_bf16 v[112:115], v[154:157], v[186:189], v[112:115]
	v_mfma_f32_16x16x32_bf16 v[100:103], v[146:149], v[194:197], v[100:103]
	v_mfma_f32_16x16x32_bf16 v[96:99], v[154:157], v[194:197], v[96:99]
	v_mfma_f32_16x16x32_bf16 v[84:87], v[146:149], v[202:205], v[84:87]
	v_mfma_f32_16x16x32_bf16 v[80:83], v[154:157], v[202:205], v[80:83]
	v_mfma_f32_16x16x32_bf16 v[124:127], v[150:153], v[182:185], v[124:127]
	v_mfma_f32_16x16x32_bf16 v[120:123], v[158:161], v[182:185], v[120:123]
	v_mfma_f32_16x16x32_bf16 v[116:119], v[150:153], v[190:193], v[116:119]
	v_mfma_f32_16x16x32_bf16 v[112:115], v[158:161], v[190:193], v[112:115]
	v_mfma_f32_16x16x32_bf16 v[100:103], v[150:153], v[198:201], v[100:103]
	v_mfma_f32_16x16x32_bf16 v[96:99], v[158:161], v[198:201], v[96:99]
	v_mfma_f32_16x16x32_bf16 v[84:87], v[150:153], v[206:209], v[84:87]
	v_mfma_f32_16x16x32_bf16 v[80:83], v[158:161], v[206:209], v[80:83]
	v_mfma_f32_16x16x32_bf16 v[108:111], v[162:165], v[178:181], v[108:111]
	v_mfma_f32_16x16x32_bf16 v[104:107], v[170:173], v[178:181], v[104:107]
	v_mfma_f32_16x16x32_bf16 v[92:95], v[162:165], v[186:189], v[92:95]
	v_mfma_f32_16x16x32_bf16 v[88:91], v[170:173], v[186:189], v[88:91]
	v_mfma_f32_16x16x32_bf16 v[76:79], v[162:165], v[194:197], v[76:79]
	v_mfma_f32_16x16x32_bf16 v[72:75], v[170:173], v[194:197], v[72:75]
	v_mfma_f32_16x16x32_bf16 v[68:71], v[162:165], v[202:205], v[68:71]
	v_mfma_f32_16x16x32_bf16 v[64:67], v[170:173], v[202:205], v[64:67]
	v_mfma_f32_16x16x32_bf16 v[108:111], v[166:169], v[182:185], v[108:111]
	v_mfma_f32_16x16x32_bf16 v[104:107], v[174:177], v[182:185], v[104:107]
	v_mfma_f32_16x16x32_bf16 v[92:95], v[166:169], v[190:193], v[92:95]
	v_mfma_f32_16x16x32_bf16 v[88:91], v[174:177], v[190:193], v[88:91]
	v_mfma_f32_16x16x32_bf16 v[76:79], v[166:169], v[198:201], v[76:79]
	v_mfma_f32_16x16x32_bf16 v[72:75], v[174:177], v[198:201], v[72:75]
	v_mfma_f32_16x16x32_bf16 v[68:71], v[166:169], v[206:209], v[68:71]
	v_mfma_f32_16x16x32_bf16 v[64:67], v[174:177], v[206:209], v[64:67]
	s_setprio 0
	s_barrier
; #define PG8_STAGE(bufoff, gbase, voff) do { _Pragma("unroll") for (int _i = 0; _i < 2; ++_i) \
;         __builtin_amdgcn_global_load_lds((const unsigned*)((const char*)(gbase) + (voff)[_i]), (PG8_LAS unsigned*)(lds + (bufoff) + ldsw + _i * 8192), 16, 0, 0); } while (0)
; #define PG8_LDA(dst, b, h) do { _Pragma("unroll") for (int m = 0; m < 4; ++m) _Pragma("unroll") for (int k = 0; k < 2; ++k) dst[m][k] = *(const PG8_LAS bf16x8*)(lds + PG8_SA(b, h) + aoff + m * 2048 + k * 1024); } while (0)
; #define PG8_MMA(ai, bj, At, Bt) do { __builtin_amdgcn_s_setprio(1); _Pragma("unroll") for (int m = 0; m < 4; ++m) _Pragma("unroll") for (int n = 0; n < 2; ++n) _Pragma("unroll") for (int k = 0; k < 2; ++k) \
;         acc[ai][bj][m][n] = __builtin_amdgcn_mfma_f32_16x16x32_bf16(Bt[n][k], At[m][k], acc[ai][bj][m][n], 0, 0, 0); __builtin_amdgcn_s_setprio(0); } while (0)
; #define PG8_WAIT_V(n) asm volatile("s_waitcnt vmcnt(" #n ")" ::: "memory")
; #define PG8_WAIT_L(n) asm volatile("s_waitcnt lgkmcnt(" #n ")" ::: "memory")
; #define PG8_BAR __builtin_amdgcn_s_barrier()
; #define PG8_SCHED __builtin_amdgcn_sched_barrier(0)
; template <class Epi, class Sched, bool ALIGN_EPI = true, bool SP2 = true>
; __device__ __forceinline__ void gemm_phase(PG8_LAS unsigned char* lds, const Gemm g, const Sched& S, const Epi& E) {
;     ...
;             PG8_LDA(At, 1, 1); PG8_STAGE(PG8_SB(1, 0), b3, voffB); PG8_STAGE(PG8_SB(1, 1), b3 + hstepB, voffB); PG8_STAGE(PG8_SA(1, 0), a3, voffA);
;             PG8_WAIT_V(8); PG8_WAIT_L(0); PG8_BAR; PG8_MMA(1, 0, At, B0); PG8_MMA(1, 1, At, B1); PG8_BAR; PG8_SCHED;
;         }
;         if constexpr (ALIGN_EPI) { if (wr == 0) PG8_BAR; }
	s_mov_b32 m0, s66
	v_lshl_add_u64 v[210:211], v[210:211], 0, s[8:9]
	ds_read_b128 v[178:181], v145 offset:49152
	ds_read_b128 v[182:185], v145 offset:50176
	ds_read_b128 v[186:189], v145 offset:51200
	ds_read_b128 v[190:193], v145 offset:52224
	ds_read_b128 v[194:197], v145 offset:53248
	ds_read_b128 v[198:201], v145 offset:54272
	ds_read_b128 v[202:205], v145 offset:55296
	ds_read_b128 v[206:209], v145 offset:56320
	global_load_lds_dwordx4 v[210:211], off
	v_lshl_add_u64 v[210:211], v[212:213], 0, s[8:9]
	s_mov_b32 m0, s65
	s_nop 0
	global_load_lds_dwordx4 v[210:211], off
	v_lshl_add_u64 v[210:211], s[28:29], 0, v[132:133]
	s_mov_b32 m0, s78
	s_nop 0
	global_load_lds_dwordx4 v[210:211], off
	v_lshl_add_u64 v[210:211], s[28:29], 0, v[128:129]
	s_mov_b32 m0, s77
	s_nop 0
	global_load_lds_dwordx4 v[210:211], off
	v_lshl_add_u64 v[210:211], v[214:215], 0, s[8:9]
	s_mov_b32 m0, s55
	s_nop 0
	global_load_lds_dwordx4 v[210:211], off
	v_lshl_add_u64 v[210:211], v[216:217], 0, s[8:9]
	s_mov_b32 m0, s56
	s_nop 0
	global_load_lds_dwordx4 v[210:211], off
	s_waitcnt vmcnt(8)
	s_waitcnt lgkmcnt(0)
	s_barrier
	s_setprio 1
	v_mfma_f32_16x16x32_bf16 v[60:63], v[146:149], v[178:181], v[60:63]
	v_mfma_f32_16x16x32_bf16 v[56:59], v[154:157], v[178:181], v[56:59]
	v_mfma_f32_16x16x32_bf16 v[52:55], v[146:149], v[186:189], v[52:55]
	v_mfma_f32_16x16x32_bf16 v[48:51], v[154:157], v[186:189], v[48:51]
	v_mfma_f32_16x16x32_bf16 v[36:39], v[146:149], v[194:197], v[36:39]
	v_mfma_f32_16x16x32_bf16 v[32:35], v[154:157], v[194:197], v[32:35]
	v_mfma_f32_16x16x32_bf16 v[20:23], v[146:149], v[202:205], v[20:23]
	v_mfma_f32_16x16x32_bf16 v[16:19], v[154:157], v[202:205], v[16:19]
	v_mfma_f32_16x16x32_bf16 v[60:63], v[150:153], v[182:185], v[60:63]
	v_mfma_f32_16x16x32_bf16 v[56:59], v[158:161], v[182:185], v[56:59]
	v_mfma_f32_16x16x32_bf16 v[52:55], v[150:153], v[190:193], v[52:55]
	v_mfma_f32_16x16x32_bf16 v[48:51], v[158:161], v[190:193], v[48:51]
	v_mfma_f32_16x16x32_bf16 v[36:39], v[150:153], v[198:201], v[36:39]
	v_mfma_f32_16x16x32_bf16 v[32:35], v[158:161], v[198:201], v[32:35]
	v_mfma_f32_16x16x32_bf16 v[20:23], v[150:153], v[206:209], v[20:23]
	v_mfma_f32_16x16x32_bf16 v[16:19], v[158:161], v[206:209], v[16:19]
	v_mfma_f32_16x16x32_bf16 v[44:47], v[162:165], v[178:181], v[44:47]
	v_mfma_f32_16x16x32_bf16 v[40:43], v[170:173], v[178:181], v[40:43]
	v_mfma_f32_16x16x32_bf16 v[28:31], v[162:165], v[186:189], v[28:31]
	v_mfma_f32_16x16x32_bf16 v[24:27], v[170:173], v[186:189], v[24:27]
	v_mfma_f32_16x16x32_bf16 v[12:15], v[162:165], v[194:197], v[12:15]
	v_mfma_f32_16x16x32_bf16 v[8:11], v[170:173], v[194:197], v[8:11]
	v_mfma_f32_16x16x32_bf16 v[4:7], v[162:165], v[202:205], v[4:7]
	v_mfma_f32_16x16x32_bf16 v[0:3], v[170:173], v[202:205], v[0:3]
	v_mfma_f32_16x16x32_bf16 v[44:47], v[166:169], v[182:185], v[44:47]
	v_mfma_f32_16x16x32_bf16 v[40:43], v[174:177], v[182:185], v[40:43]
	v_mfma_f32_16x16x32_bf16 v[28:31], v[166:169], v[190:193], v[28:31]
	v_mfma_f32_16x16x32_bf16 v[24:27], v[174:177], v[190:193], v[24:27]
	v_mfma_f32_16x16x32_bf16 v[12:15], v[166:169], v[198:201], v[12:15]
	v_mfma_f32_16x16x32_bf16 v[8:11], v[174:177], v[198:201], v[8:11]
	v_mfma_f32_16x16x32_bf16 v[4:7], v[166:169], v[206:209], v[4:7]
	v_mfma_f32_16x16x32_bf16 v[0:3], v[174:177], v[206:209], v[0:3]
	s_setprio 0
	s_barrier
	s_movk_i32 s30, 0x100
	s_andn2_b64 vcc, exec, s[26:27]
	s_mov_b64 s[28:29], -1
	s_mov_b64 s[26:27], 0
	s_cbranch_vccz .LBB0_387
	s_and_b64 vcc, exec, s[10:11]
	s_cbranch_vccz .LBB0_390
	s_barrier

; #define PG8_STAGE(bufoff, gbase, voff) do { _Pragma("unroll") for (int _i = 0; _i < 2; ++_i) \
;         __builtin_amdgcn_global_load_lds((const unsigned*)((const char*)(gbase) + (voff)[_i]), (PG8_LAS unsigned*)(lds + (bufoff) + ldsw + _i * 8192), 16, 0, 0); } while (0)
; #define PG8_LDA(dst, b, h) do { _Pragma("unroll") for (int m = 0; m < 4; ++m) _Pragma("unroll") for (int k = 0; k < 2; ++k) dst[m][k] = *(const PG8_LAS bf16x8*)(lds + PG8_SA(b, h) + aoff + m * 2048 + k * 1024); } while (0)
; #define PG8_LDB(dst, b, h) do { _Pragma("unroll") for (int n = 0; n < 2; ++n) _Pragma("unroll") for (int k = 0; k < 2; ++k) dst[n][k] = *(const PG8_LAS bf16x8*)(lds + PG8_SB(b, h) + boff + n * 2048 + k * 1024); } while (0)
; #define PG8_MMA(ai, bj, At, Bt) do { __builtin_amdgcn_s_setprio(1); _Pragma("unroll") for (int m = 0; m < 4; ++m) _Pragma("unroll") for (int n = 0; n < 2; ++n) _Pragma("unroll") for (int k = 0; k < 2; ++k) \
;         acc[ai][bj][m][n] = __builtin_amdgcn_mfma_f32_16x16x32_bf16(Bt[n][k], At[m][k], acc[ai][bj][m][n], 0, 0, 0); __builtin_amdgcn_s_setprio(0); } while (0)
; #define PG8_BAR __builtin_amdgcn_s_barrier()
; template <class Epi, class Sched, bool ALIGN_EPI = true, bool SP2 = true>
; __device__ __forceinline__ void gemm_phase(PG8_LAS unsigned char* lds, const Gemm g, const Sched& S, const Epi& E) {
;     ...
;         const char* nA = has_next ? (const char*)g.A + (size_t)nxt.pm * tstepA : cA; const char* nB = has_next ? (const char*)g.Bt + (size_t)nxt.pn * tstepB : cB;
;         for (int t = 0; t < nt; t += 2) {
;             const bool last = (t == nt - 2);
;             const char* a1 = cA + (size_t)(t + 1) * kstep;
;             const char* a2 = last ? nA : cA + (size_t)(t + 2) * kstep; const char* b2 = last ? nB : cB + (size_t)(t + 2) * kstep;
;             const char* a3 = a2 + kstep; const char* b3 = b2 + kstep;
;             PG8_LDB(B0, 0, 0); PG8_LDB(B1, 0, 1); PG8_SCHED; PG8_LDA(At, 0, 0); PG8_STAGE(PG8_SA(1, 1), a1 + hstepA, voffA);
;             PG8_WAIT_V(8); PG8_WAIT_L(0); PG8_BAR; PG8_MMA(0, 0, At, B0); PG8_MMA(0, 1, At, B1); PG8_BAR; PG8_SCHED;
;             PG8_LDA(At, 0, 1); PG8_STAGE(PG8_SB(0, 0), b2, voffB); PG8_STAGE(PG8_SB(0, 1), b2 + hstepB, voffB); PG8_STAGE(PG8_SA(0, 0), a2, voffA);
;             PG8_WAIT_V(8); PG8_WAIT_L(0); PG8_BAR; PG8_MMA(1, 0, At, B0); PG8_MMA(1, 1, At, B1); PG8_BAR; PG8_SCHED;
.LBB0_410:
	ds_read_b128 v[0:3], v143
	ds_read_b128 v[4:7], v143 offset:1024
	ds_read_b128 v[8:11], v143 offset:2048
	ds_read_b128 v[12:15], v143 offset:3072
	ds_read_b128 v[16:19], v144
	ds_read_b128 v[20:23], v144 offset:1024
	ds_read_b128 v[24:27], v144 offset:2048
	ds_read_b128 v[28:31], v144 offset:3072
	s_ashr_i32 s29, s28, 31
	s_lshl_b64 s[30:31], s[28:29], 16
	s_add_u32 s30, s43, s30
	s_addc_u32 s31, s45, s31
	s_and_b64 s[34:35], s[2:3], exec
	s_cselect_b32 s41, s31, s39
	s_cselect_b32 s40, s30, s38
	s_ashr_i32 s27, s26, 31
	s_lshl_b64 s[34:35], s[26:27], 16
	s_add_u32 s34, s46, s34
	s_addc_u32 s35, s47, s35
	s_and_b64 s[72:73], s[2:3], exec
	s_cselect_b32 s37, s35, s37
	s_cselect_b32 s36, s34, s36
	s_add_u32 s38, s38, 0x8080
	s_addc_u32 s39, s39, 0
	v_lshl_add_u64 v[64:65], s[38:39], 0, v[128:129]
	s_add_i32 m0, s25, 0xc000
	ds_read_b128 v[32:35], v145
	ds_read_b128 v[36:39], v145 offset:1024
	ds_read_b128 v[40:43], v145 offset:2048
	ds_read_b128 v[44:47], v145 offset:3072
	ds_read_b128 v[48:51], v145 offset:4096
	ds_read_b128 v[52:55], v145 offset:5120
	ds_read_b128 v[56:59], v145 offset:6144
	ds_read_b128 v[60:63], v145 offset:7168
	global_load_lds_dwordx4 v[64:65], off
	v_lshl_add_u64 v[64:65], s[38:39], 0, v[132:133]
	s_add_i32 m0, s25, 0xe000
	s_nop 0
	global_load_lds_dwordx4 v[64:65], off
	s_waitcnt vmcnt(8)
	s_waitcnt lgkmcnt(0)
	s_barrier
	s_setprio 1
	v_mfma_f32_16x16x32_bf16 v[80:83], v[0:3], v[48:51], 0
	v_mfma_f32_16x16x32_bf16 v[88:91], v[4:7], v[52:55], v[80:83]
	v_mfma_f32_16x16x32_bf16 v[80:83], v[8:11], v[48:51], 0
	v_mfma_f32_16x16x32_bf16 v[92:95], v[12:15], v[52:55], v[80:83]
	v_mfma_f32_16x16x32_bf16 v[80:83], v[0:3], v[56:59], 0
	v_mfma_f32_16x16x32_bf16 v[64:67], v[0:3], v[32:35], 0
	v_mfma_f32_16x16x32_bf16 v[68:71], v[8:11], v[32:35], 0
	v_mfma_f32_16x16x32_bf16 v[72:75], v[0:3], v[40:43], 0
	v_mfma_f32_16x16x32_bf16 v[76:79], v[8:11], v[40:43], 0
	v_mfma_f32_16x16x32_bf16 v[96:99], v[4:7], v[60:63], v[80:83]
	v_mfma_f32_16x16x32_bf16 v[80:83], v[8:11], v[56:59], 0
	v_mfma_f32_16x16x32_bf16 v[64:67], v[4:7], v[36:39], v[64:67]
	v_mfma_f32_16x16x32_bf16 v[68:71], v[12:15], v[36:39], v[68:71]
	v_mfma_f32_16x16x32_bf16 v[72:75], v[4:7], v[44:47], v[72:75]
	v_mfma_f32_16x16x32_bf16 v[76:79], v[12:15], v[44:47], v[76:79]
	v_mfma_f32_16x16x32_bf16 v[100:103], v[12:15], v[60:63], v[80:83]
	v_mfma_f32_16x16x32_bf16 v[80:83], v[16:19], v[32:35], 0
	v_mfma_f32_16x16x32_bf16 v[32:35], v[24:27], v[32:35], 0
	v_mfma_f32_16x16x32_bf16 v[104:107], v[20:23], v[36:39], v[80:83]
	v_mfma_f32_16x16x32_bf16 v[32:35], v[28:31], v[36:39], v[32:35]
	v_mfma_f32_16x16x32_bf16 v[36:39], v[16:19], v[40:43], 0
	v_mfma_f32_16x16x32_bf16 v[40:43], v[24:27], v[40:43], 0
	v_mfma_f32_16x16x32_bf16 v[36:39], v[20:23], v[44:47], v[36:39]
	v_mfma_f32_16x16x32_bf16 v[40:43], v[28:31], v[44:47], v[40:43]
	v_mfma_f32_16x16x32_bf16 v[44:47], v[16:19], v[48:51], 0
	v_mfma_f32_16x16x32_bf16 v[48:51], v[24:27], v[48:51], 0
	v_mfma_f32_16x16x32_bf16 v[146:149], v[28:31], v[52:55], v[48:51]
	v_mfma_f32_16x16x32_bf16 v[48:51], v[16:19], v[56:59], 0
	v_mfma_f32_16x16x32_bf16 v[150:153], v[20:23], v[60:63], v[48:51]
	v_mfma_f32_16x16x32_bf16 v[48:51], v[24:27], v[56:59], 0
	v_mfma_f32_16x16x32_bf16 v[44:47], v[20:23], v[52:55], v[44:47]
	v_mfma_f32_16x16x32_bf16 v[56:59], v[28:31], v[60:63], v[48:51]
	s_setprio 0
	s_barrier
	s_add_i32 s27, s59, s48
	v_lshl_add_u64 v[250:251], s[36:37], 0, v[130:131]
	s_mov_b32 m0, s27
	s_nop 0
	ds_read_b128 v[48:51], v145 offset:16384
	ds_read_b128 v[52:55], v145 offset:17408
	ds_read_b128 v[60:63], v145 offset:18432
	ds_read_b128 v[80:83], v145 offset:19456
	ds_read_b128 v[84:87], v145 offset:20480
	ds_read_b128 v[108:111], v145 offset:21504
	ds_read_b128 v[112:115], v145 offset:22528
	ds_read_b128 v[116:119], v145 offset:23552
	global_load_lds_dwordx4 v[250:251], off
	s_add_i32 m0, s27, 0x2000
	s_add_u32 s38, s36, 0x8000
	v_lshl_add_u64 v[252:253], s[36:37], 0, v[134:135]
	s_addc_u32 s39, s37, 0
	s_add_i32 s27, s60, s48
	global_load_lds_dwordx4 v[252:253], off
	v_lshl_add_u64 v[120:121], s[38:39], 0, v[130:131]
	s_mov_b32 m0, s27
	v_lshl_add_u64 v[136:137], s[40:41], 0, v[128:129]
	global_load_lds_dwordx4 v[120:121], off
	v_lshl_add_u64 v[120:121], s[38:39], 0, v[134:135]
	s_add_i32 m0, s27, 0x2000
	v_lshl_add_u64 v[138:139], s[40:41], 0, v[132:133]
	global_load_lds_dwordx4 v[120:121], off
	s_mov_b32 m0, s25
	s_nop 0
	global_load_lds_dwordx4 v[136:137], off
	s_mov_b32 m0, s49
	s_nop 0
	global_load_lds_dwordx4 v[138:139], off
	s_waitcnt vmcnt(8)
	s_waitcnt lgkmcnt(0)
	s_barrier
	s_setprio 1
	v_mfma_f32_16x16x32_bf16 v[120:123], v[0:3], v[48:51], 0
	v_mfma_f32_16x16x32_bf16 v[154:157], v[4:7], v[52:55], v[120:123]
	v_mfma_f32_16x16x32_bf16 v[120:123], v[8:11], v[48:51], 0
	v_mfma_f32_16x16x32_bf16 v[158:161], v[12:15], v[52:55], v[120:123]
	v_mfma_f32_16x16x32_bf16 v[120:123], v[0:3], v[60:63], 0
	v_mfma_f32_16x16x32_bf16 v[162:165], v[4:7], v[80:83], v[120:123]
	v_mfma_f32_16x16x32_bf16 v[120:123], v[8:11], v[60:63], 0
	v_mfma_f32_16x16x32_bf16 v[166:169], v[12:15], v[80:83], v[120:123]
	v_mfma_f32_16x16x32_bf16 v[120:123], v[0:3], v[84:87], 0
	v_mfma_f32_16x16x32_bf16 v[0:3], v[0:3], v[112:115], 0
	v_mfma_f32_16x16x32_bf16 v[170:173], v[4:7], v[108:111], v[120:123]
	v_mfma_f32_16x16x32_bf16 v[0:3], v[4:7], v[116:119], v[0:3]
	v_mfma_f32_16x16x32_bf16 v[4:7], v[8:11], v[112:115], 0
	v_mfma_f32_16x16x32_bf16 v[120:123], v[8:11], v[84:87], 0
	v_mfma_f32_16x16x32_bf16 v[4:7], v[12:15], v[116:119], v[4:7]
	v_mfma_f32_16x16x32_bf16 v[174:177], v[12:15], v[108:111], v[120:123]
	v_mfma_f32_16x16x32_bf16 v[8:11], v[16:19], v[48:51], 0
	v_mfma_f32_16x16x32_bf16 v[12:15], v[24:27], v[48:51], 0
	v_mfma_f32_16x16x32_bf16 v[48:51], v[16:19], v[60:63], 0
	v_mfma_f32_16x16x32_bf16 v[178:181], v[20:23], v[80:83], v[48:51]
	v_mfma_f32_16x16x32_bf16 v[48:51], v[24:27], v[60:63], 0
	v_mfma_f32_16x16x32_bf16 v[182:185], v[28:31], v[80:83], v[48:51]
	v_mfma_f32_16x16x32_bf16 v[48:51], v[16:19], v[84:87], 0
	v_mfma_f32_16x16x32_bf16 v[16:19], v[16:19], v[112:115], 0
	v_mfma_f32_16x16x32_bf16 v[8:11], v[20:23], v[52:55], v[8:11]
	v_mfma_f32_16x16x32_bf16 v[12:15], v[28:31], v[52:55], v[12:15]
	v_mfma_f32_16x16x32_bf16 v[186:189], v[20:23], v[108:111], v[48:51]
	v_mfma_f32_16x16x32_bf16 v[48:51], v[24:27], v[84:87], 0
	v_mfma_f32_16x16x32_bf16 v[194:197], v[20:23], v[116:119], v[16:19]
	v_mfma_f32_16x16x32_bf16 v[16:19], v[24:27], v[112:115], 0
	v_mfma_f32_16x16x32_bf16 v[190:193], v[28:31], v[108:111], v[48:51]
	v_mfma_f32_16x16x32_bf16 v[198:201], v[28:31], v[116:119], v[16:19]
	s_setprio 0
	s_barrier
; #define PG8_STAGE(bufoff, gbase, voff) do { _Pragma("unroll") for (int _i = 0; _i < 2; ++_i) \
;         __builtin_amdgcn_global_load_lds((const unsigned*)((const char*)(gbase) + (voff)[_i]), (PG8_LAS unsigned*)(lds + (bufoff) + ldsw + _i * 8192), 16, 0, 0); } while (0)
; #define PG8_LDA(dst, b, h) do { _Pragma("unroll") for (int m = 0; m < 4; ++m) _Pragma("unroll") for (int k = 0; k < 2; ++k) dst[m][k] = *(const PG8_LAS bf16x8*)(lds + PG8_SA(b, h) + aoff + m * 2048 + k * 1024); } while (0)
; #define PG8_LDB(dst, b, h) do { _Pragma("unroll") for (int n = 0; n < 2; ++n) _Pragma("unroll") for (int k = 0; k < 2; ++k) dst[n][k] = *(const PG8_LAS bf16x8*)(lds + PG8_SB(b, h) + boff + n * 2048 + k * 1024); } while (0)
; #define PG8_MMA(ai, bj, At, Bt) do { __builtin_amdgcn_s_setprio(1); _Pragma("unroll") for (int m = 0; m < 4; ++m) _Pragma("unroll") for (int n = 0; n < 2; ++n) _Pragma("unroll") for (int k = 0; k < 2; ++k) \
;         acc[ai][bj][m][n] = __builtin_amdgcn_mfma_f32_16x16x32_bf16(Bt[n][k], At[m][k], acc[ai][bj][m][n], 0, 0, 0); __builtin_amdgcn_s_setprio(0); } while (0)
; #define PG8_WAIT_V(n) asm volatile("s_waitcnt vmcnt(" #n ")" ::: "memory")
; #define PG8_WAIT_L(n) asm volatile("s_waitcnt lgkmcnt(" #n ")" ::: "memory")
; #define PG8_BAR __builtin_amdgcn_s_barrier()
; #define PG8_SCHED __builtin_amdgcn_sched_barrier(0)
; template <class Epi, class Sched, bool ALIGN_EPI = true, bool SP2 = true>
; __device__ __forceinline__ void gemm_phase(PG8_LAS unsigned char* lds, const Gemm g, const Sched& S, const Epi& E) {
;     ...
;             PG8_LDB(B0, 1, 0); PG8_LDB(B1, 1, 1); PG8_SCHED; PG8_LDA(At, 1, 0); PG8_STAGE(PG8_SA(0, 1), a2 + hstepA, voffA);
;             PG8_WAIT_V(8); PG8_WAIT_L(0); PG8_BAR; PG8_MMA(0, 0, At, B0); PG8_MMA(0, 1, At, B1); PG8_BAR; PG8_SCHED;
;             PG8_LDA(At, 1, 1); PG8_STAGE(PG8_SB(1, 0), b3, voffB); PG8_STAGE(PG8_SB(1, 1), b3 + hstepB, voffB); PG8_STAGE(PG8_SA(1, 0), a3, voffA);
;             PG8_WAIT_V(8); PG8_WAIT_L(0); PG8_BAR; PG8_MMA(1, 0, At, B0); PG8_MMA(1, 1, At, B1); PG8_BAR; PG8_SCHED;
;         }
;         if constexpr (ALIGN_EPI) { if (wr == 0) PG8_BAR; }
	s_add_i32 s27, 0, 0x18000
	s_nop 2
	v_add_u32_e32 v16, s27, v141
	s_add_i32 s29, 0, 0x1c000
	ds_read_b128 v[202:205], v16
	ds_read_b128 v[206:209], v16 offset:1024
	ds_read_b128 v[210:213], v16 offset:2048
	ds_read_b128 v[214:217], v16 offset:3072
	v_add_u32_e32 v16, s29, v141
	ds_read_b128 v[218:221], v16
	ds_read_b128 v[222:225], v16 offset:1024
	ds_read_b128 v[226:229], v16 offset:2048
	ds_read_b128 v[230:233], v16 offset:3072
	s_add_u32 s38, s40, 0x8000
	s_addc_u32 s39, s41, 0
	s_mov_b32 m0, s50
	v_lshl_add_u64 v[16:17], s[38:39], 0, v[128:129]
	ds_read_b128 v[24:27], v145 offset:32768
	ds_read_b128 v[28:31], v145 offset:33792
	ds_read_b128 v[60:63], v145 offset:34816
	ds_read_b128 v[108:111], v145 offset:35840
	ds_read_b128 v[234:237], v145 offset:36864
	ds_read_b128 v[238:241], v145 offset:37888
	ds_read_b128 v[242:245], v145 offset:38912
	ds_read_b128 v[246:249], v145 offset:39936
	global_load_lds_dwordx4 v[16:17], off
	v_lshl_add_u64 v[16:17], s[38:39], 0, v[132:133]
	s_mov_b32 m0, s51
	s_nop 0
	global_load_lds_dwordx4 v[16:17], off
	s_waitcnt vmcnt(8)
	s_waitcnt lgkmcnt(0)
	s_barrier
	s_setprio 1
	v_mfma_f32_16x16x32_bf16 v[16:19], v[202:205], v[24:27], v[64:67]
	v_mfma_f32_16x16x32_bf16 v[112:115], v[206:209], v[28:31], v[16:19]
	v_mfma_f32_16x16x32_bf16 v[16:19], v[210:213], v[24:27], v[68:71]
	v_mfma_f32_16x16x32_bf16 v[116:119], v[214:217], v[28:31], v[16:19]
	v_mfma_f32_16x16x32_bf16 v[16:19], v[202:205], v[60:63], v[72:75]
	v_mfma_f32_16x16x32_bf16 v[80:83], v[206:209], v[108:111], v[16:19]
	v_mfma_f32_16x16x32_bf16 v[16:19], v[210:213], v[60:63], v[76:79]
	v_mfma_f32_16x16x32_bf16 v[84:87], v[214:217], v[108:111], v[16:19]
	v_mfma_f32_16x16x32_bf16 v[16:19], v[202:205], v[234:237], v[88:91]
	v_mfma_f32_16x16x32_bf16 v[48:51], v[206:209], v[238:241], v[16:19]
	v_mfma_f32_16x16x32_bf16 v[16:19], v[210:213], v[234:237], v[92:95]
	v_mfma_f32_16x16x32_bf16 v[52:55], v[214:217], v[238:241], v[16:19]
	v_mfma_f32_16x16x32_bf16 v[16:19], v[202:205], v[242:245], v[96:99]
	v_mfma_f32_16x16x32_bf16 v[20:23], v[210:213], v[242:245], v[100:103]
	v_mfma_f32_16x16x32_bf16 v[16:19], v[206:209], v[246:249], v[16:19]
	v_mfma_f32_16x16x32_bf16 v[20:23], v[214:217], v[246:249], v[20:23]
	v_mfma_f32_16x16x32_bf16 v[64:67], v[218:221], v[24:27], v[104:107]
	v_mfma_f32_16x16x32_bf16 v[24:27], v[226:229], v[24:27], v[32:35]
	v_mfma_f32_16x16x32_bf16 v[124:127], v[230:233], v[28:31], v[24:27]
	v_mfma_f32_16x16x32_bf16 v[24:27], v[218:221], v[60:63], v[36:39]
	v_mfma_f32_16x16x32_bf16 v[104:107], v[222:225], v[108:111], v[24:27]
	v_mfma_f32_16x16x32_bf16 v[24:27], v[226:229], v[60:63], v[40:43]
	v_mfma_f32_16x16x32_bf16 v[108:111], v[230:233], v[108:111], v[24:27]
	v_mfma_f32_16x16x32_bf16 v[24:27], v[218:221], v[234:237], v[44:47]
	v_mfma_f32_16x16x32_bf16 v[120:123], v[222:225], v[28:31], v[64:67]
	v_mfma_f32_16x16x32_bf16 v[64:67], v[222:225], v[238:241], v[24:27]
	v_mfma_f32_16x16x32_bf16 v[24:27], v[226:229], v[234:237], v[146:149]
	v_mfma_f32_16x16x32_bf16 v[68:71], v[230:233], v[238:241], v[24:27]
	v_mfma_f32_16x16x32_bf16 v[24:27], v[218:221], v[242:245], v[150:153]
	v_mfma_f32_16x16x32_bf16 v[32:35], v[222:225], v[246:249], v[24:27]
	v_mfma_f32_16x16x32_bf16 v[24:27], v[226:229], v[242:245], v[56:59]
	v_mfma_f32_16x16x32_bf16 v[36:39], v[230:233], v[246:249], v[24:27]
	s_setprio 0
	s_barrier
	s_add_i32 s27, s27, s48
	s_nop 3
	v_lshl_add_u64 v[24:25], v[250:251], 0, s[10:11]
	s_mov_b32 m0, s27
	ds_read_b128 v[40:43], v145 offset:49152
	ds_read_b128 v[44:47], v145 offset:50176
	ds_read_b128 v[76:79], v145 offset:51200
	ds_read_b128 v[146:149], v145 offset:52224
	ds_read_b128 v[150:153], v145 offset:53248
	ds_read_b128 v[234:237], v145 offset:54272
	ds_read_b128 v[238:241], v145 offset:55296
	ds_read_b128 v[242:245], v145 offset:56320
	global_load_lds_dwordx4 v[24:25], off
	s_add_i32 m0, s27, 0x2000
	s_add_u32 s36, s36, 0x8080
	v_lshl_add_u64 v[24:25], v[252:253], 0, s[10:11]
	s_addc_u32 s37, s37, 0
	s_add_i32 s27, s29, s48
	global_load_lds_dwordx4 v[24:25], off
	v_lshl_add_u64 v[24:25], s[36:37], 0, v[130:131]
	s_mov_b32 m0, s27
	s_nop 0
	global_load_lds_dwordx4 v[24:25], off
	v_lshl_add_u64 v[24:25], s[36:37], 0, v[134:135]
	s_add_i32 m0, s27, 0x2000
	s_nop 0
	global_load_lds_dwordx4 v[24:25], off
	v_lshl_add_u64 v[24:25], v[136:137], 0, s[10:11]
	s_mov_b32 m0, s55
	s_nop 0
	global_load_lds_dwordx4 v[24:25], off
	v_lshl_add_u64 v[24:25], v[138:139], 0, s[10:11]
	s_mov_b32 m0, s56
	s_nop 0
	global_load_lds_dwordx4 v[24:25], off
	s_waitcnt vmcnt(8)
	s_waitcnt lgkmcnt(0)
	s_barrier
	s_setprio 1
	v_mfma_f32_16x16x32_bf16 v[24:27], v[202:205], v[40:43], v[154:157]
	v_mfma_f32_16x16x32_bf16 v[88:91], v[206:209], v[44:47], v[24:27]
	v_mfma_f32_16x16x32_bf16 v[24:27], v[210:213], v[40:43], v[158:161]
	v_mfma_f32_16x16x32_bf16 v[92:95], v[214:217], v[44:47], v[24:27]
	v_mfma_f32_16x16x32_bf16 v[24:27], v[202:205], v[76:79], v[162:165]
	v_mfma_f32_16x16x32_bf16 v[56:59], v[206:209], v[146:149], v[24:27]
	v_mfma_f32_16x16x32_bf16 v[24:27], v[210:213], v[76:79], v[166:169]
	v_mfma_f32_16x16x32_bf16 v[60:63], v[214:217], v[146:149], v[24:27]
	v_mfma_f32_16x16x32_bf16 v[24:27], v[202:205], v[150:153], v[170:173]
	v_mfma_f32_16x16x32_bf16 v[28:31], v[210:213], v[150:153], v[174:177]
	v_mfma_f32_16x16x32_bf16 v[0:3], v[202:205], v[238:241], v[0:3]
	v_mfma_f32_16x16x32_bf16 v[4:7], v[210:213], v[238:241], v[4:7]
	v_mfma_f32_16x16x32_bf16 v[24:27], v[206:209], v[234:237], v[24:27]
	v_mfma_f32_16x16x32_bf16 v[28:31], v[214:217], v[234:237], v[28:31]
	v_mfma_f32_16x16x32_bf16 v[0:3], v[206:209], v[242:245], v[0:3]
	v_mfma_f32_16x16x32_bf16 v[4:7], v[214:217], v[242:245], v[4:7]
	v_mfma_f32_16x16x32_bf16 v[8:11], v[218:221], v[40:43], v[8:11]
	v_mfma_f32_16x16x32_bf16 v[96:99], v[222:225], v[44:47], v[8:11]
	v_mfma_f32_16x16x32_bf16 v[8:11], v[226:229], v[40:43], v[12:15]
	v_mfma_f32_16x16x32_bf16 v[100:103], v[230:233], v[44:47], v[8:11]
	v_mfma_f32_16x16x32_bf16 v[8:11], v[218:221], v[76:79], v[178:181]
	v_mfma_f32_16x16x32_bf16 v[72:75], v[222:225], v[146:149], v[8:11]
	v_mfma_f32_16x16x32_bf16 v[8:11], v[226:229], v[76:79], v[182:185]
	v_mfma_f32_16x16x32_bf16 v[76:79], v[230:233], v[146:149], v[8:11]
	v_mfma_f32_16x16x32_bf16 v[8:11], v[218:221], v[150:153], v[186:189]
	v_mfma_f32_16x16x32_bf16 v[40:43], v[222:225], v[234:237], v[8:11]
	v_mfma_f32_16x16x32_bf16 v[8:11], v[226:229], v[150:153], v[190:193]
	v_mfma_f32_16x16x32_bf16 v[44:47], v[230:233], v[234:237], v[8:11]
	v_mfma_f32_16x16x32_bf16 v[8:11], v[218:221], v[238:241], v[194:197]
	v_mfma_f32_16x16x32_bf16 v[12:15], v[226:229], v[238:241], v[198:201]
	v_mfma_f32_16x16x32_bf16 v[8:11], v[222:225], v[242:245], v[8:11]
	v_mfma_f32_16x16x32_bf16 v[12:15], v[230:233], v[242:245], v[12:15]
	s_setprio 0
	s_barrier
	s_andn2_b64 vcc, exec, s[12:13]
	s_cbranch_vccnz .LBB0_412
	s_barrier

; #define PG8_STAGE(bufoff, gbase, voff) do { _Pragma("unroll") for (int _i = 0; _i < 2; ++_i) \
;         __builtin_amdgcn_global_load_lds((const unsigned*)((const char*)(gbase) + (voff)[_i]), (PG8_LAS unsigned*)(lds + (bufoff) + ldsw + _i * 8192), 16, 0, 0); } while (0)
; #define PG8_LDA(dst, b, h) do { _Pragma("unroll") for (int m = 0; m < 4; ++m) _Pragma("unroll") for (int k = 0; k < 2; ++k) dst[m][k] = *(const PG8_LAS bf16x8*)(lds + PG8_SA(b, h) + aoff + m * 2048 + k * 1024); } while (0)
; #define PG8_LDB(dst, b, h) do { _Pragma("unroll") for (int n = 0; n < 2; ++n) _Pragma("unroll") for (int k = 0; k < 2; ++k) dst[n][k] = *(const PG8_LAS bf16x8*)(lds + PG8_SB(b, h) + boff + n * 2048 + k * 1024); } while (0)
; #define PG8_MMA(ai, bj, At, Bt) do { __builtin_amdgcn_s_setprio(1); _Pragma("unroll") for (int m = 0; m < 4; ++m) _Pragma("unroll") for (int n = 0; n < 2; ++n) _Pragma("unroll") for (int k = 0; k < 2; ++k) \
;         acc[ai][bj][m][n] = __builtin_amdgcn_mfma_f32_16x16x32_bf16(Bt[n][k], At[m][k], acc[ai][bj][m][n], 0, 0, 0); __builtin_amdgcn_s_setprio(0); } while (0)
; #define PG8_BAR __builtin_amdgcn_s_barrier()
; template <class Epi, class Sched, bool ALIGN_EPI = true, bool SP2 = true>
; __device__ __forceinline__ void gemm_phase(PG8_LAS unsigned char* lds, const Gemm g, const Sched& S, const Epi& E) {
;     ...
;         const char* nA = has_next ? (const char*)g.A + (size_t)nxt.pm * tstepA : cA; const char* nB = has_next ? (const char*)g.Bt + (size_t)nxt.pn * tstepB : cB;
;         for (int t = 0; t < nt; t += 2) {
;             const bool last = (t == nt - 2);
;             const char* a1 = cA + (size_t)(t + 1) * kstep;
;             const char* a2 = last ? nA : cA + (size_t)(t + 2) * kstep; const char* b2 = last ? nB : cB + (size_t)(t + 2) * kstep;
;             const char* a3 = a2 + kstep; const char* b3 = b2 + kstep;
;             PG8_LDB(B0, 0, 0); PG8_LDB(B1, 0, 1); PG8_SCHED; PG8_LDA(At, 0, 0); PG8_STAGE(PG8_SA(1, 1), a1 + hstepA, voffA);
;             PG8_WAIT_V(8); PG8_WAIT_L(0); PG8_BAR; PG8_MMA(0, 0, At, B0); PG8_MMA(0, 1, At, B1); PG8_BAR; PG8_SCHED;
;             PG8_LDA(At, 0, 1); PG8_STAGE(PG8_SB(0, 0), b2, voffB); PG8_STAGE(PG8_SB(0, 1), b2 + hstepB, voffB); PG8_STAGE(PG8_SA(0, 0), a2, voffA);
;             PG8_WAIT_V(8); PG8_WAIT_L(0); PG8_BAR; PG8_MMA(1, 0, At, B0); PG8_MMA(1, 1, At, B1); PG8_BAR; PG8_SCHED;
.LBB0_432:
	ds_read_b128 v[0:3], v143
	ds_read_b128 v[4:7], v143 offset:1024
	ds_read_b128 v[8:11], v143 offset:2048
	ds_read_b128 v[12:15], v143 offset:3072
	ds_read_b128 v[16:19], v144
	ds_read_b128 v[20:23], v144 offset:1024
	ds_read_b128 v[24:27], v144 offset:2048
	ds_read_b128 v[28:31], v144 offset:3072
	s_ashr_i32 s27, s26, 31
	s_lshl_b64 s[28:29], s[26:27], 16
	s_add_u32 s28, s1, s28
	s_addc_u32 s29, s40, s29
	s_and_b64 s[30:31], s[2:3], exec
	s_cselect_b32 s39, s29, s37
	s_cselect_b32 s38, s28, s36
	s_ashr_i32 s25, s24, 31
	s_lshl_b64 s[30:31], s[24:25], 16
	s_add_u32 s30, s41, s30
	s_addc_u32 s31, s43, s31
	s_and_b64 s[62:63], s[2:3], exec
	s_cselect_b32 s35, s31, s35
	s_cselect_b32 s34, s30, s34
	s_add_u32 s36, s36, 0x8080
	s_addc_u32 s37, s37, 0
	v_lshl_add_u64 v[64:65], s[36:37], 0, v[128:129]
	s_add_i32 m0, s23, 0xc000
	ds_read_b128 v[32:35], v145
	ds_read_b128 v[36:39], v145 offset:1024
	ds_read_b128 v[40:43], v145 offset:2048
	ds_read_b128 v[44:47], v145 offset:3072
	ds_read_b128 v[48:51], v145 offset:4096
	ds_read_b128 v[52:55], v145 offset:5120
	ds_read_b128 v[56:59], v145 offset:6144
	ds_read_b128 v[60:63], v145 offset:7168
	global_load_lds_dwordx4 v[64:65], off
	v_lshl_add_u64 v[64:65], s[36:37], 0, v[132:133]
	s_add_i32 m0, s23, 0xe000
	s_nop 0
	global_load_lds_dwordx4 v[64:65], off
	s_waitcnt vmcnt(8)
	s_waitcnt lgkmcnt(0)
	s_barrier
	s_setprio 1
	v_mfma_f32_16x16x32_bf16 v[80:83], v[0:3], v[48:51], 0
	v_mfma_f32_16x16x32_bf16 v[88:91], v[4:7], v[52:55], v[80:83]
	v_mfma_f32_16x16x32_bf16 v[80:83], v[8:11], v[48:51], 0
	v_mfma_f32_16x16x32_bf16 v[92:95], v[12:15], v[52:55], v[80:83]
	v_mfma_f32_16x16x32_bf16 v[80:83], v[0:3], v[56:59], 0
	v_mfma_f32_16x16x32_bf16 v[64:67], v[0:3], v[32:35], 0
	v_mfma_f32_16x16x32_bf16 v[68:71], v[8:11], v[32:35], 0
	v_mfma_f32_16x16x32_bf16 v[72:75], v[0:3], v[40:43], 0
	v_mfma_f32_16x16x32_bf16 v[76:79], v[8:11], v[40:43], 0
	v_mfma_f32_16x16x32_bf16 v[96:99], v[4:7], v[60:63], v[80:83]
	v_mfma_f32_16x16x32_bf16 v[80:83], v[8:11], v[56:59], 0
	v_mfma_f32_16x16x32_bf16 v[64:67], v[4:7], v[36:39], v[64:67]
	v_mfma_f32_16x16x32_bf16 v[68:71], v[12:15], v[36:39], v[68:71]
	v_mfma_f32_16x16x32_bf16 v[72:75], v[4:7], v[44:47], v[72:75]
	v_mfma_f32_16x16x32_bf16 v[76:79], v[12:15], v[44:47], v[76:79]
	v_mfma_f32_16x16x32_bf16 v[100:103], v[12:15], v[60:63], v[80:83]
	v_mfma_f32_16x16x32_bf16 v[80:83], v[16:19], v[32:35], 0
	v_mfma_f32_16x16x32_bf16 v[32:35], v[24:27], v[32:35], 0
	v_mfma_f32_16x16x32_bf16 v[104:107], v[20:23], v[36:39], v[80:83]
	v_mfma_f32_16x16x32_bf16 v[32:35], v[28:31], v[36:39], v[32:35]
	v_mfma_f32_16x16x32_bf16 v[36:39], v[16:19], v[40:43], 0
	v_mfma_f32_16x16x32_bf16 v[40:43], v[24:27], v[40:43], 0
	v_mfma_f32_16x16x32_bf16 v[36:39], v[20:23], v[44:47], v[36:39]
	v_mfma_f32_16x16x32_bf16 v[40:43], v[28:31], v[44:47], v[40:43]
	v_mfma_f32_16x16x32_bf16 v[44:47], v[16:19], v[48:51], 0
	v_mfma_f32_16x16x32_bf16 v[48:51], v[24:27], v[48:51], 0
	v_mfma_f32_16x16x32_bf16 v[146:149], v[28:31], v[52:55], v[48:51]
	v_mfma_f32_16x16x32_bf16 v[48:51], v[16:19], v[56:59], 0
	v_mfma_f32_16x16x32_bf16 v[150:153], v[20:23], v[60:63], v[48:51]
	v_mfma_f32_16x16x32_bf16 v[48:51], v[24:27], v[56:59], 0
	v_mfma_f32_16x16x32_bf16 v[44:47], v[20:23], v[52:55], v[44:47]
	v_mfma_f32_16x16x32_bf16 v[56:59], v[28:31], v[60:63], v[48:51]
	s_setprio 0
	s_barrier
	s_add_i32 s25, s0, s45
	v_lshl_add_u64 v[250:251], s[34:35], 0, v[130:131]
	s_mov_b32 m0, s25
	s_nop 0
	ds_read_b128 v[48:51], v145 offset:16384
	ds_read_b128 v[52:55], v145 offset:17408
	ds_read_b128 v[60:63], v145 offset:18432
	ds_read_b128 v[80:83], v145 offset:19456
	ds_read_b128 v[84:87], v145 offset:20480
	ds_read_b128 v[108:111], v145 offset:21504
	ds_read_b128 v[112:115], v145 offset:22528
	ds_read_b128 v[116:119], v145 offset:23552
	global_load_lds_dwordx4 v[250:251], off
	s_add_i32 m0, s25, 0x2000
	s_add_u32 s36, s34, 0x8000
	v_lshl_add_u64 v[252:253], s[34:35], 0, v[134:135]
	s_addc_u32 s37, s35, 0
	s_add_i32 s25, s56, s45
	global_load_lds_dwordx4 v[252:253], off
	v_lshl_add_u64 v[120:121], s[36:37], 0, v[130:131]
	s_mov_b32 m0, s25
	v_lshl_add_u64 v[136:137], s[38:39], 0, v[128:129]
	global_load_lds_dwordx4 v[120:121], off
	v_lshl_add_u64 v[120:121], s[36:37], 0, v[134:135]
	s_add_i32 m0, s25, 0x2000
	v_lshl_add_u64 v[138:139], s[38:39], 0, v[132:133]
	global_load_lds_dwordx4 v[120:121], off
	s_mov_b32 m0, s23
	s_nop 0
	global_load_lds_dwordx4 v[136:137], off
	s_mov_b32 m0, s46
	s_nop 0
	global_load_lds_dwordx4 v[138:139], off
	s_waitcnt vmcnt(8)
	s_waitcnt lgkmcnt(0)
	s_barrier
	s_setprio 1
	v_mfma_f32_16x16x32_bf16 v[120:123], v[0:3], v[48:51], 0
	v_mfma_f32_16x16x32_bf16 v[154:157], v[4:7], v[52:55], v[120:123]
	v_mfma_f32_16x16x32_bf16 v[120:123], v[8:11], v[48:51], 0
	v_mfma_f32_16x16x32_bf16 v[158:161], v[12:15], v[52:55], v[120:123]
	v_mfma_f32_16x16x32_bf16 v[120:123], v[0:3], v[60:63], 0
	v_mfma_f32_16x16x32_bf16 v[162:165], v[4:7], v[80:83], v[120:123]
	v_mfma_f32_16x16x32_bf16 v[120:123], v[8:11], v[60:63], 0
	v_mfma_f32_16x16x32_bf16 v[166:169], v[12:15], v[80:83], v[120:123]
	v_mfma_f32_16x16x32_bf16 v[120:123], v[0:3], v[84:87], 0
	v_mfma_f32_16x16x32_bf16 v[0:3], v[0:3], v[112:115], 0
	v_mfma_f32_16x16x32_bf16 v[170:173], v[4:7], v[108:111], v[120:123]
	v_mfma_f32_16x16x32_bf16 v[0:3], v[4:7], v[116:119], v[0:3]
	v_mfma_f32_16x16x32_bf16 v[4:7], v[8:11], v[112:115], 0
	v_mfma_f32_16x16x32_bf16 v[120:123], v[8:11], v[84:87], 0
	v_mfma_f32_16x16x32_bf16 v[4:7], v[12:15], v[116:119], v[4:7]
	v_mfma_f32_16x16x32_bf16 v[174:177], v[12:15], v[108:111], v[120:123]
	v_mfma_f32_16x16x32_bf16 v[8:11], v[16:19], v[48:51], 0
	v_mfma_f32_16x16x32_bf16 v[12:15], v[24:27], v[48:51], 0
	v_mfma_f32_16x16x32_bf16 v[48:51], v[16:19], v[60:63], 0
	v_mfma_f32_16x16x32_bf16 v[178:181], v[20:23], v[80:83], v[48:51]
	v_mfma_f32_16x16x32_bf16 v[48:51], v[24:27], v[60:63], 0
	v_mfma_f32_16x16x32_bf16 v[182:185], v[28:31], v[80:83], v[48:51]
	v_mfma_f32_16x16x32_bf16 v[48:51], v[16:19], v[84:87], 0
	v_mfma_f32_16x16x32_bf16 v[16:19], v[16:19], v[112:115], 0
	v_mfma_f32_16x16x32_bf16 v[8:11], v[20:23], v[52:55], v[8:11]
	v_mfma_f32_16x16x32_bf16 v[12:15], v[28:31], v[52:55], v[12:15]
	v_mfma_f32_16x16x32_bf16 v[186:189], v[20:23], v[108:111], v[48:51]
	v_mfma_f32_16x16x32_bf16 v[48:51], v[24:27], v[84:87], 0
	v_mfma_f32_16x16x32_bf16 v[194:197], v[20:23], v[116:119], v[16:19]
	v_mfma_f32_16x16x32_bf16 v[16:19], v[24:27], v[112:115], 0
	v_mfma_f32_16x16x32_bf16 v[190:193], v[28:31], v[108:111], v[48:51]
	v_mfma_f32_16x16x32_bf16 v[198:201], v[28:31], v[116:119], v[16:19]
	s_setprio 0
	s_barrier
; #define PG8_STAGE(bufoff, gbase, voff) do { _Pragma("unroll") for (int _i = 0; _i < 2; ++_i) \
;         __builtin_amdgcn_global_load_lds((const unsigned*)((const char*)(gbase) + (voff)[_i]), (PG8_LAS unsigned*)(lds + (bufoff) + ldsw + _i * 8192), 16, 0, 0); } while (0)
; #define PG8_LDA(dst, b, h) do { _Pragma("unroll") for (int m = 0; m < 4; ++m) _Pragma("unroll") for (int k = 0; k < 2; ++k) dst[m][k] = *(const PG8_LAS bf16x8*)(lds + PG8_SA(b, h) + aoff + m * 2048 + k * 1024); } while (0)
; #define PG8_LDB(dst, b, h) do { _Pragma("unroll") for (int n = 0; n < 2; ++n) _Pragma("unroll") for (int k = 0; k < 2; ++k) dst[n][k] = *(const PG8_LAS bf16x8*)(lds + PG8_SB(b, h) + boff + n * 2048 + k * 1024); } while (0)
; #define PG8_MMA(ai, bj, At, Bt) do { __builtin_amdgcn_s_setprio(1); _Pragma("unroll") for (int m = 0; m < 4; ++m) _Pragma("unroll") for (int n = 0; n < 2; ++n) _Pragma("unroll") for (int k = 0; k < 2; ++k) \
;         acc[ai][bj][m][n] = __builtin_amdgcn_mfma_f32_16x16x32_bf16(Bt[n][k], At[m][k], acc[ai][bj][m][n], 0, 0, 0); __builtin_amdgcn_s_setprio(0); } while (0)
; #define PG8_WAIT_V(n) asm volatile("s_waitcnt vmcnt(" #n ")" ::: "memory")
; #define PG8_WAIT_L(n) asm volatile("s_waitcnt lgkmcnt(" #n ")" ::: "memory")
; #define PG8_BAR __builtin_amdgcn_s_barrier()
; #define PG8_SCHED __builtin_amdgcn_sched_barrier(0)
; template <class Epi, class Sched, bool ALIGN_EPI = true, bool SP2 = true>
; __device__ __forceinline__ void gemm_phase(PG8_LAS unsigned char* lds, const Gemm g, const Sched& S, const Epi& E) {
;     ...
;             PG8_LDB(B0, 1, 0); PG8_LDB(B1, 1, 1); PG8_SCHED; PG8_LDA(At, 1, 0); PG8_STAGE(PG8_SA(0, 1), a2 + hstepA, voffA);
;             PG8_WAIT_V(8); PG8_WAIT_L(0); PG8_BAR; PG8_MMA(0, 0, At, B0); PG8_MMA(0, 1, At, B1); PG8_BAR; PG8_SCHED;
;             PG8_LDA(At, 1, 1); PG8_STAGE(PG8_SB(1, 0), b3, voffB); PG8_STAGE(PG8_SB(1, 1), b3 + hstepB, voffB); PG8_STAGE(PG8_SA(1, 0), a3, voffA);
;             PG8_WAIT_V(8); PG8_WAIT_L(0); PG8_BAR; PG8_MMA(1, 0, At, B0); PG8_MMA(1, 1, At, B1); PG8_BAR; PG8_SCHED;
;         }
;         if constexpr (ALIGN_EPI) { if (wr == 0) PG8_BAR; }
	s_add_i32 s25, 0, 0x18000
	s_nop 2
	v_add_u32_e32 v16, s25, v141
	s_add_i32 s27, 0, 0x1c000
	ds_read_b128 v[202:205], v16
	ds_read_b128 v[206:209], v16 offset:1024
	ds_read_b128 v[210:213], v16 offset:2048
	ds_read_b128 v[214:217], v16 offset:3072
	v_add_u32_e32 v16, s27, v141
	ds_read_b128 v[218:221], v16
	ds_read_b128 v[222:225], v16 offset:1024
	ds_read_b128 v[226:229], v16 offset:2048
	ds_read_b128 v[230:233], v16 offset:3072
	s_add_u32 s36, s38, 0x8000
	s_addc_u32 s37, s39, 0
	s_mov_b32 m0, s47
	v_lshl_add_u64 v[16:17], s[36:37], 0, v[128:129]
	ds_read_b128 v[24:27], v145 offset:32768
	ds_read_b128 v[28:31], v145 offset:33792
	ds_read_b128 v[60:63], v145 offset:34816
	ds_read_b128 v[108:111], v145 offset:35840
	ds_read_b128 v[234:237], v145 offset:36864
	ds_read_b128 v[238:241], v145 offset:37888
	ds_read_b128 v[242:245], v145 offset:38912
	ds_read_b128 v[246:249], v145 offset:39936
	global_load_lds_dwordx4 v[16:17], off
	v_lshl_add_u64 v[16:17], s[36:37], 0, v[132:133]
	s_mov_b32 m0, s48
	s_nop 0
	global_load_lds_dwordx4 v[16:17], off
	s_waitcnt vmcnt(8)
	s_waitcnt lgkmcnt(0)
	s_barrier
	s_setprio 1
	v_mfma_f32_16x16x32_bf16 v[16:19], v[202:205], v[24:27], v[64:67]
	v_mfma_f32_16x16x32_bf16 v[112:115], v[206:209], v[28:31], v[16:19]
	v_mfma_f32_16x16x32_bf16 v[16:19], v[210:213], v[24:27], v[68:71]
	v_mfma_f32_16x16x32_bf16 v[116:119], v[214:217], v[28:31], v[16:19]
	v_mfma_f32_16x16x32_bf16 v[16:19], v[202:205], v[60:63], v[72:75]
	v_mfma_f32_16x16x32_bf16 v[80:83], v[206:209], v[108:111], v[16:19]
	v_mfma_f32_16x16x32_bf16 v[16:19], v[210:213], v[60:63], v[76:79]
	v_mfma_f32_16x16x32_bf16 v[84:87], v[214:217], v[108:111], v[16:19]
	v_mfma_f32_16x16x32_bf16 v[16:19], v[202:205], v[234:237], v[88:91]
	v_mfma_f32_16x16x32_bf16 v[48:51], v[206:209], v[238:241], v[16:19]
	v_mfma_f32_16x16x32_bf16 v[16:19], v[210:213], v[234:237], v[92:95]
	v_mfma_f32_16x16x32_bf16 v[52:55], v[214:217], v[238:241], v[16:19]
	v_mfma_f32_16x16x32_bf16 v[16:19], v[202:205], v[242:245], v[96:99]
	v_mfma_f32_16x16x32_bf16 v[20:23], v[210:213], v[242:245], v[100:103]
	v_mfma_f32_16x16x32_bf16 v[16:19], v[206:209], v[246:249], v[16:19]
	v_mfma_f32_16x16x32_bf16 v[20:23], v[214:217], v[246:249], v[20:23]
	v_mfma_f32_16x16x32_bf16 v[64:67], v[218:221], v[24:27], v[104:107]
	v_mfma_f32_16x16x32_bf16 v[24:27], v[226:229], v[24:27], v[32:35]
	v_mfma_f32_16x16x32_bf16 v[124:127], v[230:233], v[28:31], v[24:27]
	v_mfma_f32_16x16x32_bf16 v[24:27], v[218:221], v[60:63], v[36:39]
	v_mfma_f32_16x16x32_bf16 v[104:107], v[222:225], v[108:111], v[24:27]
	v_mfma_f32_16x16x32_bf16 v[24:27], v[226:229], v[60:63], v[40:43]
	v_mfma_f32_16x16x32_bf16 v[108:111], v[230:233], v[108:111], v[24:27]
	v_mfma_f32_16x16x32_bf16 v[24:27], v[218:221], v[234:237], v[44:47]
	v_mfma_f32_16x16x32_bf16 v[120:123], v[222:225], v[28:31], v[64:67]
	v_mfma_f32_16x16x32_bf16 v[64:67], v[222:225], v[238:241], v[24:27]
	v_mfma_f32_16x16x32_bf16 v[24:27], v[226:229], v[234:237], v[146:149]
	v_mfma_f32_16x16x32_bf16 v[68:71], v[230:233], v[238:241], v[24:27]
	v_mfma_f32_16x16x32_bf16 v[24:27], v[218:221], v[242:245], v[150:153]
	v_mfma_f32_16x16x32_bf16 v[32:35], v[222:225], v[246:249], v[24:27]
	v_mfma_f32_16x16x32_bf16 v[24:27], v[226:229], v[242:245], v[56:59]
	v_mfma_f32_16x16x32_bf16 v[36:39], v[230:233], v[246:249], v[24:27]
	s_setprio 0
	s_barrier
	s_add_i32 s25, s25, s45
	s_nop 3
	v_lshl_add_u64 v[24:25], v[250:251], 0, s[8:9]
	s_mov_b32 m0, s25
	ds_read_b128 v[40:43], v145 offset:49152
	ds_read_b128 v[44:47], v145 offset:50176
	ds_read_b128 v[76:79], v145 offset:51200
	ds_read_b128 v[146:149], v145 offset:52224
	ds_read_b128 v[150:153], v145 offset:53248
	ds_read_b128 v[234:237], v145 offset:54272
	ds_read_b128 v[238:241], v145 offset:55296
	ds_read_b128 v[242:245], v145 offset:56320
	global_load_lds_dwordx4 v[24:25], off
	s_add_i32 m0, s25, 0x2000
	s_add_u32 s34, s34, 0x8080
	v_lshl_add_u64 v[24:25], v[252:253], 0, s[8:9]
	s_addc_u32 s35, s35, 0
	s_add_i32 s25, s27, s45
	global_load_lds_dwordx4 v[24:25], off
	v_lshl_add_u64 v[24:25], s[34:35], 0, v[130:131]
	s_mov_b32 m0, s25
	s_nop 0
	global_load_lds_dwordx4 v[24:25], off
	v_lshl_add_u64 v[24:25], s[34:35], 0, v[134:135]
	s_add_i32 m0, s25, 0x2000
	s_nop 0
	global_load_lds_dwordx4 v[24:25], off
	v_lshl_add_u64 v[24:25], v[136:137], 0, s[8:9]
	s_mov_b32 m0, s49
	s_nop 0
	global_load_lds_dwordx4 v[24:25], off
	v_lshl_add_u64 v[24:25], v[138:139], 0, s[8:9]
	s_mov_b32 m0, s50
	s_nop 0
	global_load_lds_dwordx4 v[24:25], off
	s_waitcnt vmcnt(8)
	s_waitcnt lgkmcnt(0)
	s_barrier
	s_setprio 1
	v_mfma_f32_16x16x32_bf16 v[24:27], v[202:205], v[40:43], v[154:157]
	v_mfma_f32_16x16x32_bf16 v[88:91], v[206:209], v[44:47], v[24:27]
	v_mfma_f32_16x16x32_bf16 v[24:27], v[210:213], v[40:43], v[158:161]
	v_mfma_f32_16x16x32_bf16 v[92:95], v[214:217], v[44:47], v[24:27]
	v_mfma_f32_16x16x32_bf16 v[24:27], v[202:205], v[76:79], v[162:165]
	v_mfma_f32_16x16x32_bf16 v[56:59], v[206:209], v[146:149], v[24:27]
	v_mfma_f32_16x16x32_bf16 v[24:27], v[210:213], v[76:79], v[166:169]
	v_mfma_f32_16x16x32_bf16 v[60:63], v[214:217], v[146:149], v[24:27]
	v_mfma_f32_16x16x32_bf16 v[24:27], v[202:205], v[150:153], v[170:173]
	v_mfma_f32_16x16x32_bf16 v[28:31], v[210:213], v[150:153], v[174:177]
	v_mfma_f32_16x16x32_bf16 v[0:3], v[202:205], v[238:241], v[0:3]
	v_mfma_f32_16x16x32_bf16 v[4:7], v[210:213], v[238:241], v[4:7]
	v_mfma_f32_16x16x32_bf16 v[24:27], v[206:209], v[234:237], v[24:27]
	v_mfma_f32_16x16x32_bf16 v[28:31], v[214:217], v[234:237], v[28:31]
	v_mfma_f32_16x16x32_bf16 v[0:3], v[206:209], v[242:245], v[0:3]
	v_mfma_f32_16x16x32_bf16 v[4:7], v[214:217], v[242:245], v[4:7]
	v_mfma_f32_16x16x32_bf16 v[8:11], v[218:221], v[40:43], v[8:11]
	v_mfma_f32_16x16x32_bf16 v[96:99], v[222:225], v[44:47], v[8:11]
	v_mfma_f32_16x16x32_bf16 v[8:11], v[226:229], v[40:43], v[12:15]
	v_mfma_f32_16x16x32_bf16 v[100:103], v[230:233], v[44:47], v[8:11]
	v_mfma_f32_16x16x32_bf16 v[8:11], v[218:221], v[76:79], v[178:181]
	v_mfma_f32_16x16x32_bf16 v[72:75], v[222:225], v[146:149], v[8:11]
	v_mfma_f32_16x16x32_bf16 v[8:11], v[226:229], v[76:79], v[182:185]
	v_mfma_f32_16x16x32_bf16 v[76:79], v[230:233], v[146:149], v[8:11]
	v_mfma_f32_16x16x32_bf16 v[8:11], v[218:221], v[150:153], v[186:189]
	v_mfma_f32_16x16x32_bf16 v[40:43], v[222:225], v[234:237], v[8:11]
	v_mfma_f32_16x16x32_bf16 v[8:11], v[226:229], v[150:153], v[190:193]
	v_mfma_f32_16x16x32_bf16 v[44:47], v[230:233], v[234:237], v[8:11]
	v_mfma_f32_16x16x32_bf16 v[8:11], v[218:221], v[238:241], v[194:197]
	v_mfma_f32_16x16x32_bf16 v[12:15], v[226:229], v[238:241], v[198:201]
	v_mfma_f32_16x16x32_bf16 v[8:11], v[222:225], v[242:245], v[8:11]
	v_mfma_f32_16x16x32_bf16 v[12:15], v[230:233], v[242:245], v[12:15]
	s_setprio 0
	s_barrier
	s_andn2_b64 vcc, exec, s[10:11]
	s_cbranch_vccnz .LBB0_434
	s_barrier

; #define PG8_STAGE(bufoff, gbase, voff) do { _Pragma("unroll") for (int _i = 0; _i < 2; ++_i) \
;         __builtin_amdgcn_global_load_lds((const unsigned*)((const char*)(gbase) + (voff)[_i]), (PG8_LAS unsigned*)(lds + (bufoff) + ldsw + _i * 8192), 16, 0, 0); } while (0)
; #define PG8_LDA(dst, b, h) do { _Pragma("unroll") for (int m = 0; m < 4; ++m) _Pragma("unroll") for (int k = 0; k < 2; ++k) dst[m][k] = *(const PG8_LAS bf16x8*)(lds + PG8_SA(b, h) + aoff + m * 2048 + k * 1024); } while (0)
; #define PG8_LDB(dst, b, h) do { _Pragma("unroll") for (int n = 0; n < 2; ++n) _Pragma("unroll") for (int k = 0; k < 2; ++k) dst[n][k] = *(const PG8_LAS bf16x8*)(lds + PG8_SB(b, h) + boff + n * 2048 + k * 1024); } while (0)
; #define PG8_MMA(ai, bj, At, Bt) do { __builtin_amdgcn_s_setprio(1); _Pragma("unroll") for (int m = 0; m < 4; ++m) _Pragma("unroll") for (int n = 0; n < 2; ++n) _Pragma("unroll") for (int k = 0; k < 2; ++k) \
;         acc[ai][bj][m][n] = __builtin_amdgcn_mfma_f32_16x16x32_bf16(Bt[n][k], At[m][k], acc[ai][bj][m][n], 0, 0, 0); __builtin_amdgcn_s_setprio(0); } while (0)
; #define PG8_WAIT_V(n) asm volatile("s_waitcnt vmcnt(" #n ")" ::: "memory")
; #define PG8_WAIT_L(n) asm volatile("s_waitcnt lgkmcnt(" #n ")" ::: "memory")
; #define PG8_BAR __builtin_amdgcn_s_barrier()
; #define PG8_SCHED __builtin_amdgcn_sched_barrier(0)
; template <class Epi, class Sched, bool ALIGN_EPI = true, bool SP2 = true>
; __device__ __forceinline__ void gemm_phase(PG8_LAS unsigned char* lds, const Gemm g, const Sched& S, const Epi& E) {
;     ...
;             const bool last = (t == nt - 2);
;             const char* a1 = cA + (size_t)(t + 1) * kstep;
;             const char* a2 = last ? nA : cA + (size_t)(t + 2) * kstep; const char* b2 = last ? nB : cB + (size_t)(t + 2) * kstep;
;             const char* a3 = a2 + kstep; const char* b3 = b2 + kstep;
;             PG8_LDB(B0, 0, 0); PG8_LDB(B1, 0, 1); PG8_SCHED; PG8_LDA(At, 0, 0); PG8_STAGE(PG8_SA(1, 1), a1 + hstepA, voffA);
;             PG8_WAIT_V(8); PG8_WAIT_L(0); PG8_BAR; PG8_MMA(0, 0, At, B0); PG8_MMA(0, 1, At, B1); PG8_BAR; PG8_SCHED;
;             PG8_LDA(At, 0, 1); PG8_STAGE(PG8_SB(0, 0), b2, voffB); PG8_STAGE(PG8_SB(0, 1), b2 + hstepB, voffB); PG8_STAGE(PG8_SA(0, 0), a2, voffA);
.LBB0_494:
	s_add_u32 s31, s20, s30
	s_addc_u32 s38, s21, 0
	s_add_u32 s36, s31, 0x100
	s_addc_u32 s37, s38, 0
	s_and_b64 s[34:35], s[28:29], exec
	s_cselect_b32 s35, s15, s37
	s_cselect_b32 s34, s64, s36
	s_add_u32 s30, s18, s30
	s_addc_u32 s36, s19, 0
	s_add_u32 s30, s30, 0x100
	s_addc_u32 s36, s36, 0
	s_and_b64 s[28:29], s[28:29], exec
	s_cselect_b32 s37, s13, s36
	s_cselect_b32 s36, s65, s30
	s_add_u32 s40, s31, 0x10080
	ds_read_b128 v[142:145], v139
	ds_read_b128 v[146:149], v139 offset:1024
	ds_read_b128 v[150:153], v139 offset:2048
	ds_read_b128 v[154:157], v139 offset:3072
	ds_read_b128 v[158:161], v140
	ds_read_b128 v[162:165], v140 offset:1024
	ds_read_b128 v[166:169], v140 offset:2048
	ds_read_b128 v[170:173], v140 offset:3072
	s_addc_u32 s41, s38, 0
	s_add_i32 s77, s61, s47
	s_add_i32 m0, s49, 0xc000
	s_add_i32 s52, s49, 0xe000
	s_add_i32 s74, s77, 0x2000
	s_add_u32 s38, s36, 0x10000
	s_addc_u32 s39, s37, 0
	s_add_i32 s76, s62, s47
	s_add_i32 s75, s76, 0x2000
	s_add_i32 s73, 0, 0x18000
	s_add_i32 s72, 0, 0x1c000
	s_add_u32 s30, s34, 0x10000
	s_addc_u32 s31, s35, 0
	s_add_i32 s71, s73, s47
	s_add_i32 s66, s71, 0x2000
	s_add_u32 s28, s36, 0x10080
	s_addc_u32 s29, s37, 0
	s_add_i32 s79, s72, s47
	s_add_i32 s78, s79, 0x2000
	v_lshl_add_u64 v[206:207], s[40:41], 0, v[134:135]
	ds_read_b128 v[174:177], v141
	ds_read_b128 v[178:181], v141 offset:1024
	ds_read_b128 v[182:185], v141 offset:2048
	ds_read_b128 v[186:189], v141 offset:3072
	ds_read_b128 v[190:193], v141 offset:4096
	ds_read_b128 v[194:197], v141 offset:5120
	ds_read_b128 v[198:201], v141 offset:6144
	ds_read_b128 v[202:205], v141 offset:7168
	global_load_lds_dwordx4 v[206:207], off
	v_lshl_add_u64 v[206:207], s[40:41], 0, v[130:131]
	s_mov_b32 m0, s52
	s_nop 0
	global_load_lds_dwordx4 v[206:207], off
	s_waitcnt vmcnt(8)
	s_waitcnt lgkmcnt(0)
	s_barrier
	s_setprio 1
	v_mfma_f32_16x16x32_bf16 v[124:127], v[142:145], v[174:177], v[124:127]
	v_mfma_f32_16x16x32_bf16 v[120:123], v[150:153], v[174:177], v[120:123]
	v_mfma_f32_16x16x32_bf16 v[116:119], v[142:145], v[182:185], v[116:119]
	v_mfma_f32_16x16x32_bf16 v[112:115], v[150:153], v[182:185], v[112:115]
	v_mfma_f32_16x16x32_bf16 v[100:103], v[142:145], v[190:193], v[100:103]
	v_mfma_f32_16x16x32_bf16 v[96:99], v[150:153], v[190:193], v[96:99]
	v_mfma_f32_16x16x32_bf16 v[84:87], v[142:145], v[198:201], v[84:87]
	v_mfma_f32_16x16x32_bf16 v[80:83], v[150:153], v[198:201], v[80:83]
	v_mfma_f32_16x16x32_bf16 v[124:127], v[146:149], v[178:181], v[124:127]
	v_mfma_f32_16x16x32_bf16 v[120:123], v[154:157], v[178:181], v[120:123]
	v_mfma_f32_16x16x32_bf16 v[116:119], v[146:149], v[186:189], v[116:119]
	v_mfma_f32_16x16x32_bf16 v[112:115], v[154:157], v[186:189], v[112:115]
	v_mfma_f32_16x16x32_bf16 v[100:103], v[146:149], v[194:197], v[100:103]
	v_mfma_f32_16x16x32_bf16 v[96:99], v[154:157], v[194:197], v[96:99]
	v_mfma_f32_16x16x32_bf16 v[84:87], v[146:149], v[202:205], v[84:87]
	v_mfma_f32_16x16x32_bf16 v[80:83], v[154:157], v[202:205], v[80:83]
	v_mfma_f32_16x16x32_bf16 v[108:111], v[158:161], v[174:177], v[108:111]
	v_mfma_f32_16x16x32_bf16 v[104:107], v[166:169], v[174:177], v[104:107]
	v_mfma_f32_16x16x32_bf16 v[92:95], v[158:161], v[182:185], v[92:95]
	v_mfma_f32_16x16x32_bf16 v[88:91], v[166:169], v[182:185], v[88:91]
	v_mfma_f32_16x16x32_bf16 v[76:79], v[158:161], v[190:193], v[76:79]
	v_mfma_f32_16x16x32_bf16 v[72:75], v[166:169], v[190:193], v[72:75]
	v_mfma_f32_16x16x32_bf16 v[68:71], v[158:161], v[198:201], v[68:71]
	v_mfma_f32_16x16x32_bf16 v[64:67], v[166:169], v[198:201], v[64:67]
	v_mfma_f32_16x16x32_bf16 v[108:111], v[162:165], v[178:181], v[108:111]
	v_mfma_f32_16x16x32_bf16 v[104:107], v[170:173], v[178:181], v[104:107]
	v_mfma_f32_16x16x32_bf16 v[92:95], v[162:165], v[186:189], v[92:95]
	v_mfma_f32_16x16x32_bf16 v[88:91], v[170:173], v[186:189], v[88:91]
	v_mfma_f32_16x16x32_bf16 v[76:79], v[162:165], v[194:197], v[76:79]
	v_mfma_f32_16x16x32_bf16 v[72:75], v[170:173], v[194:197], v[72:75]
	v_mfma_f32_16x16x32_bf16 v[68:71], v[162:165], v[202:205], v[68:71]
	v_mfma_f32_16x16x32_bf16 v[64:67], v[170:173], v[202:205], v[64:67]
	s_setprio 0
	s_barrier
	s_mov_b32 m0, s77
	v_lshl_add_u64 v[206:207], s[36:37], 0, v[132:133]
	ds_read_b128 v[174:177], v141 offset:16384
	ds_read_b128 v[178:181], v141 offset:17408
	ds_read_b128 v[182:185], v141 offset:18432
	ds_read_b128 v[186:189], v141 offset:19456
	ds_read_b128 v[190:193], v141 offset:20480
	ds_read_b128 v[194:197], v141 offset:21504
	ds_read_b128 v[198:201], v141 offset:22528
	ds_read_b128 v[202:205], v141 offset:23552
	global_load_lds_dwordx4 v[206:207], off
	v_lshl_add_u64 v[208:209], s[36:37], 0, v[128:129]
	s_mov_b32 m0, s74
	v_lshl_add_u64 v[210:211], s[38:39], 0, v[132:133]
	global_load_lds_dwordx4 v[208:209], off
	s_mov_b32 m0, s76
	v_lshl_add_u64 v[212:213], s[34:35], 0, v[130:131]
	global_load_lds_dwordx4 v[210:211], off
	v_lshl_add_u64 v[210:211], s[38:39], 0, v[128:129]
	s_mov_b32 m0, s75
	s_nop 0
	global_load_lds_dwordx4 v[210:211], off
	v_lshl_add_u64 v[210:211], s[34:35], 0, v[134:135]
	s_mov_b32 m0, s49
	s_nop 0
	global_load_lds_dwordx4 v[210:211], off
	s_mov_b32 m0, s50
	s_nop 0
	global_load_lds_dwordx4 v[212:213], off
	s_waitcnt vmcnt(8)
	s_waitcnt lgkmcnt(0)
	s_barrier
; #define PG8_STAGE(bufoff, gbase, voff) do { _Pragma("unroll") for (int _i = 0; _i < 2; ++_i) \
;         __builtin_amdgcn_global_load_lds((const unsigned*)((const char*)(gbase) + (voff)[_i]), (PG8_LAS unsigned*)(lds + (bufoff) + ldsw + _i * 8192), 16, 0, 0); } while (0)
; #define PG8_LDA(dst, b, h) do { _Pragma("unroll") for (int m = 0; m < 4; ++m) _Pragma("unroll") for (int k = 0; k < 2; ++k) dst[m][k] = *(const PG8_LAS bf16x8*)(lds + PG8_SA(b, h) + aoff + m * 2048 + k * 1024); } while (0)
; #define PG8_LDB(dst, b, h) do { _Pragma("unroll") for (int n = 0; n < 2; ++n) _Pragma("unroll") for (int k = 0; k < 2; ++k) dst[n][k] = *(const PG8_LAS bf16x8*)(lds + PG8_SB(b, h) + boff + n * 2048 + k * 1024); } while (0)
; #define PG8_MMA(ai, bj, At, Bt) do { __builtin_amdgcn_s_setprio(1); _Pragma("unroll") for (int m = 0; m < 4; ++m) _Pragma("unroll") for (int n = 0; n < 2; ++n) _Pragma("unroll") for (int k = 0; k < 2; ++k) \
;         acc[ai][bj][m][n] = __builtin_amdgcn_mfma_f32_16x16x32_bf16(Bt[n][k], At[m][k], acc[ai][bj][m][n], 0, 0, 0); __builtin_amdgcn_s_setprio(0); } while (0)
; #define PG8_WAIT_V(n) asm volatile("s_waitcnt vmcnt(" #n ")" ::: "memory")
; #define PG8_WAIT_L(n) asm volatile("s_waitcnt lgkmcnt(" #n ")" ::: "memory")
; #define PG8_BAR __builtin_amdgcn_s_barrier()
; #define PG8_SCHED __builtin_amdgcn_sched_barrier(0)
; template <class Epi, class Sched, bool ALIGN_EPI = true, bool SP2 = true>
; __device__ __forceinline__ void gemm_phase(PG8_LAS unsigned char* lds, const Gemm g, const Sched& S, const Epi& E) {
;     ...
;             PG8_WAIT_V(8); PG8_WAIT_L(0); PG8_BAR; PG8_MMA(1, 0, At, B0); PG8_MMA(1, 1, At, B1); PG8_BAR; PG8_SCHED;
;             PG8_LDB(B0, 1, 0); PG8_LDB(B1, 1, 1); PG8_SCHED; PG8_LDA(At, 1, 0); PG8_STAGE(PG8_SA(0, 1), a2 + hstepA, voffA);
;             PG8_WAIT_V(8); PG8_WAIT_L(0); PG8_BAR; PG8_MMA(0, 0, At, B0); PG8_MMA(0, 1, At, B1); PG8_BAR; PG8_SCHED;
	s_setprio 1
	v_mfma_f32_16x16x32_bf16 v[60:63], v[142:145], v[174:177], v[60:63]
	v_mfma_f32_16x16x32_bf16 v[56:59], v[150:153], v[174:177], v[56:59]
	v_mfma_f32_16x16x32_bf16 v[52:55], v[142:145], v[182:185], v[52:55]
	v_mfma_f32_16x16x32_bf16 v[48:51], v[150:153], v[182:185], v[48:51]
	v_mfma_f32_16x16x32_bf16 v[36:39], v[142:145], v[190:193], v[36:39]
	v_mfma_f32_16x16x32_bf16 v[32:35], v[150:153], v[190:193], v[32:35]
	v_mfma_f32_16x16x32_bf16 v[20:23], v[142:145], v[198:201], v[20:23]
	v_mfma_f32_16x16x32_bf16 v[16:19], v[150:153], v[198:201], v[16:19]
	v_mfma_f32_16x16x32_bf16 v[60:63], v[146:149], v[178:181], v[60:63]
	v_mfma_f32_16x16x32_bf16 v[56:59], v[154:157], v[178:181], v[56:59]
	v_mfma_f32_16x16x32_bf16 v[52:55], v[146:149], v[186:189], v[52:55]
	v_mfma_f32_16x16x32_bf16 v[48:51], v[154:157], v[186:189], v[48:51]
	v_mfma_f32_16x16x32_bf16 v[36:39], v[146:149], v[194:197], v[36:39]
	v_mfma_f32_16x16x32_bf16 v[32:35], v[154:157], v[194:197], v[32:35]
	v_mfma_f32_16x16x32_bf16 v[20:23], v[146:149], v[202:205], v[20:23]
	v_mfma_f32_16x16x32_bf16 v[16:19], v[154:157], v[202:205], v[16:19]
	v_mfma_f32_16x16x32_bf16 v[44:47], v[158:161], v[174:177], v[44:47]
	v_mfma_f32_16x16x32_bf16 v[40:43], v[166:169], v[174:177], v[40:43]
	v_mfma_f32_16x16x32_bf16 v[28:31], v[158:161], v[182:185], v[28:31]
	v_mfma_f32_16x16x32_bf16 v[24:27], v[166:169], v[182:185], v[24:27]
	v_mfma_f32_16x16x32_bf16 v[12:15], v[158:161], v[190:193], v[12:15]
	v_mfma_f32_16x16x32_bf16 v[8:11], v[166:169], v[190:193], v[8:11]
	v_mfma_f32_16x16x32_bf16 v[4:7], v[158:161], v[198:201], v[4:7]
	v_mfma_f32_16x16x32_bf16 v[0:3], v[166:169], v[198:201], v[0:3]
	v_mfma_f32_16x16x32_bf16 v[44:47], v[162:165], v[178:181], v[44:47]
	v_mfma_f32_16x16x32_bf16 v[40:43], v[170:173], v[178:181], v[40:43]
	v_mfma_f32_16x16x32_bf16 v[28:31], v[162:165], v[186:189], v[28:31]
	v_mfma_f32_16x16x32_bf16 v[24:27], v[170:173], v[186:189], v[24:27]
	v_mfma_f32_16x16x32_bf16 v[12:15], v[162:165], v[194:197], v[12:15]
	v_mfma_f32_16x16x32_bf16 v[8:11], v[170:173], v[194:197], v[8:11]
	v_mfma_f32_16x16x32_bf16 v[4:7], v[162:165], v[202:205], v[4:7]
	v_mfma_f32_16x16x32_bf16 v[0:3], v[170:173], v[202:205], v[0:3]
	s_setprio 0
	s_barrier
	v_add_u32_e32 v154, s73, v137
	v_add_u32_e32 v170, s72, v137
	ds_read_b128 v[142:145], v154
	ds_read_b128 v[146:149], v154 offset:1024
	ds_read_b128 v[150:153], v154 offset:2048
	ds_read_b128 v[154:157], v154 offset:3072
	ds_read_b128 v[158:161], v170
	ds_read_b128 v[162:165], v170 offset:1024
	ds_read_b128 v[166:169], v170 offset:2048
	ds_read_b128 v[170:173], v170 offset:3072
	s_mov_b32 m0, s51
	v_lshl_add_u64 v[214:215], s[30:31], 0, v[134:135]
	ds_read_b128 v[174:177], v141 offset:32768
	ds_read_b128 v[178:181], v141 offset:33792
	ds_read_b128 v[182:185], v141 offset:34816
	ds_read_b128 v[186:189], v141 offset:35840
	ds_read_b128 v[190:193], v141 offset:36864
	ds_read_b128 v[194:197], v141 offset:37888
	ds_read_b128 v[198:201], v141 offset:38912
	ds_read_b128 v[202:205], v141 offset:39936
	global_load_lds_dwordx4 v[214:215], off
	v_lshl_add_u64 v[214:215], s[30:31], 0, v[130:131]
	s_mov_b32 m0, s55
	s_nop 0
	global_load_lds_dwordx4 v[214:215], off
	s_waitcnt vmcnt(8)
	s_waitcnt lgkmcnt(0)
	s_barrier
	s_setprio 1
	v_mfma_f32_16x16x32_bf16 v[124:127], v[142:145], v[174:177], v[124:127]
	v_mfma_f32_16x16x32_bf16 v[120:123], v[150:153], v[174:177], v[120:123]
	v_mfma_f32_16x16x32_bf16 v[116:119], v[142:145], v[182:185], v[116:119]
	v_mfma_f32_16x16x32_bf16 v[112:115], v[150:153], v[182:185], v[112:115]
	v_mfma_f32_16x16x32_bf16 v[100:103], v[142:145], v[190:193], v[100:103]
	v_mfma_f32_16x16x32_bf16 v[96:99], v[150:153], v[190:193], v[96:99]
	v_mfma_f32_16x16x32_bf16 v[84:87], v[142:145], v[198:201], v[84:87]
	v_mfma_f32_16x16x32_bf16 v[80:83], v[150:153], v[198:201], v[80:83]
	v_mfma_f32_16x16x32_bf16 v[124:127], v[146:149], v[178:181], v[124:127]
	v_mfma_f32_16x16x32_bf16 v[120:123], v[154:157], v[178:181], v[120:123]
	v_mfma_f32_16x16x32_bf16 v[116:119], v[146:149], v[186:189], v[116:119]
	v_mfma_f32_16x16x32_bf16 v[112:115], v[154:157], v[186:189], v[112:115]
	v_mfma_f32_16x16x32_bf16 v[100:103], v[146:149], v[194:197], v[100:103]
	v_mfma_f32_16x16x32_bf16 v[96:99], v[154:157], v[194:197], v[96:99]
	v_mfma_f32_16x16x32_bf16 v[84:87], v[146:149], v[202:205], v[84:87]
	v_mfma_f32_16x16x32_bf16 v[80:83], v[154:157], v[202:205], v[80:83]
	v_mfma_f32_16x16x32_bf16 v[108:111], v[158:161], v[174:177], v[108:111]
	v_mfma_f32_16x16x32_bf16 v[104:107], v[166:169], v[174:177], v[104:107]
	v_mfma_f32_16x16x32_bf16 v[92:95], v[158:161], v[182:185], v[92:95]
	v_mfma_f32_16x16x32_bf16 v[88:91], v[166:169], v[182:185], v[88:91]
	v_mfma_f32_16x16x32_bf16 v[76:79], v[158:161], v[190:193], v[76:79]
	v_mfma_f32_16x16x32_bf16 v[72:75], v[166:169], v[190:193], v[72:75]
	v_mfma_f32_16x16x32_bf16 v[68:71], v[158:161], v[198:201], v[68:71]
	v_mfma_f32_16x16x32_bf16 v[64:67], v[166:169], v[198:201], v[64:67]
	v_mfma_f32_16x16x32_bf16 v[108:111], v[162:165], v[178:181], v[108:111]
	v_mfma_f32_16x16x32_bf16 v[104:107], v[170:173], v[178:181], v[104:107]
	v_mfma_f32_16x16x32_bf16 v[92:95], v[162:165], v[186:189], v[92:95]
	v_mfma_f32_16x16x32_bf16 v[88:91], v[170:173], v[186:189], v[88:91]
	v_mfma_f32_16x16x32_bf16 v[76:79], v[162:165], v[194:197], v[76:79]
	v_mfma_f32_16x16x32_bf16 v[72:75], v[170:173], v[194:197], v[72:75]
	v_mfma_f32_16x16x32_bf16 v[68:71], v[162:165], v[202:205], v[68:71]
	v_mfma_f32_16x16x32_bf16 v[64:67], v[170:173], v[202:205], v[64:67]
	s_setprio 0
	s_barrier
; #define PG8_STAGE(bufoff, gbase, voff) do { _Pragma("unroll") for (int _i = 0; _i < 2; ++_i) \
;         __builtin_amdgcn_global_load_lds((const unsigned*)((const char*)(gbase) + (voff)[_i]), (PG8_LAS unsigned*)(lds + (bufoff) + ldsw + _i * 8192), 16, 0, 0); } while (0)
; #define PG8_LDA(dst, b, h) do { _Pragma("unroll") for (int m = 0; m < 4; ++m) _Pragma("unroll") for (int k = 0; k < 2; ++k) dst[m][k] = *(const PG8_LAS bf16x8*)(lds + PG8_SA(b, h) + aoff + m * 2048 + k * 1024); } while (0)
; #define PG8_MMA(ai, bj, At, Bt) do { __builtin_amdgcn_s_setprio(1); _Pragma("unroll") for (int m = 0; m < 4; ++m) _Pragma("unroll") for (int n = 0; n < 2; ++n) _Pragma("unroll") for (int k = 0; k < 2; ++k) \
;         acc[ai][bj][m][n] = __builtin_amdgcn_mfma_f32_16x16x32_bf16(Bt[n][k], At[m][k], acc[ai][bj][m][n], 0, 0, 0); __builtin_amdgcn_s_setprio(0); } while (0)
; #define PG8_WAIT_V(n) asm volatile("s_waitcnt vmcnt(" #n ")" ::: "memory")
; #define PG8_WAIT_L(n) asm volatile("s_waitcnt lgkmcnt(" #n ")" ::: "memory")
; #define PG8_BAR __builtin_amdgcn_s_barrier()
; #define PG8_SCHED __builtin_amdgcn_sched_barrier(0)
; template <class Epi, class Sched, bool ALIGN_EPI = true, bool SP2 = true>
; __device__ __forceinline__ void gemm_phase(PG8_LAS unsigned char* lds, const Gemm g, const Sched& S, const Epi& E) {
;     ...
;             PG8_LDA(At, 1, 1); PG8_STAGE(PG8_SB(1, 0), b3, voffB); PG8_STAGE(PG8_SB(1, 1), b3 + hstepB, voffB); PG8_STAGE(PG8_SA(1, 0), a3, voffA);
;             PG8_WAIT_V(8); PG8_WAIT_L(0); PG8_BAR; PG8_MMA(1, 0, At, B0); PG8_MMA(1, 1, At, B1); PG8_BAR; PG8_SCHED;
;         }
;         if constexpr (ALIGN_EPI) { if (wr == 0) PG8_BAR; }
	s_mov_b32 m0, s71
	v_lshl_add_u64 v[206:207], v[206:207], 0, s[6:7]
	ds_read_b128 v[174:177], v141 offset:49152
	ds_read_b128 v[178:181], v141 offset:50176
	ds_read_b128 v[182:185], v141 offset:51200
	ds_read_b128 v[186:189], v141 offset:52224
	ds_read_b128 v[190:193], v141 offset:53248
	ds_read_b128 v[194:197], v141 offset:54272
	ds_read_b128 v[198:201], v141 offset:55296
	ds_read_b128 v[202:205], v141 offset:56320
	global_load_lds_dwordx4 v[206:207], off
	v_lshl_add_u64 v[206:207], v[208:209], 0, s[6:7]
	s_mov_b32 m0, s66
	s_nop 0
	global_load_lds_dwordx4 v[206:207], off
	v_lshl_add_u64 v[206:207], s[28:29], 0, v[132:133]
	s_mov_b32 m0, s79
	s_nop 0
	global_load_lds_dwordx4 v[206:207], off
	v_lshl_add_u64 v[206:207], s[28:29], 0, v[128:129]
	s_mov_b32 m0, s78
	s_nop 0
	global_load_lds_dwordx4 v[206:207], off
	v_lshl_add_u64 v[206:207], v[210:211], 0, s[6:7]
	s_mov_b32 m0, s56
	s_nop 0
	global_load_lds_dwordx4 v[206:207], off
	v_lshl_add_u64 v[206:207], v[212:213], 0, s[6:7]
	s_mov_b32 m0, s57
	s_nop 0
	global_load_lds_dwordx4 v[206:207], off
	s_waitcnt vmcnt(8)
	s_waitcnt lgkmcnt(0)
	s_barrier
	s_setprio 1
	v_mfma_f32_16x16x32_bf16 v[60:63], v[142:145], v[174:177], v[60:63]
	v_mfma_f32_16x16x32_bf16 v[56:59], v[150:153], v[174:177], v[56:59]
	v_mfma_f32_16x16x32_bf16 v[52:55], v[142:145], v[182:185], v[52:55]
	v_mfma_f32_16x16x32_bf16 v[48:51], v[150:153], v[182:185], v[48:51]
	v_mfma_f32_16x16x32_bf16 v[36:39], v[142:145], v[190:193], v[36:39]
	v_mfma_f32_16x16x32_bf16 v[32:35], v[150:153], v[190:193], v[32:35]
	v_mfma_f32_16x16x32_bf16 v[20:23], v[142:145], v[198:201], v[20:23]
	v_mfma_f32_16x16x32_bf16 v[16:19], v[150:153], v[198:201], v[16:19]
	v_mfma_f32_16x16x32_bf16 v[60:63], v[146:149], v[178:181], v[60:63]
	v_mfma_f32_16x16x32_bf16 v[56:59], v[154:157], v[178:181], v[56:59]
	v_mfma_f32_16x16x32_bf16 v[52:55], v[146:149], v[186:189], v[52:55]
	v_mfma_f32_16x16x32_bf16 v[48:51], v[154:157], v[186:189], v[48:51]
	v_mfma_f32_16x16x32_bf16 v[36:39], v[146:149], v[194:197], v[36:39]
	v_mfma_f32_16x16x32_bf16 v[32:35], v[154:157], v[194:197], v[32:35]
	v_mfma_f32_16x16x32_bf16 v[20:23], v[146:149], v[202:205], v[20:23]
	v_mfma_f32_16x16x32_bf16 v[16:19], v[154:157], v[202:205], v[16:19]
	v_mfma_f32_16x16x32_bf16 v[44:47], v[158:161], v[174:177], v[44:47]
	v_mfma_f32_16x16x32_bf16 v[40:43], v[166:169], v[174:177], v[40:43]
	v_mfma_f32_16x16x32_bf16 v[28:31], v[158:161], v[182:185], v[28:31]
	v_mfma_f32_16x16x32_bf16 v[24:27], v[166:169], v[182:185], v[24:27]
	v_mfma_f32_16x16x32_bf16 v[12:15], v[158:161], v[190:193], v[12:15]
	v_mfma_f32_16x16x32_bf16 v[8:11], v[166:169], v[190:193], v[8:11]
	v_mfma_f32_16x16x32_bf16 v[4:7], v[158:161], v[198:201], v[4:7]
	v_mfma_f32_16x16x32_bf16 v[0:3], v[166:169], v[198:201], v[0:3]
	v_mfma_f32_16x16x32_bf16 v[44:47], v[162:165], v[178:181], v[44:47]
	v_mfma_f32_16x16x32_bf16 v[40:43], v[170:173], v[178:181], v[40:43]
	v_mfma_f32_16x16x32_bf16 v[28:31], v[162:165], v[186:189], v[28:31]
	v_mfma_f32_16x16x32_bf16 v[24:27], v[170:173], v[186:189], v[24:27]
	v_mfma_f32_16x16x32_bf16 v[12:15], v[162:165], v[194:197], v[12:15]
	v_mfma_f32_16x16x32_bf16 v[8:11], v[170:173], v[194:197], v[8:11]
	v_mfma_f32_16x16x32_bf16 v[4:7], v[162:165], v[202:205], v[4:7]
	v_mfma_f32_16x16x32_bf16 v[0:3], v[170:173], v[202:205], v[0:3]
	s_setprio 0
	s_barrier
	s_movk_i32 s30, 0x100
	s_andn2_b64 vcc, exec, s[26:27]
	s_mov_b64 s[28:29], -1
	s_mov_b64 s[26:27], 0
	s_cbranch_vccz .LBB0_494
	s_and_b64 vcc, exec, s[8:9]
	s_cbranch_vccz .LBB0_497
	s_barrier

; #define PG8_STAGE(bufoff, gbase, voff) do { _Pragma("unroll") for (int _i = 0; _i < 2; ++_i) \
;         __builtin_amdgcn_global_load_lds((const unsigned*)((const char*)(gbase) + (voff)[_i]), (PG8_LAS unsigned*)(lds + (bufoff) + ldsw + _i * 8192), 16, 0, 0); } while (0)
; #define PG8_LDA(dst, b, h) do { _Pragma("unroll") for (int m = 0; m < 4; ++m) _Pragma("unroll") for (int k = 0; k < 2; ++k) dst[m][k] = *(const PG8_LAS bf16x8*)(lds + PG8_SA(b, h) + aoff + m * 2048 + k * 1024); } while (0)
; #define PG8_LDB(dst, b, h) do { _Pragma("unroll") for (int n = 0; n < 2; ++n) _Pragma("unroll") for (int k = 0; k < 2; ++k) dst[n][k] = *(const PG8_LAS bf16x8*)(lds + PG8_SB(b, h) + boff + n * 2048 + k * 1024); } while (0)
; #define PG8_MMA(ai, bj, At, Bt) do { __builtin_amdgcn_s_setprio(1); _Pragma("unroll") for (int m = 0; m < 4; ++m) _Pragma("unroll") for (int n = 0; n < 2; ++n) _Pragma("unroll") for (int k = 0; k < 2; ++k) \
;         acc[ai][bj][m][n] = __builtin_amdgcn_mfma_f32_16x16x32_bf16(Bt[n][k], At[m][k], acc[ai][bj][m][n], 0, 0, 0); __builtin_amdgcn_s_setprio(0); } while (0)
; #define PG8_WAIT_V(n) asm volatile("s_waitcnt vmcnt(" #n ")" ::: "memory")
; #define PG8_WAIT_L(n) asm volatile("s_waitcnt lgkmcnt(" #n ")" ::: "memory")
; #define PG8_BAR __builtin_amdgcn_s_barrier()
; #define PG8_SCHED __builtin_amdgcn_sched_barrier(0)
; template <class Epi, class Sched, bool ALIGN_EPI = true, bool SP2 = true>
; __device__ __forceinline__ void gemm_phase(PG8_LAS unsigned char* lds, const Gemm g, const Sched& S, const Epi& E) {
;     ...
;             const bool last = (t == nt - 2);
;             const char* a1 = cA + (size_t)(t + 1) * kstep;
;             const char* a2 = last ? nA : cA + (size_t)(t + 2) * kstep; const char* b2 = last ? nB : cB + (size_t)(t + 2) * kstep;
;             const char* a3 = a2 + kstep; const char* b3 = b2 + kstep;
;             PG8_LDB(B0, 0, 0); PG8_LDB(B1, 0, 1); PG8_SCHED; PG8_LDA(At, 0, 0); PG8_STAGE(PG8_SA(1, 1), a1 + hstepA, voffA);
;             PG8_WAIT_V(8); PG8_WAIT_L(0); PG8_BAR; PG8_MMA(0, 0, At, B0); PG8_MMA(0, 1, At, B1); PG8_BAR; PG8_SCHED;
;             PG8_LDA(At, 0, 1); PG8_STAGE(PG8_SB(0, 0), b2, voffB); PG8_STAGE(PG8_SB(0, 1), b2 + hstepB, voffB); PG8_STAGE(PG8_SA(0, 0), a2, voffA);
.LBB0_994:
	ds_read_b128 v[144:147], v151
	ds_read_b128 v[154:157], v151 offset:1024
	ds_read_b128 v[158:161], v151 offset:2048
	ds_read_b128 v[162:165], v151 offset:3072
	ds_read_b128 v[166:169], v152
	ds_read_b128 v[170:173], v152 offset:1024
	ds_read_b128 v[174:177], v152 offset:2048
	ds_read_b128 v[178:181], v152 offset:3072
	s_add_u32 s38, s36, 0xfffc0080
	s_addc_u32 s39, s37, -1
	s_cmp_eq_u32 s65, 12
	s_cselect_b32 s41, s25, s39
	s_cselect_b32 s40, s61, s38
	s_cselect_b32 s39, s23, s64
	s_cselect_b32 s38, s62, s63
	v_lshl_add_u64 v[214:215], s[36:37], 0, v[138:139]
	s_add_i32 m0, s31, 0xc000
	ds_read_b128 v[182:185], v153
	ds_read_b128 v[186:189], v153 offset:1024
	ds_read_b128 v[190:193], v153 offset:2048
	ds_read_b128 v[194:197], v153 offset:3072
	ds_read_b128 v[198:201], v153 offset:4096
	ds_read_b128 v[202:205], v153 offset:5120
	ds_read_b128 v[206:209], v153 offset:6144
	ds_read_b128 v[210:213], v153 offset:7168
	global_load_lds_dwordx4 v[214:215], off
	v_lshl_add_u64 v[214:215], s[36:37], 0, v[136:137]
	s_add_i32 m0, s31, 0xe000
	s_nop 0
	global_load_lds_dwordx4 v[214:215], off
	s_waitcnt vmcnt(8)
	s_waitcnt lgkmcnt(0)
	s_barrier
	s_setprio 1
	v_mfma_f32_16x16x32_bf16 v[124:127], v[144:147], v[182:185], v[124:127]
	v_mfma_f32_16x16x32_bf16 v[120:123], v[158:161], v[182:185], v[120:123]
	v_mfma_f32_16x16x32_bf16 v[116:119], v[144:147], v[190:193], v[116:119]
	v_mfma_f32_16x16x32_bf16 v[104:107], v[158:161], v[190:193], v[104:107]
	v_mfma_f32_16x16x32_bf16 v[100:103], v[144:147], v[198:201], v[100:103]
	v_mfma_f32_16x16x32_bf16 v[88:91], v[158:161], v[198:201], v[88:91]
	v_mfma_f32_16x16x32_bf16 v[84:87], v[144:147], v[206:209], v[84:87]
	v_mfma_f32_16x16x32_bf16 v[72:75], v[158:161], v[206:209], v[72:75]
	v_mfma_f32_16x16x32_bf16 v[124:127], v[154:157], v[186:189], v[124:127]
	v_mfma_f32_16x16x32_bf16 v[120:123], v[162:165], v[186:189], v[120:123]
	v_mfma_f32_16x16x32_bf16 v[116:119], v[154:157], v[194:197], v[116:119]
	v_mfma_f32_16x16x32_bf16 v[104:107], v[162:165], v[194:197], v[104:107]
	v_mfma_f32_16x16x32_bf16 v[100:103], v[154:157], v[202:205], v[100:103]
	v_mfma_f32_16x16x32_bf16 v[88:91], v[162:165], v[202:205], v[88:91]
	v_mfma_f32_16x16x32_bf16 v[84:87], v[154:157], v[210:213], v[84:87]
	v_mfma_f32_16x16x32_bf16 v[72:75], v[162:165], v[210:213], v[72:75]
	v_mfma_f32_16x16x32_bf16 v[112:115], v[166:169], v[182:185], v[112:115]
	v_mfma_f32_16x16x32_bf16 v[108:111], v[174:177], v[182:185], v[108:111]
	v_mfma_f32_16x16x32_bf16 v[96:99], v[166:169], v[190:193], v[96:99]
	v_mfma_f32_16x16x32_bf16 v[92:95], v[174:177], v[190:193], v[92:95]
	v_mfma_f32_16x16x32_bf16 v[80:83], v[166:169], v[198:201], v[80:83]
	v_mfma_f32_16x16x32_bf16 v[76:79], v[174:177], v[198:201], v[76:79]
	v_mfma_f32_16x16x32_bf16 v[68:71], v[166:169], v[206:209], v[68:71]
	v_mfma_f32_16x16x32_bf16 v[64:67], v[174:177], v[206:209], v[64:67]
	v_mfma_f32_16x16x32_bf16 v[112:115], v[170:173], v[186:189], v[112:115]
	v_mfma_f32_16x16x32_bf16 v[108:111], v[178:181], v[186:189], v[108:111]
	v_mfma_f32_16x16x32_bf16 v[96:99], v[170:173], v[194:197], v[96:99]
	v_mfma_f32_16x16x32_bf16 v[92:95], v[178:181], v[194:197], v[92:95]
	v_mfma_f32_16x16x32_bf16 v[80:83], v[170:173], v[202:205], v[80:83]
	v_mfma_f32_16x16x32_bf16 v[76:79], v[178:181], v[202:205], v[76:79]
	v_mfma_f32_16x16x32_bf16 v[68:71], v[170:173], v[210:213], v[68:71]
	v_mfma_f32_16x16x32_bf16 v[64:67], v[178:181], v[210:213], v[64:67]
	s_setprio 0
	s_barrier
	s_add_i32 s52, s58, s47
	v_lshl_add_u64 v[214:215], s[38:39], 0, v[130:131]
	s_mov_b32 m0, s52
	ds_read_b128 v[182:185], v153 offset:16384
	ds_read_b128 v[186:189], v153 offset:17408
	ds_read_b128 v[190:193], v153 offset:18432
	ds_read_b128 v[194:197], v153 offset:19456
	ds_read_b128 v[198:201], v153 offset:20480
	ds_read_b128 v[202:205], v153 offset:21504
	ds_read_b128 v[206:209], v153 offset:22528
	ds_read_b128 v[210:213], v153 offset:23552
	global_load_lds_dwordx4 v[214:215], off
	s_add_i32 m0, s52, 0x2000
	s_add_u32 s52, s38, 0x40000
	v_lshl_add_u64 v[216:217], s[38:39], 0, v[134:135]
	s_addc_u32 s53, s39, 0
	s_add_i32 s66, s59, s47
	global_load_lds_dwordx4 v[216:217], off
	v_lshl_add_u64 v[218:219], s[52:53], 0, v[130:131]
	s_mov_b32 m0, s66
	v_lshl_add_u64 v[220:221], s[40:41], 0, v[132:133]
	global_load_lds_dwordx4 v[218:219], off
	v_lshl_add_u64 v[218:219], s[52:53], 0, v[134:135]
	s_add_i32 m0, s66, 0x2000
	s_nop 0
	global_load_lds_dwordx4 v[218:219], off
	v_lshl_add_u64 v[218:219], s[40:41], 0, v[128:129]
	s_mov_b32 m0, s31
	s_nop 0
	global_load_lds_dwordx4 v[218:219], off
	s_mov_b32 m0, s48
	s_nop 0
	global_load_lds_dwordx4 v[220:221], off
	s_waitcnt vmcnt(8)
	s_waitcnt lgkmcnt(0)
	s_barrier
; #define PG8_STAGE(bufoff, gbase, voff) do { _Pragma("unroll") for (int _i = 0; _i < 2; ++_i) \
;         __builtin_amdgcn_global_load_lds((const unsigned*)((const char*)(gbase) + (voff)[_i]), (PG8_LAS unsigned*)(lds + (bufoff) + ldsw + _i * 8192), 16, 0, 0); } while (0)
; #define PG8_LDA(dst, b, h) do { _Pragma("unroll") for (int m = 0; m < 4; ++m) _Pragma("unroll") for (int k = 0; k < 2; ++k) dst[m][k] = *(const PG8_LAS bf16x8*)(lds + PG8_SA(b, h) + aoff + m * 2048 + k * 1024); } while (0)
; #define PG8_LDB(dst, b, h) do { _Pragma("unroll") for (int n = 0; n < 2; ++n) _Pragma("unroll") for (int k = 0; k < 2; ++k) dst[n][k] = *(const PG8_LAS bf16x8*)(lds + PG8_SB(b, h) + boff + n * 2048 + k * 1024); } while (0)
; #define PG8_MMA(ai, bj, At, Bt) do { __builtin_amdgcn_s_setprio(1); _Pragma("unroll") for (int m = 0; m < 4; ++m) _Pragma("unroll") for (int n = 0; n < 2; ++n) _Pragma("unroll") for (int k = 0; k < 2; ++k) \
;         acc[ai][bj][m][n] = __builtin_amdgcn_mfma_f32_16x16x32_bf16(Bt[n][k], At[m][k], acc[ai][bj][m][n], 0, 0, 0); __builtin_amdgcn_s_setprio(0); } while (0)
; #define PG8_WAIT_V(n) asm volatile("s_waitcnt vmcnt(" #n ")" ::: "memory")
; #define PG8_WAIT_L(n) asm volatile("s_waitcnt lgkmcnt(" #n ")" ::: "memory")
; #define PG8_BAR __builtin_amdgcn_s_barrier()
; #define PG8_SCHED __builtin_amdgcn_sched_barrier(0)
; template <class Epi, class Sched, bool ALIGN_EPI = true, bool SP2 = true>
; __device__ __forceinline__ void gemm_phase(PG8_LAS unsigned char* lds, const Gemm g, const Sched& S, const Epi& E) {
;     ...
;             PG8_WAIT_V(8); PG8_WAIT_L(0); PG8_BAR; PG8_MMA(1, 0, At, B0); PG8_MMA(1, 1, At, B1); PG8_BAR; PG8_SCHED;
;             PG8_LDB(B0, 1, 0); PG8_LDB(B1, 1, 1); PG8_SCHED; PG8_LDA(At, 1, 0); PG8_STAGE(PG8_SA(0, 1), a2 + hstepA, voffA);
;             PG8_WAIT_V(8); PG8_WAIT_L(0); PG8_BAR; PG8_MMA(0, 0, At, B0); PG8_MMA(0, 1, At, B1); PG8_BAR; PG8_SCHED;
	s_setprio 1
	v_mfma_f32_16x16x32_bf16 v[60:63], v[144:147], v[182:185], v[60:63]
	v_mfma_f32_16x16x32_bf16 v[56:59], v[158:161], v[182:185], v[56:59]
	v_mfma_f32_16x16x32_bf16 v[52:55], v[144:147], v[190:193], v[52:55]
	v_mfma_f32_16x16x32_bf16 v[40:43], v[158:161], v[190:193], v[40:43]
	v_mfma_f32_16x16x32_bf16 v[36:39], v[144:147], v[198:201], v[36:39]
	v_mfma_f32_16x16x32_bf16 v[24:27], v[158:161], v[198:201], v[24:27]
	v_mfma_f32_16x16x32_bf16 v[20:23], v[144:147], v[206:209], v[20:23]
	v_mfma_f32_16x16x32_bf16 v[8:11], v[158:161], v[206:209], v[8:11]
	v_mfma_f32_16x16x32_bf16 v[60:63], v[154:157], v[186:189], v[60:63]
	v_mfma_f32_16x16x32_bf16 v[56:59], v[162:165], v[186:189], v[56:59]
	v_mfma_f32_16x16x32_bf16 v[52:55], v[154:157], v[194:197], v[52:55]
	v_mfma_f32_16x16x32_bf16 v[40:43], v[162:165], v[194:197], v[40:43]
	v_mfma_f32_16x16x32_bf16 v[36:39], v[154:157], v[202:205], v[36:39]
	v_mfma_f32_16x16x32_bf16 v[24:27], v[162:165], v[202:205], v[24:27]
	v_mfma_f32_16x16x32_bf16 v[20:23], v[154:157], v[210:213], v[20:23]
	v_mfma_f32_16x16x32_bf16 v[8:11], v[162:165], v[210:213], v[8:11]
	v_mfma_f32_16x16x32_bf16 v[48:51], v[166:169], v[182:185], v[48:51]
	v_mfma_f32_16x16x32_bf16 v[44:47], v[174:177], v[182:185], v[44:47]
	v_mfma_f32_16x16x32_bf16 v[32:35], v[166:169], v[190:193], v[32:35]
	v_mfma_f32_16x16x32_bf16 v[28:31], v[174:177], v[190:193], v[28:31]
	v_mfma_f32_16x16x32_bf16 v[16:19], v[166:169], v[198:201], v[16:19]
	v_mfma_f32_16x16x32_bf16 v[12:15], v[174:177], v[198:201], v[12:15]
	v_mfma_f32_16x16x32_bf16 v[4:7], v[166:169], v[206:209], v[4:7]
	v_mfma_f32_16x16x32_bf16 v[0:3], v[174:177], v[206:209], v[0:3]
	v_mfma_f32_16x16x32_bf16 v[48:51], v[170:173], v[186:189], v[48:51]
	v_mfma_f32_16x16x32_bf16 v[44:47], v[178:181], v[186:189], v[44:47]
	v_mfma_f32_16x16x32_bf16 v[32:35], v[170:173], v[194:197], v[32:35]
	v_mfma_f32_16x16x32_bf16 v[28:31], v[178:181], v[194:197], v[28:31]
	v_mfma_f32_16x16x32_bf16 v[16:19], v[170:173], v[202:205], v[16:19]
	v_mfma_f32_16x16x32_bf16 v[12:15], v[178:181], v[202:205], v[12:15]
	v_mfma_f32_16x16x32_bf16 v[4:7], v[170:173], v[210:213], v[4:7]
	v_mfma_f32_16x16x32_bf16 v[0:3], v[178:181], v[210:213], v[0:3]
	s_setprio 0
	s_barrier
	s_add_i32 s52, 0, 0x18000
	s_add_i32 s53, 0, 0x1c000
	v_add_u32_e32 v162, s52, v149
	v_add_u32_e32 v178, s53, v149
	ds_read_b128 v[144:147], v162
	ds_read_b128 v[154:157], v162 offset:1024
	ds_read_b128 v[158:161], v162 offset:2048
	ds_read_b128 v[162:165], v162 offset:3072
	ds_read_b128 v[166:169], v178
	ds_read_b128 v[170:173], v178 offset:1024
	ds_read_b128 v[174:177], v178 offset:2048
	ds_read_b128 v[178:181], v178 offset:3072
	s_add_u32 s40, s40, 0x40000
	s_addc_u32 s41, s41, 0
	s_mov_b32 m0, s49
	v_lshl_add_u64 v[222:223], s[40:41], 0, v[128:129]
	ds_read_b128 v[182:185], v153 offset:32768
	ds_read_b128 v[186:189], v153 offset:33792
	ds_read_b128 v[190:193], v153 offset:34816
	ds_read_b128 v[194:197], v153 offset:35840
	ds_read_b128 v[198:201], v153 offset:36864
	ds_read_b128 v[202:205], v153 offset:37888
	ds_read_b128 v[206:209], v153 offset:38912
	ds_read_b128 v[210:213], v153 offset:39936
	global_load_lds_dwordx4 v[222:223], off
	v_lshl_add_u64 v[222:223], s[40:41], 0, v[132:133]
	s_mov_b32 m0, s50
	s_nop 0
	global_load_lds_dwordx4 v[222:223], off
	s_waitcnt vmcnt(8)
	s_waitcnt lgkmcnt(0)
	s_barrier
	s_setprio 1
	v_mfma_f32_16x16x32_bf16 v[124:127], v[144:147], v[182:185], v[124:127]
	v_mfma_f32_16x16x32_bf16 v[120:123], v[158:161], v[182:185], v[120:123]
	v_mfma_f32_16x16x32_bf16 v[116:119], v[144:147], v[190:193], v[116:119]
	v_mfma_f32_16x16x32_bf16 v[104:107], v[158:161], v[190:193], v[104:107]
	v_mfma_f32_16x16x32_bf16 v[100:103], v[144:147], v[198:201], v[100:103]
	v_mfma_f32_16x16x32_bf16 v[88:91], v[158:161], v[198:201], v[88:91]
	v_mfma_f32_16x16x32_bf16 v[84:87], v[144:147], v[206:209], v[84:87]
	v_mfma_f32_16x16x32_bf16 v[72:75], v[158:161], v[206:209], v[72:75]
	v_mfma_f32_16x16x32_bf16 v[124:127], v[154:157], v[186:189], v[124:127]
	v_mfma_f32_16x16x32_bf16 v[120:123], v[162:165], v[186:189], v[120:123]
	v_mfma_f32_16x16x32_bf16 v[116:119], v[154:157], v[194:197], v[116:119]
	v_mfma_f32_16x16x32_bf16 v[104:107], v[162:165], v[194:197], v[104:107]
	v_mfma_f32_16x16x32_bf16 v[100:103], v[154:157], v[202:205], v[100:103]
	v_mfma_f32_16x16x32_bf16 v[88:91], v[162:165], v[202:205], v[88:91]
	v_mfma_f32_16x16x32_bf16 v[84:87], v[154:157], v[210:213], v[84:87]
	v_mfma_f32_16x16x32_bf16 v[72:75], v[162:165], v[210:213], v[72:75]
	v_mfma_f32_16x16x32_bf16 v[112:115], v[166:169], v[182:185], v[112:115]
	v_mfma_f32_16x16x32_bf16 v[108:111], v[174:177], v[182:185], v[108:111]
	v_mfma_f32_16x16x32_bf16 v[96:99], v[166:169], v[190:193], v[96:99]
	v_mfma_f32_16x16x32_bf16 v[92:95], v[174:177], v[190:193], v[92:95]
	v_mfma_f32_16x16x32_bf16 v[80:83], v[166:169], v[198:201], v[80:83]
	v_mfma_f32_16x16x32_bf16 v[76:79], v[174:177], v[198:201], v[76:79]
	v_mfma_f32_16x16x32_bf16 v[68:71], v[166:169], v[206:209], v[68:71]
	v_mfma_f32_16x16x32_bf16 v[64:67], v[174:177], v[206:209], v[64:67]
	v_mfma_f32_16x16x32_bf16 v[112:115], v[170:173], v[186:189], v[112:115]
	v_mfma_f32_16x16x32_bf16 v[108:111], v[178:181], v[186:189], v[108:111]
	v_mfma_f32_16x16x32_bf16 v[96:99], v[170:173], v[194:197], v[96:99]
	v_mfma_f32_16x16x32_bf16 v[92:95], v[178:181], v[194:197], v[92:95]
	v_mfma_f32_16x16x32_bf16 v[80:83], v[170:173], v[202:205], v[80:83]
	v_mfma_f32_16x16x32_bf16 v[76:79], v[178:181], v[202:205], v[76:79]
	v_mfma_f32_16x16x32_bf16 v[68:71], v[170:173], v[210:213], v[68:71]
	v_mfma_f32_16x16x32_bf16 v[64:67], v[178:181], v[210:213], v[64:67]
	s_setprio 0
	s_barrier
; #define PG8_STAGE(bufoff, gbase, voff) do { _Pragma("unroll") for (int _i = 0; _i < 2; ++_i) \
;         __builtin_amdgcn_global_load_lds((const unsigned*)((const char*)(gbase) + (voff)[_i]), (PG8_LAS unsigned*)(lds + (bufoff) + ldsw + _i * 8192), 16, 0, 0); } while (0)
; #define PG8_LDA(dst, b, h) do { _Pragma("unroll") for (int m = 0; m < 4; ++m) _Pragma("unroll") for (int k = 0; k < 2; ++k) dst[m][k] = *(const PG8_LAS bf16x8*)(lds + PG8_SA(b, h) + aoff + m * 2048 + k * 1024); } while (0)
; #define PG8_MMA(ai, bj, At, Bt) do { __builtin_amdgcn_s_setprio(1); _Pragma("unroll") for (int m = 0; m < 4; ++m) _Pragma("unroll") for (int n = 0; n < 2; ++n) _Pragma("unroll") for (int k = 0; k < 2; ++k) \
;         acc[ai][bj][m][n] = __builtin_amdgcn_mfma_f32_16x16x32_bf16(Bt[n][k], At[m][k], acc[ai][bj][m][n], 0, 0, 0); __builtin_amdgcn_s_setprio(0); } while (0)
; #define PG8_WAIT_V(n) asm volatile("s_waitcnt vmcnt(" #n ")" ::: "memory")
; #define PG8_WAIT_L(n) asm volatile("s_waitcnt lgkmcnt(" #n ")" ::: "memory")
; #define PG8_BAR __builtin_amdgcn_s_barrier()
; #define PG8_SCHED __builtin_amdgcn_sched_barrier(0)
; template <class Epi, class Sched, bool ALIGN_EPI = true, bool SP2 = true>
; __device__ __forceinline__ void gemm_phase(PG8_LAS unsigned char* lds, const Gemm g, const Sched& S, const Epi& E) {
;     ...
;             PG8_LDA(At, 1, 1); PG8_STAGE(PG8_SB(1, 0), b3, voffB); PG8_STAGE(PG8_SB(1, 1), b3 + hstepB, voffB); PG8_STAGE(PG8_SA(1, 0), a3, voffA);
;             PG8_WAIT_V(8); PG8_WAIT_L(0); PG8_BAR; PG8_MMA(1, 0, At, B0); PG8_MMA(1, 1, At, B1); PG8_BAR; PG8_SCHED;
;         }
;         if constexpr (ALIGN_EPI) { if (wr == 0) PG8_BAR; }
	s_add_i32 s40, s52, s47
	v_lshl_add_u64 v[214:215], v[214:215], 0, s[10:11]
	s_mov_b32 m0, s40
	ds_read_b128 v[182:185], v153 offset:49152
	ds_read_b128 v[186:189], v153 offset:50176
	ds_read_b128 v[190:193], v153 offset:51200
	ds_read_b128 v[194:197], v153 offset:52224
	ds_read_b128 v[198:201], v153 offset:53248
	ds_read_b128 v[202:205], v153 offset:54272
	ds_read_b128 v[206:209], v153 offset:55296
	ds_read_b128 v[210:213], v153 offset:56320
	global_load_lds_dwordx4 v[214:215], off
	s_add_i32 m0, s40, 0x2000
	s_add_u32 s38, s38, 0x40080
	v_lshl_add_u64 v[214:215], v[216:217], 0, s[10:11]
	s_addc_u32 s39, s39, 0
	s_add_i32 s40, s53, s47
	global_load_lds_dwordx4 v[214:215], off
	v_lshl_add_u64 v[214:215], s[38:39], 0, v[130:131]
	s_mov_b32 m0, s40
	s_nop 0
	global_load_lds_dwordx4 v[214:215], off
	v_lshl_add_u64 v[214:215], s[38:39], 0, v[134:135]
	s_add_i32 m0, s40, 0x2000
	s_nop 0
	global_load_lds_dwordx4 v[214:215], off
	v_lshl_add_u64 v[214:215], v[218:219], 0, s[10:11]
	s_mov_b32 m0, s54
	s_nop 0
	global_load_lds_dwordx4 v[214:215], off
	v_lshl_add_u64 v[214:215], v[220:221], 0, s[10:11]
	s_mov_b32 m0, s55
	s_nop 0
	global_load_lds_dwordx4 v[214:215], off
	s_waitcnt vmcnt(8)
	s_waitcnt lgkmcnt(0)
	s_barrier
	s_setprio 1
	v_mfma_f32_16x16x32_bf16 v[60:63], v[144:147], v[182:185], v[60:63]
	v_mfma_f32_16x16x32_bf16 v[56:59], v[158:161], v[182:185], v[56:59]
	v_mfma_f32_16x16x32_bf16 v[52:55], v[144:147], v[190:193], v[52:55]
	v_mfma_f32_16x16x32_bf16 v[40:43], v[158:161], v[190:193], v[40:43]
	v_mfma_f32_16x16x32_bf16 v[36:39], v[144:147], v[198:201], v[36:39]
	v_mfma_f32_16x16x32_bf16 v[24:27], v[158:161], v[198:201], v[24:27]
	v_mfma_f32_16x16x32_bf16 v[20:23], v[144:147], v[206:209], v[20:23]
	v_mfma_f32_16x16x32_bf16 v[8:11], v[158:161], v[206:209], v[8:11]
	v_mfma_f32_16x16x32_bf16 v[60:63], v[154:157], v[186:189], v[60:63]
	v_mfma_f32_16x16x32_bf16 v[56:59], v[162:165], v[186:189], v[56:59]
	v_mfma_f32_16x16x32_bf16 v[52:55], v[154:157], v[194:197], v[52:55]
	v_mfma_f32_16x16x32_bf16 v[40:43], v[162:165], v[194:197], v[40:43]
	v_mfma_f32_16x16x32_bf16 v[36:39], v[154:157], v[202:205], v[36:39]
	v_mfma_f32_16x16x32_bf16 v[24:27], v[162:165], v[202:205], v[24:27]
	v_mfma_f32_16x16x32_bf16 v[20:23], v[154:157], v[210:213], v[20:23]
	v_mfma_f32_16x16x32_bf16 v[8:11], v[162:165], v[210:213], v[8:11]
	v_mfma_f32_16x16x32_bf16 v[48:51], v[166:169], v[182:185], v[48:51]
	v_mfma_f32_16x16x32_bf16 v[44:47], v[174:177], v[182:185], v[44:47]
	v_mfma_f32_16x16x32_bf16 v[32:35], v[166:169], v[190:193], v[32:35]
	v_mfma_f32_16x16x32_bf16 v[28:31], v[174:177], v[190:193], v[28:31]
	v_mfma_f32_16x16x32_bf16 v[16:19], v[166:169], v[198:201], v[16:19]
	v_mfma_f32_16x16x32_bf16 v[12:15], v[174:177], v[198:201], v[12:15]
	v_mfma_f32_16x16x32_bf16 v[4:7], v[166:169], v[206:209], v[4:7]
	v_mfma_f32_16x16x32_bf16 v[0:3], v[174:177], v[206:209], v[0:3]
	v_mfma_f32_16x16x32_bf16 v[48:51], v[170:173], v[186:189], v[48:51]
	v_mfma_f32_16x16x32_bf16 v[44:47], v[178:181], v[186:189], v[44:47]
	v_mfma_f32_16x16x32_bf16 v[32:35], v[170:173], v[194:197], v[32:35]
	v_mfma_f32_16x16x32_bf16 v[28:31], v[178:181], v[194:197], v[28:31]
	v_mfma_f32_16x16x32_bf16 v[16:19], v[170:173], v[202:205], v[16:19]
	v_mfma_f32_16x16x32_bf16 v[12:15], v[178:181], v[202:205], v[12:15]
	v_mfma_f32_16x16x32_bf16 v[4:7], v[170:173], v[210:213], v[4:7]
	v_mfma_f32_16x16x32_bf16 v[0:3], v[178:181], v[210:213], v[0:3]
	s_setprio 0
	s_barrier
	s_add_i32 s65, s65, 2
	s_add_u32 s63, s63, 0x100
	s_addc_u32 s64, s64, 0
	s_add_u32 s36, s36, 0x100
	s_addc_u32 s37, s37, 0
	s_cmp_gt_u32 s65, 13
	s_cbranch_scc0 .LBB0_994
	s_and_b64 vcc, exec, s[12:13]
	s_cbranch_vccz .LBB0_997
	s_barrier

; #define PG8_STAGE(bufoff, gbase, voff) do { _Pragma("unroll") for (int _i = 0; _i < 2; ++_i) \
;         __builtin_amdgcn_global_load_lds((const unsigned*)((const char*)(gbase) + (voff)[_i]), (PG8_LAS unsigned*)(lds + (bufoff) + ldsw + _i * 8192), 16, 0, 0); } while (0)
; #define PG8_LDA(dst, b, h) do { _Pragma("unroll") for (int m = 0; m < 4; ++m) _Pragma("unroll") for (int k = 0; k < 2; ++k) dst[m][k] = *(const PG8_LAS bf16x8*)(lds + PG8_SA(b, h) + aoff + m * 2048 + k * 1024); } while (0)
; #define PG8_LDB(dst, b, h) do { _Pragma("unroll") for (int n = 0; n < 2; ++n) _Pragma("unroll") for (int k = 0; k < 2; ++k) dst[n][k] = *(const PG8_LAS bf16x8*)(lds + PG8_SB(b, h) + boff + n * 2048 + k * 1024); } while (0)
; #define PG8_MMA(ai, bj, At, Bt) do { __builtin_amdgcn_s_setprio(1); _Pragma("unroll") for (int m = 0; m < 4; ++m) _Pragma("unroll") for (int n = 0; n < 2; ++n) _Pragma("unroll") for (int k = 0; k < 2; ++k) \
;         acc[ai][bj][m][n] = __builtin_amdgcn_mfma_f32_16x16x32_bf16(Bt[n][k], At[m][k], acc[ai][bj][m][n], 0, 0, 0); __builtin_amdgcn_s_setprio(0); } while (0)
; #define PG8_WAIT_V(n) asm volatile("s_waitcnt vmcnt(" #n ")" ::: "memory")
; #define PG8_WAIT_L(n) asm volatile("s_waitcnt lgkmcnt(" #n ")" ::: "memory")
; #define PG8_BAR __builtin_amdgcn_s_barrier()
; #define PG8_SCHED __builtin_amdgcn_sched_barrier(0)
; template <class Epi, class Sched, bool ALIGN_EPI = true, bool SP2 = true>
; __device__ __forceinline__ void gemm_phase(PG8_LAS unsigned char* lds, const Gemm g, const Sched& S, const Epi& E) {
;     ...
;             const bool last = (t == nt - 2);
;             const char* a1 = cA + (size_t)(t + 1) * kstep;
;             const char* a2 = last ? nA : cA + (size_t)(t + 2) * kstep; const char* b2 = last ? nB : cB + (size_t)(t + 2) * kstep;
;             const char* a3 = a2 + kstep; const char* b3 = b2 + kstep;
;             PG8_LDB(B0, 0, 0); PG8_LDB(B1, 0, 1); PG8_SCHED; PG8_LDA(At, 0, 0); PG8_STAGE(PG8_SA(1, 1), a1 + hstepA, voffA);
;             PG8_WAIT_V(8); PG8_WAIT_L(0); PG8_BAR; PG8_MMA(0, 0, At, B0); PG8_MMA(0, 1, At, B1); PG8_BAR; PG8_SCHED;
;             PG8_LDA(At, 0, 1); PG8_STAGE(PG8_SB(0, 0), b2, voffB); PG8_STAGE(PG8_SB(0, 1), b2 + hstepB, voffB); PG8_STAGE(PG8_SA(0, 0), a2, voffA);
.LBB0_1054:
	ds_read_b128 v[140:143], v147
	ds_read_b128 v[150:153], v147 offset:1024
	ds_read_b128 v[154:157], v147 offset:2048
	ds_read_b128 v[158:161], v147 offset:3072
	ds_read_b128 v[162:165], v148
	ds_read_b128 v[166:169], v148 offset:1024
	ds_read_b128 v[170:173], v148 offset:2048
	ds_read_b128 v[174:177], v148 offset:3072
	s_add_u32 s40, s36, 0xfffc0080
	s_addc_u32 s41, s37, -1
	s_cmp_eq_u32 s72, 12
	s_cselect_b32 s43, s23, s41
	s_cselect_b32 s42, s64, s40
	s_cselect_b32 s41, s21, s71
	s_cselect_b32 s40, s65, s66
	v_lshl_add_u64 v[210:211], s[36:37], 0, v[138:139]
	s_add_i32 m0, s31, 0xc000
	ds_read_b128 v[178:181], v149
	ds_read_b128 v[182:185], v149 offset:1024
	ds_read_b128 v[186:189], v149 offset:2048
	ds_read_b128 v[190:193], v149 offset:3072
	ds_read_b128 v[194:197], v149 offset:4096
	ds_read_b128 v[198:201], v149 offset:5120
	ds_read_b128 v[202:205], v149 offset:6144
	ds_read_b128 v[206:209], v149 offset:7168
	global_load_lds_dwordx4 v[210:211], off
	v_lshl_add_u64 v[210:211], s[36:37], 0, v[136:137]
	s_add_i32 m0, s31, 0xe000
	s_nop 0
	global_load_lds_dwordx4 v[210:211], off
	s_waitcnt vmcnt(8)
	s_waitcnt lgkmcnt(0)
	s_barrier
	s_setprio 1
	v_mfma_f32_16x16x32_bf16 v[124:127], v[140:143], v[178:181], v[124:127]
	v_mfma_f32_16x16x32_bf16 v[120:123], v[154:157], v[178:181], v[120:123]
	v_mfma_f32_16x16x32_bf16 v[116:119], v[140:143], v[186:189], v[116:119]
	v_mfma_f32_16x16x32_bf16 v[104:107], v[154:157], v[186:189], v[104:107]
	v_mfma_f32_16x16x32_bf16 v[100:103], v[140:143], v[194:197], v[100:103]
	v_mfma_f32_16x16x32_bf16 v[88:91], v[154:157], v[194:197], v[88:91]
	v_mfma_f32_16x16x32_bf16 v[84:87], v[140:143], v[202:205], v[84:87]
	v_mfma_f32_16x16x32_bf16 v[72:75], v[154:157], v[202:205], v[72:75]
	v_mfma_f32_16x16x32_bf16 v[124:127], v[150:153], v[182:185], v[124:127]
	v_mfma_f32_16x16x32_bf16 v[120:123], v[158:161], v[182:185], v[120:123]
	v_mfma_f32_16x16x32_bf16 v[116:119], v[150:153], v[190:193], v[116:119]
	v_mfma_f32_16x16x32_bf16 v[104:107], v[158:161], v[190:193], v[104:107]
	v_mfma_f32_16x16x32_bf16 v[100:103], v[150:153], v[198:201], v[100:103]
	v_mfma_f32_16x16x32_bf16 v[88:91], v[158:161], v[198:201], v[88:91]
	v_mfma_f32_16x16x32_bf16 v[84:87], v[150:153], v[206:209], v[84:87]
	v_mfma_f32_16x16x32_bf16 v[72:75], v[158:161], v[206:209], v[72:75]
	v_mfma_f32_16x16x32_bf16 v[112:115], v[162:165], v[178:181], v[112:115]
	v_mfma_f32_16x16x32_bf16 v[108:111], v[170:173], v[178:181], v[108:111]
	v_mfma_f32_16x16x32_bf16 v[96:99], v[162:165], v[186:189], v[96:99]
	v_mfma_f32_16x16x32_bf16 v[92:95], v[170:173], v[186:189], v[92:95]
	v_mfma_f32_16x16x32_bf16 v[80:83], v[162:165], v[194:197], v[80:83]
	v_mfma_f32_16x16x32_bf16 v[76:79], v[170:173], v[194:197], v[76:79]
	v_mfma_f32_16x16x32_bf16 v[68:71], v[162:165], v[202:205], v[68:71]
	v_mfma_f32_16x16x32_bf16 v[64:67], v[170:173], v[202:205], v[64:67]
	v_mfma_f32_16x16x32_bf16 v[112:115], v[166:169], v[182:185], v[112:115]
	v_mfma_f32_16x16x32_bf16 v[108:111], v[174:177], v[182:185], v[108:111]
	v_mfma_f32_16x16x32_bf16 v[96:99], v[166:169], v[190:193], v[96:99]
	v_mfma_f32_16x16x32_bf16 v[92:95], v[174:177], v[190:193], v[92:95]
	v_mfma_f32_16x16x32_bf16 v[80:83], v[166:169], v[198:201], v[80:83]
	v_mfma_f32_16x16x32_bf16 v[76:79], v[174:177], v[198:201], v[76:79]
	v_mfma_f32_16x16x32_bf16 v[68:71], v[166:169], v[206:209], v[68:71]
	v_mfma_f32_16x16x32_bf16 v[64:67], v[174:177], v[206:209], v[64:67]
	s_setprio 0
	s_barrier
	s_add_i32 s52, s61, s49
	v_lshl_add_u64 v[210:211], s[40:41], 0, v[132:133]
	s_mov_b32 m0, s52
	ds_read_b128 v[178:181], v149 offset:16384
	ds_read_b128 v[182:185], v149 offset:17408
	ds_read_b128 v[186:189], v149 offset:18432
	ds_read_b128 v[190:193], v149 offset:19456
	ds_read_b128 v[194:197], v149 offset:20480
	ds_read_b128 v[198:201], v149 offset:21504
	ds_read_b128 v[202:205], v149 offset:22528
	ds_read_b128 v[206:209], v149 offset:23552
	global_load_lds_dwordx4 v[210:211], off
	s_add_i32 m0, s52, 0x2000
	s_add_u32 s52, s40, 0x40000
	v_lshl_add_u64 v[212:213], s[40:41], 0, v[128:129]
	s_addc_u32 s53, s41, 0
	s_add_i32 s68, s62, s49
	global_load_lds_dwordx4 v[212:213], off
	v_lshl_add_u64 v[214:215], s[52:53], 0, v[132:133]
	s_mov_b32 m0, s68
	v_lshl_add_u64 v[216:217], s[42:43], 0, v[130:131]
	global_load_lds_dwordx4 v[214:215], off
	v_lshl_add_u64 v[214:215], s[52:53], 0, v[128:129]
	s_add_i32 m0, s68, 0x2000
	s_nop 0
	global_load_lds_dwordx4 v[214:215], off
	v_lshl_add_u64 v[214:215], s[42:43], 0, v[134:135]
	s_mov_b32 m0, s31
	s_nop 0
	global_load_lds_dwordx4 v[214:215], off
	s_mov_b32 m0, s51
	s_nop 0
	global_load_lds_dwordx4 v[216:217], off
	s_waitcnt vmcnt(8)
	s_waitcnt lgkmcnt(0)
	s_barrier
; #define PG8_STAGE(bufoff, gbase, voff) do { _Pragma("unroll") for (int _i = 0; _i < 2; ++_i) \
;         __builtin_amdgcn_global_load_lds((const unsigned*)((const char*)(gbase) + (voff)[_i]), (PG8_LAS unsigned*)(lds + (bufoff) + ldsw + _i * 8192), 16, 0, 0); } while (0)
; #define PG8_LDA(dst, b, h) do { _Pragma("unroll") for (int m = 0; m < 4; ++m) _Pragma("unroll") for (int k = 0; k < 2; ++k) dst[m][k] = *(const PG8_LAS bf16x8*)(lds + PG8_SA(b, h) + aoff + m * 2048 + k * 1024); } while (0)
; #define PG8_LDB(dst, b, h) do { _Pragma("unroll") for (int n = 0; n < 2; ++n) _Pragma("unroll") for (int k = 0; k < 2; ++k) dst[n][k] = *(const PG8_LAS bf16x8*)(lds + PG8_SB(b, h) + boff + n * 2048 + k * 1024); } while (0)
; #define PG8_MMA(ai, bj, At, Bt) do { __builtin_amdgcn_s_setprio(1); _Pragma("unroll") for (int m = 0; m < 4; ++m) _Pragma("unroll") for (int n = 0; n < 2; ++n) _Pragma("unroll") for (int k = 0; k < 2; ++k) \
;         acc[ai][bj][m][n] = __builtin_amdgcn_mfma_f32_16x16x32_bf16(Bt[n][k], At[m][k], acc[ai][bj][m][n], 0, 0, 0); __builtin_amdgcn_s_setprio(0); } while (0)
; #define PG8_WAIT_V(n) asm volatile("s_waitcnt vmcnt(" #n ")" ::: "memory")
; #define PG8_WAIT_L(n) asm volatile("s_waitcnt lgkmcnt(" #n ")" ::: "memory")
; #define PG8_BAR __builtin_amdgcn_s_barrier()
; #define PG8_SCHED __builtin_amdgcn_sched_barrier(0)
; template <class Epi, class Sched, bool ALIGN_EPI = true, bool SP2 = true>
; __device__ __forceinline__ void gemm_phase(PG8_LAS unsigned char* lds, const Gemm g, const Sched& S, const Epi& E) {
;     ...
;             PG8_WAIT_V(8); PG8_WAIT_L(0); PG8_BAR; PG8_MMA(1, 0, At, B0); PG8_MMA(1, 1, At, B1); PG8_BAR; PG8_SCHED;
;             PG8_LDB(B0, 1, 0); PG8_LDB(B1, 1, 1); PG8_SCHED; PG8_LDA(At, 1, 0); PG8_STAGE(PG8_SA(0, 1), a2 + hstepA, voffA);
;             PG8_WAIT_V(8); PG8_WAIT_L(0); PG8_BAR; PG8_MMA(0, 0, At, B0); PG8_MMA(0, 1, At, B1); PG8_BAR; PG8_SCHED;
	s_setprio 1
	v_mfma_f32_16x16x32_bf16 v[60:63], v[140:143], v[178:181], v[60:63]
	v_mfma_f32_16x16x32_bf16 v[56:59], v[154:157], v[178:181], v[56:59]
	v_mfma_f32_16x16x32_bf16 v[52:55], v[140:143], v[186:189], v[52:55]
	v_mfma_f32_16x16x32_bf16 v[40:43], v[154:157], v[186:189], v[40:43]
	v_mfma_f32_16x16x32_bf16 v[36:39], v[140:143], v[194:197], v[36:39]
	v_mfma_f32_16x16x32_bf16 v[24:27], v[154:157], v[194:197], v[24:27]
	v_mfma_f32_16x16x32_bf16 v[20:23], v[140:143], v[202:205], v[20:23]
	v_mfma_f32_16x16x32_bf16 v[8:11], v[154:157], v[202:205], v[8:11]
	v_mfma_f32_16x16x32_bf16 v[60:63], v[150:153], v[182:185], v[60:63]
	v_mfma_f32_16x16x32_bf16 v[56:59], v[158:161], v[182:185], v[56:59]
	v_mfma_f32_16x16x32_bf16 v[52:55], v[150:153], v[190:193], v[52:55]
	v_mfma_f32_16x16x32_bf16 v[40:43], v[158:161], v[190:193], v[40:43]
	v_mfma_f32_16x16x32_bf16 v[36:39], v[150:153], v[198:201], v[36:39]
	v_mfma_f32_16x16x32_bf16 v[24:27], v[158:161], v[198:201], v[24:27]
	v_mfma_f32_16x16x32_bf16 v[20:23], v[150:153], v[206:209], v[20:23]
	v_mfma_f32_16x16x32_bf16 v[8:11], v[158:161], v[206:209], v[8:11]
	v_mfma_f32_16x16x32_bf16 v[48:51], v[162:165], v[178:181], v[48:51]
	v_mfma_f32_16x16x32_bf16 v[44:47], v[170:173], v[178:181], v[44:47]
	v_mfma_f32_16x16x32_bf16 v[32:35], v[162:165], v[186:189], v[32:35]
	v_mfma_f32_16x16x32_bf16 v[28:31], v[170:173], v[186:189], v[28:31]
	v_mfma_f32_16x16x32_bf16 v[16:19], v[162:165], v[194:197], v[16:19]
	v_mfma_f32_16x16x32_bf16 v[12:15], v[170:173], v[194:197], v[12:15]
	v_mfma_f32_16x16x32_bf16 v[4:7], v[162:165], v[202:205], v[4:7]
	v_mfma_f32_16x16x32_bf16 v[0:3], v[170:173], v[202:205], v[0:3]
	v_mfma_f32_16x16x32_bf16 v[48:51], v[166:169], v[182:185], v[48:51]
	v_mfma_f32_16x16x32_bf16 v[44:47], v[174:177], v[182:185], v[44:47]
	v_mfma_f32_16x16x32_bf16 v[32:35], v[166:169], v[190:193], v[32:35]
	v_mfma_f32_16x16x32_bf16 v[28:31], v[174:177], v[190:193], v[28:31]
	v_mfma_f32_16x16x32_bf16 v[16:19], v[166:169], v[198:201], v[16:19]
	v_mfma_f32_16x16x32_bf16 v[12:15], v[174:177], v[198:201], v[12:15]
	v_mfma_f32_16x16x32_bf16 v[4:7], v[166:169], v[206:209], v[4:7]
	v_mfma_f32_16x16x32_bf16 v[0:3], v[174:177], v[206:209], v[0:3]
	s_setprio 0
	s_barrier
	s_add_i32 s52, 0, 0x18000
	s_add_i32 s53, 0, 0x1c000
	v_add_u32_e32 v158, s52, v145
	v_add_u32_e32 v174, s53, v145
	ds_read_b128 v[140:143], v158
	ds_read_b128 v[150:153], v158 offset:1024
	ds_read_b128 v[154:157], v158 offset:2048
	ds_read_b128 v[158:161], v158 offset:3072
	ds_read_b128 v[162:165], v174
	ds_read_b128 v[166:169], v174 offset:1024
	ds_read_b128 v[170:173], v174 offset:2048
	ds_read_b128 v[174:177], v174 offset:3072
	s_add_u32 s42, s42, 0x40000
	s_addc_u32 s43, s43, 0
	s_mov_b32 m0, s54
	v_lshl_add_u64 v[218:219], s[42:43], 0, v[134:135]
	ds_read_b128 v[178:181], v149 offset:32768
	ds_read_b128 v[182:185], v149 offset:33792
	ds_read_b128 v[186:189], v149 offset:34816
	ds_read_b128 v[190:193], v149 offset:35840
	ds_read_b128 v[194:197], v149 offset:36864
	ds_read_b128 v[198:201], v149 offset:37888
	ds_read_b128 v[202:205], v149 offset:38912
	ds_read_b128 v[206:209], v149 offset:39936
	global_load_lds_dwordx4 v[218:219], off
	v_lshl_add_u64 v[218:219], s[42:43], 0, v[130:131]
	s_mov_b32 m0, s55
	s_nop 0
	global_load_lds_dwordx4 v[218:219], off
	s_waitcnt vmcnt(8)
	s_waitcnt lgkmcnt(0)
	s_barrier
	s_setprio 1
	v_mfma_f32_16x16x32_bf16 v[124:127], v[140:143], v[178:181], v[124:127]
	v_mfma_f32_16x16x32_bf16 v[120:123], v[154:157], v[178:181], v[120:123]
	v_mfma_f32_16x16x32_bf16 v[116:119], v[140:143], v[186:189], v[116:119]
	v_mfma_f32_16x16x32_bf16 v[104:107], v[154:157], v[186:189], v[104:107]
	v_mfma_f32_16x16x32_bf16 v[100:103], v[140:143], v[194:197], v[100:103]
	v_mfma_f32_16x16x32_bf16 v[88:91], v[154:157], v[194:197], v[88:91]
	v_mfma_f32_16x16x32_bf16 v[84:87], v[140:143], v[202:205], v[84:87]
	v_mfma_f32_16x16x32_bf16 v[72:75], v[154:157], v[202:205], v[72:75]
	v_mfma_f32_16x16x32_bf16 v[124:127], v[150:153], v[182:185], v[124:127]
	v_mfma_f32_16x16x32_bf16 v[120:123], v[158:161], v[182:185], v[120:123]
	v_mfma_f32_16x16x32_bf16 v[116:119], v[150:153], v[190:193], v[116:119]
	v_mfma_f32_16x16x32_bf16 v[104:107], v[158:161], v[190:193], v[104:107]
	v_mfma_f32_16x16x32_bf16 v[100:103], v[150:153], v[198:201], v[100:103]
	v_mfma_f32_16x16x32_bf16 v[88:91], v[158:161], v[198:201], v[88:91]
	v_mfma_f32_16x16x32_bf16 v[84:87], v[150:153], v[206:209], v[84:87]
	v_mfma_f32_16x16x32_bf16 v[72:75], v[158:161], v[206:209], v[72:75]
	v_mfma_f32_16x16x32_bf16 v[112:115], v[162:165], v[178:181], v[112:115]
	v_mfma_f32_16x16x32_bf16 v[108:111], v[170:173], v[178:181], v[108:111]
	v_mfma_f32_16x16x32_bf16 v[96:99], v[162:165], v[186:189], v[96:99]
	v_mfma_f32_16x16x32_bf16 v[92:95], v[170:173], v[186:189], v[92:95]
	v_mfma_f32_16x16x32_bf16 v[80:83], v[162:165], v[194:197], v[80:83]
	v_mfma_f32_16x16x32_bf16 v[76:79], v[170:173], v[194:197], v[76:79]
	v_mfma_f32_16x16x32_bf16 v[68:71], v[162:165], v[202:205], v[68:71]
	v_mfma_f32_16x16x32_bf16 v[64:67], v[170:173], v[202:205], v[64:67]
	v_mfma_f32_16x16x32_bf16 v[112:115], v[166:169], v[182:185], v[112:115]
	v_mfma_f32_16x16x32_bf16 v[108:111], v[174:177], v[182:185], v[108:111]
	v_mfma_f32_16x16x32_bf16 v[96:99], v[166:169], v[190:193], v[96:99]
	v_mfma_f32_16x16x32_bf16 v[92:95], v[174:177], v[190:193], v[92:95]
	v_mfma_f32_16x16x32_bf16 v[80:83], v[166:169], v[198:201], v[80:83]
	v_mfma_f32_16x16x32_bf16 v[76:79], v[174:177], v[198:201], v[76:79]
	v_mfma_f32_16x16x32_bf16 v[68:71], v[166:169], v[206:209], v[68:71]
	v_mfma_f32_16x16x32_bf16 v[64:67], v[174:177], v[206:209], v[64:67]
	s_setprio 0
	s_barrier
; #define PG8_STAGE(bufoff, gbase, voff) do { _Pragma("unroll") for (int _i = 0; _i < 2; ++_i) \
;         __builtin_amdgcn_global_load_lds((const unsigned*)((const char*)(gbase) + (voff)[_i]), (PG8_LAS unsigned*)(lds + (bufoff) + ldsw + _i * 8192), 16, 0, 0); } while (0)
; #define PG8_LDA(dst, b, h) do { _Pragma("unroll") for (int m = 0; m < 4; ++m) _Pragma("unroll") for (int k = 0; k < 2; ++k) dst[m][k] = *(const PG8_LAS bf16x8*)(lds + PG8_SA(b, h) + aoff + m * 2048 + k * 1024); } while (0)
; #define PG8_MMA(ai, bj, At, Bt) do { __builtin_amdgcn_s_setprio(1); _Pragma("unroll") for (int m = 0; m < 4; ++m) _Pragma("unroll") for (int n = 0; n < 2; ++n) _Pragma("unroll") for (int k = 0; k < 2; ++k) \
;         acc[ai][bj][m][n] = __builtin_amdgcn_mfma_f32_16x16x32_bf16(Bt[n][k], At[m][k], acc[ai][bj][m][n], 0, 0, 0); __builtin_amdgcn_s_setprio(0); } while (0)
; #define PG8_WAIT_V(n) asm volatile("s_waitcnt vmcnt(" #n ")" ::: "memory")
; #define PG8_WAIT_L(n) asm volatile("s_waitcnt lgkmcnt(" #n ")" ::: "memory")
; #define PG8_BAR __builtin_amdgcn_s_barrier()
; #define PG8_SCHED __builtin_amdgcn_sched_barrier(0)
; template <class Epi, class Sched, bool ALIGN_EPI = true, bool SP2 = true>
; __device__ __forceinline__ void gemm_phase(PG8_LAS unsigned char* lds, const Gemm g, const Sched& S, const Epi& E) {
;     ...
;             PG8_LDA(At, 1, 1); PG8_STAGE(PG8_SB(1, 0), b3, voffB); PG8_STAGE(PG8_SB(1, 1), b3 + hstepB, voffB); PG8_STAGE(PG8_SA(1, 0), a3, voffA);
;             PG8_WAIT_V(8); PG8_WAIT_L(0); PG8_BAR; PG8_MMA(1, 0, At, B0); PG8_MMA(1, 1, At, B1); PG8_BAR; PG8_SCHED;
;         }
;         if constexpr (ALIGN_EPI) { if (wr == 0) PG8_BAR; }
	s_add_i32 s42, s52, s49
	v_lshl_add_u64 v[210:211], v[210:211], 0, s[8:9]
	s_mov_b32 m0, s42
	ds_read_b128 v[178:181], v149 offset:49152
	ds_read_b128 v[182:185], v149 offset:50176
	ds_read_b128 v[186:189], v149 offset:51200
	ds_read_b128 v[190:193], v149 offset:52224
	ds_read_b128 v[194:197], v149 offset:53248
	ds_read_b128 v[198:201], v149 offset:54272
	ds_read_b128 v[202:205], v149 offset:55296
	ds_read_b128 v[206:209], v149 offset:56320
	global_load_lds_dwordx4 v[210:211], off
	s_add_i32 m0, s42, 0x2000
	s_add_u32 s40, s40, 0x40080
	v_lshl_add_u64 v[210:211], v[212:213], 0, s[8:9]
	s_addc_u32 s41, s41, 0
	s_add_i32 s42, s53, s49
	global_load_lds_dwordx4 v[210:211], off
	v_lshl_add_u64 v[210:211], s[40:41], 0, v[132:133]
	s_mov_b32 m0, s42
	s_nop 0
	global_load_lds_dwordx4 v[210:211], off
	v_lshl_add_u64 v[210:211], s[40:41], 0, v[128:129]
	s_add_i32 m0, s42, 0x2000
	s_nop 0
	global_load_lds_dwordx4 v[210:211], off
	v_lshl_add_u64 v[210:211], v[214:215], 0, s[8:9]
	s_mov_b32 m0, s56
	s_nop 0
	global_load_lds_dwordx4 v[210:211], off
	v_lshl_add_u64 v[210:211], v[216:217], 0, s[8:9]
	s_mov_b32 m0, s57
	s_nop 0
	global_load_lds_dwordx4 v[210:211], off
	s_waitcnt vmcnt(8)
	s_waitcnt lgkmcnt(0)
	s_barrier
	s_setprio 1
	v_mfma_f32_16x16x32_bf16 v[60:63], v[140:143], v[178:181], v[60:63]
	v_mfma_f32_16x16x32_bf16 v[56:59], v[154:157], v[178:181], v[56:59]
	v_mfma_f32_16x16x32_bf16 v[52:55], v[140:143], v[186:189], v[52:55]
	v_mfma_f32_16x16x32_bf16 v[40:43], v[154:157], v[186:189], v[40:43]
	v_mfma_f32_16x16x32_bf16 v[36:39], v[140:143], v[194:197], v[36:39]
	v_mfma_f32_16x16x32_bf16 v[24:27], v[154:157], v[194:197], v[24:27]
	v_mfma_f32_16x16x32_bf16 v[20:23], v[140:143], v[202:205], v[20:23]
	v_mfma_f32_16x16x32_bf16 v[8:11], v[154:157], v[202:205], v[8:11]
	v_mfma_f32_16x16x32_bf16 v[60:63], v[150:153], v[182:185], v[60:63]
	v_mfma_f32_16x16x32_bf16 v[56:59], v[158:161], v[182:185], v[56:59]
	v_mfma_f32_16x16x32_bf16 v[52:55], v[150:153], v[190:193], v[52:55]
	v_mfma_f32_16x16x32_bf16 v[40:43], v[158:161], v[190:193], v[40:43]
	v_mfma_f32_16x16x32_bf16 v[36:39], v[150:153], v[198:201], v[36:39]
	v_mfma_f32_16x16x32_bf16 v[24:27], v[158:161], v[198:201], v[24:27]
	v_mfma_f32_16x16x32_bf16 v[20:23], v[150:153], v[206:209], v[20:23]
	v_mfma_f32_16x16x32_bf16 v[8:11], v[158:161], v[206:209], v[8:11]
	v_mfma_f32_16x16x32_bf16 v[48:51], v[162:165], v[178:181], v[48:51]
	v_mfma_f32_16x16x32_bf16 v[44:47], v[170:173], v[178:181], v[44:47]
	v_mfma_f32_16x16x32_bf16 v[32:35], v[162:165], v[186:189], v[32:35]
	v_mfma_f32_16x16x32_bf16 v[28:31], v[170:173], v[186:189], v[28:31]
	v_mfma_f32_16x16x32_bf16 v[16:19], v[162:165], v[194:197], v[16:19]
	v_mfma_f32_16x16x32_bf16 v[12:15], v[170:173], v[194:197], v[12:15]
	v_mfma_f32_16x16x32_bf16 v[4:7], v[162:165], v[202:205], v[4:7]
	v_mfma_f32_16x16x32_bf16 v[0:3], v[170:173], v[202:205], v[0:3]
	v_mfma_f32_16x16x32_bf16 v[48:51], v[166:169], v[182:185], v[48:51]
	v_mfma_f32_16x16x32_bf16 v[44:47], v[174:177], v[182:185], v[44:47]
	v_mfma_f32_16x16x32_bf16 v[32:35], v[166:169], v[190:193], v[32:35]
	v_mfma_f32_16x16x32_bf16 v[28:31], v[174:177], v[190:193], v[28:31]
	v_mfma_f32_16x16x32_bf16 v[16:19], v[166:169], v[198:201], v[16:19]
	v_mfma_f32_16x16x32_bf16 v[12:15], v[174:177], v[198:201], v[12:15]
	v_mfma_f32_16x16x32_bf16 v[4:7], v[166:169], v[206:209], v[4:7]
	v_mfma_f32_16x16x32_bf16 v[0:3], v[174:177], v[206:209], v[0:3]
	s_setprio 0
	s_barrier
	s_add_i32 s72, s72, 2
	s_add_u32 s66, s66, 0x100
	s_addc_u32 s71, s71, 0
	s_add_u32 s36, s36, 0x100
	s_addc_u32 s37, s37, 0
	s_cmp_gt_u32 s72, 13
	s_cbranch_scc0 .LBB0_1054
	s_and_b64 vcc, exec, s[10:11]
	s_cbranch_vccz .LBB0_1057
	s_barrier

; #define PG8_STAGE(bufoff, gbase, voff) do { _Pragma("unroll") for (int _i = 0; _i < 2; ++_i) \
;         __builtin_amdgcn_global_load_lds((const unsigned*)((const char*)(gbase) + (voff)[_i]), (PG8_LAS unsigned*)(lds + (bufoff) + ldsw + _i * 8192), 16, 0, 0); } while (0)
; #define PG8_LDA(dst, b, h) do { _Pragma("unroll") for (int m = 0; m < 4; ++m) _Pragma("unroll") for (int k = 0; k < 2; ++k) dst[m][k] = *(const PG8_LAS bf16x8*)(lds + PG8_SA(b, h) + aoff + m * 2048 + k * 1024); } while (0)
; #define PG8_LDB(dst, b, h) do { _Pragma("unroll") for (int n = 0; n < 2; ++n) _Pragma("unroll") for (int k = 0; k < 2; ++k) dst[n][k] = *(const PG8_LAS bf16x8*)(lds + PG8_SB(b, h) + boff + n * 2048 + k * 1024); } while (0)
; #define PG8_MMA(ai, bj, At, Bt) do { __builtin_amdgcn_s_setprio(1); _Pragma("unroll") for (int m = 0; m < 4; ++m) _Pragma("unroll") for (int n = 0; n < 2; ++n) _Pragma("unroll") for (int k = 0; k < 2; ++k) \
;         acc[ai][bj][m][n] = __builtin_amdgcn_mfma_f32_16x16x32_bf16(Bt[n][k], At[m][k], acc[ai][bj][m][n], 0, 0, 0); __builtin_amdgcn_s_setprio(0); } while (0)
; #define PG8_WAIT_V(n) asm volatile("s_waitcnt vmcnt(" #n ")" ::: "memory")
; #define PG8_WAIT_L(n) asm volatile("s_waitcnt lgkmcnt(" #n ")" ::: "memory")
; #define PG8_BAR __builtin_amdgcn_s_barrier()
; #define PG8_SCHED __builtin_amdgcn_sched_barrier(0)
; template <class Epi, class Sched, bool ALIGN_EPI = true, bool SP2 = true>
; __device__ __forceinline__ void gemm_phase(PG8_LAS unsigned char* lds, const Gemm g, const Sched& S, const Epi& E) {
;     ...
;             PG8_LDB(B0, 0, 0); PG8_LDB(B1, 0, 1); PG8_SCHED; PG8_LDA(At, 0, 0); PG8_STAGE(PG8_SA(1, 1), a1 + hstepA, voffA);
;             PG8_WAIT_V(8); PG8_WAIT_L(0); PG8_BAR; PG8_MMA(0, 0, At, B0); PG8_MMA(0, 1, At, B1); PG8_BAR; PG8_SCHED;
;             PG8_LDA(At, 0, 1); PG8_STAGE(PG8_SB(0, 0), b2, voffB); PG8_STAGE(PG8_SB(0, 1), b2 + hstepB, voffB); PG8_STAGE(PG8_SA(0, 0), a2, voffA);
;             PG8_WAIT_V(8); PG8_WAIT_L(0); PG8_BAR; PG8_MMA(1, 0, At, B0); PG8_MMA(1, 1, At, B1); PG8_BAR; PG8_SCHED;
.LBB0_1130:
	ds_read_b128 v[150:153], v147
	ds_read_b128 v[154:157], v147 offset:1024
	ds_read_b128 v[158:161], v147 offset:2048
	ds_read_b128 v[162:165], v147 offset:3072
	ds_read_b128 v[166:169], v148
	ds_read_b128 v[170:173], v148 offset:1024
	ds_read_b128 v[174:177], v148 offset:2048
	ds_read_b128 v[178:181], v148 offset:3072
	s_add_u32 s36, s34, 0xfffc0080
	s_addc_u32 s37, s35, -1
	s_cmp_eq_u32 s73, 12
	s_cselect_b32 s41, s27, s37
	s_cselect_b32 s40, s65, s36
	s_cselect_b32 s37, s25, s72
	s_cselect_b32 s36, s66, s71
	v_lshl_add_u64 v[214:215], s[34:35], 0, v[138:139]
	s_add_i32 m0, s23, 0xc000
	ds_read_b128 v[182:185], v149
	ds_read_b128 v[186:189], v149 offset:1024
	ds_read_b128 v[190:193], v149 offset:2048
	ds_read_b128 v[194:197], v149 offset:3072
	ds_read_b128 v[198:201], v149 offset:4096
	ds_read_b128 v[202:205], v149 offset:5120
	ds_read_b128 v[206:209], v149 offset:6144
	ds_read_b128 v[210:213], v149 offset:7168
	global_load_lds_dwordx4 v[214:215], off
	v_lshl_add_u64 v[214:215], s[34:35], 0, v[136:137]
	s_add_i32 m0, s23, 0xe000
	s_nop 0
	global_load_lds_dwordx4 v[214:215], off
	s_waitcnt vmcnt(8)
	s_waitcnt lgkmcnt(0)
	s_barrier
	s_setprio 1
	v_mfma_f32_16x16x32_bf16 v[124:127], v[150:153], v[182:185], v[124:127]
	v_mfma_f32_16x16x32_bf16 v[120:123], v[158:161], v[182:185], v[120:123]
	v_mfma_f32_16x16x32_bf16 v[116:119], v[150:153], v[190:193], v[116:119]
	v_mfma_f32_16x16x32_bf16 v[112:115], v[158:161], v[190:193], v[112:115]
	v_mfma_f32_16x16x32_bf16 v[100:103], v[150:153], v[198:201], v[100:103]
	v_mfma_f32_16x16x32_bf16 v[96:99], v[158:161], v[198:201], v[96:99]
	v_mfma_f32_16x16x32_bf16 v[84:87], v[150:153], v[206:209], v[84:87]
	v_mfma_f32_16x16x32_bf16 v[80:83], v[158:161], v[206:209], v[80:83]
	v_mfma_f32_16x16x32_bf16 v[124:127], v[154:157], v[186:189], v[124:127]
	v_mfma_f32_16x16x32_bf16 v[120:123], v[162:165], v[186:189], v[120:123]
	v_mfma_f32_16x16x32_bf16 v[116:119], v[154:157], v[194:197], v[116:119]
	v_mfma_f32_16x16x32_bf16 v[112:115], v[162:165], v[194:197], v[112:115]
	v_mfma_f32_16x16x32_bf16 v[100:103], v[154:157], v[202:205], v[100:103]
	v_mfma_f32_16x16x32_bf16 v[96:99], v[162:165], v[202:205], v[96:99]
	v_mfma_f32_16x16x32_bf16 v[84:87], v[154:157], v[210:213], v[84:87]
	v_mfma_f32_16x16x32_bf16 v[80:83], v[162:165], v[210:213], v[80:83]
	v_mfma_f32_16x16x32_bf16 v[108:111], v[166:169], v[182:185], v[108:111]
	v_mfma_f32_16x16x32_bf16 v[104:107], v[174:177], v[182:185], v[104:107]
	v_mfma_f32_16x16x32_bf16 v[92:95], v[166:169], v[190:193], v[92:95]
	v_mfma_f32_16x16x32_bf16 v[88:91], v[174:177], v[190:193], v[88:91]
	v_mfma_f32_16x16x32_bf16 v[76:79], v[166:169], v[198:201], v[76:79]
	v_mfma_f32_16x16x32_bf16 v[72:75], v[174:177], v[198:201], v[72:75]
	v_mfma_f32_16x16x32_bf16 v[68:71], v[166:169], v[206:209], v[68:71]
	v_mfma_f32_16x16x32_bf16 v[64:67], v[174:177], v[206:209], v[64:67]
	v_mfma_f32_16x16x32_bf16 v[108:111], v[170:173], v[186:189], v[108:111]
	v_mfma_f32_16x16x32_bf16 v[104:107], v[178:181], v[186:189], v[104:107]
	v_mfma_f32_16x16x32_bf16 v[92:95], v[170:173], v[194:197], v[92:95]
	v_mfma_f32_16x16x32_bf16 v[88:91], v[178:181], v[194:197], v[88:91]
	v_mfma_f32_16x16x32_bf16 v[76:79], v[170:173], v[202:205], v[76:79]
	v_mfma_f32_16x16x32_bf16 v[72:75], v[178:181], v[202:205], v[72:75]
	v_mfma_f32_16x16x32_bf16 v[68:71], v[170:173], v[210:213], v[68:71]
	v_mfma_f32_16x16x32_bf16 v[64:67], v[178:181], v[210:213], v[64:67]
	s_setprio 0
	s_barrier
	s_add_i32 s52, s58, s47
	v_lshl_add_u64 v[214:215], s[36:37], 0, v[130:131]
	s_mov_b32 m0, s52
	ds_read_b128 v[182:185], v149 offset:16384
	ds_read_b128 v[186:189], v149 offset:17408
	ds_read_b128 v[190:193], v149 offset:18432
	ds_read_b128 v[194:197], v149 offset:19456
	ds_read_b128 v[198:201], v149 offset:20480
	ds_read_b128 v[202:205], v149 offset:21504
	ds_read_b128 v[206:209], v149 offset:22528
	ds_read_b128 v[210:213], v149 offset:23552
	global_load_lds_dwordx4 v[214:215], off
	s_add_i32 m0, s52, 0x2000
	s_add_u32 s52, s36, 0x40000
	v_lshl_add_u64 v[216:217], s[36:37], 0, v[134:135]
	s_addc_u32 s53, s37, 0
	s_add_i32 s68, s59, s47
	global_load_lds_dwordx4 v[216:217], off
	v_lshl_add_u64 v[218:219], s[52:53], 0, v[130:131]
	s_mov_b32 m0, s68
	v_lshl_add_u64 v[220:221], s[40:41], 0, v[132:133]
	global_load_lds_dwordx4 v[218:219], off
	v_lshl_add_u64 v[218:219], s[52:53], 0, v[134:135]
	s_add_i32 m0, s68, 0x2000
	s_nop 0
	global_load_lds_dwordx4 v[218:219], off
	v_lshl_add_u64 v[218:219], s[40:41], 0, v[128:129]
	s_mov_b32 m0, s23
	s_nop 0
	global_load_lds_dwordx4 v[218:219], off
	s_mov_b32 m0, s48
	s_nop 0
	global_load_lds_dwordx4 v[220:221], off
	s_waitcnt vmcnt(8)
	s_waitcnt lgkmcnt(0)
	s_barrier
; #define PG8_STAGE(bufoff, gbase, voff) do { _Pragma("unroll") for (int _i = 0; _i < 2; ++_i) \
;         __builtin_amdgcn_global_load_lds((const unsigned*)((const char*)(gbase) + (voff)[_i]), (PG8_LAS unsigned*)(lds + (bufoff) + ldsw + _i * 8192), 16, 0, 0); } while (0)
; #define PG8_LDA(dst, b, h) do { _Pragma("unroll") for (int m = 0; m < 4; ++m) _Pragma("unroll") for (int k = 0; k < 2; ++k) dst[m][k] = *(const PG8_LAS bf16x8*)(lds + PG8_SA(b, h) + aoff + m * 2048 + k * 1024); } while (0)
; #define PG8_LDB(dst, b, h) do { _Pragma("unroll") for (int n = 0; n < 2; ++n) _Pragma("unroll") for (int k = 0; k < 2; ++k) dst[n][k] = *(const PG8_LAS bf16x8*)(lds + PG8_SB(b, h) + boff + n * 2048 + k * 1024); } while (0)
; #define PG8_MMA(ai, bj, At, Bt) do { __builtin_amdgcn_s_setprio(1); _Pragma("unroll") for (int m = 0; m < 4; ++m) _Pragma("unroll") for (int n = 0; n < 2; ++n) _Pragma("unroll") for (int k = 0; k < 2; ++k) \
;         acc[ai][bj][m][n] = __builtin_amdgcn_mfma_f32_16x16x32_bf16(Bt[n][k], At[m][k], acc[ai][bj][m][n], 0, 0, 0); __builtin_amdgcn_s_setprio(0); } while (0)
; #define PG8_WAIT_V(n) asm volatile("s_waitcnt vmcnt(" #n ")" ::: "memory")
; #define PG8_WAIT_L(n) asm volatile("s_waitcnt lgkmcnt(" #n ")" ::: "memory")
; #define PG8_BAR __builtin_amdgcn_s_barrier()
; #define PG8_SCHED __builtin_amdgcn_sched_barrier(0)
; template <class Epi, class Sched, bool ALIGN_EPI = true, bool SP2 = true>
; __device__ __forceinline__ void gemm_phase(PG8_LAS unsigned char* lds, const Gemm g, const Sched& S, const Epi& E) {
;     ...
;             PG8_WAIT_V(8); PG8_WAIT_L(0); PG8_BAR; PG8_MMA(1, 0, At, B0); PG8_MMA(1, 1, At, B1); PG8_BAR; PG8_SCHED;
;             PG8_LDB(B0, 1, 0); PG8_LDB(B1, 1, 1); PG8_SCHED; PG8_LDA(At, 1, 0); PG8_STAGE(PG8_SA(0, 1), a2 + hstepA, voffA);
;             PG8_WAIT_V(8); PG8_WAIT_L(0); PG8_BAR; PG8_MMA(0, 0, At, B0); PG8_MMA(0, 1, At, B1); PG8_BAR; PG8_SCHED;
	s_setprio 1
	v_mfma_f32_16x16x32_bf16 v[60:63], v[150:153], v[182:185], v[60:63]
	v_mfma_f32_16x16x32_bf16 v[56:59], v[158:161], v[182:185], v[56:59]
	v_mfma_f32_16x16x32_bf16 v[52:55], v[150:153], v[190:193], v[52:55]
	v_mfma_f32_16x16x32_bf16 v[48:51], v[158:161], v[190:193], v[48:51]
	v_mfma_f32_16x16x32_bf16 v[36:39], v[150:153], v[198:201], v[36:39]
	v_mfma_f32_16x16x32_bf16 v[32:35], v[158:161], v[198:201], v[32:35]
	v_mfma_f32_16x16x32_bf16 v[20:23], v[150:153], v[206:209], v[20:23]
	v_mfma_f32_16x16x32_bf16 v[16:19], v[158:161], v[206:209], v[16:19]
	v_mfma_f32_16x16x32_bf16 v[60:63], v[154:157], v[186:189], v[60:63]
	v_mfma_f32_16x16x32_bf16 v[56:59], v[162:165], v[186:189], v[56:59]
	v_mfma_f32_16x16x32_bf16 v[52:55], v[154:157], v[194:197], v[52:55]
	v_mfma_f32_16x16x32_bf16 v[48:51], v[162:165], v[194:197], v[48:51]
	v_mfma_f32_16x16x32_bf16 v[36:39], v[154:157], v[202:205], v[36:39]
	v_mfma_f32_16x16x32_bf16 v[32:35], v[162:165], v[202:205], v[32:35]
	v_mfma_f32_16x16x32_bf16 v[20:23], v[154:157], v[210:213], v[20:23]
	v_mfma_f32_16x16x32_bf16 v[16:19], v[162:165], v[210:213], v[16:19]
	v_mfma_f32_16x16x32_bf16 v[44:47], v[166:169], v[182:185], v[44:47]
	v_mfma_f32_16x16x32_bf16 v[40:43], v[174:177], v[182:185], v[40:43]
	v_mfma_f32_16x16x32_bf16 v[28:31], v[166:169], v[190:193], v[28:31]
	v_mfma_f32_16x16x32_bf16 v[24:27], v[174:177], v[190:193], v[24:27]
	v_mfma_f32_16x16x32_bf16 v[12:15], v[166:169], v[198:201], v[12:15]
	v_mfma_f32_16x16x32_bf16 v[8:11], v[174:177], v[198:201], v[8:11]
	v_mfma_f32_16x16x32_bf16 v[4:7], v[166:169], v[206:209], v[4:7]
	v_mfma_f32_16x16x32_bf16 v[0:3], v[174:177], v[206:209], v[0:3]
	v_mfma_f32_16x16x32_bf16 v[44:47], v[170:173], v[186:189], v[44:47]
	v_mfma_f32_16x16x32_bf16 v[40:43], v[178:181], v[186:189], v[40:43]
	v_mfma_f32_16x16x32_bf16 v[28:31], v[170:173], v[194:197], v[28:31]
	v_mfma_f32_16x16x32_bf16 v[24:27], v[178:181], v[194:197], v[24:27]
	v_mfma_f32_16x16x32_bf16 v[12:15], v[170:173], v[202:205], v[12:15]
	v_mfma_f32_16x16x32_bf16 v[8:11], v[178:181], v[202:205], v[8:11]
	v_mfma_f32_16x16x32_bf16 v[4:7], v[170:173], v[210:213], v[4:7]
	v_mfma_f32_16x16x32_bf16 v[0:3], v[178:181], v[210:213], v[0:3]
	s_setprio 0
	s_barrier
	s_add_i32 s52, 0, 0x18000
	s_add_i32 s53, 0, 0x1c000
	v_add_u32_e32 v162, s52, v145
	v_add_u32_e32 v178, s53, v145
	ds_read_b128 v[150:153], v162
	ds_read_b128 v[154:157], v162 offset:1024
	ds_read_b128 v[158:161], v162 offset:2048
	ds_read_b128 v[162:165], v162 offset:3072
	ds_read_b128 v[166:169], v178
	ds_read_b128 v[170:173], v178 offset:1024
	ds_read_b128 v[174:177], v178 offset:2048
	ds_read_b128 v[178:181], v178 offset:3072
	s_add_u32 s40, s40, 0x40000
	s_addc_u32 s41, s41, 0
	s_mov_b32 m0, s49
	v_lshl_add_u64 v[222:223], s[40:41], 0, v[128:129]
	ds_read_b128 v[182:185], v149 offset:32768
	ds_read_b128 v[186:189], v149 offset:33792
	ds_read_b128 v[190:193], v149 offset:34816
	ds_read_b128 v[194:197], v149 offset:35840
	ds_read_b128 v[198:201], v149 offset:36864
	ds_read_b128 v[202:205], v149 offset:37888
	ds_read_b128 v[206:209], v149 offset:38912
	ds_read_b128 v[210:213], v149 offset:39936
	global_load_lds_dwordx4 v[222:223], off
	v_lshl_add_u64 v[222:223], s[40:41], 0, v[132:133]
	s_mov_b32 m0, s50
	s_nop 0
	global_load_lds_dwordx4 v[222:223], off
	s_waitcnt vmcnt(8)
	s_waitcnt lgkmcnt(0)
	s_barrier
	s_setprio 1
	v_mfma_f32_16x16x32_bf16 v[124:127], v[150:153], v[182:185], v[124:127]
	v_mfma_f32_16x16x32_bf16 v[120:123], v[158:161], v[182:185], v[120:123]
	v_mfma_f32_16x16x32_bf16 v[116:119], v[150:153], v[190:193], v[116:119]
	v_mfma_f32_16x16x32_bf16 v[112:115], v[158:161], v[190:193], v[112:115]
	v_mfma_f32_16x16x32_bf16 v[100:103], v[150:153], v[198:201], v[100:103]
	v_mfma_f32_16x16x32_bf16 v[96:99], v[158:161], v[198:201], v[96:99]
	v_mfma_f32_16x16x32_bf16 v[84:87], v[150:153], v[206:209], v[84:87]
	v_mfma_f32_16x16x32_bf16 v[80:83], v[158:161], v[206:209], v[80:83]
	v_mfma_f32_16x16x32_bf16 v[124:127], v[154:157], v[186:189], v[124:127]
	v_mfma_f32_16x16x32_bf16 v[120:123], v[162:165], v[186:189], v[120:123]
	v_mfma_f32_16x16x32_bf16 v[116:119], v[154:157], v[194:197], v[116:119]
	v_mfma_f32_16x16x32_bf16 v[112:115], v[162:165], v[194:197], v[112:115]
	v_mfma_f32_16x16x32_bf16 v[100:103], v[154:157], v[202:205], v[100:103]
	v_mfma_f32_16x16x32_bf16 v[96:99], v[162:165], v[202:205], v[96:99]
	v_mfma_f32_16x16x32_bf16 v[84:87], v[154:157], v[210:213], v[84:87]
	v_mfma_f32_16x16x32_bf16 v[80:83], v[162:165], v[210:213], v[80:83]
	v_mfma_f32_16x16x32_bf16 v[108:111], v[166:169], v[182:185], v[108:111]
	v_mfma_f32_16x16x32_bf16 v[104:107], v[174:177], v[182:185], v[104:107]
	v_mfma_f32_16x16x32_bf16 v[92:95], v[166:169], v[190:193], v[92:95]
	v_mfma_f32_16x16x32_bf16 v[88:91], v[174:177], v[190:193], v[88:91]
	v_mfma_f32_16x16x32_bf16 v[76:79], v[166:169], v[198:201], v[76:79]
	v_mfma_f32_16x16x32_bf16 v[72:75], v[174:177], v[198:201], v[72:75]
	v_mfma_f32_16x16x32_bf16 v[68:71], v[166:169], v[206:209], v[68:71]
	v_mfma_f32_16x16x32_bf16 v[64:67], v[174:177], v[206:209], v[64:67]
	v_mfma_f32_16x16x32_bf16 v[108:111], v[170:173], v[186:189], v[108:111]
	v_mfma_f32_16x16x32_bf16 v[104:107], v[178:181], v[186:189], v[104:107]
	v_mfma_f32_16x16x32_bf16 v[92:95], v[170:173], v[194:197], v[92:95]
	v_mfma_f32_16x16x32_bf16 v[88:91], v[178:181], v[194:197], v[88:91]
	v_mfma_f32_16x16x32_bf16 v[76:79], v[170:173], v[202:205], v[76:79]
	v_mfma_f32_16x16x32_bf16 v[72:75], v[178:181], v[202:205], v[72:75]
	v_mfma_f32_16x16x32_bf16 v[68:71], v[170:173], v[210:213], v[68:71]
	v_mfma_f32_16x16x32_bf16 v[64:67], v[178:181], v[210:213], v[64:67]
	s_setprio 0
	s_barrier
; #define PG8_STAGE(bufoff, gbase, voff) do { _Pragma("unroll") for (int _i = 0; _i < 2; ++_i) \
;         __builtin_amdgcn_global_load_lds((const unsigned*)((const char*)(gbase) + (voff)[_i]), (PG8_LAS unsigned*)(lds + (bufoff) + ldsw + _i * 8192), 16, 0, 0); } while (0)
; #define PG8_LDA(dst, b, h) do { _Pragma("unroll") for (int m = 0; m < 4; ++m) _Pragma("unroll") for (int k = 0; k < 2; ++k) dst[m][k] = *(const PG8_LAS bf16x8*)(lds + PG8_SA(b, h) + aoff + m * 2048 + k * 1024); } while (0)
; #define PG8_MMA(ai, bj, At, Bt) do { __builtin_amdgcn_s_setprio(1); _Pragma("unroll") for (int m = 0; m < 4; ++m) _Pragma("unroll") for (int n = 0; n < 2; ++n) _Pragma("unroll") for (int k = 0; k < 2; ++k) \
;         acc[ai][bj][m][n] = __builtin_amdgcn_mfma_f32_16x16x32_bf16(Bt[n][k], At[m][k], acc[ai][bj][m][n], 0, 0, 0); __builtin_amdgcn_s_setprio(0); } while (0)
; #define PG8_WAIT_V(n) asm volatile("s_waitcnt vmcnt(" #n ")" ::: "memory")
; #define PG8_WAIT_L(n) asm volatile("s_waitcnt lgkmcnt(" #n ")" ::: "memory")
; #define PG8_BAR __builtin_amdgcn_s_barrier()
; #define PG8_SCHED __builtin_amdgcn_sched_barrier(0)
; template <class Epi, class Sched, bool ALIGN_EPI = true, bool SP2 = true>
; __device__ __forceinline__ void gemm_phase(PG8_LAS unsigned char* lds, const Gemm g, const Sched& S, const Epi& E) {
;     ...
;             PG8_LDA(At, 1, 1); PG8_STAGE(PG8_SB(1, 0), b3, voffB); PG8_STAGE(PG8_SB(1, 1), b3 + hstepB, voffB); PG8_STAGE(PG8_SA(1, 0), a3, voffA);
;             PG8_WAIT_V(8); PG8_WAIT_L(0); PG8_BAR; PG8_MMA(1, 0, At, B0); PG8_MMA(1, 1, At, B1); PG8_BAR; PG8_SCHED;
;         }
	s_add_i32 s40, s52, s47
	v_lshl_add_u64 v[214:215], v[214:215], 0, s[12:13]
	s_mov_b32 m0, s40
	ds_read_b128 v[182:185], v149 offset:49152
	ds_read_b128 v[186:189], v149 offset:50176
	ds_read_b128 v[190:193], v149 offset:51200
	ds_read_b128 v[194:197], v149 offset:52224
	ds_read_b128 v[198:201], v149 offset:53248
	ds_read_b128 v[202:205], v149 offset:54272
	ds_read_b128 v[206:209], v149 offset:55296
	ds_read_b128 v[210:213], v149 offset:56320
	global_load_lds_dwordx4 v[214:215], off
	s_add_i32 m0, s40, 0x2000
	s_add_u32 s36, s36, 0x40080
	v_lshl_add_u64 v[214:215], v[216:217], 0, s[12:13]
	s_addc_u32 s37, s37, 0
	s_add_i32 s40, s53, s47
	global_load_lds_dwordx4 v[214:215], off
	v_lshl_add_u64 v[214:215], s[36:37], 0, v[130:131]
	s_mov_b32 m0, s40
	s_nop 0
	global_load_lds_dwordx4 v[214:215], off
	v_lshl_add_u64 v[214:215], s[36:37], 0, v[134:135]
	s_add_i32 m0, s40, 0x2000
	s_nop 0
	global_load_lds_dwordx4 v[214:215], off
	v_lshl_add_u64 v[214:215], v[218:219], 0, s[12:13]
	s_mov_b32 m0, s54
	s_nop 0
	global_load_lds_dwordx4 v[214:215], off
	v_lshl_add_u64 v[214:215], v[220:221], 0, s[12:13]
	s_mov_b32 m0, s55
	s_nop 0
	global_load_lds_dwordx4 v[214:215], off
	s_waitcnt vmcnt(8)
	s_waitcnt lgkmcnt(0)
	s_barrier
	s_setprio 1
	v_mfma_f32_16x16x32_bf16 v[60:63], v[150:153], v[182:185], v[60:63]
	v_mfma_f32_16x16x32_bf16 v[56:59], v[158:161], v[182:185], v[56:59]
	v_mfma_f32_16x16x32_bf16 v[52:55], v[150:153], v[190:193], v[52:55]
	v_mfma_f32_16x16x32_bf16 v[48:51], v[158:161], v[190:193], v[48:51]
	v_mfma_f32_16x16x32_bf16 v[36:39], v[150:153], v[198:201], v[36:39]
	v_mfma_f32_16x16x32_bf16 v[32:35], v[158:161], v[198:201], v[32:35]
	v_mfma_f32_16x16x32_bf16 v[20:23], v[150:153], v[206:209], v[20:23]
	v_mfma_f32_16x16x32_bf16 v[16:19], v[158:161], v[206:209], v[16:19]
	v_mfma_f32_16x16x32_bf16 v[60:63], v[154:157], v[186:189], v[60:63]
	v_mfma_f32_16x16x32_bf16 v[56:59], v[162:165], v[186:189], v[56:59]
	v_mfma_f32_16x16x32_bf16 v[52:55], v[154:157], v[194:197], v[52:55]
	v_mfma_f32_16x16x32_bf16 v[48:51], v[162:165], v[194:197], v[48:51]
	v_mfma_f32_16x16x32_bf16 v[36:39], v[154:157], v[202:205], v[36:39]
	v_mfma_f32_16x16x32_bf16 v[32:35], v[162:165], v[202:205], v[32:35]
	v_mfma_f32_16x16x32_bf16 v[20:23], v[154:157], v[210:213], v[20:23]
	v_mfma_f32_16x16x32_bf16 v[16:19], v[162:165], v[210:213], v[16:19]
	v_mfma_f32_16x16x32_bf16 v[44:47], v[166:169], v[182:185], v[44:47]
	v_mfma_f32_16x16x32_bf16 v[40:43], v[174:177], v[182:185], v[40:43]
	v_mfma_f32_16x16x32_bf16 v[28:31], v[166:169], v[190:193], v[28:31]
	v_mfma_f32_16x16x32_bf16 v[24:27], v[174:177], v[190:193], v[24:27]
	v_mfma_f32_16x16x32_bf16 v[12:15], v[166:169], v[198:201], v[12:15]
	v_mfma_f32_16x16x32_bf16 v[8:11], v[174:177], v[198:201], v[8:11]
	v_mfma_f32_16x16x32_bf16 v[4:7], v[166:169], v[206:209], v[4:7]
	v_mfma_f32_16x16x32_bf16 v[0:3], v[174:177], v[206:209], v[0:3]
	v_mfma_f32_16x16x32_bf16 v[44:47], v[170:173], v[186:189], v[44:47]
	v_mfma_f32_16x16x32_bf16 v[40:43], v[178:181], v[186:189], v[40:43]
	v_mfma_f32_16x16x32_bf16 v[28:31], v[170:173], v[194:197], v[28:31]
	v_mfma_f32_16x16x32_bf16 v[24:27], v[178:181], v[194:197], v[24:27]
	v_mfma_f32_16x16x32_bf16 v[12:15], v[170:173], v[202:205], v[12:15]
	v_mfma_f32_16x16x32_bf16 v[8:11], v[178:181], v[202:205], v[8:11]
	v_mfma_f32_16x16x32_bf16 v[4:7], v[170:173], v[210:213], v[4:7]
	v_mfma_f32_16x16x32_bf16 v[0:3], v[178:181], v[210:213], v[0:3]
	s_setprio 0
	s_barrier
	s_add_i32 s73, s73, 2
	s_add_u32 s71, s71, 0x100
	s_addc_u32 s72, s72, 0
	s_add_u32 s34, s34, 0x100
	s_addc_u32 s35, s35, 0
	s_cmp_gt_u32 s73, 13
	s_cbranch_scc0 .LBB0_1130
	s_and_b64 vcc, exec, s[14:15]
	s_cbranch_vccz .LBB0_1133
	s_barrier

; #define PG8_STAGE(bufoff, gbase, voff) do { _Pragma("unroll") for (int _i = 0; _i < 2; ++_i) \
;         __builtin_amdgcn_global_load_lds((const unsigned*)((const char*)(gbase) + (voff)[_i]), (PG8_LAS unsigned*)(lds + (bufoff) + ldsw + _i * 8192), 16, 0, 0); } while (0)
; #define PG8_LDA(dst, b, h) do { _Pragma("unroll") for (int m = 0; m < 4; ++m) _Pragma("unroll") for (int k = 0; k < 2; ++k) dst[m][k] = *(const PG8_LAS bf16x8*)(lds + PG8_SA(b, h) + aoff + m * 2048 + k * 1024); } while (0)
; #define PG8_LDB(dst, b, h) do { _Pragma("unroll") for (int n = 0; n < 2; ++n) _Pragma("unroll") for (int k = 0; k < 2; ++k) dst[n][k] = *(const PG8_LAS bf16x8*)(lds + PG8_SB(b, h) + boff + n * 2048 + k * 1024); } while (0)
; #define PG8_MMA(ai, bj, At, Bt) do { __builtin_amdgcn_s_setprio(1); _Pragma("unroll") for (int m = 0; m < 4; ++m) _Pragma("unroll") for (int n = 0; n < 2; ++n) _Pragma("unroll") for (int k = 0; k < 2; ++k) \
;         acc[ai][bj][m][n] = __builtin_amdgcn_mfma_f32_16x16x32_bf16(Bt[n][k], At[m][k], acc[ai][bj][m][n], 0, 0, 0); __builtin_amdgcn_s_setprio(0); } while (0)
; #define PG8_WAIT_V(n) asm volatile("s_waitcnt vmcnt(" #n ")" ::: "memory")
; #define PG8_WAIT_L(n) asm volatile("s_waitcnt lgkmcnt(" #n ")" ::: "memory")
; #define PG8_BAR __builtin_amdgcn_s_barrier()
; #define PG8_SCHED __builtin_amdgcn_sched_barrier(0)
; template <class Epi, class Sched, bool ALIGN_EPI = true, bool SP2 = true>
; __device__ __forceinline__ void gemm_phase(PG8_LAS unsigned char* lds, const Gemm g, const Sched& S, const Epi& E) {
;     ...
;             PG8_LDB(B0, 0, 0); PG8_LDB(B1, 0, 1); PG8_SCHED; PG8_LDA(At, 0, 0); PG8_STAGE(PG8_SA(1, 1), a1 + hstepA, voffA);
;             PG8_WAIT_V(8); PG8_WAIT_L(0); PG8_BAR; PG8_MMA(0, 0, At, B0); PG8_MMA(0, 1, At, B1); PG8_BAR; PG8_SCHED;
;             PG8_LDA(At, 0, 1); PG8_STAGE(PG8_SB(0, 0), b2, voffB); PG8_STAGE(PG8_SB(0, 1), b2 + hstepB, voffB); PG8_STAGE(PG8_SA(0, 0), a2, voffA);
;             PG8_WAIT_V(8); PG8_WAIT_L(0); PG8_BAR; PG8_MMA(1, 0, At, B0); PG8_MMA(1, 1, At, B1); PG8_BAR; PG8_SCHED;
.LBB0_1193:
	ds_read_b128 v[146:149], v143
	ds_read_b128 v[150:153], v143 offset:1024
	ds_read_b128 v[154:157], v143 offset:2048
	ds_read_b128 v[158:161], v143 offset:3072
	ds_read_b128 v[162:165], v144
	ds_read_b128 v[166:169], v144 offset:1024
	ds_read_b128 v[170:173], v144 offset:2048
	ds_read_b128 v[174:177], v144 offset:3072
	s_add_u32 s40, s38, 0xfffc0080
	s_addc_u32 s41, s39, -1
	s_cmp_eq_u32 s73, 12
	s_cselect_b32 s43, s27, s41
	s_cselect_b32 s42, s65, s40
	s_cselect_b32 s41, s25, s72
	s_cselect_b32 s40, s66, s71
	v_lshl_add_u64 v[210:211], s[38:39], 0, v[138:139]
	s_add_i32 m0, s49, 0xc000
	ds_read_b128 v[178:181], v145
	ds_read_b128 v[182:185], v145 offset:1024
	ds_read_b128 v[186:189], v145 offset:2048
	ds_read_b128 v[190:193], v145 offset:3072
	ds_read_b128 v[194:197], v145 offset:4096
	ds_read_b128 v[198:201], v145 offset:5120
	ds_read_b128 v[202:205], v145 offset:6144
	ds_read_b128 v[206:209], v145 offset:7168
	global_load_lds_dwordx4 v[210:211], off
	v_lshl_add_u64 v[210:211], s[38:39], 0, v[136:137]
	s_add_i32 m0, s49, 0xe000
	s_nop 0
	global_load_lds_dwordx4 v[210:211], off
	s_waitcnt vmcnt(8)
	s_waitcnt lgkmcnt(0)
	s_barrier
	s_setprio 1
	v_mfma_f32_16x16x32_bf16 v[124:127], v[146:149], v[178:181], v[124:127]
	v_mfma_f32_16x16x32_bf16 v[120:123], v[154:157], v[178:181], v[120:123]
	v_mfma_f32_16x16x32_bf16 v[116:119], v[146:149], v[186:189], v[116:119]
	v_mfma_f32_16x16x32_bf16 v[112:115], v[154:157], v[186:189], v[112:115]
	v_mfma_f32_16x16x32_bf16 v[100:103], v[146:149], v[194:197], v[100:103]
	v_mfma_f32_16x16x32_bf16 v[96:99], v[154:157], v[194:197], v[96:99]
	v_mfma_f32_16x16x32_bf16 v[84:87], v[146:149], v[202:205], v[84:87]
	v_mfma_f32_16x16x32_bf16 v[80:83], v[154:157], v[202:205], v[80:83]
	v_mfma_f32_16x16x32_bf16 v[124:127], v[150:153], v[182:185], v[124:127]
	v_mfma_f32_16x16x32_bf16 v[120:123], v[158:161], v[182:185], v[120:123]
	v_mfma_f32_16x16x32_bf16 v[116:119], v[150:153], v[190:193], v[116:119]
	v_mfma_f32_16x16x32_bf16 v[112:115], v[158:161], v[190:193], v[112:115]
	v_mfma_f32_16x16x32_bf16 v[100:103], v[150:153], v[198:201], v[100:103]
	v_mfma_f32_16x16x32_bf16 v[96:99], v[158:161], v[198:201], v[96:99]
	v_mfma_f32_16x16x32_bf16 v[84:87], v[150:153], v[206:209], v[84:87]
	v_mfma_f32_16x16x32_bf16 v[80:83], v[158:161], v[206:209], v[80:83]
	v_mfma_f32_16x16x32_bf16 v[108:111], v[162:165], v[178:181], v[108:111]
	v_mfma_f32_16x16x32_bf16 v[104:107], v[170:173], v[178:181], v[104:107]
	v_mfma_f32_16x16x32_bf16 v[92:95], v[162:165], v[186:189], v[92:95]
	v_mfma_f32_16x16x32_bf16 v[88:91], v[170:173], v[186:189], v[88:91]
	v_mfma_f32_16x16x32_bf16 v[76:79], v[162:165], v[194:197], v[76:79]
	v_mfma_f32_16x16x32_bf16 v[72:75], v[170:173], v[194:197], v[72:75]
	v_mfma_f32_16x16x32_bf16 v[68:71], v[162:165], v[202:205], v[68:71]
	v_mfma_f32_16x16x32_bf16 v[64:67], v[170:173], v[202:205], v[64:67]
	v_mfma_f32_16x16x32_bf16 v[108:111], v[166:169], v[182:185], v[108:111]
	v_mfma_f32_16x16x32_bf16 v[104:107], v[174:177], v[182:185], v[104:107]
	v_mfma_f32_16x16x32_bf16 v[92:95], v[166:169], v[190:193], v[92:95]
	v_mfma_f32_16x16x32_bf16 v[88:91], v[174:177], v[190:193], v[88:91]
	v_mfma_f32_16x16x32_bf16 v[76:79], v[166:169], v[198:201], v[76:79]
	v_mfma_f32_16x16x32_bf16 v[72:75], v[174:177], v[198:201], v[72:75]
	v_mfma_f32_16x16x32_bf16 v[68:71], v[166:169], v[206:209], v[68:71]
	v_mfma_f32_16x16x32_bf16 v[64:67], v[174:177], v[206:209], v[64:67]
	s_setprio 0
	s_barrier
	s_add_i32 s52, s59, s47
	v_lshl_add_u64 v[210:211], s[40:41], 0, v[132:133]
	s_mov_b32 m0, s52
	ds_read_b128 v[178:181], v145 offset:16384
	ds_read_b128 v[182:185], v145 offset:17408
	ds_read_b128 v[186:189], v145 offset:18432
	ds_read_b128 v[190:193], v145 offset:19456
	ds_read_b128 v[194:197], v145 offset:20480
	ds_read_b128 v[198:201], v145 offset:21504
	ds_read_b128 v[202:205], v145 offset:22528
	ds_read_b128 v[206:209], v145 offset:23552
	global_load_lds_dwordx4 v[210:211], off
	s_add_i32 m0, s52, 0x2000
	s_add_u32 s52, s40, 0x40000
	v_lshl_add_u64 v[212:213], s[40:41], 0, v[128:129]
	s_addc_u32 s53, s41, 0
	s_add_i32 s68, s60, s47
	global_load_lds_dwordx4 v[212:213], off
	v_lshl_add_u64 v[214:215], s[52:53], 0, v[132:133]
	s_mov_b32 m0, s68
	v_lshl_add_u64 v[216:217], s[42:43], 0, v[130:131]
	global_load_lds_dwordx4 v[214:215], off
	v_lshl_add_u64 v[214:215], s[52:53], 0, v[128:129]
	s_add_i32 m0, s68, 0x2000
	s_nop 0
	global_load_lds_dwordx4 v[214:215], off
	v_lshl_add_u64 v[214:215], s[42:43], 0, v[134:135]
	s_mov_b32 m0, s49
	s_nop 0
	global_load_lds_dwordx4 v[214:215], off
	s_mov_b32 m0, s50
	s_nop 0
	global_load_lds_dwordx4 v[216:217], off
	s_waitcnt vmcnt(8)
	s_waitcnt lgkmcnt(0)
	s_barrier
; #define PG8_STAGE(bufoff, gbase, voff) do { _Pragma("unroll") for (int _i = 0; _i < 2; ++_i) \
;         __builtin_amdgcn_global_load_lds((const unsigned*)((const char*)(gbase) + (voff)[_i]), (PG8_LAS unsigned*)(lds + (bufoff) + ldsw + _i * 8192), 16, 0, 0); } while (0)
; #define PG8_LDA(dst, b, h) do { _Pragma("unroll") for (int m = 0; m < 4; ++m) _Pragma("unroll") for (int k = 0; k < 2; ++k) dst[m][k] = *(const PG8_LAS bf16x8*)(lds + PG8_SA(b, h) + aoff + m * 2048 + k * 1024); } while (0)
; #define PG8_LDB(dst, b, h) do { _Pragma("unroll") for (int n = 0; n < 2; ++n) _Pragma("unroll") for (int k = 0; k < 2; ++k) dst[n][k] = *(const PG8_LAS bf16x8*)(lds + PG8_SB(b, h) + boff + n * 2048 + k * 1024); } while (0)
; #define PG8_MMA(ai, bj, At, Bt) do { __builtin_amdgcn_s_setprio(1); _Pragma("unroll") for (int m = 0; m < 4; ++m) _Pragma("unroll") for (int n = 0; n < 2; ++n) _Pragma("unroll") for (int k = 0; k < 2; ++k) \
;         acc[ai][bj][m][n] = __builtin_amdgcn_mfma_f32_16x16x32_bf16(Bt[n][k], At[m][k], acc[ai][bj][m][n], 0, 0, 0); __builtin_amdgcn_s_setprio(0); } while (0)
; #define PG8_WAIT_V(n) asm volatile("s_waitcnt vmcnt(" #n ")" ::: "memory")
; #define PG8_WAIT_L(n) asm volatile("s_waitcnt lgkmcnt(" #n ")" ::: "memory")
; #define PG8_BAR __builtin_amdgcn_s_barrier()
; #define PG8_SCHED __builtin_amdgcn_sched_barrier(0)
; template <class Epi, class Sched, bool ALIGN_EPI = true, bool SP2 = true>
; __device__ __forceinline__ void gemm_phase(PG8_LAS unsigned char* lds, const Gemm g, const Sched& S, const Epi& E) {
;     ...
;             PG8_WAIT_V(8); PG8_WAIT_L(0); PG8_BAR; PG8_MMA(1, 0, At, B0); PG8_MMA(1, 1, At, B1); PG8_BAR; PG8_SCHED;
;             PG8_LDB(B0, 1, 0); PG8_LDB(B1, 1, 1); PG8_SCHED; PG8_LDA(At, 1, 0); PG8_STAGE(PG8_SA(0, 1), a2 + hstepA, voffA);
;             PG8_WAIT_V(8); PG8_WAIT_L(0); PG8_BAR; PG8_MMA(0, 0, At, B0); PG8_MMA(0, 1, At, B1); PG8_BAR; PG8_SCHED;
	s_setprio 1
	v_mfma_f32_16x16x32_bf16 v[60:63], v[146:149], v[178:181], v[60:63]
	v_mfma_f32_16x16x32_bf16 v[56:59], v[154:157], v[178:181], v[56:59]
	v_mfma_f32_16x16x32_bf16 v[52:55], v[146:149], v[186:189], v[52:55]
	v_mfma_f32_16x16x32_bf16 v[48:51], v[154:157], v[186:189], v[48:51]
	v_mfma_f32_16x16x32_bf16 v[36:39], v[146:149], v[194:197], v[36:39]
	v_mfma_f32_16x16x32_bf16 v[32:35], v[154:157], v[194:197], v[32:35]
	v_mfma_f32_16x16x32_bf16 v[20:23], v[146:149], v[202:205], v[20:23]
	v_mfma_f32_16x16x32_bf16 v[16:19], v[154:157], v[202:205], v[16:19]
	v_mfma_f32_16x16x32_bf16 v[60:63], v[150:153], v[182:185], v[60:63]
	v_mfma_f32_16x16x32_bf16 v[56:59], v[158:161], v[182:185], v[56:59]
	v_mfma_f32_16x16x32_bf16 v[52:55], v[150:153], v[190:193], v[52:55]
	v_mfma_f32_16x16x32_bf16 v[48:51], v[158:161], v[190:193], v[48:51]
	v_mfma_f32_16x16x32_bf16 v[36:39], v[150:153], v[198:201], v[36:39]
	v_mfma_f32_16x16x32_bf16 v[32:35], v[158:161], v[198:201], v[32:35]
	v_mfma_f32_16x16x32_bf16 v[20:23], v[150:153], v[206:209], v[20:23]
	v_mfma_f32_16x16x32_bf16 v[16:19], v[158:161], v[206:209], v[16:19]
	v_mfma_f32_16x16x32_bf16 v[44:47], v[162:165], v[178:181], v[44:47]
	v_mfma_f32_16x16x32_bf16 v[40:43], v[170:173], v[178:181], v[40:43]
	v_mfma_f32_16x16x32_bf16 v[28:31], v[162:165], v[186:189], v[28:31]
	v_mfma_f32_16x16x32_bf16 v[24:27], v[170:173], v[186:189], v[24:27]
	v_mfma_f32_16x16x32_bf16 v[12:15], v[162:165], v[194:197], v[12:15]
	v_mfma_f32_16x16x32_bf16 v[8:11], v[170:173], v[194:197], v[8:11]
	v_mfma_f32_16x16x32_bf16 v[4:7], v[162:165], v[202:205], v[4:7]
	v_mfma_f32_16x16x32_bf16 v[0:3], v[170:173], v[202:205], v[0:3]
	v_mfma_f32_16x16x32_bf16 v[44:47], v[166:169], v[182:185], v[44:47]
	v_mfma_f32_16x16x32_bf16 v[40:43], v[174:177], v[182:185], v[40:43]
	v_mfma_f32_16x16x32_bf16 v[28:31], v[166:169], v[190:193], v[28:31]
	v_mfma_f32_16x16x32_bf16 v[24:27], v[174:177], v[190:193], v[24:27]
	v_mfma_f32_16x16x32_bf16 v[12:15], v[166:169], v[198:201], v[12:15]
	v_mfma_f32_16x16x32_bf16 v[8:11], v[174:177], v[198:201], v[8:11]
	v_mfma_f32_16x16x32_bf16 v[4:7], v[166:169], v[206:209], v[4:7]
	v_mfma_f32_16x16x32_bf16 v[0:3], v[174:177], v[206:209], v[0:3]
	s_setprio 0
	s_barrier
	s_add_i32 s52, 0, 0x18000
	s_add_i32 s53, 0, 0x1c000
	v_add_u32_e32 v158, s52, v141
	v_add_u32_e32 v174, s53, v141
	ds_read_b128 v[146:149], v158
	ds_read_b128 v[150:153], v158 offset:1024
	ds_read_b128 v[154:157], v158 offset:2048
	ds_read_b128 v[158:161], v158 offset:3072
	ds_read_b128 v[162:165], v174
	ds_read_b128 v[166:169], v174 offset:1024
	ds_read_b128 v[170:173], v174 offset:2048
	ds_read_b128 v[174:177], v174 offset:3072
	s_add_u32 s42, s42, 0x40000
	s_addc_u32 s43, s43, 0
	s_mov_b32 m0, s51
	v_lshl_add_u64 v[218:219], s[42:43], 0, v[134:135]
	ds_read_b128 v[178:181], v145 offset:32768
	ds_read_b128 v[182:185], v145 offset:33792
	ds_read_b128 v[186:189], v145 offset:34816
	ds_read_b128 v[190:193], v145 offset:35840
	ds_read_b128 v[194:197], v145 offset:36864
	ds_read_b128 v[198:201], v145 offset:37888
	ds_read_b128 v[202:205], v145 offset:38912
	ds_read_b128 v[206:209], v145 offset:39936
	global_load_lds_dwordx4 v[218:219], off
	v_lshl_add_u64 v[218:219], s[42:43], 0, v[130:131]
	s_mov_b32 m0, s54
	s_nop 0
	global_load_lds_dwordx4 v[218:219], off
	s_waitcnt vmcnt(8)
	s_waitcnt lgkmcnt(0)
	s_barrier
	s_setprio 1
	v_mfma_f32_16x16x32_bf16 v[124:127], v[146:149], v[178:181], v[124:127]
	v_mfma_f32_16x16x32_bf16 v[120:123], v[154:157], v[178:181], v[120:123]
	v_mfma_f32_16x16x32_bf16 v[116:119], v[146:149], v[186:189], v[116:119]
	v_mfma_f32_16x16x32_bf16 v[112:115], v[154:157], v[186:189], v[112:115]
	v_mfma_f32_16x16x32_bf16 v[100:103], v[146:149], v[194:197], v[100:103]
	v_mfma_f32_16x16x32_bf16 v[96:99], v[154:157], v[194:197], v[96:99]
	v_mfma_f32_16x16x32_bf16 v[84:87], v[146:149], v[202:205], v[84:87]
	v_mfma_f32_16x16x32_bf16 v[80:83], v[154:157], v[202:205], v[80:83]
	v_mfma_f32_16x16x32_bf16 v[124:127], v[150:153], v[182:185], v[124:127]
	v_mfma_f32_16x16x32_bf16 v[120:123], v[158:161], v[182:185], v[120:123]
	v_mfma_f32_16x16x32_bf16 v[116:119], v[150:153], v[190:193], v[116:119]
	v_mfma_f32_16x16x32_bf16 v[112:115], v[158:161], v[190:193], v[112:115]
	v_mfma_f32_16x16x32_bf16 v[100:103], v[150:153], v[198:201], v[100:103]
	v_mfma_f32_16x16x32_bf16 v[96:99], v[158:161], v[198:201], v[96:99]
	v_mfma_f32_16x16x32_bf16 v[84:87], v[150:153], v[206:209], v[84:87]
	v_mfma_f32_16x16x32_bf16 v[80:83], v[158:161], v[206:209], v[80:83]
	v_mfma_f32_16x16x32_bf16 v[108:111], v[162:165], v[178:181], v[108:111]
	v_mfma_f32_16x16x32_bf16 v[104:107], v[170:173], v[178:181], v[104:107]
	v_mfma_f32_16x16x32_bf16 v[92:95], v[162:165], v[186:189], v[92:95]
	v_mfma_f32_16x16x32_bf16 v[88:91], v[170:173], v[186:189], v[88:91]
	v_mfma_f32_16x16x32_bf16 v[76:79], v[162:165], v[194:197], v[76:79]
	v_mfma_f32_16x16x32_bf16 v[72:75], v[170:173], v[194:197], v[72:75]
	v_mfma_f32_16x16x32_bf16 v[68:71], v[162:165], v[202:205], v[68:71]
	v_mfma_f32_16x16x32_bf16 v[64:67], v[170:173], v[202:205], v[64:67]
	v_mfma_f32_16x16x32_bf16 v[108:111], v[166:169], v[182:185], v[108:111]
	v_mfma_f32_16x16x32_bf16 v[104:107], v[174:177], v[182:185], v[104:107]
	v_mfma_f32_16x16x32_bf16 v[92:95], v[166:169], v[190:193], v[92:95]
	v_mfma_f32_16x16x32_bf16 v[88:91], v[174:177], v[190:193], v[88:91]
	v_mfma_f32_16x16x32_bf16 v[76:79], v[166:169], v[198:201], v[76:79]
	v_mfma_f32_16x16x32_bf16 v[72:75], v[174:177], v[198:201], v[72:75]
	v_mfma_f32_16x16x32_bf16 v[68:71], v[166:169], v[206:209], v[68:71]
	v_mfma_f32_16x16x32_bf16 v[64:67], v[174:177], v[206:209], v[64:67]
	s_setprio 0
	s_barrier
; #define PG8_STAGE(bufoff, gbase, voff) do { _Pragma("unroll") for (int _i = 0; _i < 2; ++_i) \
;         __builtin_amdgcn_global_load_lds((const unsigned*)((const char*)(gbase) + (voff)[_i]), (PG8_LAS unsigned*)(lds + (bufoff) + ldsw + _i * 8192), 16, 0, 0); } while (0)
; #define PG8_LDA(dst, b, h) do { _Pragma("unroll") for (int m = 0; m < 4; ++m) _Pragma("unroll") for (int k = 0; k < 2; ++k) dst[m][k] = *(const PG8_LAS bf16x8*)(lds + PG8_SA(b, h) + aoff + m * 2048 + k * 1024); } while (0)
; #define PG8_MMA(ai, bj, At, Bt) do { __builtin_amdgcn_s_setprio(1); _Pragma("unroll") for (int m = 0; m < 4; ++m) _Pragma("unroll") for (int n = 0; n < 2; ++n) _Pragma("unroll") for (int k = 0; k < 2; ++k) \
;         acc[ai][bj][m][n] = __builtin_amdgcn_mfma_f32_16x16x32_bf16(Bt[n][k], At[m][k], acc[ai][bj][m][n], 0, 0, 0); __builtin_amdgcn_s_setprio(0); } while (0)
; #define PG8_WAIT_V(n) asm volatile("s_waitcnt vmcnt(" #n ")" ::: "memory")
; #define PG8_WAIT_L(n) asm volatile("s_waitcnt lgkmcnt(" #n ")" ::: "memory")
; #define PG8_BAR __builtin_amdgcn_s_barrier()
; #define PG8_SCHED __builtin_amdgcn_sched_barrier(0)
; template <class Epi, class Sched, bool ALIGN_EPI = true, bool SP2 = true>
; __device__ __forceinline__ void gemm_phase(PG8_LAS unsigned char* lds, const Gemm g, const Sched& S, const Epi& E) {
;     ...
;             PG8_LDA(At, 1, 1); PG8_STAGE(PG8_SB(1, 0), b3, voffB); PG8_STAGE(PG8_SB(1, 1), b3 + hstepB, voffB); PG8_STAGE(PG8_SA(1, 0), a3, voffA);
;             PG8_WAIT_V(8); PG8_WAIT_L(0); PG8_BAR; PG8_MMA(1, 0, At, B0); PG8_MMA(1, 1, At, B1); PG8_BAR; PG8_SCHED;
;         }
	s_add_i32 s42, s52, s47
	v_lshl_add_u64 v[210:211], v[210:211], 0, s[10:11]
	s_mov_b32 m0, s42
	ds_read_b128 v[178:181], v145 offset:49152
	ds_read_b128 v[182:185], v145 offset:50176
	ds_read_b128 v[186:189], v145 offset:51200
	ds_read_b128 v[190:193], v145 offset:52224
	ds_read_b128 v[194:197], v145 offset:53248
	ds_read_b128 v[198:201], v145 offset:54272
	ds_read_b128 v[202:205], v145 offset:55296
	ds_read_b128 v[206:209], v145 offset:56320
	global_load_lds_dwordx4 v[210:211], off
	s_add_i32 m0, s42, 0x2000
	s_add_u32 s40, s40, 0x40080
	v_lshl_add_u64 v[210:211], v[212:213], 0, s[10:11]
	s_addc_u32 s41, s41, 0
	s_add_i32 s42, s53, s47
	global_load_lds_dwordx4 v[210:211], off
	v_lshl_add_u64 v[210:211], s[40:41], 0, v[132:133]
	s_mov_b32 m0, s42
	s_nop 0
	global_load_lds_dwordx4 v[210:211], off
	v_lshl_add_u64 v[210:211], s[40:41], 0, v[128:129]
	s_add_i32 m0, s42, 0x2000
	s_nop 0
	global_load_lds_dwordx4 v[210:211], off
	v_lshl_add_u64 v[210:211], v[214:215], 0, s[10:11]
	s_mov_b32 m0, s55
	s_nop 0
	global_load_lds_dwordx4 v[210:211], off
	v_lshl_add_u64 v[210:211], v[216:217], 0, s[10:11]
	s_mov_b32 m0, s56
	s_nop 0
	global_load_lds_dwordx4 v[210:211], off
	s_waitcnt vmcnt(8)
	s_waitcnt lgkmcnt(0)
	s_barrier
	s_setprio 1
	v_mfma_f32_16x16x32_bf16 v[60:63], v[146:149], v[178:181], v[60:63]
	v_mfma_f32_16x16x32_bf16 v[56:59], v[154:157], v[178:181], v[56:59]
	v_mfma_f32_16x16x32_bf16 v[52:55], v[146:149], v[186:189], v[52:55]
	v_mfma_f32_16x16x32_bf16 v[48:51], v[154:157], v[186:189], v[48:51]
	v_mfma_f32_16x16x32_bf16 v[36:39], v[146:149], v[194:197], v[36:39]
	v_mfma_f32_16x16x32_bf16 v[32:35], v[154:157], v[194:197], v[32:35]
	v_mfma_f32_16x16x32_bf16 v[20:23], v[146:149], v[202:205], v[20:23]
	v_mfma_f32_16x16x32_bf16 v[16:19], v[154:157], v[202:205], v[16:19]
	v_mfma_f32_16x16x32_bf16 v[60:63], v[150:153], v[182:185], v[60:63]
	v_mfma_f32_16x16x32_bf16 v[56:59], v[158:161], v[182:185], v[56:59]
	v_mfma_f32_16x16x32_bf16 v[52:55], v[150:153], v[190:193], v[52:55]
	v_mfma_f32_16x16x32_bf16 v[48:51], v[158:161], v[190:193], v[48:51]
	v_mfma_f32_16x16x32_bf16 v[36:39], v[150:153], v[198:201], v[36:39]
	v_mfma_f32_16x16x32_bf16 v[32:35], v[158:161], v[198:201], v[32:35]
	v_mfma_f32_16x16x32_bf16 v[20:23], v[150:153], v[206:209], v[20:23]
	v_mfma_f32_16x16x32_bf16 v[16:19], v[158:161], v[206:209], v[16:19]
	v_mfma_f32_16x16x32_bf16 v[44:47], v[162:165], v[178:181], v[44:47]
	v_mfma_f32_16x16x32_bf16 v[40:43], v[170:173], v[178:181], v[40:43]
	v_mfma_f32_16x16x32_bf16 v[28:31], v[162:165], v[186:189], v[28:31]
	v_mfma_f32_16x16x32_bf16 v[24:27], v[170:173], v[186:189], v[24:27]
	v_mfma_f32_16x16x32_bf16 v[12:15], v[162:165], v[194:197], v[12:15]
	v_mfma_f32_16x16x32_bf16 v[8:11], v[170:173], v[194:197], v[8:11]
	v_mfma_f32_16x16x32_bf16 v[4:7], v[162:165], v[202:205], v[4:7]
	v_mfma_f32_16x16x32_bf16 v[0:3], v[170:173], v[202:205], v[0:3]
	v_mfma_f32_16x16x32_bf16 v[44:47], v[166:169], v[182:185], v[44:47]
	v_mfma_f32_16x16x32_bf16 v[40:43], v[174:177], v[182:185], v[40:43]
	v_mfma_f32_16x16x32_bf16 v[28:31], v[166:169], v[190:193], v[28:31]
	v_mfma_f32_16x16x32_bf16 v[24:27], v[174:177], v[190:193], v[24:27]
	v_mfma_f32_16x16x32_bf16 v[12:15], v[166:169], v[198:201], v[12:15]
	v_mfma_f32_16x16x32_bf16 v[8:11], v[174:177], v[198:201], v[8:11]
	v_mfma_f32_16x16x32_bf16 v[4:7], v[166:169], v[206:209], v[4:7]
	v_mfma_f32_16x16x32_bf16 v[0:3], v[174:177], v[206:209], v[0:3]
	s_setprio 0
	s_barrier
	s_add_i32 s73, s73, 2
	s_add_u32 s71, s71, 0x100
	s_addc_u32 s72, s72, 0
	s_add_u32 s38, s38, 0x100
	s_addc_u32 s39, s39, 0
	s_cmp_gt_u32 s73, 13
	s_cbranch_scc0 .LBB0_1193
	s_and_b64 vcc, exec, s[14:15]
	s_cbranch_vccz .LBB0_1196
	s_barrier

; #define PG8_STAGE(bufoff, gbase, voff) do { _Pragma("unroll") for (int _i = 0; _i < 2; ++_i) \
;         __builtin_amdgcn_global_load_lds((const unsigned*)((const char*)(gbase) + (voff)[_i]), (PG8_LAS unsigned*)(lds + (bufoff) + ldsw + _i * 8192), 16, 0, 0); } while (0)
; #define PG8_LDA(dst, b, h) do { _Pragma("unroll") for (int m = 0; m < 4; ++m) _Pragma("unroll") for (int k = 0; k < 2; ++k) dst[m][k] = *(const PG8_LAS bf16x8*)(lds + PG8_SA(b, h) + aoff + m * 2048 + k * 1024); } while (0)
; #define PG8_LDB(dst, b, h) do { _Pragma("unroll") for (int n = 0; n < 2; ++n) _Pragma("unroll") for (int k = 0; k < 2; ++k) dst[n][k] = *(const PG8_LAS bf16x8*)(lds + PG8_SB(b, h) + boff + n * 2048 + k * 1024); } while (0)
; #define PG8_MMA(ai, bj, At, Bt) do { __builtin_amdgcn_s_setprio(1); _Pragma("unroll") for (int m = 0; m < 4; ++m) _Pragma("unroll") for (int n = 0; n < 2; ++n) _Pragma("unroll") for (int k = 0; k < 2; ++k) \
;         acc[ai][bj][m][n] = __builtin_amdgcn_mfma_f32_16x16x32_bf16(Bt[n][k], At[m][k], acc[ai][bj][m][n], 0, 0, 0); __builtin_amdgcn_s_setprio(0); } while (0)
; #define PG8_WAIT_V(n) asm volatile("s_waitcnt vmcnt(" #n ")" ::: "memory")
; #define PG8_WAIT_L(n) asm volatile("s_waitcnt lgkmcnt(" #n ")" ::: "memory")
; #define PG8_BAR __builtin_amdgcn_s_barrier()
; #define PG8_SCHED __builtin_amdgcn_sched_barrier(0)
; template <class Epi, class Sched, bool ALIGN_EPI = true, bool SP2 = true>
; __device__ __forceinline__ void gemm_phase(PG8_LAS unsigned char* lds, const Gemm g, const Sched& S, const Epi& E) {
;     ...
;             PG8_LDB(B0, 0, 0); PG8_LDB(B1, 0, 1); PG8_SCHED; PG8_LDA(At, 0, 0); PG8_STAGE(PG8_SA(1, 1), a1 + hstepA, voffA);
;             PG8_WAIT_V(8); PG8_WAIT_L(0); PG8_BAR; PG8_MMA(0, 0, At, B0); PG8_MMA(0, 1, At, B1); PG8_BAR; PG8_SCHED;
;             PG8_LDA(At, 0, 1); PG8_STAGE(PG8_SB(0, 0), b2, voffB); PG8_STAGE(PG8_SB(0, 1), b2 + hstepB, voffB); PG8_STAGE(PG8_SA(0, 0), a2, voffA);
;             PG8_WAIT_V(8); PG8_WAIT_L(0); PG8_BAR; PG8_MMA(1, 0, At, B0); PG8_MMA(1, 1, At, B1); PG8_BAR; PG8_SCHED;
.LBB0_1311:
	ds_read_b128 v[144:147], v153
	ds_read_b128 v[156:159], v153 offset:1024
	ds_read_b128 v[160:163], v153 offset:2048
	ds_read_b128 v[164:167], v153 offset:3072
	ds_read_b128 v[168:171], v154
	ds_read_b128 v[172:175], v154 offset:1024
	ds_read_b128 v[176:179], v154 offset:2048
	ds_read_b128 v[180:183], v154 offset:3072
	s_add_u32 s38, s34, 0xfffc0080
	s_addc_u32 s39, s35, -1
	s_cmp_eq_u32 s72, 12
	s_cselect_b32 s41, s25, s39
	s_cselect_b32 s40, s64, s38
	s_cselect_b32 s39, s23, s71
	s_cselect_b32 s38, s65, s66
	v_lshl_add_u64 v[148:149], s[34:35], 0, v[138:139]
	s_add_i32 m0, s47, 0xc000
	ds_read_b128 v[184:187], v155
	ds_read_b128 v[188:191], v155 offset:1024
	ds_read_b128 v[192:195], v155 offset:2048
	ds_read_b128 v[196:199], v155 offset:3072
	ds_read_b128 v[200:203], v155 offset:4096
	ds_read_b128 v[204:207], v155 offset:5120
	ds_read_b128 v[208:211], v155 offset:6144
	ds_read_b128 v[212:215], v155 offset:7168
	global_load_lds_dwordx4 v[148:149], off
	v_lshl_add_u64 v[148:149], s[34:35], 0, v[136:137]
	s_add_i32 m0, s47, 0xe000
	s_nop 0
	global_load_lds_dwordx4 v[148:149], off
	s_waitcnt vmcnt(8)
	s_waitcnt lgkmcnt(0)
	s_barrier
	s_setprio 1
	v_mfma_f32_16x16x32_bf16 v[124:127], v[144:147], v[184:187], v[124:127]
	v_mfma_f32_16x16x32_bf16 v[120:123], v[160:163], v[184:187], v[120:123]
	v_mfma_f32_16x16x32_bf16 v[108:111], v[144:147], v[192:195], v[108:111]
	v_mfma_f32_16x16x32_bf16 v[104:107], v[160:163], v[192:195], v[104:107]
	v_mfma_f32_16x16x32_bf16 v[92:95], v[144:147], v[200:203], v[92:95]
	v_mfma_f32_16x16x32_bf16 v[88:91], v[160:163], v[200:203], v[88:91]
	v_mfma_f32_16x16x32_bf16 v[76:79], v[144:147], v[208:211], v[76:79]
	v_mfma_f32_16x16x32_bf16 v[72:75], v[160:163], v[208:211], v[72:75]
	v_mfma_f32_16x16x32_bf16 v[124:127], v[156:159], v[188:191], v[124:127]
	v_mfma_f32_16x16x32_bf16 v[120:123], v[164:167], v[188:191], v[120:123]
	v_mfma_f32_16x16x32_bf16 v[108:111], v[156:159], v[196:199], v[108:111]
	v_mfma_f32_16x16x32_bf16 v[104:107], v[164:167], v[196:199], v[104:107]
	v_mfma_f32_16x16x32_bf16 v[92:95], v[156:159], v[204:207], v[92:95]
	v_mfma_f32_16x16x32_bf16 v[88:91], v[164:167], v[204:207], v[88:91]
	v_mfma_f32_16x16x32_bf16 v[76:79], v[156:159], v[212:215], v[76:79]
	v_mfma_f32_16x16x32_bf16 v[72:75], v[164:167], v[212:215], v[72:75]
	v_mfma_f32_16x16x32_bf16 v[116:119], v[168:171], v[184:187], v[116:119]
	v_mfma_f32_16x16x32_bf16 v[112:115], v[176:179], v[184:187], v[112:115]
	v_mfma_f32_16x16x32_bf16 v[100:103], v[168:171], v[192:195], v[100:103]
	v_mfma_f32_16x16x32_bf16 v[96:99], v[176:179], v[192:195], v[96:99]
	v_mfma_f32_16x16x32_bf16 v[84:87], v[168:171], v[200:203], v[84:87]
	v_mfma_f32_16x16x32_bf16 v[80:83], v[176:179], v[200:203], v[80:83]
	v_mfma_f32_16x16x32_bf16 v[68:71], v[168:171], v[208:211], v[68:71]
	v_mfma_f32_16x16x32_bf16 v[64:67], v[176:179], v[208:211], v[64:67]
	v_mfma_f32_16x16x32_bf16 v[116:119], v[172:175], v[188:191], v[116:119]
	v_mfma_f32_16x16x32_bf16 v[112:115], v[180:183], v[188:191], v[112:115]
	v_mfma_f32_16x16x32_bf16 v[100:103], v[172:175], v[196:199], v[100:103]
	v_mfma_f32_16x16x32_bf16 v[96:99], v[180:183], v[196:199], v[96:99]
	v_mfma_f32_16x16x32_bf16 v[84:87], v[172:175], v[204:207], v[84:87]
	v_mfma_f32_16x16x32_bf16 v[80:83], v[180:183], v[204:207], v[80:83]
	v_mfma_f32_16x16x32_bf16 v[68:71], v[172:175], v[212:215], v[68:71]
	v_mfma_f32_16x16x32_bf16 v[64:67], v[180:183], v[212:215], v[64:67]
	s_setprio 0
	s_barrier
	s_add_i32 s52, s58, s46
	v_lshl_add_u64 v[148:149], s[38:39], 0, v[130:131]
	s_mov_b32 m0, s52
	ds_read_b128 v[184:187], v155 offset:16384
	ds_read_b128 v[188:191], v155 offset:17408
	ds_read_b128 v[192:195], v155 offset:18432
	ds_read_b128 v[196:199], v155 offset:19456
	ds_read_b128 v[200:203], v155 offset:20480
	ds_read_b128 v[204:207], v155 offset:21504
	ds_read_b128 v[208:211], v155 offset:22528
	ds_read_b128 v[212:215], v155 offset:23552
	global_load_lds_dwordx4 v[148:149], off
	s_add_i32 m0, s52, 0x2000
	s_add_u32 s52, s38, 0x40000
	v_lshl_add_u64 v[216:217], s[38:39], 0, v[134:135]
	s_addc_u32 s53, s39, 0
	s_add_i32 s68, s59, s46
	global_load_lds_dwordx4 v[216:217], off
	v_lshl_add_u64 v[218:219], s[52:53], 0, v[130:131]
	s_mov_b32 m0, s68
	v_lshl_add_u64 v[220:221], s[40:41], 0, v[132:133]
	global_load_lds_dwordx4 v[218:219], off
	v_lshl_add_u64 v[218:219], s[52:53], 0, v[134:135]
	s_add_i32 m0, s68, 0x2000
	s_nop 0
	global_load_lds_dwordx4 v[218:219], off
	v_lshl_add_u64 v[218:219], s[40:41], 0, v[128:129]
	s_mov_b32 m0, s47
	s_nop 0
	global_load_lds_dwordx4 v[218:219], off
	s_mov_b32 m0, s48
	s_nop 0
	global_load_lds_dwordx4 v[220:221], off
	s_waitcnt vmcnt(8)
	s_waitcnt lgkmcnt(0)
	s_barrier
; #define PG8_STAGE(bufoff, gbase, voff) do { _Pragma("unroll") for (int _i = 0; _i < 2; ++_i) \
;         __builtin_amdgcn_global_load_lds((const unsigned*)((const char*)(gbase) + (voff)[_i]), (PG8_LAS unsigned*)(lds + (bufoff) + ldsw + _i * 8192), 16, 0, 0); } while (0)
; #define PG8_LDA(dst, b, h) do { _Pragma("unroll") for (int m = 0; m < 4; ++m) _Pragma("unroll") for (int k = 0; k < 2; ++k) dst[m][k] = *(const PG8_LAS bf16x8*)(lds + PG8_SA(b, h) + aoff + m * 2048 + k * 1024); } while (0)
; #define PG8_LDB(dst, b, h) do { _Pragma("unroll") for (int n = 0; n < 2; ++n) _Pragma("unroll") for (int k = 0; k < 2; ++k) dst[n][k] = *(const PG8_LAS bf16x8*)(lds + PG8_SB(b, h) + boff + n * 2048 + k * 1024); } while (0)
; #define PG8_MMA(ai, bj, At, Bt) do { __builtin_amdgcn_s_setprio(1); _Pragma("unroll") for (int m = 0; m < 4; ++m) _Pragma("unroll") for (int n = 0; n < 2; ++n) _Pragma("unroll") for (int k = 0; k < 2; ++k) \
;         acc[ai][bj][m][n] = __builtin_amdgcn_mfma_f32_16x16x32_bf16(Bt[n][k], At[m][k], acc[ai][bj][m][n], 0, 0, 0); __builtin_amdgcn_s_setprio(0); } while (0)
; #define PG8_WAIT_V(n) asm volatile("s_waitcnt vmcnt(" #n ")" ::: "memory")
; #define PG8_WAIT_L(n) asm volatile("s_waitcnt lgkmcnt(" #n ")" ::: "memory")
; #define PG8_BAR __builtin_amdgcn_s_barrier()
; #define PG8_SCHED __builtin_amdgcn_sched_barrier(0)
; template <class Epi, class Sched, bool ALIGN_EPI = true, bool SP2 = true>
; __device__ __forceinline__ void gemm_phase(PG8_LAS unsigned char* lds, const Gemm g, const Sched& S, const Epi& E) {
;     ...
;             PG8_WAIT_V(8); PG8_WAIT_L(0); PG8_BAR; PG8_MMA(1, 0, At, B0); PG8_MMA(1, 1, At, B1); PG8_BAR; PG8_SCHED;
;             PG8_LDB(B0, 1, 0); PG8_LDB(B1, 1, 1); PG8_SCHED; PG8_LDA(At, 1, 0); PG8_STAGE(PG8_SA(0, 1), a2 + hstepA, voffA);
;             PG8_WAIT_V(8); PG8_WAIT_L(0); PG8_BAR; PG8_MMA(0, 0, At, B0); PG8_MMA(0, 1, At, B1); PG8_BAR; PG8_SCHED;
	s_setprio 1
	v_mfma_f32_16x16x32_bf16 v[60:63], v[144:147], v[184:187], v[60:63]
	v_mfma_f32_16x16x32_bf16 v[56:59], v[160:163], v[184:187], v[56:59]
	v_mfma_f32_16x16x32_bf16 v[44:47], v[144:147], v[192:195], v[44:47]
	v_mfma_f32_16x16x32_bf16 v[40:43], v[160:163], v[192:195], v[40:43]
	v_mfma_f32_16x16x32_bf16 v[28:31], v[144:147], v[200:203], v[28:31]
	v_mfma_f32_16x16x32_bf16 v[24:27], v[160:163], v[200:203], v[24:27]
	v_mfma_f32_16x16x32_bf16 v[12:15], v[144:147], v[208:211], v[12:15]
	v_mfma_f32_16x16x32_bf16 v[8:11], v[160:163], v[208:211], v[8:11]
	v_mfma_f32_16x16x32_bf16 v[60:63], v[156:159], v[188:191], v[60:63]
	v_mfma_f32_16x16x32_bf16 v[56:59], v[164:167], v[188:191], v[56:59]
	v_mfma_f32_16x16x32_bf16 v[44:47], v[156:159], v[196:199], v[44:47]
	v_mfma_f32_16x16x32_bf16 v[40:43], v[164:167], v[196:199], v[40:43]
	v_mfma_f32_16x16x32_bf16 v[28:31], v[156:159], v[204:207], v[28:31]
	v_mfma_f32_16x16x32_bf16 v[24:27], v[164:167], v[204:207], v[24:27]
	v_mfma_f32_16x16x32_bf16 v[12:15], v[156:159], v[212:215], v[12:15]
	v_mfma_f32_16x16x32_bf16 v[8:11], v[164:167], v[212:215], v[8:11]
	v_mfma_f32_16x16x32_bf16 v[52:55], v[168:171], v[184:187], v[52:55]
	v_mfma_f32_16x16x32_bf16 v[48:51], v[176:179], v[184:187], v[48:51]
	v_mfma_f32_16x16x32_bf16 v[36:39], v[168:171], v[192:195], v[36:39]
	v_mfma_f32_16x16x32_bf16 v[32:35], v[176:179], v[192:195], v[32:35]
	v_mfma_f32_16x16x32_bf16 v[20:23], v[168:171], v[200:203], v[20:23]
	v_mfma_f32_16x16x32_bf16 v[16:19], v[176:179], v[200:203], v[16:19]
	v_mfma_f32_16x16x32_bf16 v[4:7], v[168:171], v[208:211], v[4:7]
	v_mfma_f32_16x16x32_bf16 v[0:3], v[176:179], v[208:211], v[0:3]
	v_mfma_f32_16x16x32_bf16 v[52:55], v[172:175], v[188:191], v[52:55]
	v_mfma_f32_16x16x32_bf16 v[48:51], v[180:183], v[188:191], v[48:51]
	v_mfma_f32_16x16x32_bf16 v[36:39], v[172:175], v[196:199], v[36:39]
	v_mfma_f32_16x16x32_bf16 v[32:35], v[180:183], v[196:199], v[32:35]
	v_mfma_f32_16x16x32_bf16 v[20:23], v[172:175], v[204:207], v[20:23]
	v_mfma_f32_16x16x32_bf16 v[16:19], v[180:183], v[204:207], v[16:19]
	v_mfma_f32_16x16x32_bf16 v[4:7], v[172:175], v[212:215], v[4:7]
	v_mfma_f32_16x16x32_bf16 v[0:3], v[180:183], v[212:215], v[0:3]
	s_setprio 0
	s_barrier
	s_add_i32 s52, 0, 0x18000
	s_add_i32 s53, 0, 0x1c000
	v_add_u32_e32 v164, s52, v151
	v_add_u32_e32 v180, s53, v151
	ds_read_b128 v[144:147], v164
	ds_read_b128 v[156:159], v164 offset:1024
	ds_read_b128 v[160:163], v164 offset:2048
	ds_read_b128 v[164:167], v164 offset:3072
	ds_read_b128 v[168:171], v180
	ds_read_b128 v[172:175], v180 offset:1024
	ds_read_b128 v[176:179], v180 offset:2048
	ds_read_b128 v[180:183], v180 offset:3072
	s_add_u32 s40, s40, 0x40000
	s_addc_u32 s41, s41, 0
	s_mov_b32 m0, s49
	v_lshl_add_u64 v[222:223], s[40:41], 0, v[128:129]
	ds_read_b128 v[184:187], v155 offset:32768
	ds_read_b128 v[188:191], v155 offset:33792
	ds_read_b128 v[192:195], v155 offset:34816
	ds_read_b128 v[196:199], v155 offset:35840
	ds_read_b128 v[200:203], v155 offset:36864
	ds_read_b128 v[204:207], v155 offset:37888
	ds_read_b128 v[208:211], v155 offset:38912
	ds_read_b128 v[212:215], v155 offset:39936
	global_load_lds_dwordx4 v[222:223], off
	v_lshl_add_u64 v[222:223], s[40:41], 0, v[132:133]
	s_mov_b32 m0, s50
	s_nop 0
	global_load_lds_dwordx4 v[222:223], off
	s_waitcnt vmcnt(8)
	s_waitcnt lgkmcnt(0)
	s_barrier
	s_setprio 1
	v_mfma_f32_16x16x32_bf16 v[124:127], v[144:147], v[184:187], v[124:127]
	v_mfma_f32_16x16x32_bf16 v[120:123], v[160:163], v[184:187], v[120:123]
	v_mfma_f32_16x16x32_bf16 v[108:111], v[144:147], v[192:195], v[108:111]
	v_mfma_f32_16x16x32_bf16 v[104:107], v[160:163], v[192:195], v[104:107]
	v_mfma_f32_16x16x32_bf16 v[92:95], v[144:147], v[200:203], v[92:95]
	v_mfma_f32_16x16x32_bf16 v[88:91], v[160:163], v[200:203], v[88:91]
	v_mfma_f32_16x16x32_bf16 v[76:79], v[144:147], v[208:211], v[76:79]
	v_mfma_f32_16x16x32_bf16 v[72:75], v[160:163], v[208:211], v[72:75]
	v_mfma_f32_16x16x32_bf16 v[124:127], v[156:159], v[188:191], v[124:127]
	v_mfma_f32_16x16x32_bf16 v[120:123], v[164:167], v[188:191], v[120:123]
	v_mfma_f32_16x16x32_bf16 v[108:111], v[156:159], v[196:199], v[108:111]
	v_mfma_f32_16x16x32_bf16 v[104:107], v[164:167], v[196:199], v[104:107]
	v_mfma_f32_16x16x32_bf16 v[92:95], v[156:159], v[204:207], v[92:95]
	v_mfma_f32_16x16x32_bf16 v[88:91], v[164:167], v[204:207], v[88:91]
	v_mfma_f32_16x16x32_bf16 v[76:79], v[156:159], v[212:215], v[76:79]
	v_mfma_f32_16x16x32_bf16 v[72:75], v[164:167], v[212:215], v[72:75]
	v_mfma_f32_16x16x32_bf16 v[116:119], v[168:171], v[184:187], v[116:119]
	v_mfma_f32_16x16x32_bf16 v[112:115], v[176:179], v[184:187], v[112:115]
	v_mfma_f32_16x16x32_bf16 v[100:103], v[168:171], v[192:195], v[100:103]
	v_mfma_f32_16x16x32_bf16 v[96:99], v[176:179], v[192:195], v[96:99]
	v_mfma_f32_16x16x32_bf16 v[84:87], v[168:171], v[200:203], v[84:87]
	v_mfma_f32_16x16x32_bf16 v[80:83], v[176:179], v[200:203], v[80:83]
	v_mfma_f32_16x16x32_bf16 v[68:71], v[168:171], v[208:211], v[68:71]
	v_mfma_f32_16x16x32_bf16 v[64:67], v[176:179], v[208:211], v[64:67]
	v_mfma_f32_16x16x32_bf16 v[116:119], v[172:175], v[188:191], v[116:119]
	v_mfma_f32_16x16x32_bf16 v[112:115], v[180:183], v[188:191], v[112:115]
	v_mfma_f32_16x16x32_bf16 v[100:103], v[172:175], v[196:199], v[100:103]
	v_mfma_f32_16x16x32_bf16 v[96:99], v[180:183], v[196:199], v[96:99]
	v_mfma_f32_16x16x32_bf16 v[84:87], v[172:175], v[204:207], v[84:87]
	v_mfma_f32_16x16x32_bf16 v[80:83], v[180:183], v[204:207], v[80:83]
	v_mfma_f32_16x16x32_bf16 v[68:71], v[172:175], v[212:215], v[68:71]
	v_mfma_f32_16x16x32_bf16 v[64:67], v[180:183], v[212:215], v[64:67]
	s_setprio 0
	s_barrier
; #define PG8_STAGE(bufoff, gbase, voff) do { _Pragma("unroll") for (int _i = 0; _i < 2; ++_i) \
;         __builtin_amdgcn_global_load_lds((const unsigned*)((const char*)(gbase) + (voff)[_i]), (PG8_LAS unsigned*)(lds + (bufoff) + ldsw + _i * 8192), 16, 0, 0); } while (0)
; #define PG8_LDA(dst, b, h) do { _Pragma("unroll") for (int m = 0; m < 4; ++m) _Pragma("unroll") for (int k = 0; k < 2; ++k) dst[m][k] = *(const PG8_LAS bf16x8*)(lds + PG8_SA(b, h) + aoff + m * 2048 + k * 1024); } while (0)
; #define PG8_MMA(ai, bj, At, Bt) do { __builtin_amdgcn_s_setprio(1); _Pragma("unroll") for (int m = 0; m < 4; ++m) _Pragma("unroll") for (int n = 0; n < 2; ++n) _Pragma("unroll") for (int k = 0; k < 2; ++k) \
;         acc[ai][bj][m][n] = __builtin_amdgcn_mfma_f32_16x16x32_bf16(Bt[n][k], At[m][k], acc[ai][bj][m][n], 0, 0, 0); __builtin_amdgcn_s_setprio(0); } while (0)
; #define PG8_WAIT_V(n) asm volatile("s_waitcnt vmcnt(" #n ")" ::: "memory")
; #define PG8_WAIT_L(n) asm volatile("s_waitcnt lgkmcnt(" #n ")" ::: "memory")
; #define PG8_BAR __builtin_amdgcn_s_barrier()
; #define PG8_SCHED __builtin_amdgcn_sched_barrier(0)
; template <class Epi, class Sched, bool ALIGN_EPI = true, bool SP2 = true>
; __device__ __forceinline__ void gemm_phase(PG8_LAS unsigned char* lds, const Gemm g, const Sched& S, const Epi& E) {
;     ...
;             PG8_LDA(At, 1, 1); PG8_STAGE(PG8_SB(1, 0), b3, voffB); PG8_STAGE(PG8_SB(1, 1), b3 + hstepB, voffB); PG8_STAGE(PG8_SA(1, 0), a3, voffA);
;             PG8_WAIT_V(8); PG8_WAIT_L(0); PG8_BAR; PG8_MMA(1, 0, At, B0); PG8_MMA(1, 1, At, B1); PG8_BAR; PG8_SCHED;
;         }
	s_add_i32 s40, s52, s46
	v_lshl_add_u64 v[148:149], v[148:149], 0, s[10:11]
	s_mov_b32 m0, s40
	ds_read_b128 v[184:187], v155 offset:49152
	ds_read_b128 v[188:191], v155 offset:50176
	ds_read_b128 v[192:195], v155 offset:51200
	ds_read_b128 v[196:199], v155 offset:52224
	ds_read_b128 v[200:203], v155 offset:53248
	ds_read_b128 v[204:207], v155 offset:54272
	ds_read_b128 v[208:211], v155 offset:55296
	ds_read_b128 v[212:215], v155 offset:56320
	global_load_lds_dwordx4 v[148:149], off
	s_add_i32 m0, s40, 0x2000
	s_add_u32 s38, s38, 0x40080
	v_lshl_add_u64 v[148:149], v[216:217], 0, s[10:11]
	s_addc_u32 s39, s39, 0
	s_add_i32 s40, s53, s46
	global_load_lds_dwordx4 v[148:149], off
	v_lshl_add_u64 v[148:149], s[38:39], 0, v[130:131]
	s_mov_b32 m0, s40
	s_nop 0
	global_load_lds_dwordx4 v[148:149], off
	v_lshl_add_u64 v[148:149], s[38:39], 0, v[134:135]
	s_add_i32 m0, s40, 0x2000
	s_nop 0
	global_load_lds_dwordx4 v[148:149], off
	v_lshl_add_u64 v[148:149], v[218:219], 0, s[10:11]
	s_mov_b32 m0, s54
	s_nop 0
	global_load_lds_dwordx4 v[148:149], off
	v_lshl_add_u64 v[148:149], v[220:221], 0, s[10:11]
	s_mov_b32 m0, s55
	s_nop 0
	global_load_lds_dwordx4 v[148:149], off
	s_waitcnt vmcnt(8)
	s_waitcnt lgkmcnt(0)
	s_barrier
	s_setprio 1
	v_mfma_f32_16x16x32_bf16 v[60:63], v[144:147], v[184:187], v[60:63]
	v_mfma_f32_16x16x32_bf16 v[56:59], v[160:163], v[184:187], v[56:59]
	v_mfma_f32_16x16x32_bf16 v[44:47], v[144:147], v[192:195], v[44:47]
	v_mfma_f32_16x16x32_bf16 v[40:43], v[160:163], v[192:195], v[40:43]
	v_mfma_f32_16x16x32_bf16 v[28:31], v[144:147], v[200:203], v[28:31]
	v_mfma_f32_16x16x32_bf16 v[24:27], v[160:163], v[200:203], v[24:27]
	v_mfma_f32_16x16x32_bf16 v[12:15], v[144:147], v[208:211], v[12:15]
	v_mfma_f32_16x16x32_bf16 v[8:11], v[160:163], v[208:211], v[8:11]
	v_mfma_f32_16x16x32_bf16 v[60:63], v[156:159], v[188:191], v[60:63]
	v_mfma_f32_16x16x32_bf16 v[56:59], v[164:167], v[188:191], v[56:59]
	v_mfma_f32_16x16x32_bf16 v[44:47], v[156:159], v[196:199], v[44:47]
	v_mfma_f32_16x16x32_bf16 v[40:43], v[164:167], v[196:199], v[40:43]
	v_mfma_f32_16x16x32_bf16 v[28:31], v[156:159], v[204:207], v[28:31]
	v_mfma_f32_16x16x32_bf16 v[24:27], v[164:167], v[204:207], v[24:27]
	v_mfma_f32_16x16x32_bf16 v[12:15], v[156:159], v[212:215], v[12:15]
	v_mfma_f32_16x16x32_bf16 v[8:11], v[164:167], v[212:215], v[8:11]
	v_mfma_f32_16x16x32_bf16 v[52:55], v[168:171], v[184:187], v[52:55]
	v_mfma_f32_16x16x32_bf16 v[48:51], v[176:179], v[184:187], v[48:51]
	v_mfma_f32_16x16x32_bf16 v[36:39], v[168:171], v[192:195], v[36:39]
	v_mfma_f32_16x16x32_bf16 v[32:35], v[176:179], v[192:195], v[32:35]
	v_mfma_f32_16x16x32_bf16 v[20:23], v[168:171], v[200:203], v[20:23]
	v_mfma_f32_16x16x32_bf16 v[16:19], v[176:179], v[200:203], v[16:19]
	v_mfma_f32_16x16x32_bf16 v[4:7], v[168:171], v[208:211], v[4:7]
	v_mfma_f32_16x16x32_bf16 v[0:3], v[176:179], v[208:211], v[0:3]
	v_mfma_f32_16x16x32_bf16 v[52:55], v[172:175], v[188:191], v[52:55]
	v_mfma_f32_16x16x32_bf16 v[48:51], v[180:183], v[188:191], v[48:51]
	v_mfma_f32_16x16x32_bf16 v[36:39], v[172:175], v[196:199], v[36:39]
	v_mfma_f32_16x16x32_bf16 v[32:35], v[180:183], v[196:199], v[32:35]
	v_mfma_f32_16x16x32_bf16 v[20:23], v[172:175], v[204:207], v[20:23]
	v_mfma_f32_16x16x32_bf16 v[16:19], v[180:183], v[204:207], v[16:19]
	v_mfma_f32_16x16x32_bf16 v[4:7], v[172:175], v[212:215], v[4:7]
	v_mfma_f32_16x16x32_bf16 v[0:3], v[180:183], v[212:215], v[0:3]
	s_setprio 0
	s_barrier
	s_add_i32 s72, s72, 2
	s_add_u32 s66, s66, 0x100
	s_addc_u32 s71, s71, 0
	s_add_u32 s34, s34, 0x100
	s_addc_u32 s35, s35, 0
	s_cmp_gt_u32 s72, 13
	s_cbranch_scc0 .LBB0_1311
	s_and_b64 vcc, exec, s[12:13]
	s_cbranch_vccz .LBB0_1314
	s_barrier

; #define PG8_STAGE(bufoff, gbase, voff) do { _Pragma("unroll") for (int _i = 0; _i < 2; ++_i) \
;         __builtin_amdgcn_global_load_lds((const unsigned*)((const char*)(gbase) + (voff)[_i]), (PG8_LAS unsigned*)(lds + (bufoff) + ldsw + _i * 8192), 16, 0, 0); } while (0)
; #define PG8_LDA(dst, b, h) do { _Pragma("unroll") for (int m = 0; m < 4; ++m) _Pragma("unroll") for (int k = 0; k < 2; ++k) dst[m][k] = *(const PG8_LAS bf16x8*)(lds + PG8_SA(b, h) + aoff + m * 2048 + k * 1024); } while (0)
; #define PG8_LDB(dst, b, h) do { _Pragma("unroll") for (int n = 0; n < 2; ++n) _Pragma("unroll") for (int k = 0; k < 2; ++k) dst[n][k] = *(const PG8_LAS bf16x8*)(lds + PG8_SB(b, h) + boff + n * 2048 + k * 1024); } while (0)
; #define PG8_MMA(ai, bj, At, Bt) do { __builtin_amdgcn_s_setprio(1); _Pragma("unroll") for (int m = 0; m < 4; ++m) _Pragma("unroll") for (int n = 0; n < 2; ++n) _Pragma("unroll") for (int k = 0; k < 2; ++k) \
;         acc[ai][bj][m][n] = __builtin_amdgcn_mfma_f32_16x16x32_bf16(Bt[n][k], At[m][k], acc[ai][bj][m][n], 0, 0, 0); __builtin_amdgcn_s_setprio(0); } while (0)
; #define PG8_WAIT_V(n) asm volatile("s_waitcnt vmcnt(" #n ")" ::: "memory")
; #define PG8_WAIT_L(n) asm volatile("s_waitcnt lgkmcnt(" #n ")" ::: "memory")
; #define PG8_BAR __builtin_amdgcn_s_barrier()
; #define PG8_SCHED __builtin_amdgcn_sched_barrier(0)
; template <class Epi, class Sched, bool ALIGN_EPI = true, bool SP2 = true>
; __device__ __forceinline__ void gemm_phase(PG8_LAS unsigned char* lds, const Gemm g, const Sched& S, const Epi& E) {
;     ...
;             PG8_LDB(B0, 0, 0); PG8_LDB(B1, 0, 1); PG8_SCHED; PG8_LDA(At, 0, 0); PG8_STAGE(PG8_SA(1, 1), a1 + hstepA, voffA);
;             PG8_WAIT_V(8); PG8_WAIT_L(0); PG8_BAR; PG8_MMA(0, 0, At, B0); PG8_MMA(0, 1, At, B1); PG8_BAR; PG8_SCHED;
;             PG8_LDA(At, 0, 1); PG8_STAGE(PG8_SB(0, 0), b2, voffB); PG8_STAGE(PG8_SB(0, 1), b2 + hstepB, voffB); PG8_STAGE(PG8_SA(0, 0), a2, voffA);
;             PG8_WAIT_V(8); PG8_WAIT_L(0); PG8_BAR; PG8_MMA(1, 0, At, B0); PG8_MMA(1, 1, At, B1); PG8_BAR; PG8_SCHED;
.LBB0_1445:
	ds_read_b128 v[84:87], v243
	ds_read_b128 v[88:91], v243 offset:1024
	ds_read_b128 v[92:95], v243 offset:2048
	ds_read_b128 v[96:99], v243 offset:3072
	ds_read_b128 v[100:103], v244
	ds_read_b128 v[104:107], v244 offset:1024
	ds_read_b128 v[108:111], v244 offset:2048
	ds_read_b128 v[112:115], v244 offset:3072
	s_add_u32 s12, s8, 0xfffc0080
	s_addc_u32 s13, s9, -1
	s_cmp_eq_u32 s84, 12
	s_cselect_b32 s59, s7, s13
	s_cselect_b32 s58, s11, s12
	s_cselect_b32 s13, s49, s61
	s_cselect_b32 s12, s51, s60
	v_lshl_add_u64 v[208:209], s[8:9], 0, v[202:203]
	s_add_i32 m0, s63, 0xc000
	ds_read_b128 v[128:131], v245
	ds_read_b128 v[132:135], v245 offset:1024
	ds_read_b128 v[136:139], v245 offset:2048
	ds_read_b128 v[140:143], v245 offset:3072
	ds_read_b128 v[144:147], v245 offset:4096
	ds_read_b128 v[148:151], v245 offset:5120
	ds_read_b128 v[152:155], v245 offset:6144
	ds_read_b128 v[156:159], v245 offset:7168
	global_load_lds_dwordx4 v[208:209], off
	v_lshl_add_u64 v[208:209], s[8:9], 0, v[200:201]
	s_add_i32 m0, s63, 0xe000
	s_nop 0
	global_load_lds_dwordx4 v[208:209], off
	s_waitcnt vmcnt(8)
	s_waitcnt lgkmcnt(0)
	s_barrier
	s_setprio 1
	v_mfma_f32_16x16x32_bf16 v[188:191], v[84:87], v[128:131], v[188:191]
	v_mfma_f32_16x16x32_bf16 v[180:183], v[92:95], v[128:131], v[180:183]
	v_mfma_f32_16x16x32_bf16 v[172:175], v[84:87], v[136:139], v[172:175]
	v_mfma_f32_16x16x32_bf16 v[164:167], v[92:95], v[136:139], v[164:167]
	v_mfma_f32_16x16x32_bf16 v[124:127], v[84:87], v[144:147], v[124:127]
	v_mfma_f32_16x16x32_bf16 v[76:79], v[92:95], v[144:147], v[76:79]
	v_mfma_f32_16x16x32_bf16 v[120:123], v[84:87], v[152:155], v[120:123]
	v_mfma_f32_16x16x32_bf16 v[72:75], v[92:95], v[152:155], v[72:75]
	v_mfma_f32_16x16x32_bf16 v[188:191], v[88:91], v[132:135], v[188:191]
	v_mfma_f32_16x16x32_bf16 v[180:183], v[96:99], v[132:135], v[180:183]
	v_mfma_f32_16x16x32_bf16 v[172:175], v[88:91], v[140:143], v[172:175]
	v_mfma_f32_16x16x32_bf16 v[164:167], v[96:99], v[140:143], v[164:167]
	v_mfma_f32_16x16x32_bf16 v[124:127], v[88:91], v[148:151], v[124:127]
	v_mfma_f32_16x16x32_bf16 v[76:79], v[96:99], v[148:151], v[76:79]
	v_mfma_f32_16x16x32_bf16 v[120:123], v[88:91], v[156:159], v[120:123]
	v_mfma_f32_16x16x32_bf16 v[72:75], v[96:99], v[156:159], v[72:75]
	v_mfma_f32_16x16x32_bf16 v[184:187], v[100:103], v[128:131], v[184:187]
	v_mfma_f32_16x16x32_bf16 v[128:131], v[108:111], v[128:131], v[176:179]
	v_mfma_f32_16x16x32_bf16 v[116:119], v[100:103], v[144:147], v[116:119]
	v_mfma_f32_16x16x32_bf16 v[68:71], v[108:111], v[144:147], v[68:71]
	v_mfma_f32_16x16x32_bf16 v[80:83], v[100:103], v[152:155], v[80:83]
	v_mfma_f32_16x16x32_bf16 v[64:67], v[108:111], v[152:155], v[64:67]
	v_mfma_f32_16x16x32_bf16 v[184:187], v[104:107], v[132:135], v[184:187]
	v_mfma_f32_16x16x32_bf16 v[128:131], v[112:115], v[132:135], v[128:131]
	v_mfma_f32_16x16x32_bf16 v[132:135], v[100:103], v[136:139], v[168:171]
	v_mfma_f32_16x16x32_bf16 v[136:139], v[108:111], v[136:139], v[160:163]
	v_mfma_f32_16x16x32_bf16 v[116:119], v[104:107], v[148:151], v[116:119]
	v_mfma_f32_16x16x32_bf16 v[68:71], v[112:115], v[148:151], v[68:71]
	v_mfma_f32_16x16x32_bf16 v[80:83], v[104:107], v[156:159], v[80:83]
	v_mfma_f32_16x16x32_bf16 v[64:67], v[112:115], v[156:159], v[64:67]
	v_mfma_f32_16x16x32_bf16 v[132:135], v[104:107], v[140:143], v[132:135]
	v_mfma_f32_16x16x32_bf16 v[136:139], v[112:115], v[140:143], v[136:139]
	s_setprio 0
	s_barrier
	s_add_i32 s52, s78, s62
	v_lshl_add_u64 v[220:221], s[12:13], 0, v[194:195]
	s_mov_b32 m0, s52
	ds_read_b128 v[140:143], v245 offset:16384
	ds_read_b128 v[144:147], v245 offset:17408
	ds_read_b128 v[148:151], v245 offset:18432
	ds_read_b128 v[152:155], v245 offset:19456
	ds_read_b128 v[156:159], v245 offset:20480
	ds_read_b128 v[160:163], v245 offset:21504
	ds_read_b128 v[168:171], v245 offset:22528
	ds_read_b128 v[176:179], v245 offset:23552
	global_load_lds_dwordx4 v[220:221], off
	s_add_i32 m0, s52, 0x2000
	s_add_u32 s52, s12, 0x40000
	v_lshl_add_u64 v[222:223], s[12:13], 0, v[198:199]
	s_addc_u32 s53, s13, 0
	s_add_i32 s68, s79, s62
	global_load_lds_dwordx4 v[222:223], off
	v_lshl_add_u64 v[208:209], s[52:53], 0, v[194:195]
	s_mov_b32 m0, s68
	v_lshl_add_u64 v[224:225], s[58:59], 0, v[192:193]
	global_load_lds_dwordx4 v[208:209], off
	v_lshl_add_u64 v[208:209], s[52:53], 0, v[198:199]
	s_add_i32 m0, s68, 0x2000
	v_lshl_add_u64 v[226:227], s[58:59], 0, v[196:197]
	global_load_lds_dwordx4 v[208:209], off
	s_mov_b32 m0, s63
	s_nop 0
	global_load_lds_dwordx4 v[224:225], off
	s_mov_b32 m0, s64
	s_nop 0
	global_load_lds_dwordx4 v[226:227], off
	s_waitcnt vmcnt(8)
	s_waitcnt lgkmcnt(0)
	s_barrier
; #define PG8_STAGE(bufoff, gbase, voff) do { _Pragma("unroll") for (int _i = 0; _i < 2; ++_i) \
;         __builtin_amdgcn_global_load_lds((const unsigned*)((const char*)(gbase) + (voff)[_i]), (PG8_LAS unsigned*)(lds + (bufoff) + ldsw + _i * 8192), 16, 0, 0); } while (0)
; #define PG8_LDA(dst, b, h) do { _Pragma("unroll") for (int m = 0; m < 4; ++m) _Pragma("unroll") for (int k = 0; k < 2; ++k) dst[m][k] = *(const PG8_LAS bf16x8*)(lds + PG8_SA(b, h) + aoff + m * 2048 + k * 1024); } while (0)
; #define PG8_LDB(dst, b, h) do { _Pragma("unroll") for (int n = 0; n < 2; ++n) _Pragma("unroll") for (int k = 0; k < 2; ++k) dst[n][k] = *(const PG8_LAS bf16x8*)(lds + PG8_SB(b, h) + boff + n * 2048 + k * 1024); } while (0)
; #define PG8_MMA(ai, bj, At, Bt) do { __builtin_amdgcn_s_setprio(1); _Pragma("unroll") for (int m = 0; m < 4; ++m) _Pragma("unroll") for (int n = 0; n < 2; ++n) _Pragma("unroll") for (int k = 0; k < 2; ++k) \
;         acc[ai][bj][m][n] = __builtin_amdgcn_mfma_f32_16x16x32_bf16(Bt[n][k], At[m][k], acc[ai][bj][m][n], 0, 0, 0); __builtin_amdgcn_s_setprio(0); } while (0)
; #define PG8_WAIT_V(n) asm volatile("s_waitcnt vmcnt(" #n ")" ::: "memory")
; #define PG8_WAIT_L(n) asm volatile("s_waitcnt lgkmcnt(" #n ")" ::: "memory")
; #define PG8_BAR __builtin_amdgcn_s_barrier()
; #define PG8_SCHED __builtin_amdgcn_sched_barrier(0)
; template <class Epi, class Sched, bool ALIGN_EPI = true, bool SP2 = true>
; __device__ __forceinline__ void gemm_phase(PG8_LAS unsigned char* lds, const Gemm g, const Sched& S, const Epi& E) {
;     ...
;             PG8_WAIT_V(8); PG8_WAIT_L(0); PG8_BAR; PG8_MMA(1, 0, At, B0); PG8_MMA(1, 1, At, B1); PG8_BAR; PG8_SCHED;
;             PG8_LDB(B0, 1, 0); PG8_LDB(B1, 1, 1); PG8_SCHED; PG8_LDA(At, 1, 0); PG8_STAGE(PG8_SA(0, 1), a2 + hstepA, voffA);
;             PG8_WAIT_V(8); PG8_WAIT_L(0); PG8_BAR; PG8_MMA(0, 0, At, B0); PG8_MMA(0, 1, At, B1); PG8_BAR; PG8_SCHED;
	s_setprio 1
	v_mfma_f32_16x16x32_bf16 v[60:63], v[84:87], v[140:143], v[60:63]
	v_mfma_f32_16x16x32_bf16 v[52:55], v[92:95], v[140:143], v[52:55]
	v_mfma_f32_16x16x32_bf16 v[44:47], v[84:87], v[148:151], v[44:47]
	v_mfma_f32_16x16x32_bf16 v[36:39], v[92:95], v[148:151], v[36:39]
	v_mfma_f32_16x16x32_bf16 v[28:31], v[84:87], v[156:159], v[28:31]
	v_mfma_f32_16x16x32_bf16 v[12:15], v[92:95], v[156:159], v[12:15]
	v_mfma_f32_16x16x32_bf16 v[24:27], v[84:87], v[168:171], v[24:27]
	v_mfma_f32_16x16x32_bf16 v[8:11], v[92:95], v[168:171], v[8:11]
	v_mfma_f32_16x16x32_bf16 v[60:63], v[88:91], v[144:147], v[60:63]
	v_mfma_f32_16x16x32_bf16 v[52:55], v[96:99], v[144:147], v[52:55]
	v_mfma_f32_16x16x32_bf16 v[44:47], v[88:91], v[152:155], v[44:47]
	v_mfma_f32_16x16x32_bf16 v[36:39], v[96:99], v[152:155], v[36:39]
	v_mfma_f32_16x16x32_bf16 v[28:31], v[88:91], v[160:163], v[28:31]
	v_mfma_f32_16x16x32_bf16 v[12:15], v[96:99], v[160:163], v[12:15]
	v_mfma_f32_16x16x32_bf16 v[24:27], v[88:91], v[176:179], v[24:27]
	v_mfma_f32_16x16x32_bf16 v[8:11], v[96:99], v[176:179], v[8:11]
	v_mfma_f32_16x16x32_bf16 v[56:59], v[100:103], v[140:143], v[56:59]
	v_mfma_f32_16x16x32_bf16 v[48:51], v[108:111], v[140:143], v[48:51]
	v_mfma_f32_16x16x32_bf16 v[40:43], v[100:103], v[148:151], v[40:43]
	v_mfma_f32_16x16x32_bf16 v[32:35], v[108:111], v[148:151], v[32:35]
	v_mfma_f32_16x16x32_bf16 v[20:23], v[100:103], v[156:159], v[20:23]
	v_mfma_f32_16x16x32_bf16 v[4:7], v[108:111], v[156:159], v[4:7]
	v_mfma_f32_16x16x32_bf16 v[16:19], v[100:103], v[168:171], v[16:19]
	v_mfma_f32_16x16x32_bf16 v[0:3], v[108:111], v[168:171], v[0:3]
	v_mfma_f32_16x16x32_bf16 v[56:59], v[104:107], v[144:147], v[56:59]
	v_mfma_f32_16x16x32_bf16 v[48:51], v[112:115], v[144:147], v[48:51]
	v_mfma_f32_16x16x32_bf16 v[40:43], v[104:107], v[152:155], v[40:43]
	v_mfma_f32_16x16x32_bf16 v[32:35], v[112:115], v[152:155], v[32:35]
	v_mfma_f32_16x16x32_bf16 v[20:23], v[104:107], v[160:163], v[20:23]
	v_mfma_f32_16x16x32_bf16 v[4:7], v[112:115], v[160:163], v[4:7]
	v_mfma_f32_16x16x32_bf16 v[16:19], v[104:107], v[176:179], v[16:19]
	v_mfma_f32_16x16x32_bf16 v[0:3], v[112:115], v[176:179], v[0:3]
	s_setprio 0
	s_barrier
	s_add_i32 s68, 0, 0x18000
	s_add_i32 s69, 0, 0x1c000
	v_add_u32_e32 v96, s68, v242
	v_add_u32_e32 v112, s69, v242
	ds_read_b128 v[84:87], v96
	ds_read_b128 v[88:91], v96 offset:1024
	ds_read_b128 v[92:95], v96 offset:2048
	ds_read_b128 v[96:99], v96 offset:3072
	ds_read_b128 v[100:103], v112
	ds_read_b128 v[104:107], v112 offset:1024
	ds_read_b128 v[108:111], v112 offset:2048
	ds_read_b128 v[112:115], v112 offset:3072
	s_add_u32 s52, s58, 0x40000
	s_addc_u32 s53, s59, 0
	s_mov_b32 m0, s65
	v_lshl_add_u64 v[160:161], s[52:53], 0, v[192:193]
	ds_read_b128 v[140:143], v245 offset:32768
	ds_read_b128 v[144:147], v245 offset:33792
	ds_read_b128 v[148:151], v245 offset:34816
	ds_read_b128 v[152:155], v245 offset:35840
	ds_read_b128 v[156:159], v245 offset:36864
	ds_read_b128 v[208:211], v245 offset:37888
	ds_read_b128 v[212:215], v245 offset:38912
	ds_read_b128 v[216:219], v245 offset:39936
	global_load_lds_dwordx4 v[160:161], off
	v_lshl_add_u64 v[160:161], s[52:53], 0, v[196:197]
	s_mov_b32 m0, s66
	s_nop 0
	global_load_lds_dwordx4 v[160:161], off
	s_waitcnt vmcnt(8)
	s_waitcnt lgkmcnt(0)
	s_barrier
	s_setprio 1
	v_mfma_f32_16x16x32_bf16 v[160:163], v[84:87], v[140:143], v[188:191]
	v_mfma_f32_16x16x32_bf16 v[188:191], v[88:91], v[144:147], v[160:163]
	v_mfma_f32_16x16x32_bf16 v[160:163], v[92:95], v[140:143], v[180:183]
	v_mfma_f32_16x16x32_bf16 v[180:183], v[96:99], v[144:147], v[160:163]
	v_mfma_f32_16x16x32_bf16 v[160:163], v[84:87], v[148:151], v[172:175]
	v_mfma_f32_16x16x32_bf16 v[172:175], v[88:91], v[152:155], v[160:163]
	v_mfma_f32_16x16x32_bf16 v[160:163], v[92:95], v[148:151], v[164:167]
	v_mfma_f32_16x16x32_bf16 v[124:127], v[84:87], v[156:159], v[124:127]
	v_mfma_f32_16x16x32_bf16 v[76:79], v[92:95], v[156:159], v[76:79]
	v_mfma_f32_16x16x32_bf16 v[120:123], v[84:87], v[212:215], v[120:123]
	v_mfma_f32_16x16x32_bf16 v[72:75], v[92:95], v[212:215], v[72:75]
	v_mfma_f32_16x16x32_bf16 v[164:167], v[96:99], v[152:155], v[160:163]
	v_mfma_f32_16x16x32_bf16 v[124:127], v[88:91], v[208:211], v[124:127]
	v_mfma_f32_16x16x32_bf16 v[76:79], v[96:99], v[208:211], v[76:79]
	v_mfma_f32_16x16x32_bf16 v[120:123], v[88:91], v[216:219], v[120:123]
	v_mfma_f32_16x16x32_bf16 v[72:75], v[96:99], v[216:219], v[72:75]
	v_mfma_f32_16x16x32_bf16 v[128:131], v[108:111], v[140:143], v[128:131]
	v_mfma_f32_16x16x32_bf16 v[176:179], v[112:115], v[144:147], v[128:131]
	v_mfma_f32_16x16x32_bf16 v[128:131], v[100:103], v[148:151], v[132:135]
	v_mfma_f32_16x16x32_bf16 v[160:163], v[100:103], v[140:143], v[184:187]
	v_mfma_f32_16x16x32_bf16 v[168:171], v[104:107], v[152:155], v[128:131]
	v_mfma_f32_16x16x32_bf16 v[128:131], v[108:111], v[148:151], v[136:139]
	v_mfma_f32_16x16x32_bf16 v[116:119], v[100:103], v[156:159], v[116:119]
	v_mfma_f32_16x16x32_bf16 v[68:71], v[108:111], v[156:159], v[68:71]
	v_mfma_f32_16x16x32_bf16 v[80:83], v[100:103], v[212:215], v[80:83]
	v_mfma_f32_16x16x32_bf16 v[64:67], v[108:111], v[212:215], v[64:67]
	v_mfma_f32_16x16x32_bf16 v[184:187], v[104:107], v[144:147], v[160:163]
	v_mfma_f32_16x16x32_bf16 v[160:163], v[112:115], v[152:155], v[128:131]
	v_mfma_f32_16x16x32_bf16 v[116:119], v[104:107], v[208:211], v[116:119]
	v_mfma_f32_16x16x32_bf16 v[68:71], v[112:115], v[208:211], v[68:71]
	v_mfma_f32_16x16x32_bf16 v[80:83], v[104:107], v[216:219], v[80:83]
	v_mfma_f32_16x16x32_bf16 v[64:67], v[112:115], v[216:219], v[64:67]
	s_setprio 0
	s_barrier
; #define PG8_STAGE(bufoff, gbase, voff) do { _Pragma("unroll") for (int _i = 0; _i < 2; ++_i) \
;         __builtin_amdgcn_global_load_lds((const unsigned*)((const char*)(gbase) + (voff)[_i]), (PG8_LAS unsigned*)(lds + (bufoff) + ldsw + _i * 8192), 16, 0, 0); } while (0)
; #define PG8_LDA(dst, b, h) do { _Pragma("unroll") for (int m = 0; m < 4; ++m) _Pragma("unroll") for (int k = 0; k < 2; ++k) dst[m][k] = *(const PG8_LAS bf16x8*)(lds + PG8_SA(b, h) + aoff + m * 2048 + k * 1024); } while (0)
; #define PG8_MMA(ai, bj, At, Bt) do { __builtin_amdgcn_s_setprio(1); _Pragma("unroll") for (int m = 0; m < 4; ++m) _Pragma("unroll") for (int n = 0; n < 2; ++n) _Pragma("unroll") for (int k = 0; k < 2; ++k) \
;         acc[ai][bj][m][n] = __builtin_amdgcn_mfma_f32_16x16x32_bf16(Bt[n][k], At[m][k], acc[ai][bj][m][n], 0, 0, 0); __builtin_amdgcn_s_setprio(0); } while (0)
; #define PG8_WAIT_V(n) asm volatile("s_waitcnt vmcnt(" #n ")" ::: "memory")
; #define PG8_WAIT_L(n) asm volatile("s_waitcnt lgkmcnt(" #n ")" ::: "memory")
; #define PG8_BAR __builtin_amdgcn_s_barrier()
; #define PG8_SCHED __builtin_amdgcn_sched_barrier(0)
; template <class Epi, class Sched, bool ALIGN_EPI = true, bool SP2 = true>
; __device__ __forceinline__ void gemm_phase(PG8_LAS unsigned char* lds, const Gemm g, const Sched& S, const Epi& E) {
;     ...
;             PG8_LDA(At, 1, 1); PG8_STAGE(PG8_SB(1, 0), b3, voffB); PG8_STAGE(PG8_SB(1, 1), b3 + hstepB, voffB); PG8_STAGE(PG8_SA(1, 0), a3, voffA);
;             PG8_WAIT_V(8); PG8_WAIT_L(0); PG8_BAR; PG8_MMA(1, 0, At, B0); PG8_MMA(1, 1, At, B1); PG8_BAR; PG8_SCHED;
;         }
	s_add_i32 s52, s68, s62
	v_lshl_add_u64 v[208:209], v[220:221], 0, s[24:25]
	s_mov_b32 m0, s52
	ds_read_b128 v[128:131], v245 offset:49152
	ds_read_b128 v[132:135], v245 offset:50176
	ds_read_b128 v[136:139], v245 offset:51200
	ds_read_b128 v[140:143], v245 offset:52224
	ds_read_b128 v[144:147], v245 offset:53248
	ds_read_b128 v[148:151], v245 offset:54272
	ds_read_b128 v[152:155], v245 offset:55296
	ds_read_b128 v[156:159], v245 offset:56320
	global_load_lds_dwordx4 v[208:209], off
	s_add_i32 m0, s52, 0x2000
	s_add_u32 s12, s12, 0x40080
	v_lshl_add_u64 v[208:209], v[222:223], 0, s[24:25]
	s_addc_u32 s13, s13, 0
	s_add_i32 s52, s69, s62
	global_load_lds_dwordx4 v[208:209], off
	v_lshl_add_u64 v[208:209], s[12:13], 0, v[194:195]
	s_mov_b32 m0, s52
	s_nop 0
	global_load_lds_dwordx4 v[208:209], off
	v_lshl_add_u64 v[208:209], s[12:13], 0, v[198:199]
	s_add_i32 m0, s52, 0x2000
	s_nop 0
	global_load_lds_dwordx4 v[208:209], off
	v_lshl_add_u64 v[208:209], v[224:225], 0, s[24:25]
	s_mov_b32 m0, s72
	s_nop 0
	global_load_lds_dwordx4 v[208:209], off
	v_lshl_add_u64 v[208:209], v[226:227], 0, s[24:25]
	s_mov_b32 m0, s73
	s_nop 0
	global_load_lds_dwordx4 v[208:209], off
	s_waitcnt vmcnt(8)
	s_waitcnt lgkmcnt(0)
	s_barrier
	s_setprio 1
	v_mfma_f32_16x16x32_bf16 v[60:63], v[84:87], v[128:131], v[60:63]
	v_mfma_f32_16x16x32_bf16 v[52:55], v[92:95], v[128:131], v[52:55]
	v_mfma_f32_16x16x32_bf16 v[44:47], v[84:87], v[136:139], v[44:47]
	v_mfma_f32_16x16x32_bf16 v[36:39], v[92:95], v[136:139], v[36:39]
	v_mfma_f32_16x16x32_bf16 v[28:31], v[84:87], v[144:147], v[28:31]
	v_mfma_f32_16x16x32_bf16 v[12:15], v[92:95], v[144:147], v[12:15]
	v_mfma_f32_16x16x32_bf16 v[24:27], v[84:87], v[152:155], v[24:27]
	v_mfma_f32_16x16x32_bf16 v[8:11], v[92:95], v[152:155], v[8:11]
	v_mfma_f32_16x16x32_bf16 v[60:63], v[88:91], v[132:135], v[60:63]
	v_mfma_f32_16x16x32_bf16 v[52:55], v[96:99], v[132:135], v[52:55]
	v_mfma_f32_16x16x32_bf16 v[44:47], v[88:91], v[140:143], v[44:47]
	v_mfma_f32_16x16x32_bf16 v[36:39], v[96:99], v[140:143], v[36:39]
	v_mfma_f32_16x16x32_bf16 v[28:31], v[88:91], v[148:151], v[28:31]
	v_mfma_f32_16x16x32_bf16 v[12:15], v[96:99], v[148:151], v[12:15]
	v_mfma_f32_16x16x32_bf16 v[24:27], v[88:91], v[156:159], v[24:27]
	v_mfma_f32_16x16x32_bf16 v[8:11], v[96:99], v[156:159], v[8:11]
	v_mfma_f32_16x16x32_bf16 v[56:59], v[100:103], v[128:131], v[56:59]
	v_mfma_f32_16x16x32_bf16 v[48:51], v[108:111], v[128:131], v[48:51]
	v_mfma_f32_16x16x32_bf16 v[40:43], v[100:103], v[136:139], v[40:43]
	v_mfma_f32_16x16x32_bf16 v[32:35], v[108:111], v[136:139], v[32:35]
	v_mfma_f32_16x16x32_bf16 v[20:23], v[100:103], v[144:147], v[20:23]
	v_mfma_f32_16x16x32_bf16 v[4:7], v[108:111], v[144:147], v[4:7]
	v_mfma_f32_16x16x32_bf16 v[16:19], v[100:103], v[152:155], v[16:19]
	v_mfma_f32_16x16x32_bf16 v[0:3], v[108:111], v[152:155], v[0:3]
	v_mfma_f32_16x16x32_bf16 v[56:59], v[104:107], v[132:135], v[56:59]
	v_mfma_f32_16x16x32_bf16 v[48:51], v[112:115], v[132:135], v[48:51]
	v_mfma_f32_16x16x32_bf16 v[40:43], v[104:107], v[140:143], v[40:43]
	v_mfma_f32_16x16x32_bf16 v[32:35], v[112:115], v[140:143], v[32:35]
	v_mfma_f32_16x16x32_bf16 v[20:23], v[104:107], v[148:151], v[20:23]
	v_mfma_f32_16x16x32_bf16 v[4:7], v[112:115], v[148:151], v[4:7]
	v_mfma_f32_16x16x32_bf16 v[16:19], v[104:107], v[156:159], v[16:19]
	v_mfma_f32_16x16x32_bf16 v[0:3], v[112:115], v[156:159], v[0:3]
	s_setprio 0
	s_barrier
	s_add_i32 s84, s84, 2
	s_add_u32 s60, s60, 0x100
	s_addc_u32 s61, s61, 0
	s_add_u32 s8, s8, 0x100
	s_addc_u32 s9, s9, 0
	s_cmp_gt_u32 s84, 13
	s_cbranch_scc0 .LBB0_1445
	s_and_b64 vcc, exec, s[26:27]
	s_cbranch_vccz .LBB0_1448
	s_barrier

; #define PG8_STAGE(bufoff, gbase, voff) do { _Pragma("unroll") for (int _i = 0; _i < 2; ++_i) \
;         __builtin_amdgcn_global_load_lds((const unsigned*)((const char*)(gbase) + (voff)[_i]), (PG8_LAS unsigned*)(lds + (bufoff) + ldsw + _i * 8192), 16, 0, 0); } while (0)
; #define PG8_LDA(dst, b, h) do { _Pragma("unroll") for (int m = 0; m < 4; ++m) _Pragma("unroll") for (int k = 0; k < 2; ++k) dst[m][k] = *(const PG8_LAS bf16x8*)(lds + PG8_SA(b, h) + aoff + m * 2048 + k * 1024); } while (0)
; #define PG8_LDB(dst, b, h) do { _Pragma("unroll") for (int n = 0; n < 2; ++n) _Pragma("unroll") for (int k = 0; k < 2; ++k) dst[n][k] = *(const PG8_LAS bf16x8*)(lds + PG8_SB(b, h) + boff + n * 2048 + k * 1024); } while (0)
; #define PG8_MMA(ai, bj, At, Bt) do { __builtin_amdgcn_s_setprio(1); _Pragma("unroll") for (int m = 0; m < 4; ++m) _Pragma("unroll") for (int n = 0; n < 2; ++n) _Pragma("unroll") for (int k = 0; k < 2; ++k) \
;         acc[ai][bj][m][n] = __builtin_amdgcn_mfma_f32_16x16x32_bf16(Bt[n][k], At[m][k], acc[ai][bj][m][n], 0, 0, 0); __builtin_amdgcn_s_setprio(0); } while (0)
; #define PG8_WAIT_V(n) asm volatile("s_waitcnt vmcnt(" #n ")" ::: "memory")
; #define PG8_WAIT_L(n) asm volatile("s_waitcnt lgkmcnt(" #n ")" ::: "memory")
; #define PG8_BAR __builtin_amdgcn_s_barrier()
; #define PG8_SCHED __builtin_amdgcn_sched_barrier(0)
; template <class Epi, class Sched, bool ALIGN_EPI = true, bool SP2 = true>
; __device__ __forceinline__ void gemm_phase(PG8_LAS unsigned char* lds, const Gemm g, const Sched& S, const Epi& E) {
;     ...
;             const char* a1 = cA + (size_t)(t + 1) * kstep;
;             const char* a2 = last ? nA : cA + (size_t)(t + 2) * kstep; const char* b2 = last ? nB : cB + (size_t)(t + 2) * kstep;
;             const char* a3 = a2 + kstep; const char* b3 = b2 + kstep;
;             PG8_LDB(B0, 0, 0); PG8_LDB(B1, 0, 1); PG8_SCHED; PG8_LDA(At, 0, 0); PG8_STAGE(PG8_SA(1, 1), a1 + hstepA, voffA);
;             PG8_WAIT_V(8); PG8_WAIT_L(0); PG8_BAR; PG8_MMA(0, 0, At, B0); PG8_MMA(0, 1, At, B1); PG8_BAR; PG8_SCHED;
;             PG8_LDA(At, 0, 1); PG8_STAGE(PG8_SB(0, 0), b2, voffB); PG8_STAGE(PG8_SB(0, 1), b2 + hstepB, voffB); PG8_STAGE(PG8_SA(0, 0), a2, voffA);
;             PG8_WAIT_V(8); PG8_WAIT_L(0); PG8_BAR; PG8_MMA(1, 0, At, B0); PG8_MMA(1, 1, At, B1); PG8_BAR; PG8_SCHED;
.LBB0_1530:
	s_add_u32 s47, s34, s46
	s_addc_u32 s52, s35, 0
	s_add_u32 s50, s47, 0x100
	s_addc_u32 s51, s52, 0
	s_and_b64 s[48:49], s[42:43], exec
	s_cselect_b32 s49, s23, s51
	s_cselect_b32 s48, s80, s50
	s_add_u32 s46, s28, s46
	s_addc_u32 s50, s29, 0
	s_add_u32 s46, s46, 0x100
	s_addc_u32 s50, s50, 0
	s_add_i32 s53, 0, 0x10000
	s_and_b64 s[42:43], s[42:43], exec
	s_cselect_b32 s51, s21, s50
	s_cselect_b32 s50, s81, s46
	s_add_i32 s43, 0, 0x14000
	s_add_u32 s56, s47, 0x40080
	s_addc_u32 s57, s52, 0
	s_add_i32 s89, s53, s71
	s_add_i32 m0, s27, 0xc000
	s_add_i32 s52, s27, 0xe000
	s_add_i32 s86, s89, 0x2000
	v_add_u32_e32 v143, s53, v140
	s_add_u32 s54, s50, 0x40000
	ds_read_b128 v[144:147], v143
	ds_read_b128 v[148:151], v143 offset:1024
	ds_read_b128 v[152:155], v143 offset:2048
	ds_read_b128 v[156:159], v143 offset:3072
	v_add_u32_e32 v143, s43, v140
	s_addc_u32 s55, s51, 0
	s_add_i32 s88, s43, s71
	ds_read_b128 v[160:163], v143
	ds_read_b128 v[164:167], v143 offset:1024
	ds_read_b128 v[168:171], v143 offset:2048
	ds_read_b128 v[172:175], v143 offset:3072
	s_add_i32 s87, s88, 0x2000
	s_add_i32 s85, 0, 0x18000
	s_add_i32 s84, 0, 0x1c000
	s_add_u32 s46, s48, 0x40000
	s_addc_u32 s47, s49, 0
	s_add_i32 s83, s85, s71
	s_add_i32 s82, s83, 0x2000
	s_add_u32 s42, s50, 0x40080
	s_addc_u32 s43, s51, 0
	s_add_i32 s91, s84, s71
	s_add_i32 s90, s91, 0x2000
	v_lshl_add_u64 v[208:209], s[56:57], 0, v[134:135]
	ds_read_b128 v[176:179], v142
	ds_read_b128 v[180:183], v142 offset:1024
	ds_read_b128 v[184:187], v142 offset:2048
	ds_read_b128 v[188:191], v142 offset:3072
	ds_read_b128 v[192:195], v142 offset:4096
	ds_read_b128 v[196:199], v142 offset:5120
	ds_read_b128 v[200:203], v142 offset:6144
	ds_read_b128 v[204:207], v142 offset:7168
	global_load_lds_dwordx4 v[208:209], off
	v_lshl_add_u64 v[208:209], s[56:57], 0, v[132:133]
	s_mov_b32 m0, s52
	s_nop 0
	global_load_lds_dwordx4 v[208:209], off
	s_waitcnt vmcnt(8)
	s_waitcnt lgkmcnt(0)
	s_barrier
	s_setprio 1
	v_mfma_f32_16x16x32_bf16 v[124:127], v[144:147], v[176:179], v[124:127]
	v_mfma_f32_16x16x32_bf16 v[120:123], v[152:155], v[176:179], v[120:123]
	v_mfma_f32_16x16x32_bf16 v[116:119], v[144:147], v[184:187], v[116:119]
	v_mfma_f32_16x16x32_bf16 v[112:115], v[152:155], v[184:187], v[112:115]
	v_mfma_f32_16x16x32_bf16 v[100:103], v[144:147], v[192:195], v[100:103]
	v_mfma_f32_16x16x32_bf16 v[96:99], v[152:155], v[192:195], v[96:99]
	v_mfma_f32_16x16x32_bf16 v[84:87], v[144:147], v[200:203], v[84:87]
	v_mfma_f32_16x16x32_bf16 v[80:83], v[152:155], v[200:203], v[80:83]
	v_mfma_f32_16x16x32_bf16 v[124:127], v[148:151], v[180:183], v[124:127]
	v_mfma_f32_16x16x32_bf16 v[120:123], v[156:159], v[180:183], v[120:123]
	v_mfma_f32_16x16x32_bf16 v[116:119], v[148:151], v[188:191], v[116:119]
	v_mfma_f32_16x16x32_bf16 v[112:115], v[156:159], v[188:191], v[112:115]
	v_mfma_f32_16x16x32_bf16 v[100:103], v[148:151], v[196:199], v[100:103]
	v_mfma_f32_16x16x32_bf16 v[96:99], v[156:159], v[196:199], v[96:99]
	v_mfma_f32_16x16x32_bf16 v[84:87], v[148:151], v[204:207], v[84:87]
	v_mfma_f32_16x16x32_bf16 v[80:83], v[156:159], v[204:207], v[80:83]
	v_mfma_f32_16x16x32_bf16 v[108:111], v[160:163], v[176:179], v[108:111]
	v_mfma_f32_16x16x32_bf16 v[104:107], v[168:171], v[176:179], v[104:107]
	v_mfma_f32_16x16x32_bf16 v[92:95], v[160:163], v[184:187], v[92:95]
	v_mfma_f32_16x16x32_bf16 v[88:91], v[168:171], v[184:187], v[88:91]
	v_mfma_f32_16x16x32_bf16 v[76:79], v[160:163], v[192:195], v[76:79]
	v_mfma_f32_16x16x32_bf16 v[72:75], v[168:171], v[192:195], v[72:75]
	v_mfma_f32_16x16x32_bf16 v[68:71], v[160:163], v[200:203], v[68:71]
	v_mfma_f32_16x16x32_bf16 v[64:67], v[168:171], v[200:203], v[64:67]
	v_mfma_f32_16x16x32_bf16 v[108:111], v[164:167], v[180:183], v[108:111]
	v_mfma_f32_16x16x32_bf16 v[104:107], v[172:175], v[180:183], v[104:107]
	v_mfma_f32_16x16x32_bf16 v[92:95], v[164:167], v[188:191], v[92:95]
	v_mfma_f32_16x16x32_bf16 v[88:91], v[172:175], v[188:191], v[88:91]
	v_mfma_f32_16x16x32_bf16 v[76:79], v[164:167], v[196:199], v[76:79]
	v_mfma_f32_16x16x32_bf16 v[72:75], v[172:175], v[196:199], v[72:75]
	v_mfma_f32_16x16x32_bf16 v[68:71], v[164:167], v[204:207], v[68:71]
	v_mfma_f32_16x16x32_bf16 v[64:67], v[172:175], v[204:207], v[64:67]
	s_setprio 0
	s_barrier
	s_mov_b32 m0, s89
	v_lshl_add_u64 v[208:209], s[50:51], 0, v[128:129]
	ds_read_b128 v[176:179], v142 offset:16384
	ds_read_b128 v[180:183], v142 offset:17408
	ds_read_b128 v[184:187], v142 offset:18432
	ds_read_b128 v[188:191], v142 offset:19456
	ds_read_b128 v[192:195], v142 offset:20480
	ds_read_b128 v[196:199], v142 offset:21504
	ds_read_b128 v[200:203], v142 offset:22528
	ds_read_b128 v[204:207], v142 offset:23552
	global_load_lds_dwordx4 v[208:209], off
	v_lshl_add_u64 v[210:211], s[50:51], 0, v[130:131]
	s_mov_b32 m0, s86
	v_lshl_add_u64 v[212:213], s[54:55], 0, v[128:129]
	global_load_lds_dwordx4 v[210:211], off
	s_mov_b32 m0, s88
	v_lshl_add_u64 v[214:215], s[48:49], 0, v[132:133]
	global_load_lds_dwordx4 v[212:213], off
	v_lshl_add_u64 v[212:213], s[54:55], 0, v[130:131]
	s_mov_b32 m0, s87
	s_nop 0
	global_load_lds_dwordx4 v[212:213], off
	v_lshl_add_u64 v[212:213], s[48:49], 0, v[134:135]
	s_mov_b32 m0, s27
	s_nop 0
	global_load_lds_dwordx4 v[212:213], off
	s_mov_b32 m0, s73
	s_nop 0
	global_load_lds_dwordx4 v[214:215], off
	s_waitcnt vmcnt(8)
	s_waitcnt lgkmcnt(0)
	s_barrier
; #define PG8_STAGE(bufoff, gbase, voff) do { _Pragma("unroll") for (int _i = 0; _i < 2; ++_i) \
;         __builtin_amdgcn_global_load_lds((const unsigned*)((const char*)(gbase) + (voff)[_i]), (PG8_LAS unsigned*)(lds + (bufoff) + ldsw + _i * 8192), 16, 0, 0); } while (0)
; #define PG8_LDA(dst, b, h) do { _Pragma("unroll") for (int m = 0; m < 4; ++m) _Pragma("unroll") for (int k = 0; k < 2; ++k) dst[m][k] = *(const PG8_LAS bf16x8*)(lds + PG8_SA(b, h) + aoff + m * 2048 + k * 1024); } while (0)
; #define PG8_LDB(dst, b, h) do { _Pragma("unroll") for (int n = 0; n < 2; ++n) _Pragma("unroll") for (int k = 0; k < 2; ++k) dst[n][k] = *(const PG8_LAS bf16x8*)(lds + PG8_SB(b, h) + boff + n * 2048 + k * 1024); } while (0)
; #define PG8_MMA(ai, bj, At, Bt) do { __builtin_amdgcn_s_setprio(1); _Pragma("unroll") for (int m = 0; m < 4; ++m) _Pragma("unroll") for (int n = 0; n < 2; ++n) _Pragma("unroll") for (int k = 0; k < 2; ++k) \
;         acc[ai][bj][m][n] = __builtin_amdgcn_mfma_f32_16x16x32_bf16(Bt[n][k], At[m][k], acc[ai][bj][m][n], 0, 0, 0); __builtin_amdgcn_s_setprio(0); } while (0)
; #define PG8_WAIT_V(n) asm volatile("s_waitcnt vmcnt(" #n ")" ::: "memory")
; #define PG8_WAIT_L(n) asm volatile("s_waitcnt lgkmcnt(" #n ")" ::: "memory")
; #define PG8_BAR __builtin_amdgcn_s_barrier()
; #define PG8_SCHED __builtin_amdgcn_sched_barrier(0)
; template <class Epi, class Sched, bool ALIGN_EPI = true, bool SP2 = true>
; __device__ __forceinline__ void gemm_phase(PG8_LAS unsigned char* lds, const Gemm g, const Sched& S, const Epi& E) {
;     ...
;             PG8_WAIT_V(8); PG8_WAIT_L(0); PG8_BAR; PG8_MMA(1, 0, At, B0); PG8_MMA(1, 1, At, B1); PG8_BAR; PG8_SCHED;
;             PG8_LDB(B0, 1, 0); PG8_LDB(B1, 1, 1); PG8_SCHED; PG8_LDA(At, 1, 0); PG8_STAGE(PG8_SA(0, 1), a2 + hstepA, voffA);
;             PG8_WAIT_V(8); PG8_WAIT_L(0); PG8_BAR; PG8_MMA(0, 0, At, B0); PG8_MMA(0, 1, At, B1); PG8_BAR; PG8_SCHED;
	s_setprio 1
	v_mfma_f32_16x16x32_bf16 v[60:63], v[144:147], v[176:179], v[60:63]
	v_mfma_f32_16x16x32_bf16 v[56:59], v[152:155], v[176:179], v[56:59]
	v_mfma_f32_16x16x32_bf16 v[52:55], v[144:147], v[184:187], v[52:55]
	v_mfma_f32_16x16x32_bf16 v[48:51], v[152:155], v[184:187], v[48:51]
	v_mfma_f32_16x16x32_bf16 v[36:39], v[144:147], v[192:195], v[36:39]
	v_mfma_f32_16x16x32_bf16 v[32:35], v[152:155], v[192:195], v[32:35]
	v_mfma_f32_16x16x32_bf16 v[20:23], v[144:147], v[200:203], v[20:23]
	v_mfma_f32_16x16x32_bf16 v[16:19], v[152:155], v[200:203], v[16:19]
	v_mfma_f32_16x16x32_bf16 v[60:63], v[148:151], v[180:183], v[60:63]
	v_mfma_f32_16x16x32_bf16 v[56:59], v[156:159], v[180:183], v[56:59]
	v_mfma_f32_16x16x32_bf16 v[52:55], v[148:151], v[188:191], v[52:55]
	v_mfma_f32_16x16x32_bf16 v[48:51], v[156:159], v[188:191], v[48:51]
	v_mfma_f32_16x16x32_bf16 v[36:39], v[148:151], v[196:199], v[36:39]
	v_mfma_f32_16x16x32_bf16 v[32:35], v[156:159], v[196:199], v[32:35]
	v_mfma_f32_16x16x32_bf16 v[20:23], v[148:151], v[204:207], v[20:23]
	v_mfma_f32_16x16x32_bf16 v[16:19], v[156:159], v[204:207], v[16:19]
	v_mfma_f32_16x16x32_bf16 v[44:47], v[160:163], v[176:179], v[44:47]
	v_mfma_f32_16x16x32_bf16 v[40:43], v[168:171], v[176:179], v[40:43]
	v_mfma_f32_16x16x32_bf16 v[28:31], v[160:163], v[184:187], v[28:31]
	v_mfma_f32_16x16x32_bf16 v[24:27], v[168:171], v[184:187], v[24:27]
	v_mfma_f32_16x16x32_bf16 v[12:15], v[160:163], v[192:195], v[12:15]
	v_mfma_f32_16x16x32_bf16 v[8:11], v[168:171], v[192:195], v[8:11]
	v_mfma_f32_16x16x32_bf16 v[4:7], v[160:163], v[200:203], v[4:7]
	v_mfma_f32_16x16x32_bf16 v[0:3], v[168:171], v[200:203], v[0:3]
	v_mfma_f32_16x16x32_bf16 v[44:47], v[164:167], v[180:183], v[44:47]
	v_mfma_f32_16x16x32_bf16 v[40:43], v[172:175], v[180:183], v[40:43]
	v_mfma_f32_16x16x32_bf16 v[28:31], v[164:167], v[188:191], v[28:31]
	v_mfma_f32_16x16x32_bf16 v[24:27], v[172:175], v[188:191], v[24:27]
	v_mfma_f32_16x16x32_bf16 v[12:15], v[164:167], v[196:199], v[12:15]
	v_mfma_f32_16x16x32_bf16 v[8:11], v[172:175], v[196:199], v[8:11]
	v_mfma_f32_16x16x32_bf16 v[4:7], v[164:167], v[204:207], v[4:7]
	v_mfma_f32_16x16x32_bf16 v[0:3], v[172:175], v[204:207], v[0:3]
	s_setprio 0
	s_barrier
	v_add_u32_e32 v143, s85, v140
	ds_read_b128 v[144:147], v143
	ds_read_b128 v[148:151], v143 offset:1024
	ds_read_b128 v[152:155], v143 offset:2048
	ds_read_b128 v[156:159], v143 offset:3072
	v_add_u32_e32 v143, s84, v140
	ds_read_b128 v[160:163], v143
	ds_read_b128 v[164:167], v143 offset:1024
	ds_read_b128 v[168:171], v143 offset:2048
	ds_read_b128 v[172:175], v143 offset:3072
	s_mov_b32 m0, s74
	v_lshl_add_u64 v[216:217], s[46:47], 0, v[134:135]
	ds_read_b128 v[176:179], v142 offset:32768
	ds_read_b128 v[180:183], v142 offset:33792
	ds_read_b128 v[184:187], v142 offset:34816
	ds_read_b128 v[188:191], v142 offset:35840
	ds_read_b128 v[192:195], v142 offset:36864
	ds_read_b128 v[196:199], v142 offset:37888
	ds_read_b128 v[200:203], v142 offset:38912
	ds_read_b128 v[204:207], v142 offset:39936
	global_load_lds_dwordx4 v[216:217], off
	v_lshl_add_u64 v[216:217], s[46:47], 0, v[132:133]
	s_mov_b32 m0, s75
	s_nop 0
	global_load_lds_dwordx4 v[216:217], off
	s_waitcnt vmcnt(8)
	s_waitcnt lgkmcnt(0)
	s_barrier
	s_setprio 1
	v_mfma_f32_16x16x32_bf16 v[124:127], v[144:147], v[176:179], v[124:127]
	v_mfma_f32_16x16x32_bf16 v[120:123], v[152:155], v[176:179], v[120:123]
	v_mfma_f32_16x16x32_bf16 v[116:119], v[144:147], v[184:187], v[116:119]
	v_mfma_f32_16x16x32_bf16 v[112:115], v[152:155], v[184:187], v[112:115]
	v_mfma_f32_16x16x32_bf16 v[100:103], v[144:147], v[192:195], v[100:103]
	v_mfma_f32_16x16x32_bf16 v[96:99], v[152:155], v[192:195], v[96:99]
	v_mfma_f32_16x16x32_bf16 v[84:87], v[144:147], v[200:203], v[84:87]
	v_mfma_f32_16x16x32_bf16 v[80:83], v[152:155], v[200:203], v[80:83]
	v_mfma_f32_16x16x32_bf16 v[124:127], v[148:151], v[180:183], v[124:127]
	v_mfma_f32_16x16x32_bf16 v[120:123], v[156:159], v[180:183], v[120:123]
	v_mfma_f32_16x16x32_bf16 v[116:119], v[148:151], v[188:191], v[116:119]
	v_mfma_f32_16x16x32_bf16 v[112:115], v[156:159], v[188:191], v[112:115]
	v_mfma_f32_16x16x32_bf16 v[100:103], v[148:151], v[196:199], v[100:103]
	v_mfma_f32_16x16x32_bf16 v[96:99], v[156:159], v[196:199], v[96:99]
	v_mfma_f32_16x16x32_bf16 v[84:87], v[148:151], v[204:207], v[84:87]
	v_mfma_f32_16x16x32_bf16 v[80:83], v[156:159], v[204:207], v[80:83]
	v_mfma_f32_16x16x32_bf16 v[108:111], v[160:163], v[176:179], v[108:111]
	v_mfma_f32_16x16x32_bf16 v[104:107], v[168:171], v[176:179], v[104:107]
	v_mfma_f32_16x16x32_bf16 v[92:95], v[160:163], v[184:187], v[92:95]
	v_mfma_f32_16x16x32_bf16 v[88:91], v[168:171], v[184:187], v[88:91]
	v_mfma_f32_16x16x32_bf16 v[76:79], v[160:163], v[192:195], v[76:79]
	v_mfma_f32_16x16x32_bf16 v[72:75], v[168:171], v[192:195], v[72:75]
	v_mfma_f32_16x16x32_bf16 v[68:71], v[160:163], v[200:203], v[68:71]
	v_mfma_f32_16x16x32_bf16 v[64:67], v[168:171], v[200:203], v[64:67]
	v_mfma_f32_16x16x32_bf16 v[108:111], v[164:167], v[180:183], v[108:111]
	v_mfma_f32_16x16x32_bf16 v[104:107], v[172:175], v[180:183], v[104:107]
	v_mfma_f32_16x16x32_bf16 v[92:95], v[164:167], v[188:191], v[92:95]
	v_mfma_f32_16x16x32_bf16 v[88:91], v[172:175], v[188:191], v[88:91]
	v_mfma_f32_16x16x32_bf16 v[76:79], v[164:167], v[196:199], v[76:79]
	v_mfma_f32_16x16x32_bf16 v[72:75], v[172:175], v[196:199], v[72:75]
	v_mfma_f32_16x16x32_bf16 v[68:71], v[164:167], v[204:207], v[68:71]
	v_mfma_f32_16x16x32_bf16 v[64:67], v[172:175], v[204:207], v[64:67]
	s_setprio 0
	s_barrier
; #define PG8_STAGE(bufoff, gbase, voff) do { _Pragma("unroll") for (int _i = 0; _i < 2; ++_i) \
;         __builtin_amdgcn_global_load_lds((const unsigned*)((const char*)(gbase) + (voff)[_i]), (PG8_LAS unsigned*)(lds + (bufoff) + ldsw + _i * 8192), 16, 0, 0); } while (0)
; #define PG8_LDA(dst, b, h) do { _Pragma("unroll") for (int m = 0; m < 4; ++m) _Pragma("unroll") for (int k = 0; k < 2; ++k) dst[m][k] = *(const PG8_LAS bf16x8*)(lds + PG8_SA(b, h) + aoff + m * 2048 + k * 1024); } while (0)
; #define PG8_MMA(ai, bj, At, Bt) do { __builtin_amdgcn_s_setprio(1); _Pragma("unroll") for (int m = 0; m < 4; ++m) _Pragma("unroll") for (int n = 0; n < 2; ++n) _Pragma("unroll") for (int k = 0; k < 2; ++k) \
;         acc[ai][bj][m][n] = __builtin_amdgcn_mfma_f32_16x16x32_bf16(Bt[n][k], At[m][k], acc[ai][bj][m][n], 0, 0, 0); __builtin_amdgcn_s_setprio(0); } while (0)
; #define PG8_WAIT_V(n) asm volatile("s_waitcnt vmcnt(" #n ")" ::: "memory")
; #define PG8_WAIT_L(n) asm volatile("s_waitcnt lgkmcnt(" #n ")" ::: "memory")
; #define PG8_BAR __builtin_amdgcn_s_barrier()
; #define PG8_SCHED __builtin_amdgcn_sched_barrier(0)
; template <class Epi, class Sched, bool ALIGN_EPI = true, bool SP2 = true>
; __device__ __forceinline__ void gemm_phase(PG8_LAS unsigned char* lds, const Gemm g, const Sched& S, const Epi& E) {
;     ...
;             PG8_LDA(At, 1, 1); PG8_STAGE(PG8_SB(1, 0), b3, voffB); PG8_STAGE(PG8_SB(1, 1), b3 + hstepB, voffB); PG8_STAGE(PG8_SA(1, 0), a3, voffA);
;             PG8_WAIT_V(8); PG8_WAIT_L(0); PG8_BAR; PG8_MMA(1, 0, At, B0); PG8_MMA(1, 1, At, B1); PG8_BAR; PG8_SCHED;
;         }
	s_mov_b32 m0, s83
	v_lshl_add_u64 v[208:209], v[208:209], 0, s[4:5]
	ds_read_b128 v[176:179], v142 offset:49152
	ds_read_b128 v[180:183], v142 offset:50176
	ds_read_b128 v[184:187], v142 offset:51200
	ds_read_b128 v[188:191], v142 offset:52224
	ds_read_b128 v[192:195], v142 offset:53248
	ds_read_b128 v[196:199], v142 offset:54272
	ds_read_b128 v[200:203], v142 offset:55296
	ds_read_b128 v[204:207], v142 offset:56320
	global_load_lds_dwordx4 v[208:209], off
	v_lshl_add_u64 v[208:209], v[210:211], 0, s[4:5]
	s_mov_b32 m0, s82
	s_nop 0
	global_load_lds_dwordx4 v[208:209], off
	v_lshl_add_u64 v[208:209], s[42:43], 0, v[128:129]
	s_mov_b32 m0, s91
	s_nop 0
	global_load_lds_dwordx4 v[208:209], off
	v_lshl_add_u64 v[208:209], s[42:43], 0, v[130:131]
	s_mov_b32 m0, s90
	s_nop 0
	global_load_lds_dwordx4 v[208:209], off
	v_lshl_add_u64 v[208:209], v[212:213], 0, s[4:5]
	s_mov_b32 m0, s76
	s_nop 0
	global_load_lds_dwordx4 v[208:209], off
	v_lshl_add_u64 v[208:209], v[214:215], 0, s[4:5]
	s_mov_b32 m0, s77
	s_nop 0
	global_load_lds_dwordx4 v[208:209], off
	s_waitcnt vmcnt(8)
	s_waitcnt lgkmcnt(0)
	s_barrier
	s_setprio 1
	v_mfma_f32_16x16x32_bf16 v[60:63], v[144:147], v[176:179], v[60:63]
	v_mfma_f32_16x16x32_bf16 v[56:59], v[152:155], v[176:179], v[56:59]
	v_mfma_f32_16x16x32_bf16 v[52:55], v[144:147], v[184:187], v[52:55]
	v_mfma_f32_16x16x32_bf16 v[48:51], v[152:155], v[184:187], v[48:51]
	v_mfma_f32_16x16x32_bf16 v[36:39], v[144:147], v[192:195], v[36:39]
	v_mfma_f32_16x16x32_bf16 v[32:35], v[152:155], v[192:195], v[32:35]
	v_mfma_f32_16x16x32_bf16 v[20:23], v[144:147], v[200:203], v[20:23]
	v_mfma_f32_16x16x32_bf16 v[16:19], v[152:155], v[200:203], v[16:19]
	v_mfma_f32_16x16x32_bf16 v[60:63], v[148:151], v[180:183], v[60:63]
	v_mfma_f32_16x16x32_bf16 v[56:59], v[156:159], v[180:183], v[56:59]
	v_mfma_f32_16x16x32_bf16 v[52:55], v[148:151], v[188:191], v[52:55]
	v_mfma_f32_16x16x32_bf16 v[48:51], v[156:159], v[188:191], v[48:51]
	v_mfma_f32_16x16x32_bf16 v[36:39], v[148:151], v[196:199], v[36:39]
	v_mfma_f32_16x16x32_bf16 v[32:35], v[156:159], v[196:199], v[32:35]
	v_mfma_f32_16x16x32_bf16 v[20:23], v[148:151], v[204:207], v[20:23]
	v_mfma_f32_16x16x32_bf16 v[16:19], v[156:159], v[204:207], v[16:19]
	v_mfma_f32_16x16x32_bf16 v[44:47], v[160:163], v[176:179], v[44:47]
	v_mfma_f32_16x16x32_bf16 v[40:43], v[168:171], v[176:179], v[40:43]
	v_mfma_f32_16x16x32_bf16 v[28:31], v[160:163], v[184:187], v[28:31]
	v_mfma_f32_16x16x32_bf16 v[24:27], v[168:171], v[184:187], v[24:27]
	v_mfma_f32_16x16x32_bf16 v[12:15], v[160:163], v[192:195], v[12:15]
	v_mfma_f32_16x16x32_bf16 v[8:11], v[168:171], v[192:195], v[8:11]
	v_mfma_f32_16x16x32_bf16 v[4:7], v[160:163], v[200:203], v[4:7]
	v_mfma_f32_16x16x32_bf16 v[0:3], v[168:171], v[200:203], v[0:3]
	v_mfma_f32_16x16x32_bf16 v[44:47], v[164:167], v[180:183], v[44:47]
	v_mfma_f32_16x16x32_bf16 v[40:43], v[172:175], v[180:183], v[40:43]
	v_mfma_f32_16x16x32_bf16 v[28:31], v[164:167], v[188:191], v[28:31]
	v_mfma_f32_16x16x32_bf16 v[24:27], v[172:175], v[188:191], v[24:27]
	v_mfma_f32_16x16x32_bf16 v[12:15], v[164:167], v[196:199], v[12:15]
	v_mfma_f32_16x16x32_bf16 v[8:11], v[172:175], v[196:199], v[8:11]
	v_mfma_f32_16x16x32_bf16 v[4:7], v[164:167], v[204:207], v[4:7]
	v_mfma_f32_16x16x32_bf16 v[0:3], v[172:175], v[204:207], v[0:3]
	s_setprio 0
	s_barrier
	s_movk_i32 s46, 0x100
	s_andn2_b64 vcc, exec, s[40:41]
	s_mov_b64 s[42:43], -1
	s_mov_b64 s[40:41], 0
	s_cbranch_vccz .LBB0_1530
	s_and_b64 vcc, exec, s[18:19]
	s_cbranch_vccz .LBB0_1533
	s_barrier

; #define PG8_STAGE(bufoff, gbase, voff) do { _Pragma("unroll") for (int _i = 0; _i < 2; ++_i) \
;         __builtin_amdgcn_global_load_lds((const unsigned*)((const char*)(gbase) + (voff)[_i]), (PG8_LAS unsigned*)(lds + (bufoff) + ldsw + _i * 8192), 16, 0, 0); } while (0)
; #define PG8_LDA(dst, b, h) do { _Pragma("unroll") for (int m = 0; m < 4; ++m) _Pragma("unroll") for (int k = 0; k < 2; ++k) dst[m][k] = *(const PG8_LAS bf16x8*)(lds + PG8_SA(b, h) + aoff + m * 2048 + k * 1024); } while (0)
; #define PG8_LDB(dst, b, h) do { _Pragma("unroll") for (int n = 0; n < 2; ++n) _Pragma("unroll") for (int k = 0; k < 2; ++k) dst[n][k] = *(const PG8_LAS bf16x8*)(lds + PG8_SB(b, h) + boff + n * 2048 + k * 1024); } while (0)
; #define PG8_MMA(ai, bj, At, Bt) do { __builtin_amdgcn_s_setprio(1); _Pragma("unroll") for (int m = 0; m < 4; ++m) _Pragma("unroll") for (int n = 0; n < 2; ++n) _Pragma("unroll") for (int k = 0; k < 2; ++k) \
;         acc[ai][bj][m][n] = __builtin_amdgcn_mfma_f32_16x16x32_bf16(Bt[n][k], At[m][k], acc[ai][bj][m][n], 0, 0, 0); __builtin_amdgcn_s_setprio(0); } while (0)
; #define PG8_WAIT_V(n) asm volatile("s_waitcnt vmcnt(" #n ")" ::: "memory")
; #define PG8_WAIT_L(n) asm volatile("s_waitcnt lgkmcnt(" #n ")" ::: "memory")
; #define PG8_BAR __builtin_amdgcn_s_barrier()
; #define PG8_SCHED __builtin_amdgcn_sched_barrier(0)
; template <class Epi, class Sched, bool ALIGN_EPI = true, bool SP2 = true>
; __device__ __forceinline__ void gemm_phase(PG8_LAS unsigned char* lds, const Gemm g, const Sched& S, const Epi& E) {
;     ...
;             PG8_LDB(B0, 0, 0); PG8_LDB(B1, 0, 1); PG8_SCHED; PG8_LDA(At, 0, 0); PG8_STAGE(PG8_SA(1, 1), a1 + hstepA, voffA);
;             PG8_WAIT_V(8); PG8_WAIT_L(0); PG8_BAR; PG8_MMA(0, 0, At, B0); PG8_MMA(0, 1, At, B1); PG8_BAR; PG8_SCHED;
;             PG8_LDA(At, 0, 1); PG8_STAGE(PG8_SB(0, 0), b2, voffB); PG8_STAGE(PG8_SB(0, 1), b2 + hstepB, voffB); PG8_STAGE(PG8_SA(0, 0), a2, voffA);
;             PG8_WAIT_V(8); PG8_WAIT_L(0); PG8_BAR; PG8_MMA(1, 0, At, B0); PG8_MMA(1, 1, At, B1); PG8_BAR; PG8_SCHED;
.LBB0_1620:
	ds_read_b128 v[144:147], v153
	ds_read_b128 v[156:159], v153 offset:1024
	ds_read_b128 v[160:163], v153 offset:2048
	ds_read_b128 v[164:167], v153 offset:3072
	ds_read_b128 v[168:171], v154
	ds_read_b128 v[172:175], v154 offset:1024
	ds_read_b128 v[176:179], v154 offset:2048
	ds_read_b128 v[180:183], v154 offset:3072
	s_add_u32 s26, s24, 0x100
	s_addc_u32 s27, s25, 0
	s_cmp_eq_u32 s63, 40
	s_cselect_b32 s31, s5, s27
	s_cselect_b32 s30, s4, s26
	s_cselect_b32 s29, s23, s62
	s_cselect_b32 s28, s22, s61
	v_lshl_add_u64 v[148:149], s[24:25], 0, v[138:139]
	s_add_i32 m0, s41, 0xc000
	ds_read_b128 v[184:187], v155
	ds_read_b128 v[188:191], v155 offset:1024
	ds_read_b128 v[192:195], v155 offset:2048
	ds_read_b128 v[196:199], v155 offset:3072
	ds_read_b128 v[200:203], v155 offset:4096
	ds_read_b128 v[204:207], v155 offset:5120
	ds_read_b128 v[208:211], v155 offset:6144
	ds_read_b128 v[212:215], v155 offset:7168
	global_load_lds_dwordx4 v[148:149], off
	v_lshl_add_u64 v[148:149], s[24:25], 0, v[136:137]
	s_add_i32 m0, s41, 0xe000
	s_nop 0
	global_load_lds_dwordx4 v[148:149], off
	s_waitcnt vmcnt(8)
	s_waitcnt lgkmcnt(0)
	s_barrier
	s_setprio 1
	v_mfma_f32_16x16x32_bf16 v[124:127], v[144:147], v[184:187], v[124:127]
	v_mfma_f32_16x16x32_bf16 v[120:123], v[160:163], v[184:187], v[120:123]
	v_mfma_f32_16x16x32_bf16 v[108:111], v[144:147], v[192:195], v[108:111]
	v_mfma_f32_16x16x32_bf16 v[104:107], v[160:163], v[192:195], v[104:107]
	v_mfma_f32_16x16x32_bf16 v[92:95], v[144:147], v[200:203], v[92:95]
	v_mfma_f32_16x16x32_bf16 v[88:91], v[160:163], v[200:203], v[88:91]
	v_mfma_f32_16x16x32_bf16 v[76:79], v[144:147], v[208:211], v[76:79]
	v_mfma_f32_16x16x32_bf16 v[72:75], v[160:163], v[208:211], v[72:75]
	v_mfma_f32_16x16x32_bf16 v[124:127], v[156:159], v[188:191], v[124:127]
	v_mfma_f32_16x16x32_bf16 v[120:123], v[164:167], v[188:191], v[120:123]
	v_mfma_f32_16x16x32_bf16 v[108:111], v[156:159], v[196:199], v[108:111]
	v_mfma_f32_16x16x32_bf16 v[104:107], v[164:167], v[196:199], v[104:107]
	v_mfma_f32_16x16x32_bf16 v[92:95], v[156:159], v[204:207], v[92:95]
	v_mfma_f32_16x16x32_bf16 v[88:91], v[164:167], v[204:207], v[88:91]
	v_mfma_f32_16x16x32_bf16 v[76:79], v[156:159], v[212:215], v[76:79]
	v_mfma_f32_16x16x32_bf16 v[72:75], v[164:167], v[212:215], v[72:75]
	v_mfma_f32_16x16x32_bf16 v[116:119], v[168:171], v[184:187], v[116:119]
	v_mfma_f32_16x16x32_bf16 v[112:115], v[176:179], v[184:187], v[112:115]
	v_mfma_f32_16x16x32_bf16 v[100:103], v[168:171], v[192:195], v[100:103]
	v_mfma_f32_16x16x32_bf16 v[96:99], v[176:179], v[192:195], v[96:99]
	v_mfma_f32_16x16x32_bf16 v[84:87], v[168:171], v[200:203], v[84:87]
	v_mfma_f32_16x16x32_bf16 v[80:83], v[176:179], v[200:203], v[80:83]
	v_mfma_f32_16x16x32_bf16 v[68:71], v[168:171], v[208:211], v[68:71]
	v_mfma_f32_16x16x32_bf16 v[64:67], v[176:179], v[208:211], v[64:67]
	v_mfma_f32_16x16x32_bf16 v[116:119], v[172:175], v[188:191], v[116:119]
	v_mfma_f32_16x16x32_bf16 v[112:115], v[180:183], v[188:191], v[112:115]
	v_mfma_f32_16x16x32_bf16 v[100:103], v[172:175], v[196:199], v[100:103]
	v_mfma_f32_16x16x32_bf16 v[96:99], v[180:183], v[196:199], v[96:99]
	v_mfma_f32_16x16x32_bf16 v[84:87], v[172:175], v[204:207], v[84:87]
	v_mfma_f32_16x16x32_bf16 v[80:83], v[180:183], v[204:207], v[80:83]
	v_mfma_f32_16x16x32_bf16 v[68:71], v[172:175], v[212:215], v[68:71]
	v_mfma_f32_16x16x32_bf16 v[64:67], v[180:183], v[212:215], v[64:67]
	s_setprio 0
	s_barrier
	s_add_i32 s24, s49, s40
	v_lshl_add_u64 v[148:149], s[28:29], 0, v[130:131]
	s_mov_b32 m0, s24
	ds_read_b128 v[184:187], v155 offset:16384
	ds_read_b128 v[188:191], v155 offset:17408
	ds_read_b128 v[192:195], v155 offset:18432
	ds_read_b128 v[196:199], v155 offset:19456
	ds_read_b128 v[200:203], v155 offset:20480
	ds_read_b128 v[204:207], v155 offset:21504
	ds_read_b128 v[208:211], v155 offset:22528
	ds_read_b128 v[212:215], v155 offset:23552
	global_load_lds_dwordx4 v[148:149], off
	s_add_i32 m0, s24, 0x2000
	s_add_u32 s24, s28, 0xb0000
	v_lshl_add_u64 v[216:217], s[28:29], 0, v[134:135]
	s_addc_u32 s25, s29, 0
	s_add_i32 s52, s50, s40
	global_load_lds_dwordx4 v[216:217], off
	v_lshl_add_u64 v[218:219], s[24:25], 0, v[130:131]
	s_mov_b32 m0, s52
	v_lshl_add_u64 v[220:221], s[30:31], 0, v[132:133]
	global_load_lds_dwordx4 v[218:219], off
	v_lshl_add_u64 v[218:219], s[24:25], 0, v[134:135]
	s_add_i32 m0, s52, 0x2000
	s_nop 0
	global_load_lds_dwordx4 v[218:219], off
	v_lshl_add_u64 v[218:219], s[30:31], 0, v[128:129]
	s_mov_b32 m0, s41
	s_nop 0
	global_load_lds_dwordx4 v[218:219], off
	s_mov_b32 m0, s42
	s_nop 0
	global_load_lds_dwordx4 v[220:221], off
	s_waitcnt vmcnt(8)
	s_waitcnt lgkmcnt(0)
	s_barrier
; #define PG8_STAGE(bufoff, gbase, voff) do { _Pragma("unroll") for (int _i = 0; _i < 2; ++_i) \
;         __builtin_amdgcn_global_load_lds((const unsigned*)((const char*)(gbase) + (voff)[_i]), (PG8_LAS unsigned*)(lds + (bufoff) + ldsw + _i * 8192), 16, 0, 0); } while (0)
; #define PG8_LDA(dst, b, h) do { _Pragma("unroll") for (int m = 0; m < 4; ++m) _Pragma("unroll") for (int k = 0; k < 2; ++k) dst[m][k] = *(const PG8_LAS bf16x8*)(lds + PG8_SA(b, h) + aoff + m * 2048 + k * 1024); } while (0)
; #define PG8_LDB(dst, b, h) do { _Pragma("unroll") for (int n = 0; n < 2; ++n) _Pragma("unroll") for (int k = 0; k < 2; ++k) dst[n][k] = *(const PG8_LAS bf16x8*)(lds + PG8_SB(b, h) + boff + n * 2048 + k * 1024); } while (0)
; #define PG8_MMA(ai, bj, At, Bt) do { __builtin_amdgcn_s_setprio(1); _Pragma("unroll") for (int m = 0; m < 4; ++m) _Pragma("unroll") for (int n = 0; n < 2; ++n) _Pragma("unroll") for (int k = 0; k < 2; ++k) \
;         acc[ai][bj][m][n] = __builtin_amdgcn_mfma_f32_16x16x32_bf16(Bt[n][k], At[m][k], acc[ai][bj][m][n], 0, 0, 0); __builtin_amdgcn_s_setprio(0); } while (0)
; #define PG8_WAIT_V(n) asm volatile("s_waitcnt vmcnt(" #n ")" ::: "memory")
; #define PG8_WAIT_L(n) asm volatile("s_waitcnt lgkmcnt(" #n ")" ::: "memory")
; #define PG8_BAR __builtin_amdgcn_s_barrier()
; #define PG8_SCHED __builtin_amdgcn_sched_barrier(0)
; template <class Epi, class Sched, bool ALIGN_EPI = true, bool SP2 = true>
; __device__ __forceinline__ void gemm_phase(PG8_LAS unsigned char* lds, const Gemm g, const Sched& S, const Epi& E) {
;     ...
;             PG8_WAIT_V(8); PG8_WAIT_L(0); PG8_BAR; PG8_MMA(1, 0, At, B0); PG8_MMA(1, 1, At, B1); PG8_BAR; PG8_SCHED;
;             PG8_LDB(B0, 1, 0); PG8_LDB(B1, 1, 1); PG8_SCHED; PG8_LDA(At, 1, 0); PG8_STAGE(PG8_SA(0, 1), a2 + hstepA, voffA);
;             PG8_WAIT_V(8); PG8_WAIT_L(0); PG8_BAR; PG8_MMA(0, 0, At, B0); PG8_MMA(0, 1, At, B1); PG8_BAR; PG8_SCHED;
	s_setprio 1
	v_mfma_f32_16x16x32_bf16 v[60:63], v[144:147], v[184:187], v[60:63]
	v_mfma_f32_16x16x32_bf16 v[56:59], v[160:163], v[184:187], v[56:59]
	v_mfma_f32_16x16x32_bf16 v[44:47], v[144:147], v[192:195], v[44:47]
	v_mfma_f32_16x16x32_bf16 v[40:43], v[160:163], v[192:195], v[40:43]
	v_mfma_f32_16x16x32_bf16 v[28:31], v[144:147], v[200:203], v[28:31]
	v_mfma_f32_16x16x32_bf16 v[24:27], v[160:163], v[200:203], v[24:27]
	v_mfma_f32_16x16x32_bf16 v[12:15], v[144:147], v[208:211], v[12:15]
	v_mfma_f32_16x16x32_bf16 v[8:11], v[160:163], v[208:211], v[8:11]
	v_mfma_f32_16x16x32_bf16 v[60:63], v[156:159], v[188:191], v[60:63]
	v_mfma_f32_16x16x32_bf16 v[56:59], v[164:167], v[188:191], v[56:59]
	v_mfma_f32_16x16x32_bf16 v[44:47], v[156:159], v[196:199], v[44:47]
	v_mfma_f32_16x16x32_bf16 v[40:43], v[164:167], v[196:199], v[40:43]
	v_mfma_f32_16x16x32_bf16 v[28:31], v[156:159], v[204:207], v[28:31]
	v_mfma_f32_16x16x32_bf16 v[24:27], v[164:167], v[204:207], v[24:27]
	v_mfma_f32_16x16x32_bf16 v[12:15], v[156:159], v[212:215], v[12:15]
	v_mfma_f32_16x16x32_bf16 v[8:11], v[164:167], v[212:215], v[8:11]
	v_mfma_f32_16x16x32_bf16 v[52:55], v[168:171], v[184:187], v[52:55]
	v_mfma_f32_16x16x32_bf16 v[48:51], v[176:179], v[184:187], v[48:51]
	v_mfma_f32_16x16x32_bf16 v[36:39], v[168:171], v[192:195], v[36:39]
	v_mfma_f32_16x16x32_bf16 v[32:35], v[176:179], v[192:195], v[32:35]
	v_mfma_f32_16x16x32_bf16 v[20:23], v[168:171], v[200:203], v[20:23]
	v_mfma_f32_16x16x32_bf16 v[16:19], v[176:179], v[200:203], v[16:19]
	v_mfma_f32_16x16x32_bf16 v[4:7], v[168:171], v[208:211], v[4:7]
	v_mfma_f32_16x16x32_bf16 v[0:3], v[176:179], v[208:211], v[0:3]
	v_mfma_f32_16x16x32_bf16 v[52:55], v[172:175], v[188:191], v[52:55]
	v_mfma_f32_16x16x32_bf16 v[48:51], v[180:183], v[188:191], v[48:51]
	v_mfma_f32_16x16x32_bf16 v[36:39], v[172:175], v[196:199], v[36:39]
	v_mfma_f32_16x16x32_bf16 v[32:35], v[180:183], v[196:199], v[32:35]
	v_mfma_f32_16x16x32_bf16 v[20:23], v[172:175], v[204:207], v[20:23]
	v_mfma_f32_16x16x32_bf16 v[16:19], v[180:183], v[204:207], v[16:19]
	v_mfma_f32_16x16x32_bf16 v[4:7], v[172:175], v[212:215], v[4:7]
	v_mfma_f32_16x16x32_bf16 v[0:3], v[180:183], v[212:215], v[0:3]
	s_setprio 0
	s_barrier
	s_add_i32 s52, 0, 0x18000
	s_add_i32 s53, 0, 0x1c000
	v_add_u32_e32 v164, s52, v151
	v_add_u32_e32 v180, s53, v151
	ds_read_b128 v[144:147], v164
	ds_read_b128 v[156:159], v164 offset:1024
	ds_read_b128 v[160:163], v164 offset:2048
	ds_read_b128 v[164:167], v164 offset:3072
	ds_read_b128 v[168:171], v180
	ds_read_b128 v[172:175], v180 offset:1024
	ds_read_b128 v[176:179], v180 offset:2048
	ds_read_b128 v[180:183], v180 offset:3072
	s_add_u32 s24, s30, 0xb0000
	s_addc_u32 s25, s31, 0
	s_mov_b32 m0, s43
	v_lshl_add_u64 v[222:223], s[24:25], 0, v[128:129]
	ds_read_b128 v[184:187], v155 offset:32768
	ds_read_b128 v[188:191], v155 offset:33792
	ds_read_b128 v[192:195], v155 offset:34816
	ds_read_b128 v[196:199], v155 offset:35840
	ds_read_b128 v[200:203], v155 offset:36864
	ds_read_b128 v[204:207], v155 offset:37888
	ds_read_b128 v[208:211], v155 offset:38912
	ds_read_b128 v[212:215], v155 offset:39936
	global_load_lds_dwordx4 v[222:223], off
	v_lshl_add_u64 v[222:223], s[24:25], 0, v[132:133]
	s_mov_b32 m0, s45
	s_nop 0
	global_load_lds_dwordx4 v[222:223], off
	s_waitcnt vmcnt(8)
	s_waitcnt lgkmcnt(0)
	s_barrier
	s_setprio 1
	v_mfma_f32_16x16x32_bf16 v[124:127], v[144:147], v[184:187], v[124:127]
	v_mfma_f32_16x16x32_bf16 v[120:123], v[160:163], v[184:187], v[120:123]
	v_mfma_f32_16x16x32_bf16 v[108:111], v[144:147], v[192:195], v[108:111]
	v_mfma_f32_16x16x32_bf16 v[104:107], v[160:163], v[192:195], v[104:107]
	v_mfma_f32_16x16x32_bf16 v[92:95], v[144:147], v[200:203], v[92:95]
	v_mfma_f32_16x16x32_bf16 v[88:91], v[160:163], v[200:203], v[88:91]
	v_mfma_f32_16x16x32_bf16 v[76:79], v[144:147], v[208:211], v[76:79]
	v_mfma_f32_16x16x32_bf16 v[72:75], v[160:163], v[208:211], v[72:75]
	v_mfma_f32_16x16x32_bf16 v[124:127], v[156:159], v[188:191], v[124:127]
	v_mfma_f32_16x16x32_bf16 v[120:123], v[164:167], v[188:191], v[120:123]
	v_mfma_f32_16x16x32_bf16 v[108:111], v[156:159], v[196:199], v[108:111]
	v_mfma_f32_16x16x32_bf16 v[104:107], v[164:167], v[196:199], v[104:107]
	v_mfma_f32_16x16x32_bf16 v[92:95], v[156:159], v[204:207], v[92:95]
	v_mfma_f32_16x16x32_bf16 v[88:91], v[164:167], v[204:207], v[88:91]
	v_mfma_f32_16x16x32_bf16 v[76:79], v[156:159], v[212:215], v[76:79]
	v_mfma_f32_16x16x32_bf16 v[72:75], v[164:167], v[212:215], v[72:75]
	v_mfma_f32_16x16x32_bf16 v[116:119], v[168:171], v[184:187], v[116:119]
	v_mfma_f32_16x16x32_bf16 v[112:115], v[176:179], v[184:187], v[112:115]
	v_mfma_f32_16x16x32_bf16 v[100:103], v[168:171], v[192:195], v[100:103]
	v_mfma_f32_16x16x32_bf16 v[96:99], v[176:179], v[192:195], v[96:99]
	v_mfma_f32_16x16x32_bf16 v[84:87], v[168:171], v[200:203], v[84:87]
	v_mfma_f32_16x16x32_bf16 v[80:83], v[176:179], v[200:203], v[80:83]
	v_mfma_f32_16x16x32_bf16 v[68:71], v[168:171], v[208:211], v[68:71]
	v_mfma_f32_16x16x32_bf16 v[64:67], v[176:179], v[208:211], v[64:67]
	v_mfma_f32_16x16x32_bf16 v[116:119], v[172:175], v[188:191], v[116:119]
	v_mfma_f32_16x16x32_bf16 v[112:115], v[180:183], v[188:191], v[112:115]
	v_mfma_f32_16x16x32_bf16 v[100:103], v[172:175], v[196:199], v[100:103]
	v_mfma_f32_16x16x32_bf16 v[96:99], v[180:183], v[196:199], v[96:99]
	v_mfma_f32_16x16x32_bf16 v[84:87], v[172:175], v[204:207], v[84:87]
	v_mfma_f32_16x16x32_bf16 v[80:83], v[180:183], v[204:207], v[80:83]
	v_mfma_f32_16x16x32_bf16 v[68:71], v[172:175], v[212:215], v[68:71]
	v_mfma_f32_16x16x32_bf16 v[64:67], v[180:183], v[212:215], v[64:67]
	s_setprio 0
	s_barrier
; #define PG8_STAGE(bufoff, gbase, voff) do { _Pragma("unroll") for (int _i = 0; _i < 2; ++_i) \
;         __builtin_amdgcn_global_load_lds((const unsigned*)((const char*)(gbase) + (voff)[_i]), (PG8_LAS unsigned*)(lds + (bufoff) + ldsw + _i * 8192), 16, 0, 0); } while (0)
; #define PG8_LDA(dst, b, h) do { _Pragma("unroll") for (int m = 0; m < 4; ++m) _Pragma("unroll") for (int k = 0; k < 2; ++k) dst[m][k] = *(const PG8_LAS bf16x8*)(lds + PG8_SA(b, h) + aoff + m * 2048 + k * 1024); } while (0)
; #define PG8_MMA(ai, bj, At, Bt) do { __builtin_amdgcn_s_setprio(1); _Pragma("unroll") for (int m = 0; m < 4; ++m) _Pragma("unroll") for (int n = 0; n < 2; ++n) _Pragma("unroll") for (int k = 0; k < 2; ++k) \
;         acc[ai][bj][m][n] = __builtin_amdgcn_mfma_f32_16x16x32_bf16(Bt[n][k], At[m][k], acc[ai][bj][m][n], 0, 0, 0); __builtin_amdgcn_s_setprio(0); } while (0)
; #define PG8_WAIT_V(n) asm volatile("s_waitcnt vmcnt(" #n ")" ::: "memory")
; #define PG8_WAIT_L(n) asm volatile("s_waitcnt lgkmcnt(" #n ")" ::: "memory")
; #define PG8_BAR __builtin_amdgcn_s_barrier()
; #define PG8_SCHED __builtin_amdgcn_sched_barrier(0)
; template <class Epi, class Sched, bool ALIGN_EPI = true, bool SP2 = true>
; __device__ __forceinline__ void gemm_phase(PG8_LAS unsigned char* lds, const Gemm g, const Sched& S, const Epi& E) {
;     ...
;             PG8_LDA(At, 1, 1); PG8_STAGE(PG8_SB(1, 0), b3, voffB); PG8_STAGE(PG8_SB(1, 1), b3 + hstepB, voffB); PG8_STAGE(PG8_SA(1, 0), a3, voffA);
;             PG8_WAIT_V(8); PG8_WAIT_L(0); PG8_BAR; PG8_MMA(1, 0, At, B0); PG8_MMA(1, 1, At, B1); PG8_BAR; PG8_SCHED;
;         }
	s_add_i32 s24, s52, s40
	v_lshl_add_u64 v[148:149], v[148:149], 0, s[12:13]
	s_mov_b32 m0, s24
	ds_read_b128 v[184:187], v155 offset:49152
	ds_read_b128 v[188:191], v155 offset:50176
	ds_read_b128 v[192:195], v155 offset:51200
	ds_read_b128 v[196:199], v155 offset:52224
	ds_read_b128 v[200:203], v155 offset:53248
	ds_read_b128 v[204:207], v155 offset:54272
	ds_read_b128 v[208:211], v155 offset:55296
	ds_read_b128 v[212:215], v155 offset:56320
	global_load_lds_dwordx4 v[148:149], off
	s_add_i32 m0, s24, 0x2000
	s_add_u32 s24, s28, 0xb0080
	v_lshl_add_u64 v[148:149], v[216:217], 0, s[12:13]
	s_addc_u32 s25, s29, 0
	s_add_i32 s28, s53, s40
	global_load_lds_dwordx4 v[148:149], off
	v_lshl_add_u64 v[148:149], s[24:25], 0, v[130:131]
	s_mov_b32 m0, s28
	s_nop 0
	global_load_lds_dwordx4 v[148:149], off
	v_lshl_add_u64 v[148:149], s[24:25], 0, v[134:135]
	s_add_i32 m0, s28, 0x2000
	s_nop 0
	global_load_lds_dwordx4 v[148:149], off
	v_lshl_add_u64 v[148:149], v[218:219], 0, s[12:13]
	s_mov_b32 m0, s47
	s_nop 0
	global_load_lds_dwordx4 v[148:149], off
	v_lshl_add_u64 v[148:149], v[220:221], 0, s[12:13]
	s_mov_b32 m0, s48
	s_nop 0
	global_load_lds_dwordx4 v[148:149], off
	s_waitcnt vmcnt(8)
	s_waitcnt lgkmcnt(0)
	s_barrier
	s_setprio 1
	v_mfma_f32_16x16x32_bf16 v[60:63], v[144:147], v[184:187], v[60:63]
	v_mfma_f32_16x16x32_bf16 v[56:59], v[160:163], v[184:187], v[56:59]
	v_mfma_f32_16x16x32_bf16 v[44:47], v[144:147], v[192:195], v[44:47]
	v_mfma_f32_16x16x32_bf16 v[40:43], v[160:163], v[192:195], v[40:43]
	v_mfma_f32_16x16x32_bf16 v[28:31], v[144:147], v[200:203], v[28:31]
	v_mfma_f32_16x16x32_bf16 v[24:27], v[160:163], v[200:203], v[24:27]
	v_mfma_f32_16x16x32_bf16 v[12:15], v[144:147], v[208:211], v[12:15]
	v_mfma_f32_16x16x32_bf16 v[8:11], v[160:163], v[208:211], v[8:11]
	v_mfma_f32_16x16x32_bf16 v[60:63], v[156:159], v[188:191], v[60:63]
	v_mfma_f32_16x16x32_bf16 v[56:59], v[164:167], v[188:191], v[56:59]
	v_mfma_f32_16x16x32_bf16 v[44:47], v[156:159], v[196:199], v[44:47]
	v_mfma_f32_16x16x32_bf16 v[40:43], v[164:167], v[196:199], v[40:43]
	v_mfma_f32_16x16x32_bf16 v[28:31], v[156:159], v[204:207], v[28:31]
	v_mfma_f32_16x16x32_bf16 v[24:27], v[164:167], v[204:207], v[24:27]
	v_mfma_f32_16x16x32_bf16 v[12:15], v[156:159], v[212:215], v[12:15]
	v_mfma_f32_16x16x32_bf16 v[8:11], v[164:167], v[212:215], v[8:11]
	v_mfma_f32_16x16x32_bf16 v[52:55], v[168:171], v[184:187], v[52:55]
	v_mfma_f32_16x16x32_bf16 v[48:51], v[176:179], v[184:187], v[48:51]
	v_mfma_f32_16x16x32_bf16 v[36:39], v[168:171], v[192:195], v[36:39]
	v_mfma_f32_16x16x32_bf16 v[32:35], v[176:179], v[192:195], v[32:35]
	v_mfma_f32_16x16x32_bf16 v[20:23], v[168:171], v[200:203], v[20:23]
	v_mfma_f32_16x16x32_bf16 v[16:19], v[176:179], v[200:203], v[16:19]
	v_mfma_f32_16x16x32_bf16 v[4:7], v[168:171], v[208:211], v[4:7]
	v_mfma_f32_16x16x32_bf16 v[0:3], v[176:179], v[208:211], v[0:3]
	v_mfma_f32_16x16x32_bf16 v[52:55], v[172:175], v[188:191], v[52:55]
	v_mfma_f32_16x16x32_bf16 v[48:51], v[180:183], v[188:191], v[48:51]
	v_mfma_f32_16x16x32_bf16 v[36:39], v[172:175], v[196:199], v[36:39]
	v_mfma_f32_16x16x32_bf16 v[32:35], v[180:183], v[196:199], v[32:35]
	v_mfma_f32_16x16x32_bf16 v[20:23], v[172:175], v[204:207], v[20:23]
	v_mfma_f32_16x16x32_bf16 v[16:19], v[180:183], v[204:207], v[16:19]
	v_mfma_f32_16x16x32_bf16 v[4:7], v[172:175], v[212:215], v[4:7]
	v_mfma_f32_16x16x32_bf16 v[0:3], v[180:183], v[212:215], v[0:3]
	s_setprio 0
	s_barrier
	s_add_i32 s63, s63, 2
	s_add_u32 s61, s61, 0x100
	s_addc_u32 s62, s62, 0
	s_cmp_gt_u32 s63, 41
	s_mov_b64 s[24:25], s[26:27]
	s_cbranch_scc0 .LBB0_1620
	s_and_b64 vcc, exec, s[14:15]
	s_cbranch_vccz .LBB0_1623
	s_barrier

; #define PG8_STAGE(bufoff, gbase, voff) do { _Pragma("unroll") for (int _i = 0; _i < 2; ++_i) \
;         __builtin_amdgcn_global_load_lds((const unsigned*)((const char*)(gbase) + (voff)[_i]), (PG8_LAS unsigned*)(lds + (bufoff) + ldsw + _i * 8192), 16, 0, 0); } while (0)
; #define PG8_LDA(dst, b, h) do { _Pragma("unroll") for (int m = 0; m < 4; ++m) _Pragma("unroll") for (int k = 0; k < 2; ++k) dst[m][k] = *(const PG8_LAS bf16x8*)(lds + PG8_SA(b, h) + aoff + m * 2048 + k * 1024); } while (0)
; #define PG8_LDB(dst, b, h) do { _Pragma("unroll") for (int n = 0; n < 2; ++n) _Pragma("unroll") for (int k = 0; k < 2; ++k) dst[n][k] = *(const PG8_LAS bf16x8*)(lds + PG8_SB(b, h) + boff + n * 2048 + k * 1024); } while (0)
; #define PG8_MMA(ai, bj, At, Bt) do { __builtin_amdgcn_s_setprio(1); _Pragma("unroll") for (int m = 0; m < 4; ++m) _Pragma("unroll") for (int n = 0; n < 2; ++n) _Pragma("unroll") for (int k = 0; k < 2; ++k) \
;         acc[ai][bj][m][n] = __builtin_amdgcn_mfma_f32_16x16x32_bf16(Bt[n][k], At[m][k], acc[ai][bj][m][n], 0, 0, 0); __builtin_amdgcn_s_setprio(0); } while (0)
; #define PG8_WAIT_V(n) asm volatile("s_waitcnt vmcnt(" #n ")" ::: "memory")
; #define PG8_WAIT_L(n) asm volatile("s_waitcnt lgkmcnt(" #n ")" ::: "memory")
; #define PG8_BAR __builtin_amdgcn_s_barrier()
; #define PG8_SCHED __builtin_amdgcn_sched_barrier(0)
; template <class Epi, class Sched, bool ALIGN_EPI = true, bool SP2 = true>
; __device__ __forceinline__ void gemm_phase(PG8_LAS unsigned char* lds, const Gemm g, const Sched& S, const Epi& E) {
;     ...
;             PG8_LDB(B0, 0, 0); PG8_LDB(B1, 0, 1); PG8_SCHED; PG8_LDA(At, 0, 0); PG8_STAGE(PG8_SA(1, 1), a1 + hstepA, voffA);
;             PG8_WAIT_V(8); PG8_WAIT_L(0); PG8_BAR; PG8_MMA(0, 0, At, B0); PG8_MMA(0, 1, At, B1); PG8_BAR; PG8_SCHED;
;             PG8_LDA(At, 0, 1); PG8_STAGE(PG8_SB(0, 0), b2, voffB); PG8_STAGE(PG8_SB(0, 1), b2 + hstepB, voffB); PG8_STAGE(PG8_SA(0, 0), a2, voffA);
;             PG8_WAIT_V(8); PG8_WAIT_L(0); PG8_BAR; PG8_MMA(1, 0, At, B0); PG8_MMA(1, 1, At, B1); PG8_BAR; PG8_SCHED;
.LBB0_1690:
	ds_read_b128 v[44:47], v227
	ds_read_b128 v[48:51], v227 offset:1024
	ds_read_b128 v[52:55], v227 offset:2048
	ds_read_b128 v[60:63], v227 offset:3072
	ds_read_b128 v[64:67], v228
	ds_read_b128 v[68:71], v228 offset:1024
	ds_read_b128 v[72:75], v228 offset:2048
	ds_read_b128 v[76:79], v228 offset:3072
	s_add_u32 s52, s50, 0xfffc0080
	s_addc_u32 s53, s51, -1
	s_cmp_eq_u32 s79, 12
	s_cselect_b32 s57, s3, s53
	s_cselect_b32 s56, s41, s52
	s_cselect_b32 s55, s39, s78
	s_cselect_b32 s54, s49, s77
	v_lshl_add_u64 v[192:193], s[50:51], 0, v[220:221]
	s_add_i32 m0, s61, 0xc000
	ds_read_b128 v[80:83], v229
	ds_read_b128 v[84:87], v229 offset:1024
	ds_read_b128 v[88:91], v229 offset:2048
	ds_read_b128 v[92:95], v229 offset:3072
	ds_read_b128 v[96:99], v229 offset:4096
	ds_read_b128 v[100:103], v229 offset:5120
	ds_read_b128 v[104:107], v229 offset:6144
	ds_read_b128 v[108:111], v229 offset:7168
	global_load_lds_dwordx4 v[192:193], off
	v_lshl_add_u64 v[192:193], s[50:51], 0, v[218:219]
	s_add_i32 m0, s61, 0xe000
	s_nop 0
	global_load_lds_dwordx4 v[192:193], off
	s_waitcnt vmcnt(8)
	s_waitcnt lgkmcnt(0)
	s_barrier
	s_setprio 1
	v_mfma_f32_16x16x32_bf16 v[188:191], v[44:47], v[80:83], v[188:191]
	v_mfma_f32_16x16x32_bf16 v[180:183], v[52:55], v[80:83], v[180:183]
	v_mfma_f32_16x16x32_bf16 v[172:175], v[44:47], v[88:91], v[172:175]
	v_mfma_f32_16x16x32_bf16 v[164:167], v[52:55], v[88:91], v[164:167]
	v_mfma_f32_16x16x32_bf16 v[156:159], v[44:47], v[96:99], v[156:159]
	v_mfma_f32_16x16x32_bf16 v[148:151], v[52:55], v[96:99], v[148:151]
	v_mfma_f32_16x16x32_bf16 v[140:143], v[44:47], v[104:107], v[140:143]
	v_mfma_f32_16x16x32_bf16 v[132:135], v[52:55], v[104:107], v[132:135]
	v_mfma_f32_16x16x32_bf16 v[188:191], v[48:51], v[84:87], v[188:191]
	v_mfma_f32_16x16x32_bf16 v[180:183], v[60:63], v[84:87], v[180:183]
	v_mfma_f32_16x16x32_bf16 v[172:175], v[48:51], v[92:95], v[172:175]
	v_mfma_f32_16x16x32_bf16 v[164:167], v[60:63], v[92:95], v[164:167]
	v_mfma_f32_16x16x32_bf16 v[156:159], v[48:51], v[100:103], v[156:159]
	v_mfma_f32_16x16x32_bf16 v[148:151], v[60:63], v[100:103], v[148:151]
	v_mfma_f32_16x16x32_bf16 v[140:143], v[48:51], v[108:111], v[140:143]
	v_mfma_f32_16x16x32_bf16 v[132:135], v[60:63], v[108:111], v[132:135]
	v_mfma_f32_16x16x32_bf16 v[184:187], v[64:67], v[80:83], v[184:187]
	v_mfma_f32_16x16x32_bf16 v[80:83], v[72:75], v[80:83], v[176:179]
	v_mfma_f32_16x16x32_bf16 v[184:187], v[68:71], v[84:87], v[184:187]
	v_mfma_f32_16x16x32_bf16 v[80:83], v[76:79], v[84:87], v[80:83]
	v_mfma_f32_16x16x32_bf16 v[84:87], v[64:67], v[88:91], v[168:171]
	v_mfma_f32_16x16x32_bf16 v[88:91], v[72:75], v[88:91], v[160:163]
	v_mfma_f32_16x16x32_bf16 v[84:87], v[68:71], v[92:95], v[84:87]
	v_mfma_f32_16x16x32_bf16 v[88:91], v[76:79], v[92:95], v[88:91]
	v_mfma_f32_16x16x32_bf16 v[92:95], v[64:67], v[96:99], v[152:155]
	v_mfma_f32_16x16x32_bf16 v[96:99], v[72:75], v[96:99], v[144:147]
	v_mfma_f32_16x16x32_bf16 v[92:95], v[68:71], v[100:103], v[92:95]
	v_mfma_f32_16x16x32_bf16 v[96:99], v[76:79], v[100:103], v[96:99]
	v_mfma_f32_16x16x32_bf16 v[100:103], v[64:67], v[104:107], v[136:139]
	v_mfma_f32_16x16x32_bf16 v[104:107], v[72:75], v[104:107], v[128:131]
	v_mfma_f32_16x16x32_bf16 v[100:103], v[68:71], v[108:111], v[100:103]
	v_mfma_f32_16x16x32_bf16 v[104:107], v[76:79], v[108:111], v[104:107]
	s_setprio 0
	s_barrier
	s_add_i32 s52, s73, s60
	v_lshl_add_u64 v[208:209], s[54:55], 0, v[212:213]
	s_mov_b32 m0, s52
	ds_read_b128 v[108:111], v229 offset:16384
	ds_read_b128 v[128:131], v229 offset:17408
	ds_read_b128 v[136:139], v229 offset:18432
	ds_read_b128 v[144:147], v229 offset:19456
	ds_read_b128 v[152:155], v229 offset:20480
	ds_read_b128 v[160:163], v229 offset:21504
	ds_read_b128 v[168:171], v229 offset:22528
	ds_read_b128 v[176:179], v229 offset:23552
	global_load_lds_dwordx4 v[208:209], off
	s_add_i32 m0, s52, 0x2000
	s_add_u32 s52, s54, 0x40000
	v_lshl_add_u64 v[222:223], s[54:55], 0, v[216:217]
	s_addc_u32 s53, s55, 0
	s_add_i32 s68, s74, s60
	global_load_lds_dwordx4 v[222:223], off
	v_lshl_add_u64 v[192:193], s[52:53], 0, v[212:213]
	s_mov_b32 m0, s68
	v_lshl_add_u64 v[224:225], s[56:57], 0, v[210:211]
	global_load_lds_dwordx4 v[192:193], off
	v_lshl_add_u64 v[192:193], s[52:53], 0, v[216:217]
	s_add_i32 m0, s68, 0x2000
	v_lshl_add_u64 v[230:231], s[56:57], 0, v[214:215]
	global_load_lds_dwordx4 v[192:193], off
	s_mov_b32 m0, s61
	s_nop 0
	global_load_lds_dwordx4 v[224:225], off
	s_mov_b32 m0, s62
	s_nop 0
	global_load_lds_dwordx4 v[230:231], off
	s_waitcnt vmcnt(8)
	s_waitcnt lgkmcnt(0)
	s_barrier
; #define PG8_STAGE(bufoff, gbase, voff) do { _Pragma("unroll") for (int _i = 0; _i < 2; ++_i) \
;         __builtin_amdgcn_global_load_lds((const unsigned*)((const char*)(gbase) + (voff)[_i]), (PG8_LAS unsigned*)(lds + (bufoff) + ldsw + _i * 8192), 16, 0, 0); } while (0)
; #define PG8_LDA(dst, b, h) do { _Pragma("unroll") for (int m = 0; m < 4; ++m) _Pragma("unroll") for (int k = 0; k < 2; ++k) dst[m][k] = *(const PG8_LAS bf16x8*)(lds + PG8_SA(b, h) + aoff + m * 2048 + k * 1024); } while (0)
; #define PG8_LDB(dst, b, h) do { _Pragma("unroll") for (int n = 0; n < 2; ++n) _Pragma("unroll") for (int k = 0; k < 2; ++k) dst[n][k] = *(const PG8_LAS bf16x8*)(lds + PG8_SB(b, h) + boff + n * 2048 + k * 1024); } while (0)
; #define PG8_MMA(ai, bj, At, Bt) do { __builtin_amdgcn_s_setprio(1); _Pragma("unroll") for (int m = 0; m < 4; ++m) _Pragma("unroll") for (int n = 0; n < 2; ++n) _Pragma("unroll") for (int k = 0; k < 2; ++k) \
;         acc[ai][bj][m][n] = __builtin_amdgcn_mfma_f32_16x16x32_bf16(Bt[n][k], At[m][k], acc[ai][bj][m][n], 0, 0, 0); __builtin_amdgcn_s_setprio(0); } while (0)
; #define PG8_WAIT_V(n) asm volatile("s_waitcnt vmcnt(" #n ")" ::: "memory")
; #define PG8_WAIT_L(n) asm volatile("s_waitcnt lgkmcnt(" #n ")" ::: "memory")
; #define PG8_BAR __builtin_amdgcn_s_barrier()
; #define PG8_SCHED __builtin_amdgcn_sched_barrier(0)
; template <class Epi, class Sched, bool ALIGN_EPI = true, bool SP2 = true>
; __device__ __forceinline__ void gemm_phase(PG8_LAS unsigned char* lds, const Gemm g, const Sched& S, const Epi& E) {
;     ...
;             PG8_WAIT_V(8); PG8_WAIT_L(0); PG8_BAR; PG8_MMA(1, 0, At, B0); PG8_MMA(1, 1, At, B1); PG8_BAR; PG8_SCHED;
;             PG8_LDB(B0, 1, 0); PG8_LDB(B1, 1, 1); PG8_SCHED; PG8_LDA(At, 1, 0); PG8_STAGE(PG8_SA(0, 1), a2 + hstepA, voffA);
;             PG8_WAIT_V(8); PG8_WAIT_L(0); PG8_BAR; PG8_MMA(0, 0, At, B0); PG8_MMA(0, 1, At, B1); PG8_BAR; PG8_SCHED;
	s_setprio 1
	v_mfma_f32_16x16x32_bf16 v[124:127], v[44:47], v[108:111], v[124:127]
	v_mfma_f32_16x16x32_bf16 v[116:119], v[52:55], v[108:111], v[116:119]
	v_mfma_f32_16x16x32_bf16 v[56:59], v[44:47], v[136:139], v[56:59]
	v_mfma_f32_16x16x32_bf16 v[36:39], v[52:55], v[136:139], v[36:39]
	v_mfma_f32_16x16x32_bf16 v[28:31], v[44:47], v[152:155], v[28:31]
	v_mfma_f32_16x16x32_bf16 v[20:23], v[52:55], v[152:155], v[20:23]
	v_mfma_f32_16x16x32_bf16 v[12:15], v[44:47], v[168:171], v[12:15]
	v_mfma_f32_16x16x32_bf16 v[4:7], v[52:55], v[168:171], v[4:7]
	v_mfma_f32_16x16x32_bf16 v[124:127], v[48:51], v[128:131], v[124:127]
	v_mfma_f32_16x16x32_bf16 v[116:119], v[60:63], v[128:131], v[116:119]
	v_mfma_f32_16x16x32_bf16 v[56:59], v[48:51], v[144:147], v[56:59]
	v_mfma_f32_16x16x32_bf16 v[36:39], v[60:63], v[144:147], v[36:39]
	v_mfma_f32_16x16x32_bf16 v[28:31], v[48:51], v[160:163], v[28:31]
	v_mfma_f32_16x16x32_bf16 v[20:23], v[60:63], v[160:163], v[20:23]
	v_mfma_f32_16x16x32_bf16 v[12:15], v[48:51], v[176:179], v[12:15]
	v_mfma_f32_16x16x32_bf16 v[4:7], v[60:63], v[176:179], v[4:7]
	v_mfma_f32_16x16x32_bf16 v[40:43], v[64:67], v[136:139], v[40:43]
	v_mfma_f32_16x16x32_bf16 v[32:35], v[72:75], v[136:139], v[32:35]
	v_mfma_f32_16x16x32_bf16 v[24:27], v[64:67], v[152:155], v[24:27]
	v_mfma_f32_16x16x32_bf16 v[16:19], v[72:75], v[152:155], v[16:19]
	v_mfma_f32_16x16x32_bf16 v[8:11], v[64:67], v[168:171], v[8:11]
	v_mfma_f32_16x16x32_bf16 v[0:3], v[72:75], v[168:171], v[0:3]
	v_mfma_f32_16x16x32_bf16 v[44:47], v[64:67], v[108:111], v[120:123]
	v_mfma_f32_16x16x32_bf16 v[48:51], v[72:75], v[108:111], v[112:115]
	v_mfma_f32_16x16x32_bf16 v[40:43], v[68:71], v[144:147], v[40:43]
	v_mfma_f32_16x16x32_bf16 v[32:35], v[76:79], v[144:147], v[32:35]
	v_mfma_f32_16x16x32_bf16 v[24:27], v[68:71], v[160:163], v[24:27]
	v_mfma_f32_16x16x32_bf16 v[16:19], v[76:79], v[160:163], v[16:19]
	v_mfma_f32_16x16x32_bf16 v[8:11], v[68:71], v[176:179], v[8:11]
	v_mfma_f32_16x16x32_bf16 v[0:3], v[76:79], v[176:179], v[0:3]
	v_mfma_f32_16x16x32_bf16 v[44:47], v[68:71], v[128:131], v[44:47]
	v_mfma_f32_16x16x32_bf16 v[48:51], v[76:79], v[128:131], v[48:51]
	s_setprio 0
	s_barrier
	s_add_i32 s68, 0, 0x18000
	s_add_i32 s69, 0, 0x1c000
	v_add_u32_e32 v68, s68, v226
	v_add_u32_e32 v112, s69, v226
	ds_read_b128 v[52:55], v68
	ds_read_b128 v[60:63], v68 offset:1024
	ds_read_b128 v[64:67], v68 offset:2048
	ds_read_b128 v[68:71], v68 offset:3072
	ds_read_b128 v[72:75], v112
	ds_read_b128 v[76:79], v112 offset:1024
	ds_read_b128 v[108:111], v112 offset:2048
	ds_read_b128 v[192:195], v112 offset:3072
	s_add_u32 s52, s56, 0x40000
	s_addc_u32 s53, s57, 0
	s_mov_b32 m0, s63
	v_lshl_add_u64 v[152:153], s[52:53], 0, v[210:211]
	ds_read_b128 v[112:115], v229 offset:32768
	ds_read_b128 v[120:123], v229 offset:33792
	ds_read_b128 v[128:131], v229 offset:34816
	ds_read_b128 v[136:139], v229 offset:35840
	ds_read_b128 v[144:147], v229 offset:36864
	ds_read_b128 v[196:199], v229 offset:37888
	ds_read_b128 v[200:203], v229 offset:38912
	ds_read_b128 v[204:207], v229 offset:39936
	global_load_lds_dwordx4 v[152:153], off
	v_lshl_add_u64 v[152:153], s[52:53], 0, v[214:215]
	s_mov_b32 m0, s64
	s_nop 0
	global_load_lds_dwordx4 v[152:153], off
	s_waitcnt vmcnt(8)
	s_waitcnt lgkmcnt(0)
	s_barrier
	s_setprio 1
	v_mfma_f32_16x16x32_bf16 v[152:155], v[52:55], v[112:115], v[188:191]
	v_mfma_f32_16x16x32_bf16 v[188:191], v[60:63], v[120:123], v[152:155]
	v_mfma_f32_16x16x32_bf16 v[152:155], v[64:67], v[112:115], v[180:183]
	v_mfma_f32_16x16x32_bf16 v[180:183], v[68:71], v[120:123], v[152:155]
	v_mfma_f32_16x16x32_bf16 v[152:155], v[52:55], v[128:131], v[172:175]
	v_mfma_f32_16x16x32_bf16 v[172:175], v[60:63], v[136:139], v[152:155]
	v_mfma_f32_16x16x32_bf16 v[152:155], v[64:67], v[128:131], v[164:167]
	v_mfma_f32_16x16x32_bf16 v[164:167], v[68:71], v[136:139], v[152:155]
	v_mfma_f32_16x16x32_bf16 v[152:155], v[52:55], v[144:147], v[156:159]
	v_mfma_f32_16x16x32_bf16 v[148:151], v[64:67], v[144:147], v[148:151]
	v_mfma_f32_16x16x32_bf16 v[140:143], v[52:55], v[200:203], v[140:143]
	v_mfma_f32_16x16x32_bf16 v[132:135], v[64:67], v[200:203], v[132:135]
	v_mfma_f32_16x16x32_bf16 v[156:159], v[60:63], v[196:199], v[152:155]
	v_mfma_f32_16x16x32_bf16 v[148:151], v[68:71], v[196:199], v[148:151]
	v_mfma_f32_16x16x32_bf16 v[140:143], v[60:63], v[204:207], v[140:143]
	v_mfma_f32_16x16x32_bf16 v[132:135], v[68:71], v[204:207], v[132:135]
	v_mfma_f32_16x16x32_bf16 v[80:83], v[108:111], v[112:115], v[80:83]
	v_mfma_f32_16x16x32_bf16 v[176:179], v[192:195], v[120:123], v[80:83]
	v_mfma_f32_16x16x32_bf16 v[80:83], v[72:75], v[128:131], v[84:87]
	v_mfma_f32_16x16x32_bf16 v[168:171], v[76:79], v[136:139], v[80:83]
	v_mfma_f32_16x16x32_bf16 v[80:83], v[108:111], v[128:131], v[88:91]
	v_mfma_f32_16x16x32_bf16 v[152:155], v[72:75], v[112:115], v[184:187]
	v_mfma_f32_16x16x32_bf16 v[160:163], v[192:195], v[136:139], v[80:83]
	v_mfma_f32_16x16x32_bf16 v[80:83], v[72:75], v[144:147], v[92:95]
	v_mfma_f32_16x16x32_bf16 v[184:187], v[76:79], v[120:123], v[152:155]
	v_mfma_f32_16x16x32_bf16 v[152:155], v[76:79], v[196:199], v[80:83]
	v_mfma_f32_16x16x32_bf16 v[80:83], v[108:111], v[144:147], v[96:99]
	v_mfma_f32_16x16x32_bf16 v[144:147], v[192:195], v[196:199], v[80:83]
	v_mfma_f32_16x16x32_bf16 v[80:83], v[72:75], v[200:203], v[100:103]
	v_mfma_f32_16x16x32_bf16 v[136:139], v[76:79], v[204:207], v[80:83]
	v_mfma_f32_16x16x32_bf16 v[80:83], v[108:111], v[200:203], v[104:107]
	v_mfma_f32_16x16x32_bf16 v[128:131], v[192:195], v[204:207], v[80:83]
	s_setprio 0
	s_barrier
; #define PG8_STAGE(bufoff, gbase, voff) do { _Pragma("unroll") for (int _i = 0; _i < 2; ++_i) \
;         __builtin_amdgcn_global_load_lds((const unsigned*)((const char*)(gbase) + (voff)[_i]), (PG8_LAS unsigned*)(lds + (bufoff) + ldsw + _i * 8192), 16, 0, 0); } while (0)
; #define PG8_LDA(dst, b, h) do { _Pragma("unroll") for (int m = 0; m < 4; ++m) _Pragma("unroll") for (int k = 0; k < 2; ++k) dst[m][k] = *(const PG8_LAS bf16x8*)(lds + PG8_SA(b, h) + aoff + m * 2048 + k * 1024); } while (0)
; #define PG8_MMA(ai, bj, At, Bt) do { __builtin_amdgcn_s_setprio(1); _Pragma("unroll") for (int m = 0; m < 4; ++m) _Pragma("unroll") for (int n = 0; n < 2; ++n) _Pragma("unroll") for (int k = 0; k < 2; ++k) \
;         acc[ai][bj][m][n] = __builtin_amdgcn_mfma_f32_16x16x32_bf16(Bt[n][k], At[m][k], acc[ai][bj][m][n], 0, 0, 0); __builtin_amdgcn_s_setprio(0); } while (0)
; #define PG8_WAIT_V(n) asm volatile("s_waitcnt vmcnt(" #n ")" ::: "memory")
; #define PG8_WAIT_L(n) asm volatile("s_waitcnt lgkmcnt(" #n ")" ::: "memory")
; #define PG8_BAR __builtin_amdgcn_s_barrier()
; #define PG8_SCHED __builtin_amdgcn_sched_barrier(0)
; template <class Epi, class Sched, bool ALIGN_EPI = true, bool SP2 = true>
; __device__ __forceinline__ void gemm_phase(PG8_LAS unsigned char* lds, const Gemm g, const Sched& S, const Epi& E) {
;     ...
;             PG8_LDA(At, 1, 1); PG8_STAGE(PG8_SB(1, 0), b3, voffB); PG8_STAGE(PG8_SB(1, 1), b3 + hstepB, voffB); PG8_STAGE(PG8_SA(1, 0), a3, voffA);
;             PG8_WAIT_V(8); PG8_WAIT_L(0); PG8_BAR; PG8_MMA(1, 0, At, B0); PG8_MMA(1, 1, At, B1); PG8_BAR; PG8_SCHED;
;         }
	s_add_i32 s52, s68, s60
	v_lshl_add_u64 v[112:113], v[208:209], 0, s[14:15]
	s_mov_b32 m0, s52
	s_nop 1
	ds_read_b128 v[80:83], v229 offset:49152
	ds_read_b128 v[84:87], v229 offset:50176
	ds_read_b128 v[88:91], v229 offset:51200
	ds_read_b128 v[92:95], v229 offset:52224
	ds_read_b128 v[96:99], v229 offset:53248
	ds_read_b128 v[100:103], v229 offset:54272
	ds_read_b128 v[104:107], v229 offset:55296
	ds_read_b128 v[196:199], v229 offset:56320
	global_load_lds_dwordx4 v[112:113], off
	s_add_i32 m0, s52, 0x2000
	s_add_u32 s52, s54, 0x40080
	v_lshl_add_u64 v[112:113], v[222:223], 0, s[14:15]
	s_addc_u32 s53, s55, 0
	s_add_i32 s54, s69, s60
	global_load_lds_dwordx4 v[112:113], off
	v_lshl_add_u64 v[112:113], s[52:53], 0, v[212:213]
	s_mov_b32 m0, s54
	s_nop 0
	global_load_lds_dwordx4 v[112:113], off
	v_lshl_add_u64 v[112:113], s[52:53], 0, v[216:217]
	s_add_i32 m0, s54, 0x2000
	s_nop 0
	global_load_lds_dwordx4 v[112:113], off
	v_lshl_add_u64 v[112:113], v[224:225], 0, s[14:15]
	s_mov_b32 m0, s66
	s_nop 0
	global_load_lds_dwordx4 v[112:113], off
	v_lshl_add_u64 v[112:113], v[230:231], 0, s[14:15]
	s_mov_b32 m0, s71
	s_nop 0
	global_load_lds_dwordx4 v[112:113], off
	s_waitcnt vmcnt(8)
	s_waitcnt lgkmcnt(0)
	s_barrier
	s_setprio 1
	v_mfma_f32_16x16x32_bf16 v[112:115], v[52:55], v[80:83], v[124:127]
	v_mfma_f32_16x16x32_bf16 v[124:127], v[60:63], v[84:87], v[112:115]
	v_mfma_f32_16x16x32_bf16 v[112:115], v[64:67], v[80:83], v[116:119]
	v_mfma_f32_16x16x32_bf16 v[56:59], v[52:55], v[88:91], v[56:59]
	v_mfma_f32_16x16x32_bf16 v[36:39], v[64:67], v[88:91], v[36:39]
	v_mfma_f32_16x16x32_bf16 v[28:31], v[52:55], v[96:99], v[28:31]
	v_mfma_f32_16x16x32_bf16 v[20:23], v[64:67], v[96:99], v[20:23]
	v_mfma_f32_16x16x32_bf16 v[12:15], v[52:55], v[104:107], v[12:15]
	v_mfma_f32_16x16x32_bf16 v[4:7], v[64:67], v[104:107], v[4:7]
	v_mfma_f32_16x16x32_bf16 v[116:119], v[68:71], v[84:87], v[112:115]
	v_mfma_f32_16x16x32_bf16 v[56:59], v[60:63], v[92:95], v[56:59]
	v_mfma_f32_16x16x32_bf16 v[36:39], v[68:71], v[92:95], v[36:39]
	v_mfma_f32_16x16x32_bf16 v[28:31], v[60:63], v[100:103], v[28:31]
	v_mfma_f32_16x16x32_bf16 v[20:23], v[68:71], v[100:103], v[20:23]
	v_mfma_f32_16x16x32_bf16 v[12:15], v[60:63], v[196:199], v[12:15]
	v_mfma_f32_16x16x32_bf16 v[4:7], v[68:71], v[196:199], v[4:7]
	v_mfma_f32_16x16x32_bf16 v[44:47], v[72:75], v[80:83], v[44:47]
	v_mfma_f32_16x16x32_bf16 v[120:123], v[76:79], v[84:87], v[44:47]
	v_mfma_f32_16x16x32_bf16 v[44:47], v[108:111], v[80:83], v[48:51]
	v_mfma_f32_16x16x32_bf16 v[40:43], v[72:75], v[88:91], v[40:43]
	v_mfma_f32_16x16x32_bf16 v[32:35], v[108:111], v[88:91], v[32:35]
	v_mfma_f32_16x16x32_bf16 v[24:27], v[72:75], v[96:99], v[24:27]
	v_mfma_f32_16x16x32_bf16 v[16:19], v[108:111], v[96:99], v[16:19]
	v_mfma_f32_16x16x32_bf16 v[8:11], v[72:75], v[104:107], v[8:11]
	v_mfma_f32_16x16x32_bf16 v[0:3], v[108:111], v[104:107], v[0:3]
	v_mfma_f32_16x16x32_bf16 v[112:115], v[192:195], v[84:87], v[44:47]
	v_mfma_f32_16x16x32_bf16 v[40:43], v[76:79], v[92:95], v[40:43]
	v_mfma_f32_16x16x32_bf16 v[32:35], v[192:195], v[92:95], v[32:35]
	v_mfma_f32_16x16x32_bf16 v[24:27], v[76:79], v[100:103], v[24:27]
	v_mfma_f32_16x16x32_bf16 v[16:19], v[192:195], v[100:103], v[16:19]
	v_mfma_f32_16x16x32_bf16 v[8:11], v[76:79], v[196:199], v[8:11]
	v_mfma_f32_16x16x32_bf16 v[0:3], v[192:195], v[196:199], v[0:3]
	s_setprio 0
	s_barrier
	s_add_i32 s79, s79, 2
	s_add_u32 s77, s77, 0x100
	s_addc_u32 s78, s78, 0
	s_add_u32 s50, s50, 0x100
	s_addc_u32 s51, s51, 0
	s_cmp_gt_u32 s79, 13
	s_cbranch_scc0 .LBB0_1690
	s_and_b64 vcc, exec, s[16:17]
	s_cbranch_vccz .LBB0_1693
	s_barrier

; #define PG8_STAGE(bufoff, gbase, voff) do { _Pragma("unroll") for (int _i = 0; _i < 2; ++_i) \
;         __builtin_amdgcn_global_load_lds((const unsigned*)((const char*)(gbase) + (voff)[_i]), (PG8_LAS unsigned*)(lds + (bufoff) + ldsw + _i * 8192), 16, 0, 0); } while (0)
; #define PG8_LDA(dst, b, h) do { _Pragma("unroll") for (int m = 0; m < 4; ++m) _Pragma("unroll") for (int k = 0; k < 2; ++k) dst[m][k] = *(const PG8_LAS bf16x8*)(lds + PG8_SA(b, h) + aoff + m * 2048 + k * 1024); } while (0)
; #define PG8_LDB(dst, b, h) do { _Pragma("unroll") for (int n = 0; n < 2; ++n) _Pragma("unroll") for (int k = 0; k < 2; ++k) dst[n][k] = *(const PG8_LAS bf16x8*)(lds + PG8_SB(b, h) + boff + n * 2048 + k * 1024); } while (0)
; #define PG8_MMA(ai, bj, At, Bt) do { __builtin_amdgcn_s_setprio(1); _Pragma("unroll") for (int m = 0; m < 4; ++m) _Pragma("unroll") for (int n = 0; n < 2; ++n) _Pragma("unroll") for (int k = 0; k < 2; ++k) \
;         acc[ai][bj][m][n] = __builtin_amdgcn_mfma_f32_16x16x32_bf16(Bt[n][k], At[m][k], acc[ai][bj][m][n], 0, 0, 0); __builtin_amdgcn_s_setprio(0); } while (0)
; #define PG8_WAIT_V(n) asm volatile("s_waitcnt vmcnt(" #n ")" ::: "memory")
; #define PG8_WAIT_L(n) asm volatile("s_waitcnt lgkmcnt(" #n ")" ::: "memory")
; #define PG8_BAR __builtin_amdgcn_s_barrier()
; #define PG8_SCHED __builtin_amdgcn_sched_barrier(0)
; template <class Epi, class Sched, bool ALIGN_EPI = true, bool SP2 = true>
; __device__ __forceinline__ void gemm_phase(PG8_LAS unsigned char* lds, const Gemm g, const Sched& S, const Epi& E) {
;     ...
;             const bool last = (t == nt - 2);
;             const char* a1 = cA + (size_t)(t + 1) * kstep;
;             const char* a2 = last ? nA : cA + (size_t)(t + 2) * kstep; const char* b2 = last ? nB : cB + (size_t)(t + 2) * kstep;
;             const char* a3 = a2 + kstep; const char* b3 = b2 + kstep;
;             PG8_LDB(B0, 0, 0); PG8_LDB(B1, 0, 1); PG8_SCHED; PG8_LDA(At, 0, 0); PG8_STAGE(PG8_SA(1, 1), a1 + hstepA, voffA);
;             PG8_WAIT_V(8); PG8_WAIT_L(0); PG8_BAR; PG8_MMA(0, 0, At, B0); PG8_MMA(0, 1, At, B1); PG8_BAR; PG8_SCHED;
;             PG8_LDA(At, 0, 1); PG8_STAGE(PG8_SB(0, 0), b2, voffB); PG8_STAGE(PG8_SB(0, 1), b2 + hstepB, voffB); PG8_STAGE(PG8_SA(0, 0), a2, voffA);
;             PG8_WAIT_V(8); PG8_WAIT_L(0); PG8_BAR; PG8_MMA(1, 0, At, B0); PG8_MMA(1, 1, At, B1); PG8_BAR; PG8_SCHED;
.LBB0_1785:
	s_add_i32 s73, s34, 2
	s_add_u32 s30, s28, 0x100
	s_addc_u32 s31, s29, 0
	s_add_i32 s52, 0, 0x10000
	s_cmp_eq_u32 s62, s34
	s_cselect_b32 s39, s25, s31
	s_cselect_b32 s38, s24, s30
	v_add_u32_e32 v147, s52, v144
	s_cselect_b32 s35, s27, s72
	s_cselect_b32 s34, s26, s71
	s_add_i32 s53, 0, 0x14000
	ds_read_b128 v[148:151], v147
	ds_read_b128 v[152:155], v147 offset:1024
	ds_read_b128 v[156:159], v147 offset:2048
	ds_read_b128 v[160:163], v147 offset:3072
	v_add_u32_e32 v147, s53, v144
	ds_read_b128 v[164:167], v147
	ds_read_b128 v[168:171], v147 offset:1024
	ds_read_b128 v[172:175], v147 offset:2048
	ds_read_b128 v[176:179], v147 offset:3072
	v_lshl_add_u64 v[212:213], s[28:29], 0, v[138:139]
	s_add_i32 m0, s56, 0xc000
	ds_read_b128 v[180:183], v146
	ds_read_b128 v[184:187], v146 offset:1024
	ds_read_b128 v[188:191], v146 offset:2048
	ds_read_b128 v[192:195], v146 offset:3072
	ds_read_b128 v[196:199], v146 offset:4096
	ds_read_b128 v[200:203], v146 offset:5120
	ds_read_b128 v[204:207], v146 offset:6144
	ds_read_b128 v[208:211], v146 offset:7168
	global_load_lds_dwordx4 v[212:213], off
	v_lshl_add_u64 v[212:213], s[28:29], 0, v[136:137]
	s_add_i32 m0, s56, 0xe000
	s_nop 0
	global_load_lds_dwordx4 v[212:213], off
	s_waitcnt vmcnt(8)
	s_waitcnt lgkmcnt(0)
	s_barrier
	s_setprio 1
	v_mfma_f32_16x16x32_bf16 v[124:127], v[148:151], v[180:183], v[124:127]
	v_mfma_f32_16x16x32_bf16 v[120:123], v[156:159], v[180:183], v[120:123]
	v_mfma_f32_16x16x32_bf16 v[116:119], v[148:151], v[188:191], v[116:119]
	v_mfma_f32_16x16x32_bf16 v[112:115], v[156:159], v[188:191], v[112:115]
	v_mfma_f32_16x16x32_bf16 v[100:103], v[148:151], v[196:199], v[100:103]
	v_mfma_f32_16x16x32_bf16 v[96:99], v[156:159], v[196:199], v[96:99]
	v_mfma_f32_16x16x32_bf16 v[84:87], v[148:151], v[204:207], v[84:87]
	v_mfma_f32_16x16x32_bf16 v[80:83], v[156:159], v[204:207], v[80:83]
	v_mfma_f32_16x16x32_bf16 v[124:127], v[152:155], v[184:187], v[124:127]
	v_mfma_f32_16x16x32_bf16 v[120:123], v[160:163], v[184:187], v[120:123]
	v_mfma_f32_16x16x32_bf16 v[116:119], v[152:155], v[192:195], v[116:119]
	v_mfma_f32_16x16x32_bf16 v[112:115], v[160:163], v[192:195], v[112:115]
	v_mfma_f32_16x16x32_bf16 v[100:103], v[152:155], v[200:203], v[100:103]
	v_mfma_f32_16x16x32_bf16 v[96:99], v[160:163], v[200:203], v[96:99]
	v_mfma_f32_16x16x32_bf16 v[84:87], v[152:155], v[208:211], v[84:87]
	v_mfma_f32_16x16x32_bf16 v[80:83], v[160:163], v[208:211], v[80:83]
	v_mfma_f32_16x16x32_bf16 v[108:111], v[164:167], v[180:183], v[108:111]
	v_mfma_f32_16x16x32_bf16 v[104:107], v[172:175], v[180:183], v[104:107]
	v_mfma_f32_16x16x32_bf16 v[92:95], v[164:167], v[188:191], v[92:95]
	v_mfma_f32_16x16x32_bf16 v[88:91], v[172:175], v[188:191], v[88:91]
	v_mfma_f32_16x16x32_bf16 v[76:79], v[164:167], v[196:199], v[76:79]
	v_mfma_f32_16x16x32_bf16 v[72:75], v[172:175], v[196:199], v[72:75]
	v_mfma_f32_16x16x32_bf16 v[68:71], v[164:167], v[204:207], v[68:71]
	v_mfma_f32_16x16x32_bf16 v[64:67], v[172:175], v[204:207], v[64:67]
	v_mfma_f32_16x16x32_bf16 v[108:111], v[168:171], v[184:187], v[108:111]
	v_mfma_f32_16x16x32_bf16 v[104:107], v[176:179], v[184:187], v[104:107]
	v_mfma_f32_16x16x32_bf16 v[92:95], v[168:171], v[192:195], v[92:95]
	v_mfma_f32_16x16x32_bf16 v[88:91], v[176:179], v[192:195], v[88:91]
	v_mfma_f32_16x16x32_bf16 v[76:79], v[168:171], v[200:203], v[76:79]
	v_mfma_f32_16x16x32_bf16 v[72:75], v[176:179], v[200:203], v[72:75]
	v_mfma_f32_16x16x32_bf16 v[68:71], v[168:171], v[208:211], v[68:71]
	v_mfma_f32_16x16x32_bf16 v[64:67], v[176:179], v[208:211], v[64:67]
	s_setprio 0
	s_barrier
	s_add_i32 s28, s52, s54
	v_lshl_add_u64 v[212:213], s[34:35], 0, v[128:129]
	s_mov_b32 m0, s28
	ds_read_b128 v[180:183], v146 offset:16384
	ds_read_b128 v[184:187], v146 offset:17408
	ds_read_b128 v[188:191], v146 offset:18432
	ds_read_b128 v[192:195], v146 offset:19456
	ds_read_b128 v[196:199], v146 offset:20480
	ds_read_b128 v[200:203], v146 offset:21504
	ds_read_b128 v[204:207], v146 offset:22528
	ds_read_b128 v[208:211], v146 offset:23552
	global_load_lds_dwordx4 v[212:213], off
	s_add_i32 m0, s28, 0x2000
	s_add_u32 s28, s34, 0xb0000
	v_lshl_add_u64 v[214:215], s[34:35], 0, v[130:131]
	s_addc_u32 s29, s35, 0
	s_add_i32 s52, s53, s54
	global_load_lds_dwordx4 v[214:215], off
	v_lshl_add_u64 v[216:217], s[28:29], 0, v[128:129]
	s_mov_b32 m0, s52
	v_lshl_add_u64 v[218:219], s[38:39], 0, v[132:133]
	global_load_lds_dwordx4 v[216:217], off
	v_lshl_add_u64 v[216:217], s[28:29], 0, v[130:131]
	s_add_i32 m0, s52, 0x2000
	s_nop 0
	global_load_lds_dwordx4 v[216:217], off
	v_lshl_add_u64 v[216:217], s[38:39], 0, v[134:135]
	s_mov_b32 m0, s56
	s_nop 0
	global_load_lds_dwordx4 v[216:217], off
	s_mov_b32 m0, s57
	s_nop 0
	global_load_lds_dwordx4 v[218:219], off
	s_waitcnt vmcnt(8)
	s_waitcnt lgkmcnt(0)
	s_barrier
; #define PG8_STAGE(bufoff, gbase, voff) do { _Pragma("unroll") for (int _i = 0; _i < 2; ++_i) \
;         __builtin_amdgcn_global_load_lds((const unsigned*)((const char*)(gbase) + (voff)[_i]), (PG8_LAS unsigned*)(lds + (bufoff) + ldsw + _i * 8192), 16, 0, 0); } while (0)
; #define PG8_LDA(dst, b, h) do { _Pragma("unroll") for (int m = 0; m < 4; ++m) _Pragma("unroll") for (int k = 0; k < 2; ++k) dst[m][k] = *(const PG8_LAS bf16x8*)(lds + PG8_SA(b, h) + aoff + m * 2048 + k * 1024); } while (0)
; #define PG8_LDB(dst, b, h) do { _Pragma("unroll") for (int n = 0; n < 2; ++n) _Pragma("unroll") for (int k = 0; k < 2; ++k) dst[n][k] = *(const PG8_LAS bf16x8*)(lds + PG8_SB(b, h) + boff + n * 2048 + k * 1024); } while (0)
; #define PG8_MMA(ai, bj, At, Bt) do { __builtin_amdgcn_s_setprio(1); _Pragma("unroll") for (int m = 0; m < 4; ++m) _Pragma("unroll") for (int n = 0; n < 2; ++n) _Pragma("unroll") for (int k = 0; k < 2; ++k) \
;         acc[ai][bj][m][n] = __builtin_amdgcn_mfma_f32_16x16x32_bf16(Bt[n][k], At[m][k], acc[ai][bj][m][n], 0, 0, 0); __builtin_amdgcn_s_setprio(0); } while (0)
; #define PG8_WAIT_V(n) asm volatile("s_waitcnt vmcnt(" #n ")" ::: "memory")
; #define PG8_WAIT_L(n) asm volatile("s_waitcnt lgkmcnt(" #n ")" ::: "memory")
; #define PG8_BAR __builtin_amdgcn_s_barrier()
; #define PG8_SCHED __builtin_amdgcn_sched_barrier(0)
; template <class Epi, class Sched, bool ALIGN_EPI = true, bool SP2 = true>
; __device__ __forceinline__ void gemm_phase(PG8_LAS unsigned char* lds, const Gemm g, const Sched& S, const Epi& E) {
;     ...
;             PG8_WAIT_V(8); PG8_WAIT_L(0); PG8_BAR; PG8_MMA(1, 0, At, B0); PG8_MMA(1, 1, At, B1); PG8_BAR; PG8_SCHED;
;             PG8_LDB(B0, 1, 0); PG8_LDB(B1, 1, 1); PG8_SCHED; PG8_LDA(At, 1, 0); PG8_STAGE(PG8_SA(0, 1), a2 + hstepA, voffA);
;             PG8_WAIT_V(8); PG8_WAIT_L(0); PG8_BAR; PG8_MMA(0, 0, At, B0); PG8_MMA(0, 1, At, B1); PG8_BAR; PG8_SCHED;
	s_setprio 1
	v_mfma_f32_16x16x32_bf16 v[60:63], v[148:151], v[180:183], v[60:63]
	v_mfma_f32_16x16x32_bf16 v[56:59], v[156:159], v[180:183], v[56:59]
	v_mfma_f32_16x16x32_bf16 v[52:55], v[148:151], v[188:191], v[52:55]
	v_mfma_f32_16x16x32_bf16 v[48:51], v[156:159], v[188:191], v[48:51]
	v_mfma_f32_16x16x32_bf16 v[36:39], v[148:151], v[196:199], v[36:39]
	v_mfma_f32_16x16x32_bf16 v[32:35], v[156:159], v[196:199], v[32:35]
	v_mfma_f32_16x16x32_bf16 v[20:23], v[148:151], v[204:207], v[20:23]
	v_mfma_f32_16x16x32_bf16 v[16:19], v[156:159], v[204:207], v[16:19]
	v_mfma_f32_16x16x32_bf16 v[60:63], v[152:155], v[184:187], v[60:63]
	v_mfma_f32_16x16x32_bf16 v[56:59], v[160:163], v[184:187], v[56:59]
	v_mfma_f32_16x16x32_bf16 v[52:55], v[152:155], v[192:195], v[52:55]
	v_mfma_f32_16x16x32_bf16 v[48:51], v[160:163], v[192:195], v[48:51]
	v_mfma_f32_16x16x32_bf16 v[36:39], v[152:155], v[200:203], v[36:39]
	v_mfma_f32_16x16x32_bf16 v[32:35], v[160:163], v[200:203], v[32:35]
	v_mfma_f32_16x16x32_bf16 v[20:23], v[152:155], v[208:211], v[20:23]
	v_mfma_f32_16x16x32_bf16 v[16:19], v[160:163], v[208:211], v[16:19]
	v_mfma_f32_16x16x32_bf16 v[44:47], v[164:167], v[180:183], v[44:47]
	v_mfma_f32_16x16x32_bf16 v[40:43], v[172:175], v[180:183], v[40:43]
	v_mfma_f32_16x16x32_bf16 v[28:31], v[164:167], v[188:191], v[28:31]
	v_mfma_f32_16x16x32_bf16 v[24:27], v[172:175], v[188:191], v[24:27]
	v_mfma_f32_16x16x32_bf16 v[12:15], v[164:167], v[196:199], v[12:15]
	v_mfma_f32_16x16x32_bf16 v[8:11], v[172:175], v[196:199], v[8:11]
	v_mfma_f32_16x16x32_bf16 v[4:7], v[164:167], v[204:207], v[4:7]
	v_mfma_f32_16x16x32_bf16 v[0:3], v[172:175], v[204:207], v[0:3]
	v_mfma_f32_16x16x32_bf16 v[44:47], v[168:171], v[184:187], v[44:47]
	v_mfma_f32_16x16x32_bf16 v[40:43], v[176:179], v[184:187], v[40:43]
	v_mfma_f32_16x16x32_bf16 v[28:31], v[168:171], v[192:195], v[28:31]
	v_mfma_f32_16x16x32_bf16 v[24:27], v[176:179], v[192:195], v[24:27]
	v_mfma_f32_16x16x32_bf16 v[12:15], v[168:171], v[200:203], v[12:15]
	v_mfma_f32_16x16x32_bf16 v[8:11], v[176:179], v[200:203], v[8:11]
	v_mfma_f32_16x16x32_bf16 v[4:7], v[168:171], v[208:211], v[4:7]
	v_mfma_f32_16x16x32_bf16 v[0:3], v[176:179], v[208:211], v[0:3]
	s_setprio 0
	s_barrier
	s_add_i32 s52, 0, 0x18000
	v_add_u32_e32 v147, s52, v144
	s_add_i32 s53, 0, 0x1c000
	ds_read_b128 v[148:151], v147
	ds_read_b128 v[152:155], v147 offset:1024
	ds_read_b128 v[156:159], v147 offset:2048
	ds_read_b128 v[160:163], v147 offset:3072
	v_add_u32_e32 v147, s53, v144
	ds_read_b128 v[164:167], v147
	ds_read_b128 v[168:171], v147 offset:1024
	ds_read_b128 v[172:175], v147 offset:2048
	ds_read_b128 v[176:179], v147 offset:3072
	s_add_u32 s28, s38, 0xb0000
	s_addc_u32 s29, s39, 0
	s_mov_b32 m0, s58
	v_lshl_add_u64 v[220:221], s[28:29], 0, v[134:135]
	ds_read_b128 v[180:183], v146 offset:32768
	ds_read_b128 v[184:187], v146 offset:33792
	ds_read_b128 v[188:191], v146 offset:34816
	ds_read_b128 v[192:195], v146 offset:35840
	ds_read_b128 v[196:199], v146 offset:36864
	ds_read_b128 v[200:203], v146 offset:37888
	ds_read_b128 v[204:207], v146 offset:38912
	ds_read_b128 v[208:211], v146 offset:39936
	global_load_lds_dwordx4 v[220:221], off
	v_lshl_add_u64 v[220:221], s[28:29], 0, v[132:133]
	s_mov_b32 m0, s59
	s_nop 0
	global_load_lds_dwordx4 v[220:221], off
	s_waitcnt vmcnt(8)
	s_waitcnt lgkmcnt(0)
	s_barrier
	s_setprio 1
	v_mfma_f32_16x16x32_bf16 v[124:127], v[148:151], v[180:183], v[124:127]
	v_mfma_f32_16x16x32_bf16 v[120:123], v[156:159], v[180:183], v[120:123]
	v_mfma_f32_16x16x32_bf16 v[116:119], v[148:151], v[188:191], v[116:119]
	v_mfma_f32_16x16x32_bf16 v[112:115], v[156:159], v[188:191], v[112:115]
	v_mfma_f32_16x16x32_bf16 v[100:103], v[148:151], v[196:199], v[100:103]
	v_mfma_f32_16x16x32_bf16 v[96:99], v[156:159], v[196:199], v[96:99]
	v_mfma_f32_16x16x32_bf16 v[84:87], v[148:151], v[204:207], v[84:87]
	v_mfma_f32_16x16x32_bf16 v[80:83], v[156:159], v[204:207], v[80:83]
	v_mfma_f32_16x16x32_bf16 v[124:127], v[152:155], v[184:187], v[124:127]
	v_mfma_f32_16x16x32_bf16 v[120:123], v[160:163], v[184:187], v[120:123]
	v_mfma_f32_16x16x32_bf16 v[116:119], v[152:155], v[192:195], v[116:119]
	v_mfma_f32_16x16x32_bf16 v[112:115], v[160:163], v[192:195], v[112:115]
	v_mfma_f32_16x16x32_bf16 v[100:103], v[152:155], v[200:203], v[100:103]
	v_mfma_f32_16x16x32_bf16 v[96:99], v[160:163], v[200:203], v[96:99]
	v_mfma_f32_16x16x32_bf16 v[84:87], v[152:155], v[208:211], v[84:87]
	v_mfma_f32_16x16x32_bf16 v[80:83], v[160:163], v[208:211], v[80:83]
	v_mfma_f32_16x16x32_bf16 v[108:111], v[164:167], v[180:183], v[108:111]
	v_mfma_f32_16x16x32_bf16 v[104:107], v[172:175], v[180:183], v[104:107]
	v_mfma_f32_16x16x32_bf16 v[92:95], v[164:167], v[188:191], v[92:95]
	v_mfma_f32_16x16x32_bf16 v[88:91], v[172:175], v[188:191], v[88:91]
	v_mfma_f32_16x16x32_bf16 v[76:79], v[164:167], v[196:199], v[76:79]
	v_mfma_f32_16x16x32_bf16 v[72:75], v[172:175], v[196:199], v[72:75]
	v_mfma_f32_16x16x32_bf16 v[68:71], v[164:167], v[204:207], v[68:71]
	v_mfma_f32_16x16x32_bf16 v[64:67], v[172:175], v[204:207], v[64:67]
	v_mfma_f32_16x16x32_bf16 v[108:111], v[168:171], v[184:187], v[108:111]
	v_mfma_f32_16x16x32_bf16 v[104:107], v[176:179], v[184:187], v[104:107]
	v_mfma_f32_16x16x32_bf16 v[92:95], v[168:171], v[192:195], v[92:95]
	v_mfma_f32_16x16x32_bf16 v[88:91], v[176:179], v[192:195], v[88:91]
	v_mfma_f32_16x16x32_bf16 v[76:79], v[168:171], v[200:203], v[76:79]
	v_mfma_f32_16x16x32_bf16 v[72:75], v[176:179], v[200:203], v[72:75]
	v_mfma_f32_16x16x32_bf16 v[68:71], v[168:171], v[208:211], v[68:71]
	v_mfma_f32_16x16x32_bf16 v[64:67], v[176:179], v[208:211], v[64:67]
	s_setprio 0
	s_barrier
; #define PG8_STAGE(bufoff, gbase, voff) do { _Pragma("unroll") for (int _i = 0; _i < 2; ++_i) \
;         __builtin_amdgcn_global_load_lds((const unsigned*)((const char*)(gbase) + (voff)[_i]), (PG8_LAS unsigned*)(lds + (bufoff) + ldsw + _i * 8192), 16, 0, 0); } while (0)
; #define PG8_LDA(dst, b, h) do { _Pragma("unroll") for (int m = 0; m < 4; ++m) _Pragma("unroll") for (int k = 0; k < 2; ++k) dst[m][k] = *(const PG8_LAS bf16x8*)(lds + PG8_SA(b, h) + aoff + m * 2048 + k * 1024); } while (0)
; #define PG8_MMA(ai, bj, At, Bt) do { __builtin_amdgcn_s_setprio(1); _Pragma("unroll") for (int m = 0; m < 4; ++m) _Pragma("unroll") for (int n = 0; n < 2; ++n) _Pragma("unroll") for (int k = 0; k < 2; ++k) \
;         acc[ai][bj][m][n] = __builtin_amdgcn_mfma_f32_16x16x32_bf16(Bt[n][k], At[m][k], acc[ai][bj][m][n], 0, 0, 0); __builtin_amdgcn_s_setprio(0); } while (0)
; #define PG8_WAIT_V(n) asm volatile("s_waitcnt vmcnt(" #n ")" ::: "memory")
; #define PG8_WAIT_L(n) asm volatile("s_waitcnt lgkmcnt(" #n ")" ::: "memory")
; #define PG8_BAR __builtin_amdgcn_s_barrier()
; #define PG8_SCHED __builtin_amdgcn_sched_barrier(0)
; template <class Epi, class Sched, bool ALIGN_EPI = true, bool SP2 = true>
; __device__ __forceinline__ void gemm_phase(PG8_LAS unsigned char* lds, const Gemm g, const Sched& S, const Epi& E) {
;     ...
;             PG8_LDA(At, 1, 1); PG8_STAGE(PG8_SB(1, 0), b3, voffB); PG8_STAGE(PG8_SB(1, 1), b3 + hstepB, voffB); PG8_STAGE(PG8_SA(1, 0), a3, voffA);
;             PG8_WAIT_V(8); PG8_WAIT_L(0); PG8_BAR; PG8_MMA(1, 0, At, B0); PG8_MMA(1, 1, At, B1); PG8_BAR; PG8_SCHED;
;         }
	s_add_i32 s28, s52, s54
	v_lshl_add_u64 v[212:213], v[212:213], 0, s[8:9]
	s_mov_b32 m0, s28
	ds_read_b128 v[180:183], v146 offset:49152
	ds_read_b128 v[184:187], v146 offset:50176
	ds_read_b128 v[188:191], v146 offset:51200
	ds_read_b128 v[192:195], v146 offset:52224
	ds_read_b128 v[196:199], v146 offset:53248
	ds_read_b128 v[200:203], v146 offset:54272
	ds_read_b128 v[204:207], v146 offset:55296
	ds_read_b128 v[208:211], v146 offset:56320
	global_load_lds_dwordx4 v[212:213], off
	s_add_i32 m0, s28, 0x2000
	s_add_u32 s28, s34, 0xb0080
	v_lshl_add_u64 v[212:213], v[214:215], 0, s[8:9]
	s_addc_u32 s29, s35, 0
	s_add_i32 s34, s53, s54
	global_load_lds_dwordx4 v[212:213], off
	v_lshl_add_u64 v[212:213], s[28:29], 0, v[128:129]
	s_mov_b32 m0, s34
	s_nop 0
	global_load_lds_dwordx4 v[212:213], off
	v_lshl_add_u64 v[212:213], s[28:29], 0, v[130:131]
	s_add_i32 m0, s34, 0x2000
	s_nop 0
	global_load_lds_dwordx4 v[212:213], off
	v_lshl_add_u64 v[212:213], v[216:217], 0, s[8:9]
	s_mov_b32 m0, s60
	s_nop 0
	global_load_lds_dwordx4 v[212:213], off
	v_lshl_add_u64 v[212:213], v[218:219], 0, s[8:9]
	s_mov_b32 m0, s61
	s_nop 0
	global_load_lds_dwordx4 v[212:213], off
	s_waitcnt vmcnt(8)
	s_waitcnt lgkmcnt(0)
	s_barrier
	s_setprio 1
	v_mfma_f32_16x16x32_bf16 v[60:63], v[148:151], v[180:183], v[60:63]
	v_mfma_f32_16x16x32_bf16 v[56:59], v[156:159], v[180:183], v[56:59]
	v_mfma_f32_16x16x32_bf16 v[52:55], v[148:151], v[188:191], v[52:55]
	v_mfma_f32_16x16x32_bf16 v[48:51], v[156:159], v[188:191], v[48:51]
	v_mfma_f32_16x16x32_bf16 v[36:39], v[148:151], v[196:199], v[36:39]
	v_mfma_f32_16x16x32_bf16 v[32:35], v[156:159], v[196:199], v[32:35]
	v_mfma_f32_16x16x32_bf16 v[20:23], v[148:151], v[204:207], v[20:23]
	v_mfma_f32_16x16x32_bf16 v[16:19], v[156:159], v[204:207], v[16:19]
	v_mfma_f32_16x16x32_bf16 v[60:63], v[152:155], v[184:187], v[60:63]
	v_mfma_f32_16x16x32_bf16 v[56:59], v[160:163], v[184:187], v[56:59]
	v_mfma_f32_16x16x32_bf16 v[52:55], v[152:155], v[192:195], v[52:55]
	v_mfma_f32_16x16x32_bf16 v[48:51], v[160:163], v[192:195], v[48:51]
	v_mfma_f32_16x16x32_bf16 v[36:39], v[152:155], v[200:203], v[36:39]
	v_mfma_f32_16x16x32_bf16 v[32:35], v[160:163], v[200:203], v[32:35]
	v_mfma_f32_16x16x32_bf16 v[20:23], v[152:155], v[208:211], v[20:23]
	v_mfma_f32_16x16x32_bf16 v[16:19], v[160:163], v[208:211], v[16:19]
	v_mfma_f32_16x16x32_bf16 v[44:47], v[164:167], v[180:183], v[44:47]
	v_mfma_f32_16x16x32_bf16 v[40:43], v[172:175], v[180:183], v[40:43]
	v_mfma_f32_16x16x32_bf16 v[28:31], v[164:167], v[188:191], v[28:31]
	v_mfma_f32_16x16x32_bf16 v[24:27], v[172:175], v[188:191], v[24:27]
	v_mfma_f32_16x16x32_bf16 v[12:15], v[164:167], v[196:199], v[12:15]
	v_mfma_f32_16x16x32_bf16 v[8:11], v[172:175], v[196:199], v[8:11]
	v_mfma_f32_16x16x32_bf16 v[4:7], v[164:167], v[204:207], v[4:7]
	v_mfma_f32_16x16x32_bf16 v[0:3], v[172:175], v[204:207], v[0:3]
	v_mfma_f32_16x16x32_bf16 v[44:47], v[168:171], v[184:187], v[44:47]
	v_mfma_f32_16x16x32_bf16 v[40:43], v[176:179], v[184:187], v[40:43]
	v_mfma_f32_16x16x32_bf16 v[28:31], v[168:171], v[192:195], v[28:31]
	v_mfma_f32_16x16x32_bf16 v[24:27], v[176:179], v[192:195], v[24:27]
	v_mfma_f32_16x16x32_bf16 v[12:15], v[168:171], v[200:203], v[12:15]
	v_mfma_f32_16x16x32_bf16 v[8:11], v[176:179], v[200:203], v[8:11]
	v_mfma_f32_16x16x32_bf16 v[4:7], v[168:171], v[208:211], v[4:7]
	v_mfma_f32_16x16x32_bf16 v[0:3], v[176:179], v[208:211], v[0:3]
	s_setprio 0
	s_barrier
	s_add_u32 s71, s71, 0x100
	s_addc_u32 s72, s72, 0
	s_cmp_ge_u32 s73, s47
	s_mov_b64 s[28:29], s[30:31]
	s_mov_b32 s34, s73
	s_cbranch_scc0 .LBB0_1785
	s_and_b64 vcc, exec, s[22:23]
	s_cbranch_vccz .LBB0_1788
	s_barrier
